# v27 + K-loop LDS-DMA loads use scalar-base + 32-bit lane-offset addressing (12 of 16 per two K-tiles), 7 of the 64-bit VALU address adds removed
# speedup vs baseline: 1.0028x; 1.0028x over previous
.Lpeel_13:
	ds_read_b128 v[152:155], v149
	ds_read_b128 v[156:159], v149 offset:1024
	s_add_i32 s37, s25, 2
	s_add_u32 s40, s38, 0xfff80080
	s_addc_u32 s41, s39, -1
	s_cmp_eq_u32 s36, s25
	s_cselect_b32 s43, s27, s41
	s_cselect_b32 s42, s26, s40
	s_cselect_b32 s41, s29, s23
	s_cselect_b32 s40, s28, s21
	s_add_i32 m0, s35, 0xc000
	global_load_lds_dwordx4 v140, s[38:39]
	s_add_i32 m0, s35, 0xe000
	s_nop 0
	global_load_lds_dwordx4 v142, s[38:39]
	s_waitcnt vmcnt(8)
	s_waitcnt lgkmcnt(0)
	s_barrier
	s_setprio 1
	s_waitcnt lgkmcnt(0)
	v_mfma_f32_16x16x32_bf16 v[126:129], v[152:155], v[184:187], 0
	v_mfma_f32_16x16x32_bf16 v[122:125], v[160:163], v[184:187], 0
	v_mfma_f32_16x16x32_bf16 v[110:113], v[152:155], v[196:199], 0
	v_mfma_f32_16x16x32_bf16 v[106:109], v[160:163], v[196:199], 0
	v_mfma_f32_16x16x32_bf16 v[94:97], v[152:155], v[204:207], 0
	v_mfma_f32_16x16x32_bf16 v[90:93], v[160:163], v[204:207], 0
	v_mfma_f32_16x16x32_bf16 v[78:81], v[152:155], v[212:215], 0
	v_mfma_f32_16x16x32_bf16 v[74:77], v[160:163], v[212:215], 0
	v_mfma_f32_16x16x32_bf16 v[126:129], v[156:159], v[188:191], v[126:129]
	v_mfma_f32_16x16x32_bf16 v[122:125], v[164:167], v[188:191], v[122:125]
	v_mfma_f32_16x16x32_bf16 v[110:113], v[156:159], v[200:203], v[110:113]
	v_mfma_f32_16x16x32_bf16 v[106:109], v[164:167], v[200:203], v[106:109]
	v_mfma_f32_16x16x32_bf16 v[94:97], v[156:159], v[208:211], v[94:97]
	v_mfma_f32_16x16x32_bf16 v[90:93], v[164:167], v[208:211], v[90:93]
	v_mfma_f32_16x16x32_bf16 v[78:81], v[156:159], v[216:219], v[78:81]
	v_mfma_f32_16x16x32_bf16 v[74:77], v[164:167], v[216:219], v[74:77]
	s_setprio 0
	s_setprio 1
	v_mfma_f32_16x16x32_bf16 v[118:121], v[168:171], v[184:187], 0
	v_mfma_f32_16x16x32_bf16 v[114:117], v[176:179], v[184:187], 0
	v_mfma_f32_16x16x32_bf16 v[102:105], v[168:171], v[196:199], 0
	v_mfma_f32_16x16x32_bf16 v[98:101], v[176:179], v[196:199], 0
	v_mfma_f32_16x16x32_bf16 v[86:89], v[168:171], v[204:207], 0
	v_mfma_f32_16x16x32_bf16 v[82:85], v[176:179], v[204:207], 0
	v_mfma_f32_16x16x32_bf16 v[70:73], v[168:171], v[212:215], 0
	v_mfma_f32_16x16x32_bf16 v[66:69], v[176:179], v[212:215], 0
	v_mfma_f32_16x16x32_bf16 v[118:121], v[172:175], v[188:191], v[118:121]
	v_mfma_f32_16x16x32_bf16 v[114:117], v[180:183], v[188:191], v[114:117]
	v_mfma_f32_16x16x32_bf16 v[102:105], v[172:175], v[200:203], v[102:105]
	v_mfma_f32_16x16x32_bf16 v[98:101], v[180:183], v[200:203], v[98:101]
	v_mfma_f32_16x16x32_bf16 v[86:89], v[172:175], v[208:211], v[86:89]
	v_mfma_f32_16x16x32_bf16 v[82:85], v[180:183], v[208:211], v[82:85]
	v_mfma_f32_16x16x32_bf16 v[70:73], v[172:175], v[216:219], v[70:73]
	v_mfma_f32_16x16x32_bf16 v[66:69], v[180:183], v[216:219], v[66:69]
	s_setprio 0
	s_barrier
	s_add_i32 s25, s54, s33
	v_lshl_add_u64 v[144:145], s[40:41], 0, v[132:133]
	s_mov_b32 m0, s25
	ds_read_b128 v[184:187], v151 offset:16384
	ds_read_b128 v[188:191], v151 offset:17408
	ds_read_b128 v[196:199], v151 offset:18432
	ds_read_b128 v[200:203], v151 offset:19456
	ds_read_b128 v[204:207], v151 offset:20480
	ds_read_b128 v[208:211], v151 offset:21504
	ds_read_b128 v[212:215], v151 offset:22528
	ds_read_b128 v[216:219], v151 offset:23552
	global_load_lds_dwordx4 v132, s[40:41]
	s_add_i32 m0, s25, 0x2000
	s_add_u32 s44, s40, 0x80000
	v_lshl_add_u64 v[192:193], s[40:41], 0, v[136:137]
	s_addc_u32 s45, s41, 0
	s_add_i32 s25, s55, s33
	global_load_lds_dwordx4 v136, s[40:41]
	s_mov_b32 m0, s25
	v_lshl_add_u64 v[222:223], s[42:43], 0, v[134:135]
	global_load_lds_dwordx4 v132, s[44:45]
	s_add_i32 m0, s25, 0x2000
	s_nop 0
	global_load_lds_dwordx4 v136, s[44:45]
	v_lshl_add_u64 v[220:221], s[42:43], 0, v[130:131]
	s_mov_b32 m0, s35
	s_nop 0
	global_load_lds_dwordx4 v130, s[42:43]
	s_mov_b32 m0, s47
	s_nop 0
	global_load_lds_dwordx4 v134, s[42:43]
	s_waitcnt vmcnt(8)
	s_waitcnt lgkmcnt(0)
	s_barrier
	s_setprio 1
	s_waitcnt lgkmcnt(0)
	v_mfma_f32_16x16x32_bf16 v[62:65], v[152:155], v[184:187], 0
	v_mfma_f32_16x16x32_bf16 v[58:61], v[160:163], v[184:187], 0
	v_mfma_f32_16x16x32_bf16 v[46:49], v[152:155], v[196:199], 0
	v_mfma_f32_16x16x32_bf16 v[42:45], v[160:163], v[196:199], 0
	v_mfma_f32_16x16x32_bf16 v[30:33], v[152:155], v[204:207], 0
	v_mfma_f32_16x16x32_bf16 v[26:29], v[160:163], v[204:207], 0
	v_mfma_f32_16x16x32_bf16 v[14:17], v[152:155], v[212:215], 0
	v_mfma_f32_16x16x32_bf16 v[10:13], v[160:163], v[212:215], 0
	v_mfma_f32_16x16x32_bf16 v[62:65], v[156:159], v[188:191], v[62:65]
	v_mfma_f32_16x16x32_bf16 v[58:61], v[164:167], v[188:191], v[58:61]
	v_mfma_f32_16x16x32_bf16 v[46:49], v[156:159], v[200:203], v[46:49]
	v_mfma_f32_16x16x32_bf16 v[42:45], v[164:167], v[200:203], v[42:45]
	v_mfma_f32_16x16x32_bf16 v[30:33], v[156:159], v[208:211], v[30:33]
	v_mfma_f32_16x16x32_bf16 v[26:29], v[164:167], v[208:211], v[26:29]
	v_mfma_f32_16x16x32_bf16 v[14:17], v[156:159], v[216:219], v[14:17]
	v_mfma_f32_16x16x32_bf16 v[10:13], v[164:167], v[216:219], v[10:13]
	s_setprio 0
	s_setprio 1
	v_mfma_f32_16x16x32_bf16 v[54:57], v[168:171], v[184:187], 0
	v_mfma_f32_16x16x32_bf16 v[50:53], v[176:179], v[184:187], 0
	v_mfma_f32_16x16x32_bf16 v[38:41], v[168:171], v[196:199], 0
	v_mfma_f32_16x16x32_bf16 v[34:37], v[176:179], v[196:199], 0
	v_mfma_f32_16x16x32_bf16 v[22:25], v[168:171], v[204:207], 0
	v_mfma_f32_16x16x32_bf16 v[18:21], v[176:179], v[204:207], 0
	v_mfma_f32_16x16x32_bf16 v[6:9], v[168:171], v[212:215], 0
	v_mfma_f32_16x16x32_bf16 v[2:5], v[176:179], v[212:215], 0
	v_mfma_f32_16x16x32_bf16 v[54:57], v[172:175], v[188:191], v[54:57]
	v_mfma_f32_16x16x32_bf16 v[50:53], v[180:183], v[188:191], v[50:53]
	v_mfma_f32_16x16x32_bf16 v[38:41], v[172:175], v[200:203], v[38:41]
	v_mfma_f32_16x16x32_bf16 v[34:37], v[180:183], v[200:203], v[34:37]
	v_mfma_f32_16x16x32_bf16 v[22:25], v[172:175], v[208:211], v[22:25]
	v_mfma_f32_16x16x32_bf16 v[18:21], v[180:183], v[208:211], v[18:21]
	v_mfma_f32_16x16x32_bf16 v[6:9], v[172:175], v[216:219], v[6:9]
	v_mfma_f32_16x16x32_bf16 v[2:5], v[180:183], v[216:219], v[2:5]
	s_setprio 0
	s_barrier
	s_add_i32 s25, 0, 0x18000
	s_add_i32 s44, 0, 0x1c000
	v_add_u32_e32 v164, s25, v147
	v_add_u32_e32 v180, s44, v147
	ds_read_b128 v[152:155], v164
	ds_read_b128 v[156:159], v164 offset:1024
	ds_read_b128 v[160:163], v164 offset:2048
	ds_read_b128 v[164:167], v164 offset:3072
	ds_read_b128 v[168:171], v180
	ds_read_b128 v[172:175], v180 offset:1024
	ds_read_b128 v[176:179], v180 offset:2048
	ds_read_b128 v[180:183], v180 offset:3072
	s_add_u32 s42, s42, 0x80000
	s_addc_u32 s43, s43, 0
	s_mov_b32 m0, s48
	ds_read_b128 v[184:187], v151 offset:32768
	ds_read_b128 v[188:191], v151 offset:33792
	ds_read_b128 v[196:199], v151 offset:34816
	ds_read_b128 v[200:203], v151 offset:35840
	ds_read_b128 v[204:207], v151 offset:36864
	ds_read_b128 v[208:211], v151 offset:37888
	ds_read_b128 v[212:215], v151 offset:38912
	ds_read_b128 v[216:219], v151 offset:39936
	global_load_lds_dwordx4 v130, s[42:43]
	v_lshl_add_u64 v[224:225], s[42:43], 0, v[134:135]
	s_mov_b32 m0, s49
	s_nop 0
	global_load_lds_dwordx4 v134, s[42:43]
	s_waitcnt vmcnt(8)
	s_waitcnt lgkmcnt(0)
	s_barrier
	s_setprio 1
	s_waitcnt lgkmcnt(0)
	v_mfma_f32_16x16x32_bf16 v[126:129], v[152:155], v[184:187], v[126:129]
	v_mfma_f32_16x16x32_bf16 v[122:125], v[160:163], v[184:187], v[122:125]
	v_mfma_f32_16x16x32_bf16 v[110:113], v[152:155], v[196:199], v[110:113]
	v_mfma_f32_16x16x32_bf16 v[106:109], v[160:163], v[196:199], v[106:109]
	v_mfma_f32_16x16x32_bf16 v[94:97], v[152:155], v[204:207], v[94:97]
	v_mfma_f32_16x16x32_bf16 v[90:93], v[160:163], v[204:207], v[90:93]
	v_mfma_f32_16x16x32_bf16 v[78:81], v[152:155], v[212:215], v[78:81]
	v_mfma_f32_16x16x32_bf16 v[74:77], v[160:163], v[212:215], v[74:77]
	v_mfma_f32_16x16x32_bf16 v[126:129], v[156:159], v[188:191], v[126:129]
	v_mfma_f32_16x16x32_bf16 v[122:125], v[164:167], v[188:191], v[122:125]
	v_mfma_f32_16x16x32_bf16 v[110:113], v[156:159], v[200:203], v[110:113]
	v_mfma_f32_16x16x32_bf16 v[106:109], v[164:167], v[200:203], v[106:109]
	v_mfma_f32_16x16x32_bf16 v[94:97], v[156:159], v[208:211], v[94:97]
	v_mfma_f32_16x16x32_bf16 v[90:93], v[164:167], v[208:211], v[90:93]
	v_mfma_f32_16x16x32_bf16 v[78:81], v[156:159], v[216:219], v[78:81]
	v_mfma_f32_16x16x32_bf16 v[74:77], v[164:167], v[216:219], v[74:77]
	s_setprio 0
	s_setprio 1
	v_mfma_f32_16x16x32_bf16 v[118:121], v[168:171], v[184:187], v[118:121]
	v_mfma_f32_16x16x32_bf16 v[114:117], v[176:179], v[184:187], v[114:117]
	v_mfma_f32_16x16x32_bf16 v[102:105], v[168:171], v[196:199], v[102:105]
	v_mfma_f32_16x16x32_bf16 v[98:101], v[176:179], v[196:199], v[98:101]
	v_mfma_f32_16x16x32_bf16 v[86:89], v[168:171], v[204:207], v[86:89]
	v_mfma_f32_16x16x32_bf16 v[82:85], v[176:179], v[204:207], v[82:85]
	v_mfma_f32_16x16x32_bf16 v[70:73], v[168:171], v[212:215], v[70:73]
	v_mfma_f32_16x16x32_bf16 v[66:69], v[176:179], v[212:215], v[66:69]
	v_mfma_f32_16x16x32_bf16 v[118:121], v[172:175], v[188:191], v[118:121]
	v_mfma_f32_16x16x32_bf16 v[114:117], v[180:183], v[188:191], v[114:117]
	v_mfma_f32_16x16x32_bf16 v[102:105], v[172:175], v[200:203], v[102:105]
	v_mfma_f32_16x16x32_bf16 v[98:101], v[180:183], v[200:203], v[98:101]
	v_mfma_f32_16x16x32_bf16 v[86:89], v[172:175], v[208:211], v[86:89]
	v_mfma_f32_16x16x32_bf16 v[82:85], v[180:183], v[208:211], v[82:85]
	v_mfma_f32_16x16x32_bf16 v[70:73], v[172:175], v[216:219], v[70:73]
	v_mfma_f32_16x16x32_bf16 v[66:69], v[180:183], v[216:219], v[66:69]
	s_setprio 0
	s_barrier
	s_add_i32 s25, s25, s33
	v_lshl_add_u64 v[144:145], v[144:145], 0, s[16:17]
	s_mov_b32 m0, s25
	ds_read_b128 v[184:187], v151 offset:49152
	ds_read_b128 v[188:191], v151 offset:50176
	ds_read_b128 v[196:199], v151 offset:51200
	ds_read_b128 v[200:203], v151 offset:52224
	ds_read_b128 v[204:207], v151 offset:53248
	ds_read_b128 v[208:211], v151 offset:54272
	ds_read_b128 v[212:215], v151 offset:55296
	ds_read_b128 v[216:219], v151 offset:56320
	global_load_lds_dwordx4 v[144:145], off
	s_add_i32 m0, s25, 0x2000
	s_add_u32 s40, s40, 0x80080
	v_lshl_add_u64 v[144:145], v[192:193], 0, s[16:17]
	s_addc_u32 s41, s41, 0
	s_add_i32 s25, s44, s33
	global_load_lds_dwordx4 v[144:145], off
	s_mov_b32 m0, s25
	s_nop 0
	global_load_lds_dwordx4 v132, s[40:41]
	s_add_i32 m0, s25, 0x2000
	s_nop 0
	global_load_lds_dwordx4 v136, s[40:41]
	v_lshl_add_u64 v[144:145], v[220:221], 0, s[16:17]
	s_mov_b32 m0, s50
	s_nop 0
	global_load_lds_dwordx4 v[144:145], off
	v_lshl_add_u64 v[144:145], v[222:223], 0, s[16:17]
	s_mov_b32 m0, s51
	s_nop 0
	global_load_lds_dwordx4 v[144:145], off
	s_waitcnt vmcnt(8)
	s_waitcnt lgkmcnt(0)
	s_barrier
	s_setprio 1
	s_waitcnt lgkmcnt(0)
	v_mfma_f32_16x16x32_bf16 v[62:65], v[152:155], v[184:187], v[62:65]
	v_mfma_f32_16x16x32_bf16 v[58:61], v[160:163], v[184:187], v[58:61]
	v_mfma_f32_16x16x32_bf16 v[46:49], v[152:155], v[196:199], v[46:49]
	v_mfma_f32_16x16x32_bf16 v[42:45], v[160:163], v[196:199], v[42:45]
	v_mfma_f32_16x16x32_bf16 v[30:33], v[152:155], v[204:207], v[30:33]
	v_mfma_f32_16x16x32_bf16 v[26:29], v[160:163], v[204:207], v[26:29]
	v_mfma_f32_16x16x32_bf16 v[14:17], v[152:155], v[212:215], v[14:17]
	v_mfma_f32_16x16x32_bf16 v[10:13], v[160:163], v[212:215], v[10:13]
	v_mfma_f32_16x16x32_bf16 v[62:65], v[156:159], v[188:191], v[62:65]
	v_mfma_f32_16x16x32_bf16 v[58:61], v[164:167], v[188:191], v[58:61]
	v_mfma_f32_16x16x32_bf16 v[46:49], v[156:159], v[200:203], v[46:49]
	v_mfma_f32_16x16x32_bf16 v[42:45], v[164:167], v[200:203], v[42:45]
	v_mfma_f32_16x16x32_bf16 v[30:33], v[156:159], v[208:211], v[30:33]
	v_mfma_f32_16x16x32_bf16 v[26:29], v[164:167], v[208:211], v[26:29]
	v_mfma_f32_16x16x32_bf16 v[14:17], v[156:159], v[216:219], v[14:17]
	v_mfma_f32_16x16x32_bf16 v[10:13], v[164:167], v[216:219], v[10:13]
	s_setprio 0
	s_setprio 1
	v_mfma_f32_16x16x32_bf16 v[54:57], v[168:171], v[184:187], v[54:57]
	v_mfma_f32_16x16x32_bf16 v[50:53], v[176:179], v[184:187], v[50:53]
	v_mfma_f32_16x16x32_bf16 v[38:41], v[168:171], v[196:199], v[38:41]
	v_mfma_f32_16x16x32_bf16 v[34:37], v[176:179], v[196:199], v[34:37]
	v_mfma_f32_16x16x32_bf16 v[22:25], v[168:171], v[204:207], v[22:25]
	v_mfma_f32_16x16x32_bf16 v[18:21], v[176:179], v[204:207], v[18:21]
	v_mfma_f32_16x16x32_bf16 v[6:9], v[168:171], v[212:215], v[6:9]
	v_mfma_f32_16x16x32_bf16 v[2:5], v[176:179], v[212:215], v[2:5]
	v_mfma_f32_16x16x32_bf16 v[54:57], v[172:175], v[188:191], v[54:57]
	v_mfma_f32_16x16x32_bf16 v[50:53], v[180:183], v[188:191], v[50:53]
	v_mfma_f32_16x16x32_bf16 v[38:41], v[172:175], v[200:203], v[38:41]
	v_mfma_f32_16x16x32_bf16 v[34:37], v[180:183], v[200:203], v[34:37]
	v_mfma_f32_16x16x32_bf16 v[22:25], v[172:175], v[208:211], v[22:25]
	v_mfma_f32_16x16x32_bf16 v[18:21], v[180:183], v[208:211], v[18:21]
	v_mfma_f32_16x16x32_bf16 v[6:9], v[172:175], v[216:219], v[6:9]
	v_mfma_f32_16x16x32_bf16 v[2:5], v[180:183], v[216:219], v[2:5]
	s_setprio 0
	s_barrier
	s_add_u32 s38, s38, 0x100
	s_addc_u32 s39, s39, 0
	s_add_u32 s21, s21, 0x100
	s_addc_u32 s23, s23, 0
	s_cmp_ge_i32 s37, s62
	s_mov_b32 s25, s37
	s_cbranch_scc0 .LBB0_221
	s_branch .Lpeeldone_13
.LBB0_221:
	ds_read_b128 v[152:155], v149
	ds_read_b128 v[156:159], v149 offset:1024
	ds_read_b128 v[160:163], v149 offset:2048
	ds_read_b128 v[164:167], v149 offset:3072
	ds_read_b128 v[168:171], v150
	ds_read_b128 v[172:175], v150 offset:1024
	ds_read_b128 v[176:179], v150 offset:2048
	ds_read_b128 v[180:183], v150 offset:3072
	s_add_i32 s37, s25, 2
	s_add_u32 s40, s38, 0xfff80080
	s_addc_u32 s41, s39, -1
	s_cmp_eq_u32 s36, s25
	s_cselect_b32 s43, s27, s41
	s_cselect_b32 s42, s26, s40
	s_cselect_b32 s41, s29, s23
	s_cselect_b32 s40, s28, s21
	s_add_i32 m0, s35, 0xc000
	ds_read_b128 v[184:187], v151
	ds_read_b128 v[188:191], v151 offset:1024
	ds_read_b128 v[196:199], v151 offset:2048
	ds_read_b128 v[200:203], v151 offset:3072
	ds_read_b128 v[204:207], v151 offset:4096
	ds_read_b128 v[208:211], v151 offset:5120
	ds_read_b128 v[212:215], v151 offset:6144
	ds_read_b128 v[216:219], v151 offset:7168
	global_load_lds_dwordx4 v140, s[38:39]
	s_add_i32 m0, s35, 0xe000
	s_nop 0
	global_load_lds_dwordx4 v142, s[38:39]
	s_waitcnt vmcnt(8)
	s_waitcnt lgkmcnt(0)
	s_barrier
	s_setprio 1
	s_waitcnt lgkmcnt(0)
	v_mfma_f32_16x16x32_bf16 v[126:129], v[152:155], v[184:187], v[126:129]
	v_mfma_f32_16x16x32_bf16 v[122:125], v[160:163], v[184:187], v[122:125]
	v_mfma_f32_16x16x32_bf16 v[110:113], v[152:155], v[196:199], v[110:113]
	v_mfma_f32_16x16x32_bf16 v[106:109], v[160:163], v[196:199], v[106:109]
	v_mfma_f32_16x16x32_bf16 v[94:97], v[152:155], v[204:207], v[94:97]
	v_mfma_f32_16x16x32_bf16 v[90:93], v[160:163], v[204:207], v[90:93]
	v_mfma_f32_16x16x32_bf16 v[78:81], v[152:155], v[212:215], v[78:81]
	v_mfma_f32_16x16x32_bf16 v[74:77], v[160:163], v[212:215], v[74:77]
	v_mfma_f32_16x16x32_bf16 v[126:129], v[156:159], v[188:191], v[126:129]
	v_mfma_f32_16x16x32_bf16 v[122:125], v[164:167], v[188:191], v[122:125]
	v_mfma_f32_16x16x32_bf16 v[110:113], v[156:159], v[200:203], v[110:113]
	v_mfma_f32_16x16x32_bf16 v[106:109], v[164:167], v[200:203], v[106:109]
	v_mfma_f32_16x16x32_bf16 v[94:97], v[156:159], v[208:211], v[94:97]
	v_mfma_f32_16x16x32_bf16 v[90:93], v[164:167], v[208:211], v[90:93]
	v_mfma_f32_16x16x32_bf16 v[78:81], v[156:159], v[216:219], v[78:81]
	v_mfma_f32_16x16x32_bf16 v[74:77], v[164:167], v[216:219], v[74:77]
	s_setprio 0
	s_setprio 1
	v_mfma_f32_16x16x32_bf16 v[118:121], v[168:171], v[184:187], v[118:121]
	v_mfma_f32_16x16x32_bf16 v[114:117], v[176:179], v[184:187], v[114:117]
	v_mfma_f32_16x16x32_bf16 v[102:105], v[168:171], v[196:199], v[102:105]
	v_mfma_f32_16x16x32_bf16 v[98:101], v[176:179], v[196:199], v[98:101]
	v_mfma_f32_16x16x32_bf16 v[86:89], v[168:171], v[204:207], v[86:89]
	v_mfma_f32_16x16x32_bf16 v[82:85], v[176:179], v[204:207], v[82:85]
	v_mfma_f32_16x16x32_bf16 v[70:73], v[168:171], v[212:215], v[70:73]
	v_mfma_f32_16x16x32_bf16 v[66:69], v[176:179], v[212:215], v[66:69]
	v_mfma_f32_16x16x32_bf16 v[118:121], v[172:175], v[188:191], v[118:121]
	v_mfma_f32_16x16x32_bf16 v[114:117], v[180:183], v[188:191], v[114:117]
	v_mfma_f32_16x16x32_bf16 v[102:105], v[172:175], v[200:203], v[102:105]
	v_mfma_f32_16x16x32_bf16 v[98:101], v[180:183], v[200:203], v[98:101]
	v_mfma_f32_16x16x32_bf16 v[86:89], v[172:175], v[208:211], v[86:89]
	v_mfma_f32_16x16x32_bf16 v[82:85], v[180:183], v[208:211], v[82:85]
	v_mfma_f32_16x16x32_bf16 v[70:73], v[172:175], v[216:219], v[70:73]
	v_mfma_f32_16x16x32_bf16 v[66:69], v[180:183], v[216:219], v[66:69]
	s_setprio 0
	s_barrier
	s_add_i32 s25, s54, s33
	v_lshl_add_u64 v[144:145], s[40:41], 0, v[132:133]
	s_mov_b32 m0, s25
	ds_read_b128 v[184:187], v151 offset:16384
	ds_read_b128 v[188:191], v151 offset:17408
	ds_read_b128 v[196:199], v151 offset:18432
	ds_read_b128 v[200:203], v151 offset:19456
	ds_read_b128 v[204:207], v151 offset:20480
	ds_read_b128 v[208:211], v151 offset:21504
	ds_read_b128 v[212:215], v151 offset:22528
	ds_read_b128 v[216:219], v151 offset:23552
	global_load_lds_dwordx4 v132, s[40:41]
	s_add_i32 m0, s25, 0x2000
	s_add_u32 s44, s40, 0x80000
	v_lshl_add_u64 v[192:193], s[40:41], 0, v[136:137]
	s_addc_u32 s45, s41, 0
	s_add_i32 s25, s55, s33
	global_load_lds_dwordx4 v136, s[40:41]
	s_mov_b32 m0, s25
	v_lshl_add_u64 v[222:223], s[42:43], 0, v[134:135]
	global_load_lds_dwordx4 v132, s[44:45]
	s_add_i32 m0, s25, 0x2000
	s_nop 0
	global_load_lds_dwordx4 v136, s[44:45]
	v_lshl_add_u64 v[220:221], s[42:43], 0, v[130:131]
	s_mov_b32 m0, s35
	s_nop 0
	global_load_lds_dwordx4 v130, s[42:43]
	s_mov_b32 m0, s47
	s_nop 0
	global_load_lds_dwordx4 v134, s[42:43]
	s_waitcnt vmcnt(8)
	s_waitcnt lgkmcnt(0)
	s_barrier
	s_setprio 1
	s_waitcnt lgkmcnt(0)
	v_mfma_f32_16x16x32_bf16 v[62:65], v[152:155], v[184:187], v[62:65]
	v_mfma_f32_16x16x32_bf16 v[58:61], v[160:163], v[184:187], v[58:61]
	v_mfma_f32_16x16x32_bf16 v[46:49], v[152:155], v[196:199], v[46:49]
	v_mfma_f32_16x16x32_bf16 v[42:45], v[160:163], v[196:199], v[42:45]
	v_mfma_f32_16x16x32_bf16 v[30:33], v[152:155], v[204:207], v[30:33]
	v_mfma_f32_16x16x32_bf16 v[26:29], v[160:163], v[204:207], v[26:29]
	v_mfma_f32_16x16x32_bf16 v[14:17], v[152:155], v[212:215], v[14:17]
	v_mfma_f32_16x16x32_bf16 v[10:13], v[160:163], v[212:215], v[10:13]
	v_mfma_f32_16x16x32_bf16 v[62:65], v[156:159], v[188:191], v[62:65]
	v_mfma_f32_16x16x32_bf16 v[58:61], v[164:167], v[188:191], v[58:61]
	v_mfma_f32_16x16x32_bf16 v[46:49], v[156:159], v[200:203], v[46:49]
	v_mfma_f32_16x16x32_bf16 v[42:45], v[164:167], v[200:203], v[42:45]
	v_mfma_f32_16x16x32_bf16 v[30:33], v[156:159], v[208:211], v[30:33]
	v_mfma_f32_16x16x32_bf16 v[26:29], v[164:167], v[208:211], v[26:29]
	v_mfma_f32_16x16x32_bf16 v[14:17], v[156:159], v[216:219], v[14:17]
	v_mfma_f32_16x16x32_bf16 v[10:13], v[164:167], v[216:219], v[10:13]
	s_setprio 0
	s_setprio 1
	v_mfma_f32_16x16x32_bf16 v[54:57], v[168:171], v[184:187], v[54:57]
	v_mfma_f32_16x16x32_bf16 v[50:53], v[176:179], v[184:187], v[50:53]
	v_mfma_f32_16x16x32_bf16 v[38:41], v[168:171], v[196:199], v[38:41]
	v_mfma_f32_16x16x32_bf16 v[34:37], v[176:179], v[196:199], v[34:37]
	v_mfma_f32_16x16x32_bf16 v[22:25], v[168:171], v[204:207], v[22:25]
	v_mfma_f32_16x16x32_bf16 v[18:21], v[176:179], v[204:207], v[18:21]
	v_mfma_f32_16x16x32_bf16 v[6:9], v[168:171], v[212:215], v[6:9]
	v_mfma_f32_16x16x32_bf16 v[2:5], v[176:179], v[212:215], v[2:5]
	v_mfma_f32_16x16x32_bf16 v[54:57], v[172:175], v[188:191], v[54:57]
	v_mfma_f32_16x16x32_bf16 v[50:53], v[180:183], v[188:191], v[50:53]
	v_mfma_f32_16x16x32_bf16 v[38:41], v[172:175], v[200:203], v[38:41]
	v_mfma_f32_16x16x32_bf16 v[34:37], v[180:183], v[200:203], v[34:37]
	v_mfma_f32_16x16x32_bf16 v[22:25], v[172:175], v[208:211], v[22:25]
	v_mfma_f32_16x16x32_bf16 v[18:21], v[180:183], v[208:211], v[18:21]
	v_mfma_f32_16x16x32_bf16 v[6:9], v[172:175], v[216:219], v[6:9]
	v_mfma_f32_16x16x32_bf16 v[2:5], v[180:183], v[216:219], v[2:5]
	s_setprio 0
	s_barrier
	s_add_i32 s25, 0, 0x18000
	s_add_i32 s44, 0, 0x1c000
	v_add_u32_e32 v164, s25, v147
	v_add_u32_e32 v180, s44, v147
	ds_read_b128 v[152:155], v164
	ds_read_b128 v[156:159], v164 offset:1024
	ds_read_b128 v[160:163], v164 offset:2048
	ds_read_b128 v[164:167], v164 offset:3072
	ds_read_b128 v[168:171], v180
	ds_read_b128 v[172:175], v180 offset:1024
	ds_read_b128 v[176:179], v180 offset:2048
	ds_read_b128 v[180:183], v180 offset:3072
	s_add_u32 s42, s42, 0x80000
	s_addc_u32 s43, s43, 0
	s_mov_b32 m0, s48
	ds_read_b128 v[184:187], v151 offset:32768
	ds_read_b128 v[188:191], v151 offset:33792
	ds_read_b128 v[196:199], v151 offset:34816
	ds_read_b128 v[200:203], v151 offset:35840
	ds_read_b128 v[204:207], v151 offset:36864
	ds_read_b128 v[208:211], v151 offset:37888
	ds_read_b128 v[212:215], v151 offset:38912
	ds_read_b128 v[216:219], v151 offset:39936
	global_load_lds_dwordx4 v130, s[42:43]
	v_lshl_add_u64 v[224:225], s[42:43], 0, v[134:135]
	s_mov_b32 m0, s49
	s_nop 0
	global_load_lds_dwordx4 v134, s[42:43]
	s_waitcnt vmcnt(8)
	s_waitcnt lgkmcnt(0)
	s_barrier
	s_setprio 1
	s_waitcnt lgkmcnt(0)
	v_mfma_f32_16x16x32_bf16 v[126:129], v[152:155], v[184:187], v[126:129]
	v_mfma_f32_16x16x32_bf16 v[122:125], v[160:163], v[184:187], v[122:125]
	v_mfma_f32_16x16x32_bf16 v[110:113], v[152:155], v[196:199], v[110:113]
	v_mfma_f32_16x16x32_bf16 v[106:109], v[160:163], v[196:199], v[106:109]
	v_mfma_f32_16x16x32_bf16 v[94:97], v[152:155], v[204:207], v[94:97]
	v_mfma_f32_16x16x32_bf16 v[90:93], v[160:163], v[204:207], v[90:93]
	v_mfma_f32_16x16x32_bf16 v[78:81], v[152:155], v[212:215], v[78:81]
	v_mfma_f32_16x16x32_bf16 v[74:77], v[160:163], v[212:215], v[74:77]
	v_mfma_f32_16x16x32_bf16 v[126:129], v[156:159], v[188:191], v[126:129]
	v_mfma_f32_16x16x32_bf16 v[122:125], v[164:167], v[188:191], v[122:125]
	v_mfma_f32_16x16x32_bf16 v[110:113], v[156:159], v[200:203], v[110:113]
	v_mfma_f32_16x16x32_bf16 v[106:109], v[164:167], v[200:203], v[106:109]
	v_mfma_f32_16x16x32_bf16 v[94:97], v[156:159], v[208:211], v[94:97]
	v_mfma_f32_16x16x32_bf16 v[90:93], v[164:167], v[208:211], v[90:93]
	v_mfma_f32_16x16x32_bf16 v[78:81], v[156:159], v[216:219], v[78:81]
	v_mfma_f32_16x16x32_bf16 v[74:77], v[164:167], v[216:219], v[74:77]
	s_setprio 0
	s_setprio 1
	v_mfma_f32_16x16x32_bf16 v[118:121], v[168:171], v[184:187], v[118:121]
	v_mfma_f32_16x16x32_bf16 v[114:117], v[176:179], v[184:187], v[114:117]
	v_mfma_f32_16x16x32_bf16 v[102:105], v[168:171], v[196:199], v[102:105]
	v_mfma_f32_16x16x32_bf16 v[98:101], v[176:179], v[196:199], v[98:101]
	v_mfma_f32_16x16x32_bf16 v[86:89], v[168:171], v[204:207], v[86:89]
	v_mfma_f32_16x16x32_bf16 v[82:85], v[176:179], v[204:207], v[82:85]
	v_mfma_f32_16x16x32_bf16 v[70:73], v[168:171], v[212:215], v[70:73]
	v_mfma_f32_16x16x32_bf16 v[66:69], v[176:179], v[212:215], v[66:69]
	v_mfma_f32_16x16x32_bf16 v[118:121], v[172:175], v[188:191], v[118:121]
	v_mfma_f32_16x16x32_bf16 v[114:117], v[180:183], v[188:191], v[114:117]
	v_mfma_f32_16x16x32_bf16 v[102:105], v[172:175], v[200:203], v[102:105]
	v_mfma_f32_16x16x32_bf16 v[98:101], v[180:183], v[200:203], v[98:101]
	v_mfma_f32_16x16x32_bf16 v[86:89], v[172:175], v[208:211], v[86:89]
	v_mfma_f32_16x16x32_bf16 v[82:85], v[180:183], v[208:211], v[82:85]
	v_mfma_f32_16x16x32_bf16 v[70:73], v[172:175], v[216:219], v[70:73]
	v_mfma_f32_16x16x32_bf16 v[66:69], v[180:183], v[216:219], v[66:69]
	s_setprio 0
	s_barrier
	s_add_i32 s25, s25, s33
	v_lshl_add_u64 v[144:145], v[144:145], 0, s[16:17]
	s_mov_b32 m0, s25
	ds_read_b128 v[184:187], v151 offset:49152
	ds_read_b128 v[188:191], v151 offset:50176
	ds_read_b128 v[196:199], v151 offset:51200
	ds_read_b128 v[200:203], v151 offset:52224
	ds_read_b128 v[204:207], v151 offset:53248
	ds_read_b128 v[208:211], v151 offset:54272
	ds_read_b128 v[212:215], v151 offset:55296
	ds_read_b128 v[216:219], v151 offset:56320
	global_load_lds_dwordx4 v[144:145], off
	s_add_i32 m0, s25, 0x2000
	s_add_u32 s40, s40, 0x80080
	v_lshl_add_u64 v[144:145], v[192:193], 0, s[16:17]
	s_addc_u32 s41, s41, 0
	s_add_i32 s25, s44, s33
	global_load_lds_dwordx4 v[144:145], off
	s_mov_b32 m0, s25
	s_nop 0
	global_load_lds_dwordx4 v132, s[40:41]
	s_add_i32 m0, s25, 0x2000
	s_nop 0
	global_load_lds_dwordx4 v136, s[40:41]
	v_lshl_add_u64 v[144:145], v[220:221], 0, s[16:17]
	s_mov_b32 m0, s50
	s_nop 0
	global_load_lds_dwordx4 v[144:145], off
	v_lshl_add_u64 v[144:145], v[222:223], 0, s[16:17]
	s_mov_b32 m0, s51
	s_nop 0
	global_load_lds_dwordx4 v[144:145], off
	s_waitcnt vmcnt(8)
	s_waitcnt lgkmcnt(0)
	s_barrier
	s_setprio 1
	s_waitcnt lgkmcnt(0)
	v_mfma_f32_16x16x32_bf16 v[62:65], v[152:155], v[184:187], v[62:65]
	v_mfma_f32_16x16x32_bf16 v[58:61], v[160:163], v[184:187], v[58:61]
	v_mfma_f32_16x16x32_bf16 v[46:49], v[152:155], v[196:199], v[46:49]
	v_mfma_f32_16x16x32_bf16 v[42:45], v[160:163], v[196:199], v[42:45]
	v_mfma_f32_16x16x32_bf16 v[30:33], v[152:155], v[204:207], v[30:33]
	v_mfma_f32_16x16x32_bf16 v[26:29], v[160:163], v[204:207], v[26:29]
	v_mfma_f32_16x16x32_bf16 v[14:17], v[152:155], v[212:215], v[14:17]
	v_mfma_f32_16x16x32_bf16 v[10:13], v[160:163], v[212:215], v[10:13]
	v_mfma_f32_16x16x32_bf16 v[62:65], v[156:159], v[188:191], v[62:65]
	v_mfma_f32_16x16x32_bf16 v[58:61], v[164:167], v[188:191], v[58:61]
	v_mfma_f32_16x16x32_bf16 v[46:49], v[156:159], v[200:203], v[46:49]
	v_mfma_f32_16x16x32_bf16 v[42:45], v[164:167], v[200:203], v[42:45]
	v_mfma_f32_16x16x32_bf16 v[30:33], v[156:159], v[208:211], v[30:33]
	v_mfma_f32_16x16x32_bf16 v[26:29], v[164:167], v[208:211], v[26:29]
	v_mfma_f32_16x16x32_bf16 v[14:17], v[156:159], v[216:219], v[14:17]
	v_mfma_f32_16x16x32_bf16 v[10:13], v[164:167], v[216:219], v[10:13]
	s_setprio 0
	s_setprio 1
	v_mfma_f32_16x16x32_bf16 v[54:57], v[168:171], v[184:187], v[54:57]
	v_mfma_f32_16x16x32_bf16 v[50:53], v[176:179], v[184:187], v[50:53]
	v_mfma_f32_16x16x32_bf16 v[38:41], v[168:171], v[196:199], v[38:41]
	v_mfma_f32_16x16x32_bf16 v[34:37], v[176:179], v[196:199], v[34:37]
	v_mfma_f32_16x16x32_bf16 v[22:25], v[168:171], v[204:207], v[22:25]
	v_mfma_f32_16x16x32_bf16 v[18:21], v[176:179], v[204:207], v[18:21]
	v_mfma_f32_16x16x32_bf16 v[6:9], v[168:171], v[212:215], v[6:9]
	v_mfma_f32_16x16x32_bf16 v[2:5], v[176:179], v[212:215], v[2:5]
	v_mfma_f32_16x16x32_bf16 v[54:57], v[172:175], v[188:191], v[54:57]
	v_mfma_f32_16x16x32_bf16 v[50:53], v[180:183], v[188:191], v[50:53]
	v_mfma_f32_16x16x32_bf16 v[38:41], v[172:175], v[200:203], v[38:41]
	v_mfma_f32_16x16x32_bf16 v[34:37], v[180:183], v[200:203], v[34:37]
	v_mfma_f32_16x16x32_bf16 v[22:25], v[172:175], v[208:211], v[22:25]
	v_mfma_f32_16x16x32_bf16 v[18:21], v[180:183], v[208:211], v[18:21]
	v_mfma_f32_16x16x32_bf16 v[6:9], v[172:175], v[216:219], v[6:9]
	v_mfma_f32_16x16x32_bf16 v[2:5], v[180:183], v[216:219], v[2:5]
	s_setprio 0
	s_barrier
	s_add_u32 s38, s38, 0x100
	s_addc_u32 s39, s39, 0
	s_add_u32 s21, s21, 0x100
	s_addc_u32 s23, s23, 0
	s_cmp_ge_i32 s37, s62
	s_mov_b32 s25, s37
	s_cbranch_scc0 .LBB0_221

.Lpeel_12:
	ds_read_b128 v[130:133], v215
	ds_read_b128 v[134:137], v215 offset:1024
	ds_read_b128 v[138:141], v215 offset:2048
	ds_read_b128 v[142:145], v215 offset:3072
	ds_read_b128 v[146:149], v216
	ds_read_b128 v[150:153], v216 offset:1024
	ds_read_b128 v[154:157], v216 offset:2048
	ds_read_b128 v[158:161], v216 offset:3072
	s_add_i32 s38, s34, 2
	s_add_u32 s35, s30, 0xffea0080
	s_addc_u32 s36, s31, -1
	s_cmp_eq_u32 s28, s34
	s_cselect_b32 s34, s26, s23
	s_cselect_b32 s37, s25, s36
	s_cselect_b32 s36, s24, s35
	s_cselect_b32 s35, s27, s29
	s_add_i32 m0, s40, 0xc000
	ds_read_b128 v[162:165], v217
	ds_read_b128 v[166:169], v217 offset:1024
	ds_read_b128 v[170:173], v217 offset:2048
	ds_read_b128 v[174:177], v217 offset:3072
	ds_read_b128 v[196:199], v217 offset:4096
	ds_read_b128 v[200:203], v217 offset:5120
	ds_read_b128 v[204:207], v217 offset:6144
	ds_read_b128 v[208:211], v217 offset:7168
	global_load_lds_dwordx4 v188, s[30:31]
	s_add_i32 m0, s40, 0xe000
	s_nop 0
	global_load_lds_dwordx4 v190, s[30:31]
	s_waitcnt vmcnt(8)
	s_waitcnt lgkmcnt(0)
	s_barrier
	s_setprio 1
	s_waitcnt lgkmcnt(0)
	v_mfma_f32_16x16x32_bf16 v[126:129], v[130:133], v[162:165], 0
	v_mfma_f32_16x16x32_bf16 v[122:125], v[138:141], v[162:165], 0
	v_mfma_f32_16x16x32_bf16 v[118:121], v[130:133], v[170:173], 0
	v_mfma_f32_16x16x32_bf16 v[114:117], v[138:141], v[170:173], 0
	v_mfma_f32_16x16x32_bf16 v[94:97], v[130:133], v[196:199], 0
	v_mfma_f32_16x16x32_bf16 v[90:93], v[138:141], v[196:199], 0
	v_mfma_f32_16x16x32_bf16 v[86:89], v[130:133], v[204:207], 0
	v_mfma_f32_16x16x32_bf16 v[82:85], v[138:141], v[204:207], 0
	v_mfma_f32_16x16x32_bf16 v[126:129], v[134:137], v[166:169], v[126:129]
	v_mfma_f32_16x16x32_bf16 v[122:125], v[142:145], v[166:169], v[122:125]
	v_mfma_f32_16x16x32_bf16 v[118:121], v[134:137], v[174:177], v[118:121]
	v_mfma_f32_16x16x32_bf16 v[114:117], v[142:145], v[174:177], v[114:117]
	v_mfma_f32_16x16x32_bf16 v[94:97], v[134:137], v[200:203], v[94:97]
	v_mfma_f32_16x16x32_bf16 v[90:93], v[142:145], v[200:203], v[90:93]
	v_mfma_f32_16x16x32_bf16 v[86:89], v[134:137], v[208:211], v[86:89]
	v_mfma_f32_16x16x32_bf16 v[82:85], v[142:145], v[208:211], v[82:85]
	s_setprio 0
	s_setprio 1
	v_mfma_f32_16x16x32_bf16 v[110:113], v[146:149], v[162:165], 0
	v_mfma_f32_16x16x32_bf16 v[106:109], v[154:157], v[162:165], 0
	v_mfma_f32_16x16x32_bf16 v[102:105], v[146:149], v[170:173], 0
	v_mfma_f32_16x16x32_bf16 v[98:101], v[154:157], v[170:173], 0
	v_mfma_f32_16x16x32_bf16 v[78:81], v[146:149], v[196:199], 0
	v_mfma_f32_16x16x32_bf16 v[74:77], v[154:157], v[196:199], 0
	v_mfma_f32_16x16x32_bf16 v[70:73], v[146:149], v[204:207], 0
	v_mfma_f32_16x16x32_bf16 v[66:69], v[154:157], v[204:207], 0
	v_mfma_f32_16x16x32_bf16 v[110:113], v[150:153], v[166:169], v[110:113]
	v_mfma_f32_16x16x32_bf16 v[106:109], v[158:161], v[166:169], v[106:109]
	v_mfma_f32_16x16x32_bf16 v[102:105], v[150:153], v[174:177], v[102:105]
	v_mfma_f32_16x16x32_bf16 v[98:101], v[158:161], v[174:177], v[98:101]
	v_mfma_f32_16x16x32_bf16 v[78:81], v[150:153], v[200:203], v[78:81]
	v_mfma_f32_16x16x32_bf16 v[74:77], v[158:161], v[200:203], v[74:77]
	v_mfma_f32_16x16x32_bf16 v[70:73], v[150:153], v[208:211], v[70:73]
	v_mfma_f32_16x16x32_bf16 v[66:69], v[158:161], v[208:211], v[66:69]
	s_setprio 0
	s_barrier
	s_add_i32 s39, s53, s33
	v_lshl_add_u64 v[192:193], s[34:35], 0, v[180:181]
	s_mov_b32 m0, s39
	ds_read_b128 v[162:165], v217 offset:16384
	ds_read_b128 v[166:169], v217 offset:17408
	ds_read_b128 v[170:173], v217 offset:18432
	ds_read_b128 v[174:177], v217 offset:19456
	ds_read_b128 v[196:199], v217 offset:20480
	ds_read_b128 v[200:203], v217 offset:21504
	ds_read_b128 v[204:207], v217 offset:22528
	ds_read_b128 v[208:211], v217 offset:23552
	global_load_lds_dwordx4 v180, s[34:35]
	s_add_i32 m0, s39, 0x2000
	s_add_u32 s62, s34, 0x160000
	v_lshl_add_u64 v[218:219], s[34:35], 0, v[184:185]
	s_addc_u32 s63, s35, 0
	s_add_i32 s39, s54, s33
	global_load_lds_dwordx4 v184, s[34:35]
	s_mov_b32 m0, s39
	v_lshl_add_u64 v[222:223], s[36:37], 0, v[182:183]
	global_load_lds_dwordx4 v180, s[62:63]
	s_add_i32 m0, s39, 0x2000
	s_nop 0
	global_load_lds_dwordx4 v184, s[62:63]
	v_lshl_add_u64 v[220:221], s[36:37], 0, v[178:179]
	s_mov_b32 m0, s40
	s_nop 0
	global_load_lds_dwordx4 v178, s[36:37]
	s_mov_b32 m0, s41
	s_nop 0
	global_load_lds_dwordx4 v182, s[36:37]
	s_waitcnt vmcnt(8)
	s_waitcnt lgkmcnt(0)
	s_barrier
	s_setprio 1
	s_waitcnt lgkmcnt(0)
	v_mfma_f32_16x16x32_bf16 v[62:65], v[130:133], v[162:165], 0
	v_mfma_f32_16x16x32_bf16 v[58:61], v[138:141], v[162:165], 0
	v_mfma_f32_16x16x32_bf16 v[54:57], v[130:133], v[170:173], 0
	v_mfma_f32_16x16x32_bf16 v[50:53], v[138:141], v[170:173], 0
	v_mfma_f32_16x16x32_bf16 v[30:33], v[130:133], v[196:199], 0
	v_mfma_f32_16x16x32_bf16 v[26:29], v[138:141], v[196:199], 0
	v_mfma_f32_16x16x32_bf16 v[22:25], v[130:133], v[204:207], 0
	v_mfma_f32_16x16x32_bf16 v[18:21], v[138:141], v[204:207], 0
	v_mfma_f32_16x16x32_bf16 v[62:65], v[134:137], v[166:169], v[62:65]
	v_mfma_f32_16x16x32_bf16 v[58:61], v[142:145], v[166:169], v[58:61]
	v_mfma_f32_16x16x32_bf16 v[54:57], v[134:137], v[174:177], v[54:57]
	v_mfma_f32_16x16x32_bf16 v[50:53], v[142:145], v[174:177], v[50:53]
	v_mfma_f32_16x16x32_bf16 v[30:33], v[134:137], v[200:203], v[30:33]
	v_mfma_f32_16x16x32_bf16 v[26:29], v[142:145], v[200:203], v[26:29]
	v_mfma_f32_16x16x32_bf16 v[22:25], v[134:137], v[208:211], v[22:25]
	v_mfma_f32_16x16x32_bf16 v[18:21], v[142:145], v[208:211], v[18:21]
	s_setprio 0
	s_setprio 1
	v_mfma_f32_16x16x32_bf16 v[46:49], v[146:149], v[162:165], 0
	v_mfma_f32_16x16x32_bf16 v[42:45], v[154:157], v[162:165], 0
	v_mfma_f32_16x16x32_bf16 v[38:41], v[146:149], v[170:173], 0
	v_mfma_f32_16x16x32_bf16 v[34:37], v[154:157], v[170:173], 0
	v_mfma_f32_16x16x32_bf16 v[14:17], v[146:149], v[196:199], 0
	v_mfma_f32_16x16x32_bf16 v[10:13], v[154:157], v[196:199], 0
	v_mfma_f32_16x16x32_bf16 v[6:9], v[146:149], v[204:207], 0
	v_mfma_f32_16x16x32_bf16 v[2:5], v[154:157], v[204:207], 0
	v_mfma_f32_16x16x32_bf16 v[46:49], v[150:153], v[166:169], v[46:49]
	v_mfma_f32_16x16x32_bf16 v[42:45], v[158:161], v[166:169], v[42:45]
	v_mfma_f32_16x16x32_bf16 v[38:41], v[150:153], v[174:177], v[38:41]
	v_mfma_f32_16x16x32_bf16 v[34:37], v[158:161], v[174:177], v[34:37]
	v_mfma_f32_16x16x32_bf16 v[14:17], v[150:153], v[200:203], v[14:17]
	v_mfma_f32_16x16x32_bf16 v[10:13], v[158:161], v[200:203], v[10:13]
	v_mfma_f32_16x16x32_bf16 v[6:9], v[150:153], v[208:211], v[6:9]
	v_mfma_f32_16x16x32_bf16 v[2:5], v[158:161], v[208:211], v[2:5]
	s_setprio 0
	s_barrier
	s_add_i32 s39, 0, 0x18000
	s_add_i32 s62, 0, 0x1c000
	v_add_u32_e32 v142, s39, v213
	v_add_u32_e32 v158, s62, v213
	ds_read_b128 v[130:133], v142
	ds_read_b128 v[134:137], v142 offset:1024
	ds_read_b128 v[138:141], v142 offset:2048
	ds_read_b128 v[142:145], v142 offset:3072
	ds_read_b128 v[146:149], v158
	ds_read_b128 v[150:153], v158 offset:1024
	ds_read_b128 v[154:157], v158 offset:2048
	ds_read_b128 v[158:161], v158 offset:3072
	s_add_u32 s36, s36, 0x160000
	s_addc_u32 s37, s37, 0
	s_mov_b32 m0, s42
	ds_read_b128 v[162:165], v217 offset:32768
	ds_read_b128 v[166:169], v217 offset:33792
	ds_read_b128 v[170:173], v217 offset:34816
	ds_read_b128 v[174:177], v217 offset:35840
	ds_read_b128 v[196:199], v217 offset:36864
	ds_read_b128 v[200:203], v217 offset:37888
	ds_read_b128 v[204:207], v217 offset:38912
	ds_read_b128 v[208:211], v217 offset:39936
	global_load_lds_dwordx4 v178, s[36:37]
	v_lshl_add_u64 v[224:225], s[36:37], 0, v[182:183]
	s_mov_b32 m0, s43
	s_nop 0
	global_load_lds_dwordx4 v182, s[36:37]
	s_waitcnt vmcnt(8)
	s_waitcnt lgkmcnt(0)
	s_barrier
	s_setprio 1
	s_waitcnt lgkmcnt(0)
	v_mfma_f32_16x16x32_bf16 v[126:129], v[130:133], v[162:165], v[126:129]
	v_mfma_f32_16x16x32_bf16 v[122:125], v[138:141], v[162:165], v[122:125]
	v_mfma_f32_16x16x32_bf16 v[118:121], v[130:133], v[170:173], v[118:121]
	v_mfma_f32_16x16x32_bf16 v[114:117], v[138:141], v[170:173], v[114:117]
	v_mfma_f32_16x16x32_bf16 v[94:97], v[130:133], v[196:199], v[94:97]
	v_mfma_f32_16x16x32_bf16 v[90:93], v[138:141], v[196:199], v[90:93]
	v_mfma_f32_16x16x32_bf16 v[86:89], v[130:133], v[204:207], v[86:89]
	v_mfma_f32_16x16x32_bf16 v[82:85], v[138:141], v[204:207], v[82:85]
	v_mfma_f32_16x16x32_bf16 v[126:129], v[134:137], v[166:169], v[126:129]
	v_mfma_f32_16x16x32_bf16 v[122:125], v[142:145], v[166:169], v[122:125]
	v_mfma_f32_16x16x32_bf16 v[118:121], v[134:137], v[174:177], v[118:121]
	v_mfma_f32_16x16x32_bf16 v[114:117], v[142:145], v[174:177], v[114:117]
	v_mfma_f32_16x16x32_bf16 v[94:97], v[134:137], v[200:203], v[94:97]
	v_mfma_f32_16x16x32_bf16 v[90:93], v[142:145], v[200:203], v[90:93]
	v_mfma_f32_16x16x32_bf16 v[86:89], v[134:137], v[208:211], v[86:89]
	v_mfma_f32_16x16x32_bf16 v[82:85], v[142:145], v[208:211], v[82:85]
	s_setprio 0
	s_setprio 1
	v_mfma_f32_16x16x32_bf16 v[110:113], v[146:149], v[162:165], v[110:113]
	v_mfma_f32_16x16x32_bf16 v[106:109], v[154:157], v[162:165], v[106:109]
	v_mfma_f32_16x16x32_bf16 v[102:105], v[146:149], v[170:173], v[102:105]
	v_mfma_f32_16x16x32_bf16 v[98:101], v[154:157], v[170:173], v[98:101]
	v_mfma_f32_16x16x32_bf16 v[78:81], v[146:149], v[196:199], v[78:81]
	v_mfma_f32_16x16x32_bf16 v[74:77], v[154:157], v[196:199], v[74:77]
	v_mfma_f32_16x16x32_bf16 v[70:73], v[146:149], v[204:207], v[70:73]
	v_mfma_f32_16x16x32_bf16 v[66:69], v[154:157], v[204:207], v[66:69]
	v_mfma_f32_16x16x32_bf16 v[110:113], v[150:153], v[166:169], v[110:113]
	v_mfma_f32_16x16x32_bf16 v[106:109], v[158:161], v[166:169], v[106:109]
	v_mfma_f32_16x16x32_bf16 v[102:105], v[150:153], v[174:177], v[102:105]
	v_mfma_f32_16x16x32_bf16 v[98:101], v[158:161], v[174:177], v[98:101]
	v_mfma_f32_16x16x32_bf16 v[78:81], v[150:153], v[200:203], v[78:81]
	v_mfma_f32_16x16x32_bf16 v[74:77], v[158:161], v[200:203], v[74:77]
	v_mfma_f32_16x16x32_bf16 v[70:73], v[150:153], v[208:211], v[70:73]
	v_mfma_f32_16x16x32_bf16 v[66:69], v[158:161], v[208:211], v[66:69]
	s_setprio 0
	s_barrier
	s_add_i32 s36, s39, s33
	v_lshl_add_u64 v[192:193], v[192:193], 0, s[18:19]
	s_mov_b32 m0, s36
	ds_read_b128 v[162:165], v217 offset:49152
	ds_read_b128 v[166:169], v217 offset:50176
	ds_read_b128 v[170:173], v217 offset:51200
	ds_read_b128 v[174:177], v217 offset:52224
	ds_read_b128 v[196:199], v217 offset:53248
	ds_read_b128 v[200:203], v217 offset:54272
	ds_read_b128 v[204:207], v217 offset:55296
	ds_read_b128 v[208:211], v217 offset:56320
	global_load_lds_dwordx4 v[192:193], off
	s_add_i32 m0, s36, 0x2000
	s_add_u32 s34, s34, 0x160080
	v_lshl_add_u64 v[192:193], v[218:219], 0, s[18:19]
	s_addc_u32 s35, s35, 0
	s_add_i32 s36, s62, s33
	global_load_lds_dwordx4 v[192:193], off
	s_mov_b32 m0, s36
	s_nop 0
	global_load_lds_dwordx4 v180, s[34:35]
	s_add_i32 m0, s36, 0x2000
	s_nop 0
	global_load_lds_dwordx4 v184, s[34:35]
	v_lshl_add_u64 v[192:193], v[220:221], 0, s[18:19]
	s_mov_b32 m0, s46
	s_nop 0
	global_load_lds_dwordx4 v[192:193], off
	v_lshl_add_u64 v[192:193], v[222:223], 0, s[18:19]
	s_mov_b32 m0, s47
	s_nop 0
	global_load_lds_dwordx4 v[192:193], off
	s_waitcnt vmcnt(8)
	s_waitcnt lgkmcnt(0)
	s_barrier
	s_setprio 1
	s_waitcnt lgkmcnt(0)
	v_mfma_f32_16x16x32_bf16 v[62:65], v[130:133], v[162:165], v[62:65]
	v_mfma_f32_16x16x32_bf16 v[58:61], v[138:141], v[162:165], v[58:61]
	v_mfma_f32_16x16x32_bf16 v[54:57], v[130:133], v[170:173], v[54:57]
	v_mfma_f32_16x16x32_bf16 v[50:53], v[138:141], v[170:173], v[50:53]
	v_mfma_f32_16x16x32_bf16 v[30:33], v[130:133], v[196:199], v[30:33]
	v_mfma_f32_16x16x32_bf16 v[26:29], v[138:141], v[196:199], v[26:29]
	v_mfma_f32_16x16x32_bf16 v[22:25], v[130:133], v[204:207], v[22:25]
	v_mfma_f32_16x16x32_bf16 v[18:21], v[138:141], v[204:207], v[18:21]
	v_mfma_f32_16x16x32_bf16 v[62:65], v[134:137], v[166:169], v[62:65]
	v_mfma_f32_16x16x32_bf16 v[58:61], v[142:145], v[166:169], v[58:61]
	v_mfma_f32_16x16x32_bf16 v[54:57], v[134:137], v[174:177], v[54:57]
	v_mfma_f32_16x16x32_bf16 v[50:53], v[142:145], v[174:177], v[50:53]
	v_mfma_f32_16x16x32_bf16 v[30:33], v[134:137], v[200:203], v[30:33]
	v_mfma_f32_16x16x32_bf16 v[26:29], v[142:145], v[200:203], v[26:29]
	v_mfma_f32_16x16x32_bf16 v[22:25], v[134:137], v[208:211], v[22:25]
	v_mfma_f32_16x16x32_bf16 v[18:21], v[142:145], v[208:211], v[18:21]
	s_setprio 0
	s_setprio 1
	v_mfma_f32_16x16x32_bf16 v[46:49], v[146:149], v[162:165], v[46:49]
	v_mfma_f32_16x16x32_bf16 v[42:45], v[154:157], v[162:165], v[42:45]
	v_mfma_f32_16x16x32_bf16 v[38:41], v[146:149], v[170:173], v[38:41]
	v_mfma_f32_16x16x32_bf16 v[34:37], v[154:157], v[170:173], v[34:37]
	v_mfma_f32_16x16x32_bf16 v[14:17], v[146:149], v[196:199], v[14:17]
	v_mfma_f32_16x16x32_bf16 v[10:13], v[154:157], v[196:199], v[10:13]
	v_mfma_f32_16x16x32_bf16 v[6:9], v[146:149], v[204:207], v[6:9]
	v_mfma_f32_16x16x32_bf16 v[2:5], v[154:157], v[204:207], v[2:5]
	v_mfma_f32_16x16x32_bf16 v[46:49], v[150:153], v[166:169], v[46:49]
	v_mfma_f32_16x16x32_bf16 v[42:45], v[158:161], v[166:169], v[42:45]
	v_mfma_f32_16x16x32_bf16 v[38:41], v[150:153], v[174:177], v[38:41]
	v_mfma_f32_16x16x32_bf16 v[34:37], v[158:161], v[174:177], v[34:37]
	v_mfma_f32_16x16x32_bf16 v[14:17], v[150:153], v[200:203], v[14:17]
	v_mfma_f32_16x16x32_bf16 v[10:13], v[158:161], v[200:203], v[10:13]
	v_mfma_f32_16x16x32_bf16 v[6:9], v[150:153], v[208:211], v[6:9]
	v_mfma_f32_16x16x32_bf16 v[2:5], v[158:161], v[208:211], v[2:5]
	s_setprio 0
	s_barrier
	s_add_u32 s30, s30, 0x100
	s_addc_u32 s31, s31, 0
	s_add_u32 s23, s23, 0x100
	s_addc_u32 s29, s29, 0
	s_cmp_ge_i32 s38, s61
	s_mov_b32 s34, s38
	s_cbranch_scc0 .LBB0_357
	s_branch .Lpeeldone_12
.LBB0_357:
	ds_read_b128 v[130:133], v215
	ds_read_b128 v[134:137], v215 offset:1024
	ds_read_b128 v[138:141], v215 offset:2048
	ds_read_b128 v[142:145], v215 offset:3072
	ds_read_b128 v[146:149], v216
	ds_read_b128 v[150:153], v216 offset:1024
	ds_read_b128 v[154:157], v216 offset:2048
	ds_read_b128 v[158:161], v216 offset:3072
	s_add_i32 s38, s34, 2
	s_add_u32 s35, s30, 0xffea0080
	s_addc_u32 s36, s31, -1
	s_cmp_eq_u32 s28, s34
	s_cselect_b32 s34, s26, s23
	s_cselect_b32 s37, s25, s36
	s_cselect_b32 s36, s24, s35
	s_cselect_b32 s35, s27, s29
	s_add_i32 m0, s40, 0xc000
	ds_read_b128 v[162:165], v217
	ds_read_b128 v[166:169], v217 offset:1024
	ds_read_b128 v[170:173], v217 offset:2048
	ds_read_b128 v[174:177], v217 offset:3072
	ds_read_b128 v[196:199], v217 offset:4096
	ds_read_b128 v[200:203], v217 offset:5120
	ds_read_b128 v[204:207], v217 offset:6144
	ds_read_b128 v[208:211], v217 offset:7168
	global_load_lds_dwordx4 v188, s[30:31]
	s_add_i32 m0, s40, 0xe000
	s_nop 0
	global_load_lds_dwordx4 v190, s[30:31]
	s_waitcnt vmcnt(8)
	s_waitcnt lgkmcnt(0)
	s_barrier
	s_setprio 1
	s_waitcnt lgkmcnt(0)
	v_mfma_f32_16x16x32_bf16 v[126:129], v[130:133], v[162:165], v[126:129]
	v_mfma_f32_16x16x32_bf16 v[122:125], v[138:141], v[162:165], v[122:125]
	v_mfma_f32_16x16x32_bf16 v[118:121], v[130:133], v[170:173], v[118:121]
	v_mfma_f32_16x16x32_bf16 v[114:117], v[138:141], v[170:173], v[114:117]
	v_mfma_f32_16x16x32_bf16 v[94:97], v[130:133], v[196:199], v[94:97]
	v_mfma_f32_16x16x32_bf16 v[90:93], v[138:141], v[196:199], v[90:93]
	v_mfma_f32_16x16x32_bf16 v[86:89], v[130:133], v[204:207], v[86:89]
	v_mfma_f32_16x16x32_bf16 v[82:85], v[138:141], v[204:207], v[82:85]
	v_mfma_f32_16x16x32_bf16 v[126:129], v[134:137], v[166:169], v[126:129]
	v_mfma_f32_16x16x32_bf16 v[122:125], v[142:145], v[166:169], v[122:125]
	v_mfma_f32_16x16x32_bf16 v[118:121], v[134:137], v[174:177], v[118:121]
	v_mfma_f32_16x16x32_bf16 v[114:117], v[142:145], v[174:177], v[114:117]
	v_mfma_f32_16x16x32_bf16 v[94:97], v[134:137], v[200:203], v[94:97]
	v_mfma_f32_16x16x32_bf16 v[90:93], v[142:145], v[200:203], v[90:93]
	v_mfma_f32_16x16x32_bf16 v[86:89], v[134:137], v[208:211], v[86:89]
	v_mfma_f32_16x16x32_bf16 v[82:85], v[142:145], v[208:211], v[82:85]
	s_setprio 0
	s_setprio 1
	v_mfma_f32_16x16x32_bf16 v[110:113], v[146:149], v[162:165], v[110:113]
	v_mfma_f32_16x16x32_bf16 v[106:109], v[154:157], v[162:165], v[106:109]
	v_mfma_f32_16x16x32_bf16 v[102:105], v[146:149], v[170:173], v[102:105]
	v_mfma_f32_16x16x32_bf16 v[98:101], v[154:157], v[170:173], v[98:101]
	v_mfma_f32_16x16x32_bf16 v[78:81], v[146:149], v[196:199], v[78:81]
	v_mfma_f32_16x16x32_bf16 v[74:77], v[154:157], v[196:199], v[74:77]
	v_mfma_f32_16x16x32_bf16 v[70:73], v[146:149], v[204:207], v[70:73]
	v_mfma_f32_16x16x32_bf16 v[66:69], v[154:157], v[204:207], v[66:69]
	v_mfma_f32_16x16x32_bf16 v[110:113], v[150:153], v[166:169], v[110:113]
	v_mfma_f32_16x16x32_bf16 v[106:109], v[158:161], v[166:169], v[106:109]
	v_mfma_f32_16x16x32_bf16 v[102:105], v[150:153], v[174:177], v[102:105]
	v_mfma_f32_16x16x32_bf16 v[98:101], v[158:161], v[174:177], v[98:101]
	v_mfma_f32_16x16x32_bf16 v[78:81], v[150:153], v[200:203], v[78:81]
	v_mfma_f32_16x16x32_bf16 v[74:77], v[158:161], v[200:203], v[74:77]
	v_mfma_f32_16x16x32_bf16 v[70:73], v[150:153], v[208:211], v[70:73]
	v_mfma_f32_16x16x32_bf16 v[66:69], v[158:161], v[208:211], v[66:69]
	s_setprio 0
	s_barrier
	s_add_i32 s39, s53, s33
	v_lshl_add_u64 v[192:193], s[34:35], 0, v[180:181]
	s_mov_b32 m0, s39
	ds_read_b128 v[162:165], v217 offset:16384
	ds_read_b128 v[166:169], v217 offset:17408
	ds_read_b128 v[170:173], v217 offset:18432
	ds_read_b128 v[174:177], v217 offset:19456
	ds_read_b128 v[196:199], v217 offset:20480
	ds_read_b128 v[200:203], v217 offset:21504
	ds_read_b128 v[204:207], v217 offset:22528
	ds_read_b128 v[208:211], v217 offset:23552
	global_load_lds_dwordx4 v180, s[34:35]
	s_add_i32 m0, s39, 0x2000
	s_add_u32 s62, s34, 0x160000
	v_lshl_add_u64 v[218:219], s[34:35], 0, v[184:185]
	s_addc_u32 s63, s35, 0
	s_add_i32 s39, s54, s33
	global_load_lds_dwordx4 v184, s[34:35]
	s_mov_b32 m0, s39
	v_lshl_add_u64 v[222:223], s[36:37], 0, v[182:183]
	global_load_lds_dwordx4 v180, s[62:63]
	s_add_i32 m0, s39, 0x2000
	s_nop 0
	global_load_lds_dwordx4 v184, s[62:63]
	v_lshl_add_u64 v[220:221], s[36:37], 0, v[178:179]
	s_mov_b32 m0, s40
	s_nop 0
	global_load_lds_dwordx4 v178, s[36:37]
	s_mov_b32 m0, s41
	s_nop 0
	global_load_lds_dwordx4 v182, s[36:37]
	s_waitcnt vmcnt(8)
	s_waitcnt lgkmcnt(0)
	s_barrier
	s_setprio 1
	s_waitcnt lgkmcnt(0)
	v_mfma_f32_16x16x32_bf16 v[62:65], v[130:133], v[162:165], v[62:65]
	v_mfma_f32_16x16x32_bf16 v[58:61], v[138:141], v[162:165], v[58:61]
	v_mfma_f32_16x16x32_bf16 v[54:57], v[130:133], v[170:173], v[54:57]
	v_mfma_f32_16x16x32_bf16 v[50:53], v[138:141], v[170:173], v[50:53]
	v_mfma_f32_16x16x32_bf16 v[30:33], v[130:133], v[196:199], v[30:33]
	v_mfma_f32_16x16x32_bf16 v[26:29], v[138:141], v[196:199], v[26:29]
	v_mfma_f32_16x16x32_bf16 v[22:25], v[130:133], v[204:207], v[22:25]
	v_mfma_f32_16x16x32_bf16 v[18:21], v[138:141], v[204:207], v[18:21]
	v_mfma_f32_16x16x32_bf16 v[62:65], v[134:137], v[166:169], v[62:65]
	v_mfma_f32_16x16x32_bf16 v[58:61], v[142:145], v[166:169], v[58:61]
	v_mfma_f32_16x16x32_bf16 v[54:57], v[134:137], v[174:177], v[54:57]
	v_mfma_f32_16x16x32_bf16 v[50:53], v[142:145], v[174:177], v[50:53]
	v_mfma_f32_16x16x32_bf16 v[30:33], v[134:137], v[200:203], v[30:33]
	v_mfma_f32_16x16x32_bf16 v[26:29], v[142:145], v[200:203], v[26:29]
	v_mfma_f32_16x16x32_bf16 v[22:25], v[134:137], v[208:211], v[22:25]
	v_mfma_f32_16x16x32_bf16 v[18:21], v[142:145], v[208:211], v[18:21]
	s_setprio 0
	s_setprio 1
	v_mfma_f32_16x16x32_bf16 v[46:49], v[146:149], v[162:165], v[46:49]
	v_mfma_f32_16x16x32_bf16 v[42:45], v[154:157], v[162:165], v[42:45]
	v_mfma_f32_16x16x32_bf16 v[38:41], v[146:149], v[170:173], v[38:41]
	v_mfma_f32_16x16x32_bf16 v[34:37], v[154:157], v[170:173], v[34:37]
	v_mfma_f32_16x16x32_bf16 v[14:17], v[146:149], v[196:199], v[14:17]
	v_mfma_f32_16x16x32_bf16 v[10:13], v[154:157], v[196:199], v[10:13]
	v_mfma_f32_16x16x32_bf16 v[6:9], v[146:149], v[204:207], v[6:9]
	v_mfma_f32_16x16x32_bf16 v[2:5], v[154:157], v[204:207], v[2:5]
	v_mfma_f32_16x16x32_bf16 v[46:49], v[150:153], v[166:169], v[46:49]
	v_mfma_f32_16x16x32_bf16 v[42:45], v[158:161], v[166:169], v[42:45]
	v_mfma_f32_16x16x32_bf16 v[38:41], v[150:153], v[174:177], v[38:41]
	v_mfma_f32_16x16x32_bf16 v[34:37], v[158:161], v[174:177], v[34:37]
	v_mfma_f32_16x16x32_bf16 v[14:17], v[150:153], v[200:203], v[14:17]
	v_mfma_f32_16x16x32_bf16 v[10:13], v[158:161], v[200:203], v[10:13]
	v_mfma_f32_16x16x32_bf16 v[6:9], v[150:153], v[208:211], v[6:9]
	v_mfma_f32_16x16x32_bf16 v[2:5], v[158:161], v[208:211], v[2:5]
	s_setprio 0
	s_barrier
	s_add_i32 s39, 0, 0x18000
	s_add_i32 s62, 0, 0x1c000
	v_add_u32_e32 v142, s39, v213
	v_add_u32_e32 v158, s62, v213
	ds_read_b128 v[130:133], v142
	ds_read_b128 v[134:137], v142 offset:1024
	ds_read_b128 v[138:141], v142 offset:2048
	ds_read_b128 v[142:145], v142 offset:3072
	ds_read_b128 v[146:149], v158
	ds_read_b128 v[150:153], v158 offset:1024
	ds_read_b128 v[154:157], v158 offset:2048
	ds_read_b128 v[158:161], v158 offset:3072
	s_add_u32 s36, s36, 0x160000
	s_addc_u32 s37, s37, 0
	s_mov_b32 m0, s42
	ds_read_b128 v[162:165], v217 offset:32768
	ds_read_b128 v[166:169], v217 offset:33792
	ds_read_b128 v[170:173], v217 offset:34816
	ds_read_b128 v[174:177], v217 offset:35840
	ds_read_b128 v[196:199], v217 offset:36864
	ds_read_b128 v[200:203], v217 offset:37888
	ds_read_b128 v[204:207], v217 offset:38912
	ds_read_b128 v[208:211], v217 offset:39936
	global_load_lds_dwordx4 v178, s[36:37]
	v_lshl_add_u64 v[224:225], s[36:37], 0, v[182:183]
	s_mov_b32 m0, s43
	s_nop 0
	global_load_lds_dwordx4 v182, s[36:37]
	s_waitcnt vmcnt(8)
	s_waitcnt lgkmcnt(0)
	s_barrier
	s_setprio 1
	s_waitcnt lgkmcnt(0)
	v_mfma_f32_16x16x32_bf16 v[126:129], v[130:133], v[162:165], v[126:129]
	v_mfma_f32_16x16x32_bf16 v[122:125], v[138:141], v[162:165], v[122:125]
	v_mfma_f32_16x16x32_bf16 v[118:121], v[130:133], v[170:173], v[118:121]
	v_mfma_f32_16x16x32_bf16 v[114:117], v[138:141], v[170:173], v[114:117]
	v_mfma_f32_16x16x32_bf16 v[94:97], v[130:133], v[196:199], v[94:97]
	v_mfma_f32_16x16x32_bf16 v[90:93], v[138:141], v[196:199], v[90:93]
	v_mfma_f32_16x16x32_bf16 v[86:89], v[130:133], v[204:207], v[86:89]
	v_mfma_f32_16x16x32_bf16 v[82:85], v[138:141], v[204:207], v[82:85]
	v_mfma_f32_16x16x32_bf16 v[126:129], v[134:137], v[166:169], v[126:129]
	v_mfma_f32_16x16x32_bf16 v[122:125], v[142:145], v[166:169], v[122:125]
	v_mfma_f32_16x16x32_bf16 v[118:121], v[134:137], v[174:177], v[118:121]
	v_mfma_f32_16x16x32_bf16 v[114:117], v[142:145], v[174:177], v[114:117]
	v_mfma_f32_16x16x32_bf16 v[94:97], v[134:137], v[200:203], v[94:97]
	v_mfma_f32_16x16x32_bf16 v[90:93], v[142:145], v[200:203], v[90:93]
	v_mfma_f32_16x16x32_bf16 v[86:89], v[134:137], v[208:211], v[86:89]
	v_mfma_f32_16x16x32_bf16 v[82:85], v[142:145], v[208:211], v[82:85]
	s_setprio 0
	s_setprio 1
	v_mfma_f32_16x16x32_bf16 v[110:113], v[146:149], v[162:165], v[110:113]
	v_mfma_f32_16x16x32_bf16 v[106:109], v[154:157], v[162:165], v[106:109]
	v_mfma_f32_16x16x32_bf16 v[102:105], v[146:149], v[170:173], v[102:105]
	v_mfma_f32_16x16x32_bf16 v[98:101], v[154:157], v[170:173], v[98:101]
	v_mfma_f32_16x16x32_bf16 v[78:81], v[146:149], v[196:199], v[78:81]
	v_mfma_f32_16x16x32_bf16 v[74:77], v[154:157], v[196:199], v[74:77]
	v_mfma_f32_16x16x32_bf16 v[70:73], v[146:149], v[204:207], v[70:73]
	v_mfma_f32_16x16x32_bf16 v[66:69], v[154:157], v[204:207], v[66:69]
	v_mfma_f32_16x16x32_bf16 v[110:113], v[150:153], v[166:169], v[110:113]
	v_mfma_f32_16x16x32_bf16 v[106:109], v[158:161], v[166:169], v[106:109]
	v_mfma_f32_16x16x32_bf16 v[102:105], v[150:153], v[174:177], v[102:105]
	v_mfma_f32_16x16x32_bf16 v[98:101], v[158:161], v[174:177], v[98:101]
	v_mfma_f32_16x16x32_bf16 v[78:81], v[150:153], v[200:203], v[78:81]
	v_mfma_f32_16x16x32_bf16 v[74:77], v[158:161], v[200:203], v[74:77]
	v_mfma_f32_16x16x32_bf16 v[70:73], v[150:153], v[208:211], v[70:73]
	v_mfma_f32_16x16x32_bf16 v[66:69], v[158:161], v[208:211], v[66:69]
	s_setprio 0
	s_barrier
	s_add_i32 s36, s39, s33
	v_lshl_add_u64 v[192:193], v[192:193], 0, s[18:19]
	s_mov_b32 m0, s36
	ds_read_b128 v[162:165], v217 offset:49152
	ds_read_b128 v[166:169], v217 offset:50176
	ds_read_b128 v[170:173], v217 offset:51200
	ds_read_b128 v[174:177], v217 offset:52224
	ds_read_b128 v[196:199], v217 offset:53248
	ds_read_b128 v[200:203], v217 offset:54272
	ds_read_b128 v[204:207], v217 offset:55296
	ds_read_b128 v[208:211], v217 offset:56320
	global_load_lds_dwordx4 v[192:193], off
	s_add_i32 m0, s36, 0x2000
	s_add_u32 s34, s34, 0x160080
	v_lshl_add_u64 v[192:193], v[218:219], 0, s[18:19]
	s_addc_u32 s35, s35, 0
	s_add_i32 s36, s62, s33
	global_load_lds_dwordx4 v[192:193], off
	s_mov_b32 m0, s36
	s_nop 0
	global_load_lds_dwordx4 v180, s[34:35]
	s_add_i32 m0, s36, 0x2000
	s_nop 0
	global_load_lds_dwordx4 v184, s[34:35]
	v_lshl_add_u64 v[192:193], v[220:221], 0, s[18:19]
	s_mov_b32 m0, s46
	s_nop 0
	global_load_lds_dwordx4 v[192:193], off
	v_lshl_add_u64 v[192:193], v[222:223], 0, s[18:19]
	s_mov_b32 m0, s47
	s_nop 0
	global_load_lds_dwordx4 v[192:193], off
	s_waitcnt vmcnt(8)
	s_waitcnt lgkmcnt(0)
	s_barrier
	s_setprio 1
	s_waitcnt lgkmcnt(0)
	v_mfma_f32_16x16x32_bf16 v[62:65], v[130:133], v[162:165], v[62:65]
	v_mfma_f32_16x16x32_bf16 v[58:61], v[138:141], v[162:165], v[58:61]
	v_mfma_f32_16x16x32_bf16 v[54:57], v[130:133], v[170:173], v[54:57]
	v_mfma_f32_16x16x32_bf16 v[50:53], v[138:141], v[170:173], v[50:53]
	v_mfma_f32_16x16x32_bf16 v[30:33], v[130:133], v[196:199], v[30:33]
	v_mfma_f32_16x16x32_bf16 v[26:29], v[138:141], v[196:199], v[26:29]
	v_mfma_f32_16x16x32_bf16 v[22:25], v[130:133], v[204:207], v[22:25]
	v_mfma_f32_16x16x32_bf16 v[18:21], v[138:141], v[204:207], v[18:21]
	v_mfma_f32_16x16x32_bf16 v[62:65], v[134:137], v[166:169], v[62:65]
	v_mfma_f32_16x16x32_bf16 v[58:61], v[142:145], v[166:169], v[58:61]
	v_mfma_f32_16x16x32_bf16 v[54:57], v[134:137], v[174:177], v[54:57]
	v_mfma_f32_16x16x32_bf16 v[50:53], v[142:145], v[174:177], v[50:53]
	v_mfma_f32_16x16x32_bf16 v[30:33], v[134:137], v[200:203], v[30:33]
	v_mfma_f32_16x16x32_bf16 v[26:29], v[142:145], v[200:203], v[26:29]
	v_mfma_f32_16x16x32_bf16 v[22:25], v[134:137], v[208:211], v[22:25]
	v_mfma_f32_16x16x32_bf16 v[18:21], v[142:145], v[208:211], v[18:21]
	s_setprio 0
	s_setprio 1
	v_mfma_f32_16x16x32_bf16 v[46:49], v[146:149], v[162:165], v[46:49]
	v_mfma_f32_16x16x32_bf16 v[42:45], v[154:157], v[162:165], v[42:45]
	v_mfma_f32_16x16x32_bf16 v[38:41], v[146:149], v[170:173], v[38:41]
	v_mfma_f32_16x16x32_bf16 v[34:37], v[154:157], v[170:173], v[34:37]
	v_mfma_f32_16x16x32_bf16 v[14:17], v[146:149], v[196:199], v[14:17]
	v_mfma_f32_16x16x32_bf16 v[10:13], v[154:157], v[196:199], v[10:13]
	v_mfma_f32_16x16x32_bf16 v[6:9], v[146:149], v[204:207], v[6:9]
	v_mfma_f32_16x16x32_bf16 v[2:5], v[154:157], v[204:207], v[2:5]
	v_mfma_f32_16x16x32_bf16 v[46:49], v[150:153], v[166:169], v[46:49]
	v_mfma_f32_16x16x32_bf16 v[42:45], v[158:161], v[166:169], v[42:45]
	v_mfma_f32_16x16x32_bf16 v[38:41], v[150:153], v[174:177], v[38:41]
	v_mfma_f32_16x16x32_bf16 v[34:37], v[158:161], v[174:177], v[34:37]
	v_mfma_f32_16x16x32_bf16 v[14:17], v[150:153], v[200:203], v[14:17]
	v_mfma_f32_16x16x32_bf16 v[10:13], v[158:161], v[200:203], v[10:13]
	v_mfma_f32_16x16x32_bf16 v[6:9], v[150:153], v[208:211], v[6:9]
	v_mfma_f32_16x16x32_bf16 v[2:5], v[158:161], v[208:211], v[2:5]
	s_setprio 0
	s_barrier
	s_add_u32 s30, s30, 0x100
	s_addc_u32 s31, s31, 0
	s_add_u32 s23, s23, 0x100
	s_addc_u32 s29, s29, 0
	s_cmp_ge_i32 s38, s61
	s_mov_b32 s34, s38
	s_cbranch_scc0 .LBB0_357

.Lpeel_11:
	ds_read_b128 v[148:151], v145
	ds_read_b128 v[152:155], v145 offset:1024
	s_add_u32 s36, s34, 0xfff80080
	s_addc_u32 s37, s35, -1
	s_cmp_eq_u32 s58, 28
	s_cselect_b32 s39, s21, s37
	s_cselect_b32 s38, s54, s36
	s_cselect_b32 s37, s23, s57
	s_cselect_b32 s36, s55, s56
	s_add_i32 m0, s27, 0xc000
	global_load_lds_dwordx4 v138, s[34:35]
	s_add_i32 m0, s27, 0xe000
	s_nop 0
	global_load_lds_dwordx4 v140, s[34:35]
	s_waitcnt vmcnt(8)
	s_waitcnt lgkmcnt(0)
	s_barrier
	s_setprio 1
	s_waitcnt lgkmcnt(0)
	v_mfma_f32_16x16x32_bf16 v[126:129], v[148:151], v[180:183], 0
	v_mfma_f32_16x16x32_bf16 v[122:125], v[156:159], v[180:183], 0
	v_mfma_f32_16x16x32_bf16 v[118:121], v[148:151], v[188:191], 0
	v_mfma_f32_16x16x32_bf16 v[114:117], v[156:159], v[188:191], 0
	v_mfma_f32_16x16x32_bf16 v[102:105], v[148:151], v[200:203], 0
	v_mfma_f32_16x16x32_bf16 v[98:101], v[156:159], v[200:203], 0
	v_mfma_f32_16x16x32_bf16 v[86:89], v[148:151], v[208:211], 0
	v_mfma_f32_16x16x32_bf16 v[82:85], v[156:159], v[208:211], 0
	v_mfma_f32_16x16x32_bf16 v[126:129], v[152:155], v[184:187], v[126:129]
	v_mfma_f32_16x16x32_bf16 v[122:125], v[160:163], v[184:187], v[122:125]
	v_mfma_f32_16x16x32_bf16 v[118:121], v[152:155], v[196:199], v[118:121]
	v_mfma_f32_16x16x32_bf16 v[114:117], v[160:163], v[196:199], v[114:117]
	v_mfma_f32_16x16x32_bf16 v[102:105], v[152:155], v[204:207], v[102:105]
	v_mfma_f32_16x16x32_bf16 v[98:101], v[160:163], v[204:207], v[98:101]
	v_mfma_f32_16x16x32_bf16 v[86:89], v[152:155], v[212:215], v[86:89]
	v_mfma_f32_16x16x32_bf16 v[82:85], v[160:163], v[212:215], v[82:85]
	s_setprio 0
	s_setprio 1
	v_mfma_f32_16x16x32_bf16 v[110:113], v[164:167], v[180:183], 0
	v_mfma_f32_16x16x32_bf16 v[106:109], v[172:175], v[180:183], 0
	v_mfma_f32_16x16x32_bf16 v[94:97], v[164:167], v[188:191], 0
	v_mfma_f32_16x16x32_bf16 v[90:93], v[172:175], v[188:191], 0
	v_mfma_f32_16x16x32_bf16 v[78:81], v[164:167], v[200:203], 0
	v_mfma_f32_16x16x32_bf16 v[74:77], v[172:175], v[200:203], 0
	v_mfma_f32_16x16x32_bf16 v[70:73], v[164:167], v[208:211], 0
	v_mfma_f32_16x16x32_bf16 v[66:69], v[172:175], v[208:211], 0
	v_mfma_f32_16x16x32_bf16 v[110:113], v[168:171], v[184:187], v[110:113]
	v_mfma_f32_16x16x32_bf16 v[106:109], v[176:179], v[184:187], v[106:109]
	v_mfma_f32_16x16x32_bf16 v[94:97], v[168:171], v[196:199], v[94:97]
	v_mfma_f32_16x16x32_bf16 v[90:93], v[176:179], v[196:199], v[90:93]
	v_mfma_f32_16x16x32_bf16 v[78:81], v[168:171], v[204:207], v[78:81]
	v_mfma_f32_16x16x32_bf16 v[74:77], v[176:179], v[204:207], v[74:77]
	v_mfma_f32_16x16x32_bf16 v[70:73], v[168:171], v[212:215], v[70:73]
	v_mfma_f32_16x16x32_bf16 v[66:69], v[176:179], v[212:215], v[66:69]
	s_setprio 0
	s_barrier
	s_add_i32 s59, s47, s33
	v_lshl_add_u64 v[192:193], s[36:37], 0, v[134:135]
	s_mov_b32 m0, s59
	ds_read_b128 v[180:183], v147 offset:16384
	ds_read_b128 v[184:187], v147 offset:17408
	ds_read_b128 v[188:191], v147 offset:18432
	ds_read_b128 v[196:199], v147 offset:19456
	ds_read_b128 v[200:203], v147 offset:20480
	ds_read_b128 v[204:207], v147 offset:21504
	ds_read_b128 v[208:211], v147 offset:22528
	ds_read_b128 v[212:215], v147 offset:23552
	global_load_lds_dwordx4 v134, s[36:37]
	s_add_i32 m0, s59, 0x2000
	s_add_u32 s60, s36, 0x80000
	v_lshl_add_u64 v[216:217], s[36:37], 0, v[130:131]
	s_addc_u32 s61, s37, 0
	s_add_i32 s59, s48, s33
	global_load_lds_dwordx4 v130, s[36:37]
	s_mov_b32 m0, s59
	v_lshl_add_u64 v[220:221], s[38:39], 0, v[132:133]
	global_load_lds_dwordx4 v134, s[60:61]
	s_add_i32 m0, s59, 0x2000
	s_nop 0
	global_load_lds_dwordx4 v130, s[60:61]
	v_lshl_add_u64 v[218:219], s[38:39], 0, v[136:137]
	s_mov_b32 m0, s27
	s_nop 0
	global_load_lds_dwordx4 v136, s[38:39]
	s_mov_b32 m0, s41
	s_nop 0
	global_load_lds_dwordx4 v132, s[38:39]
	s_waitcnt vmcnt(8)
	s_waitcnt lgkmcnt(0)
	s_barrier
	s_setprio 1
	s_waitcnt lgkmcnt(0)
	v_mfma_f32_16x16x32_bf16 v[62:65], v[148:151], v[180:183], 0
	v_mfma_f32_16x16x32_bf16 v[58:61], v[156:159], v[180:183], 0
	v_mfma_f32_16x16x32_bf16 v[54:57], v[148:151], v[188:191], 0
	v_mfma_f32_16x16x32_bf16 v[50:53], v[156:159], v[188:191], 0
	v_mfma_f32_16x16x32_bf16 v[38:41], v[148:151], v[200:203], 0
	v_mfma_f32_16x16x32_bf16 v[34:37], v[156:159], v[200:203], 0
	v_mfma_f32_16x16x32_bf16 v[22:25], v[148:151], v[208:211], 0
	v_mfma_f32_16x16x32_bf16 v[18:21], v[156:159], v[208:211], 0
	v_mfma_f32_16x16x32_bf16 v[62:65], v[152:155], v[184:187], v[62:65]
	v_mfma_f32_16x16x32_bf16 v[58:61], v[160:163], v[184:187], v[58:61]
	v_mfma_f32_16x16x32_bf16 v[54:57], v[152:155], v[196:199], v[54:57]
	v_mfma_f32_16x16x32_bf16 v[50:53], v[160:163], v[196:199], v[50:53]
	v_mfma_f32_16x16x32_bf16 v[38:41], v[152:155], v[204:207], v[38:41]
	v_mfma_f32_16x16x32_bf16 v[34:37], v[160:163], v[204:207], v[34:37]
	v_mfma_f32_16x16x32_bf16 v[22:25], v[152:155], v[212:215], v[22:25]
	v_mfma_f32_16x16x32_bf16 v[18:21], v[160:163], v[212:215], v[18:21]
	s_setprio 0
	s_setprio 1
	v_mfma_f32_16x16x32_bf16 v[46:49], v[164:167], v[180:183], 0
	v_mfma_f32_16x16x32_bf16 v[42:45], v[172:175], v[180:183], 0
	v_mfma_f32_16x16x32_bf16 v[30:33], v[164:167], v[188:191], 0
	v_mfma_f32_16x16x32_bf16 v[26:29], v[172:175], v[188:191], 0
	v_mfma_f32_16x16x32_bf16 v[14:17], v[164:167], v[200:203], 0
	v_mfma_f32_16x16x32_bf16 v[10:13], v[172:175], v[200:203], 0
	v_mfma_f32_16x16x32_bf16 v[6:9], v[164:167], v[208:211], 0
	v_mfma_f32_16x16x32_bf16 v[2:5], v[172:175], v[208:211], 0
	v_mfma_f32_16x16x32_bf16 v[46:49], v[168:171], v[184:187], v[46:49]
	v_mfma_f32_16x16x32_bf16 v[42:45], v[176:179], v[184:187], v[42:45]
	v_mfma_f32_16x16x32_bf16 v[30:33], v[168:171], v[196:199], v[30:33]
	v_mfma_f32_16x16x32_bf16 v[26:29], v[176:179], v[196:199], v[26:29]
	v_mfma_f32_16x16x32_bf16 v[14:17], v[168:171], v[204:207], v[14:17]
	v_mfma_f32_16x16x32_bf16 v[10:13], v[176:179], v[204:207], v[10:13]
	v_mfma_f32_16x16x32_bf16 v[6:9], v[168:171], v[212:215], v[6:9]
	v_mfma_f32_16x16x32_bf16 v[2:5], v[176:179], v[212:215], v[2:5]
	s_setprio 0
	s_barrier
	s_add_i32 s59, 0, 0x18000
	s_add_i32 s60, 0, 0x1c000
	v_add_u32_e32 v160, s59, v143
	v_add_u32_e32 v176, s60, v143
	ds_read_b128 v[148:151], v160
	ds_read_b128 v[152:155], v160 offset:1024
	ds_read_b128 v[156:159], v160 offset:2048
	ds_read_b128 v[160:163], v160 offset:3072
	ds_read_b128 v[164:167], v176
	ds_read_b128 v[168:171], v176 offset:1024
	ds_read_b128 v[172:175], v176 offset:2048
	ds_read_b128 v[176:179], v176 offset:3072
	s_add_u32 s38, s38, 0x80000
	s_addc_u32 s39, s39, 0
	s_mov_b32 m0, s42
	ds_read_b128 v[180:183], v147 offset:32768
	ds_read_b128 v[184:187], v147 offset:33792
	ds_read_b128 v[188:191], v147 offset:34816
	ds_read_b128 v[196:199], v147 offset:35840
	ds_read_b128 v[200:203], v147 offset:36864
	ds_read_b128 v[204:207], v147 offset:37888
	ds_read_b128 v[208:211], v147 offset:38912
	ds_read_b128 v[212:215], v147 offset:39936
	global_load_lds_dwordx4 v136, s[38:39]
	v_lshl_add_u64 v[222:223], s[38:39], 0, v[132:133]
	s_mov_b32 m0, s43
	s_nop 0
	global_load_lds_dwordx4 v132, s[38:39]
	s_waitcnt vmcnt(8)
	s_waitcnt lgkmcnt(0)
	s_barrier
	s_setprio 1
	s_waitcnt lgkmcnt(0)
	v_mfma_f32_16x16x32_bf16 v[126:129], v[148:151], v[180:183], v[126:129]
	v_mfma_f32_16x16x32_bf16 v[122:125], v[156:159], v[180:183], v[122:125]
	v_mfma_f32_16x16x32_bf16 v[118:121], v[148:151], v[188:191], v[118:121]
	v_mfma_f32_16x16x32_bf16 v[114:117], v[156:159], v[188:191], v[114:117]
	v_mfma_f32_16x16x32_bf16 v[102:105], v[148:151], v[200:203], v[102:105]
	v_mfma_f32_16x16x32_bf16 v[98:101], v[156:159], v[200:203], v[98:101]
	v_mfma_f32_16x16x32_bf16 v[86:89], v[148:151], v[208:211], v[86:89]
	v_mfma_f32_16x16x32_bf16 v[82:85], v[156:159], v[208:211], v[82:85]
	v_mfma_f32_16x16x32_bf16 v[126:129], v[152:155], v[184:187], v[126:129]
	v_mfma_f32_16x16x32_bf16 v[122:125], v[160:163], v[184:187], v[122:125]
	v_mfma_f32_16x16x32_bf16 v[118:121], v[152:155], v[196:199], v[118:121]
	v_mfma_f32_16x16x32_bf16 v[114:117], v[160:163], v[196:199], v[114:117]
	v_mfma_f32_16x16x32_bf16 v[102:105], v[152:155], v[204:207], v[102:105]
	v_mfma_f32_16x16x32_bf16 v[98:101], v[160:163], v[204:207], v[98:101]
	v_mfma_f32_16x16x32_bf16 v[86:89], v[152:155], v[212:215], v[86:89]
	v_mfma_f32_16x16x32_bf16 v[82:85], v[160:163], v[212:215], v[82:85]
	s_setprio 0
	s_setprio 1
	v_mfma_f32_16x16x32_bf16 v[110:113], v[164:167], v[180:183], v[110:113]
	v_mfma_f32_16x16x32_bf16 v[106:109], v[172:175], v[180:183], v[106:109]
	v_mfma_f32_16x16x32_bf16 v[94:97], v[164:167], v[188:191], v[94:97]
	v_mfma_f32_16x16x32_bf16 v[90:93], v[172:175], v[188:191], v[90:93]
	v_mfma_f32_16x16x32_bf16 v[78:81], v[164:167], v[200:203], v[78:81]
	v_mfma_f32_16x16x32_bf16 v[74:77], v[172:175], v[200:203], v[74:77]
	v_mfma_f32_16x16x32_bf16 v[70:73], v[164:167], v[208:211], v[70:73]
	v_mfma_f32_16x16x32_bf16 v[66:69], v[172:175], v[208:211], v[66:69]
	v_mfma_f32_16x16x32_bf16 v[110:113], v[168:171], v[184:187], v[110:113]
	v_mfma_f32_16x16x32_bf16 v[106:109], v[176:179], v[184:187], v[106:109]
	v_mfma_f32_16x16x32_bf16 v[94:97], v[168:171], v[196:199], v[94:97]
	v_mfma_f32_16x16x32_bf16 v[90:93], v[176:179], v[196:199], v[90:93]
	v_mfma_f32_16x16x32_bf16 v[78:81], v[168:171], v[204:207], v[78:81]
	v_mfma_f32_16x16x32_bf16 v[74:77], v[176:179], v[204:207], v[74:77]
	v_mfma_f32_16x16x32_bf16 v[70:73], v[168:171], v[212:215], v[70:73]
	v_mfma_f32_16x16x32_bf16 v[66:69], v[176:179], v[212:215], v[66:69]
	s_setprio 0
	s_barrier
	s_add_i32 s38, s59, s33
	v_lshl_add_u64 v[192:193], v[192:193], 0, s[6:7]
	s_mov_b32 m0, s38
	ds_read_b128 v[180:183], v147 offset:49152
	ds_read_b128 v[184:187], v147 offset:50176
	ds_read_b128 v[188:191], v147 offset:51200
	ds_read_b128 v[196:199], v147 offset:52224
	ds_read_b128 v[200:203], v147 offset:53248
	ds_read_b128 v[204:207], v147 offset:54272
	ds_read_b128 v[208:211], v147 offset:55296
	ds_read_b128 v[212:215], v147 offset:56320
	global_load_lds_dwordx4 v[192:193], off
	s_add_i32 m0, s38, 0x2000
	s_add_u32 s36, s36, 0x80080
	v_lshl_add_u64 v[192:193], v[216:217], 0, s[6:7]
	s_addc_u32 s37, s37, 0
	s_add_i32 s38, s60, s33
	global_load_lds_dwordx4 v[192:193], off
	s_mov_b32 m0, s38
	s_nop 0
	global_load_lds_dwordx4 v134, s[36:37]
	s_add_i32 m0, s38, 0x2000
	s_nop 0
	global_load_lds_dwordx4 v130, s[36:37]
	v_lshl_add_u64 v[192:193], v[218:219], 0, s[6:7]
	s_mov_b32 m0, s45
	s_nop 0
	global_load_lds_dwordx4 v[192:193], off
	v_lshl_add_u64 v[192:193], v[220:221], 0, s[6:7]
	s_mov_b32 m0, s46
	s_nop 0
	global_load_lds_dwordx4 v[192:193], off
	s_waitcnt vmcnt(8)
	s_waitcnt lgkmcnt(0)
	s_barrier
	s_setprio 1
	s_waitcnt lgkmcnt(0)
	v_mfma_f32_16x16x32_bf16 v[62:65], v[148:151], v[180:183], v[62:65]
	v_mfma_f32_16x16x32_bf16 v[58:61], v[156:159], v[180:183], v[58:61]
	v_mfma_f32_16x16x32_bf16 v[54:57], v[148:151], v[188:191], v[54:57]
	v_mfma_f32_16x16x32_bf16 v[50:53], v[156:159], v[188:191], v[50:53]
	v_mfma_f32_16x16x32_bf16 v[38:41], v[148:151], v[200:203], v[38:41]
	v_mfma_f32_16x16x32_bf16 v[34:37], v[156:159], v[200:203], v[34:37]
	v_mfma_f32_16x16x32_bf16 v[22:25], v[148:151], v[208:211], v[22:25]
	v_mfma_f32_16x16x32_bf16 v[18:21], v[156:159], v[208:211], v[18:21]
	v_mfma_f32_16x16x32_bf16 v[62:65], v[152:155], v[184:187], v[62:65]
	v_mfma_f32_16x16x32_bf16 v[58:61], v[160:163], v[184:187], v[58:61]
	v_mfma_f32_16x16x32_bf16 v[54:57], v[152:155], v[196:199], v[54:57]
	v_mfma_f32_16x16x32_bf16 v[50:53], v[160:163], v[196:199], v[50:53]
	v_mfma_f32_16x16x32_bf16 v[38:41], v[152:155], v[204:207], v[38:41]
	v_mfma_f32_16x16x32_bf16 v[34:37], v[160:163], v[204:207], v[34:37]
	v_mfma_f32_16x16x32_bf16 v[22:25], v[152:155], v[212:215], v[22:25]
	v_mfma_f32_16x16x32_bf16 v[18:21], v[160:163], v[212:215], v[18:21]
	s_setprio 0
	s_setprio 1
	v_mfma_f32_16x16x32_bf16 v[46:49], v[164:167], v[180:183], v[46:49]
	v_mfma_f32_16x16x32_bf16 v[42:45], v[172:175], v[180:183], v[42:45]
	v_mfma_f32_16x16x32_bf16 v[30:33], v[164:167], v[188:191], v[30:33]
	v_mfma_f32_16x16x32_bf16 v[26:29], v[172:175], v[188:191], v[26:29]
	v_mfma_f32_16x16x32_bf16 v[14:17], v[164:167], v[200:203], v[14:17]
	v_mfma_f32_16x16x32_bf16 v[10:13], v[172:175], v[200:203], v[10:13]
	v_mfma_f32_16x16x32_bf16 v[6:9], v[164:167], v[208:211], v[6:9]
	v_mfma_f32_16x16x32_bf16 v[2:5], v[172:175], v[208:211], v[2:5]
	v_mfma_f32_16x16x32_bf16 v[46:49], v[168:171], v[184:187], v[46:49]
	v_mfma_f32_16x16x32_bf16 v[42:45], v[176:179], v[184:187], v[42:45]
	v_mfma_f32_16x16x32_bf16 v[30:33], v[168:171], v[196:199], v[30:33]
	v_mfma_f32_16x16x32_bf16 v[26:29], v[176:179], v[196:199], v[26:29]
	v_mfma_f32_16x16x32_bf16 v[14:17], v[168:171], v[204:207], v[14:17]
	v_mfma_f32_16x16x32_bf16 v[10:13], v[176:179], v[204:207], v[10:13]
	v_mfma_f32_16x16x32_bf16 v[6:9], v[168:171], v[212:215], v[6:9]
	v_mfma_f32_16x16x32_bf16 v[2:5], v[176:179], v[212:215], v[2:5]
	s_setprio 0
	s_barrier
	s_add_i32 s58, s58, 2
	s_add_u32 s34, s34, 0x100
	s_addc_u32 s35, s35, 0
	s_add_u32 s56, s56, 0x100
	s_addc_u32 s57, s57, 0
	s_cmp_gt_u32 s58, 29
	s_cbranch_scc0 .LBB0_541
	s_branch .Lpeeldone_11
.LBB0_541:
	ds_read_b128 v[148:151], v145
	ds_read_b128 v[152:155], v145 offset:1024
	ds_read_b128 v[156:159], v145 offset:2048
	ds_read_b128 v[160:163], v145 offset:3072
	ds_read_b128 v[164:167], v146
	ds_read_b128 v[168:171], v146 offset:1024
	ds_read_b128 v[172:175], v146 offset:2048
	ds_read_b128 v[176:179], v146 offset:3072
	s_add_u32 s36, s34, 0xfff80080
	s_addc_u32 s37, s35, -1
	s_cmp_eq_u32 s58, 28
	s_cselect_b32 s39, s21, s37
	s_cselect_b32 s38, s54, s36
	s_cselect_b32 s37, s23, s57
	s_cselect_b32 s36, s55, s56
	s_add_i32 m0, s27, 0xc000
	ds_read_b128 v[180:183], v147
	ds_read_b128 v[184:187], v147 offset:1024
	ds_read_b128 v[188:191], v147 offset:2048
	ds_read_b128 v[196:199], v147 offset:3072
	ds_read_b128 v[200:203], v147 offset:4096
	ds_read_b128 v[204:207], v147 offset:5120
	ds_read_b128 v[208:211], v147 offset:6144
	ds_read_b128 v[212:215], v147 offset:7168
	global_load_lds_dwordx4 v138, s[34:35]
	s_add_i32 m0, s27, 0xe000
	s_nop 0
	global_load_lds_dwordx4 v140, s[34:35]
	s_waitcnt vmcnt(8)
	s_waitcnt lgkmcnt(0)
	s_barrier
	s_setprio 1
	s_waitcnt lgkmcnt(0)
	v_mfma_f32_16x16x32_bf16 v[126:129], v[148:151], v[180:183], v[126:129]
	v_mfma_f32_16x16x32_bf16 v[122:125], v[156:159], v[180:183], v[122:125]
	v_mfma_f32_16x16x32_bf16 v[118:121], v[148:151], v[188:191], v[118:121]
	v_mfma_f32_16x16x32_bf16 v[114:117], v[156:159], v[188:191], v[114:117]
	v_mfma_f32_16x16x32_bf16 v[102:105], v[148:151], v[200:203], v[102:105]
	v_mfma_f32_16x16x32_bf16 v[98:101], v[156:159], v[200:203], v[98:101]
	v_mfma_f32_16x16x32_bf16 v[86:89], v[148:151], v[208:211], v[86:89]
	v_mfma_f32_16x16x32_bf16 v[82:85], v[156:159], v[208:211], v[82:85]
	v_mfma_f32_16x16x32_bf16 v[126:129], v[152:155], v[184:187], v[126:129]
	v_mfma_f32_16x16x32_bf16 v[122:125], v[160:163], v[184:187], v[122:125]
	v_mfma_f32_16x16x32_bf16 v[118:121], v[152:155], v[196:199], v[118:121]
	v_mfma_f32_16x16x32_bf16 v[114:117], v[160:163], v[196:199], v[114:117]
	v_mfma_f32_16x16x32_bf16 v[102:105], v[152:155], v[204:207], v[102:105]
	v_mfma_f32_16x16x32_bf16 v[98:101], v[160:163], v[204:207], v[98:101]
	v_mfma_f32_16x16x32_bf16 v[86:89], v[152:155], v[212:215], v[86:89]
	v_mfma_f32_16x16x32_bf16 v[82:85], v[160:163], v[212:215], v[82:85]
	s_setprio 0
	s_setprio 1
	v_mfma_f32_16x16x32_bf16 v[110:113], v[164:167], v[180:183], v[110:113]
	v_mfma_f32_16x16x32_bf16 v[106:109], v[172:175], v[180:183], v[106:109]
	v_mfma_f32_16x16x32_bf16 v[94:97], v[164:167], v[188:191], v[94:97]
	v_mfma_f32_16x16x32_bf16 v[90:93], v[172:175], v[188:191], v[90:93]
	v_mfma_f32_16x16x32_bf16 v[78:81], v[164:167], v[200:203], v[78:81]
	v_mfma_f32_16x16x32_bf16 v[74:77], v[172:175], v[200:203], v[74:77]
	v_mfma_f32_16x16x32_bf16 v[70:73], v[164:167], v[208:211], v[70:73]
	v_mfma_f32_16x16x32_bf16 v[66:69], v[172:175], v[208:211], v[66:69]
	v_mfma_f32_16x16x32_bf16 v[110:113], v[168:171], v[184:187], v[110:113]
	v_mfma_f32_16x16x32_bf16 v[106:109], v[176:179], v[184:187], v[106:109]
	v_mfma_f32_16x16x32_bf16 v[94:97], v[168:171], v[196:199], v[94:97]
	v_mfma_f32_16x16x32_bf16 v[90:93], v[176:179], v[196:199], v[90:93]
	v_mfma_f32_16x16x32_bf16 v[78:81], v[168:171], v[204:207], v[78:81]
	v_mfma_f32_16x16x32_bf16 v[74:77], v[176:179], v[204:207], v[74:77]
	v_mfma_f32_16x16x32_bf16 v[70:73], v[168:171], v[212:215], v[70:73]
	v_mfma_f32_16x16x32_bf16 v[66:69], v[176:179], v[212:215], v[66:69]
	s_setprio 0
	s_barrier
	s_add_i32 s59, s47, s33
	v_lshl_add_u64 v[192:193], s[36:37], 0, v[134:135]
	s_mov_b32 m0, s59
	ds_read_b128 v[180:183], v147 offset:16384
	ds_read_b128 v[184:187], v147 offset:17408
	ds_read_b128 v[188:191], v147 offset:18432
	ds_read_b128 v[196:199], v147 offset:19456
	ds_read_b128 v[200:203], v147 offset:20480
	ds_read_b128 v[204:207], v147 offset:21504
	ds_read_b128 v[208:211], v147 offset:22528
	ds_read_b128 v[212:215], v147 offset:23552
	global_load_lds_dwordx4 v134, s[36:37]
	s_add_i32 m0, s59, 0x2000
	s_add_u32 s60, s36, 0x80000
	v_lshl_add_u64 v[216:217], s[36:37], 0, v[130:131]
	s_addc_u32 s61, s37, 0
	s_add_i32 s59, s48, s33
	global_load_lds_dwordx4 v130, s[36:37]
	s_mov_b32 m0, s59
	v_lshl_add_u64 v[220:221], s[38:39], 0, v[132:133]
	global_load_lds_dwordx4 v134, s[60:61]
	s_add_i32 m0, s59, 0x2000
	s_nop 0
	global_load_lds_dwordx4 v130, s[60:61]
	v_lshl_add_u64 v[218:219], s[38:39], 0, v[136:137]
	s_mov_b32 m0, s27
	s_nop 0
	global_load_lds_dwordx4 v136, s[38:39]
	s_mov_b32 m0, s41
	s_nop 0
	global_load_lds_dwordx4 v132, s[38:39]
	s_waitcnt vmcnt(8)
	s_waitcnt lgkmcnt(0)
	s_barrier
	s_setprio 1
	s_waitcnt lgkmcnt(0)
	v_mfma_f32_16x16x32_bf16 v[62:65], v[148:151], v[180:183], v[62:65]
	v_mfma_f32_16x16x32_bf16 v[58:61], v[156:159], v[180:183], v[58:61]
	v_mfma_f32_16x16x32_bf16 v[54:57], v[148:151], v[188:191], v[54:57]
	v_mfma_f32_16x16x32_bf16 v[50:53], v[156:159], v[188:191], v[50:53]
	v_mfma_f32_16x16x32_bf16 v[38:41], v[148:151], v[200:203], v[38:41]
	v_mfma_f32_16x16x32_bf16 v[34:37], v[156:159], v[200:203], v[34:37]
	v_mfma_f32_16x16x32_bf16 v[22:25], v[148:151], v[208:211], v[22:25]
	v_mfma_f32_16x16x32_bf16 v[18:21], v[156:159], v[208:211], v[18:21]
	v_mfma_f32_16x16x32_bf16 v[62:65], v[152:155], v[184:187], v[62:65]
	v_mfma_f32_16x16x32_bf16 v[58:61], v[160:163], v[184:187], v[58:61]
	v_mfma_f32_16x16x32_bf16 v[54:57], v[152:155], v[196:199], v[54:57]
	v_mfma_f32_16x16x32_bf16 v[50:53], v[160:163], v[196:199], v[50:53]
	v_mfma_f32_16x16x32_bf16 v[38:41], v[152:155], v[204:207], v[38:41]
	v_mfma_f32_16x16x32_bf16 v[34:37], v[160:163], v[204:207], v[34:37]
	v_mfma_f32_16x16x32_bf16 v[22:25], v[152:155], v[212:215], v[22:25]
	v_mfma_f32_16x16x32_bf16 v[18:21], v[160:163], v[212:215], v[18:21]
	s_setprio 0
	s_setprio 1
	v_mfma_f32_16x16x32_bf16 v[46:49], v[164:167], v[180:183], v[46:49]
	v_mfma_f32_16x16x32_bf16 v[42:45], v[172:175], v[180:183], v[42:45]
	v_mfma_f32_16x16x32_bf16 v[30:33], v[164:167], v[188:191], v[30:33]
	v_mfma_f32_16x16x32_bf16 v[26:29], v[172:175], v[188:191], v[26:29]
	v_mfma_f32_16x16x32_bf16 v[14:17], v[164:167], v[200:203], v[14:17]
	v_mfma_f32_16x16x32_bf16 v[10:13], v[172:175], v[200:203], v[10:13]
	v_mfma_f32_16x16x32_bf16 v[6:9], v[164:167], v[208:211], v[6:9]
	v_mfma_f32_16x16x32_bf16 v[2:5], v[172:175], v[208:211], v[2:5]
	v_mfma_f32_16x16x32_bf16 v[46:49], v[168:171], v[184:187], v[46:49]
	v_mfma_f32_16x16x32_bf16 v[42:45], v[176:179], v[184:187], v[42:45]
	v_mfma_f32_16x16x32_bf16 v[30:33], v[168:171], v[196:199], v[30:33]
	v_mfma_f32_16x16x32_bf16 v[26:29], v[176:179], v[196:199], v[26:29]
	v_mfma_f32_16x16x32_bf16 v[14:17], v[168:171], v[204:207], v[14:17]
	v_mfma_f32_16x16x32_bf16 v[10:13], v[176:179], v[204:207], v[10:13]
	v_mfma_f32_16x16x32_bf16 v[6:9], v[168:171], v[212:215], v[6:9]
	v_mfma_f32_16x16x32_bf16 v[2:5], v[176:179], v[212:215], v[2:5]
	s_setprio 0
	s_barrier
	s_add_i32 s59, 0, 0x18000
	s_add_i32 s60, 0, 0x1c000
	v_add_u32_e32 v160, s59, v143
	v_add_u32_e32 v176, s60, v143
	ds_read_b128 v[148:151], v160
	ds_read_b128 v[152:155], v160 offset:1024
	ds_read_b128 v[156:159], v160 offset:2048
	ds_read_b128 v[160:163], v160 offset:3072
	ds_read_b128 v[164:167], v176
	ds_read_b128 v[168:171], v176 offset:1024
	ds_read_b128 v[172:175], v176 offset:2048
	ds_read_b128 v[176:179], v176 offset:3072
	s_add_u32 s38, s38, 0x80000
	s_addc_u32 s39, s39, 0
	s_mov_b32 m0, s42
	ds_read_b128 v[180:183], v147 offset:32768
	ds_read_b128 v[184:187], v147 offset:33792
	ds_read_b128 v[188:191], v147 offset:34816
	ds_read_b128 v[196:199], v147 offset:35840
	ds_read_b128 v[200:203], v147 offset:36864
	ds_read_b128 v[204:207], v147 offset:37888
	ds_read_b128 v[208:211], v147 offset:38912
	ds_read_b128 v[212:215], v147 offset:39936
	global_load_lds_dwordx4 v136, s[38:39]
	v_lshl_add_u64 v[222:223], s[38:39], 0, v[132:133]
	s_mov_b32 m0, s43
	s_nop 0
	global_load_lds_dwordx4 v132, s[38:39]
	s_waitcnt vmcnt(8)
	s_waitcnt lgkmcnt(0)
	s_barrier
	s_setprio 1
	s_waitcnt lgkmcnt(0)
	v_mfma_f32_16x16x32_bf16 v[126:129], v[148:151], v[180:183], v[126:129]
	v_mfma_f32_16x16x32_bf16 v[122:125], v[156:159], v[180:183], v[122:125]
	v_mfma_f32_16x16x32_bf16 v[118:121], v[148:151], v[188:191], v[118:121]
	v_mfma_f32_16x16x32_bf16 v[114:117], v[156:159], v[188:191], v[114:117]
	v_mfma_f32_16x16x32_bf16 v[102:105], v[148:151], v[200:203], v[102:105]
	v_mfma_f32_16x16x32_bf16 v[98:101], v[156:159], v[200:203], v[98:101]
	v_mfma_f32_16x16x32_bf16 v[86:89], v[148:151], v[208:211], v[86:89]
	v_mfma_f32_16x16x32_bf16 v[82:85], v[156:159], v[208:211], v[82:85]
	v_mfma_f32_16x16x32_bf16 v[126:129], v[152:155], v[184:187], v[126:129]
	v_mfma_f32_16x16x32_bf16 v[122:125], v[160:163], v[184:187], v[122:125]
	v_mfma_f32_16x16x32_bf16 v[118:121], v[152:155], v[196:199], v[118:121]
	v_mfma_f32_16x16x32_bf16 v[114:117], v[160:163], v[196:199], v[114:117]
	v_mfma_f32_16x16x32_bf16 v[102:105], v[152:155], v[204:207], v[102:105]
	v_mfma_f32_16x16x32_bf16 v[98:101], v[160:163], v[204:207], v[98:101]
	v_mfma_f32_16x16x32_bf16 v[86:89], v[152:155], v[212:215], v[86:89]
	v_mfma_f32_16x16x32_bf16 v[82:85], v[160:163], v[212:215], v[82:85]
	s_setprio 0
	s_setprio 1
	v_mfma_f32_16x16x32_bf16 v[110:113], v[164:167], v[180:183], v[110:113]
	v_mfma_f32_16x16x32_bf16 v[106:109], v[172:175], v[180:183], v[106:109]
	v_mfma_f32_16x16x32_bf16 v[94:97], v[164:167], v[188:191], v[94:97]
	v_mfma_f32_16x16x32_bf16 v[90:93], v[172:175], v[188:191], v[90:93]
	v_mfma_f32_16x16x32_bf16 v[78:81], v[164:167], v[200:203], v[78:81]
	v_mfma_f32_16x16x32_bf16 v[74:77], v[172:175], v[200:203], v[74:77]
	v_mfma_f32_16x16x32_bf16 v[70:73], v[164:167], v[208:211], v[70:73]
	v_mfma_f32_16x16x32_bf16 v[66:69], v[172:175], v[208:211], v[66:69]
	v_mfma_f32_16x16x32_bf16 v[110:113], v[168:171], v[184:187], v[110:113]
	v_mfma_f32_16x16x32_bf16 v[106:109], v[176:179], v[184:187], v[106:109]
	v_mfma_f32_16x16x32_bf16 v[94:97], v[168:171], v[196:199], v[94:97]
	v_mfma_f32_16x16x32_bf16 v[90:93], v[176:179], v[196:199], v[90:93]
	v_mfma_f32_16x16x32_bf16 v[78:81], v[168:171], v[204:207], v[78:81]
	v_mfma_f32_16x16x32_bf16 v[74:77], v[176:179], v[204:207], v[74:77]
	v_mfma_f32_16x16x32_bf16 v[70:73], v[168:171], v[212:215], v[70:73]
	v_mfma_f32_16x16x32_bf16 v[66:69], v[176:179], v[212:215], v[66:69]
	s_setprio 0
	s_barrier
	s_add_i32 s38, s59, s33
	v_lshl_add_u64 v[192:193], v[192:193], 0, s[6:7]
	s_mov_b32 m0, s38
	ds_read_b128 v[180:183], v147 offset:49152
	ds_read_b128 v[184:187], v147 offset:50176
	ds_read_b128 v[188:191], v147 offset:51200
	ds_read_b128 v[196:199], v147 offset:52224
	ds_read_b128 v[200:203], v147 offset:53248
	ds_read_b128 v[204:207], v147 offset:54272
	ds_read_b128 v[208:211], v147 offset:55296
	ds_read_b128 v[212:215], v147 offset:56320
	global_load_lds_dwordx4 v[192:193], off
	s_add_i32 m0, s38, 0x2000
	s_add_u32 s36, s36, 0x80080
	v_lshl_add_u64 v[192:193], v[216:217], 0, s[6:7]
	s_addc_u32 s37, s37, 0
	s_add_i32 s38, s60, s33
	global_load_lds_dwordx4 v[192:193], off
	s_mov_b32 m0, s38
	s_nop 0
	global_load_lds_dwordx4 v134, s[36:37]
	s_add_i32 m0, s38, 0x2000
	s_nop 0
	global_load_lds_dwordx4 v130, s[36:37]
	v_lshl_add_u64 v[192:193], v[218:219], 0, s[6:7]
	s_mov_b32 m0, s45
	s_nop 0
	global_load_lds_dwordx4 v[192:193], off
	v_lshl_add_u64 v[192:193], v[220:221], 0, s[6:7]
	s_mov_b32 m0, s46
	s_nop 0
	global_load_lds_dwordx4 v[192:193], off
	s_waitcnt vmcnt(8)
	s_waitcnt lgkmcnt(0)
	s_barrier
	s_setprio 1
	s_waitcnt lgkmcnt(0)
	v_mfma_f32_16x16x32_bf16 v[62:65], v[148:151], v[180:183], v[62:65]
	v_mfma_f32_16x16x32_bf16 v[58:61], v[156:159], v[180:183], v[58:61]
	v_mfma_f32_16x16x32_bf16 v[54:57], v[148:151], v[188:191], v[54:57]
	v_mfma_f32_16x16x32_bf16 v[50:53], v[156:159], v[188:191], v[50:53]
	v_mfma_f32_16x16x32_bf16 v[38:41], v[148:151], v[200:203], v[38:41]
	v_mfma_f32_16x16x32_bf16 v[34:37], v[156:159], v[200:203], v[34:37]
	v_mfma_f32_16x16x32_bf16 v[22:25], v[148:151], v[208:211], v[22:25]
	v_mfma_f32_16x16x32_bf16 v[18:21], v[156:159], v[208:211], v[18:21]
	v_mfma_f32_16x16x32_bf16 v[62:65], v[152:155], v[184:187], v[62:65]
	v_mfma_f32_16x16x32_bf16 v[58:61], v[160:163], v[184:187], v[58:61]
	v_mfma_f32_16x16x32_bf16 v[54:57], v[152:155], v[196:199], v[54:57]
	v_mfma_f32_16x16x32_bf16 v[50:53], v[160:163], v[196:199], v[50:53]
	v_mfma_f32_16x16x32_bf16 v[38:41], v[152:155], v[204:207], v[38:41]
	v_mfma_f32_16x16x32_bf16 v[34:37], v[160:163], v[204:207], v[34:37]
	v_mfma_f32_16x16x32_bf16 v[22:25], v[152:155], v[212:215], v[22:25]
	v_mfma_f32_16x16x32_bf16 v[18:21], v[160:163], v[212:215], v[18:21]
	s_setprio 0
	s_setprio 1
	v_mfma_f32_16x16x32_bf16 v[46:49], v[164:167], v[180:183], v[46:49]
	v_mfma_f32_16x16x32_bf16 v[42:45], v[172:175], v[180:183], v[42:45]
	v_mfma_f32_16x16x32_bf16 v[30:33], v[164:167], v[188:191], v[30:33]
	v_mfma_f32_16x16x32_bf16 v[26:29], v[172:175], v[188:191], v[26:29]
	v_mfma_f32_16x16x32_bf16 v[14:17], v[164:167], v[200:203], v[14:17]
	v_mfma_f32_16x16x32_bf16 v[10:13], v[172:175], v[200:203], v[10:13]
	v_mfma_f32_16x16x32_bf16 v[6:9], v[164:167], v[208:211], v[6:9]
	v_mfma_f32_16x16x32_bf16 v[2:5], v[172:175], v[208:211], v[2:5]
	v_mfma_f32_16x16x32_bf16 v[46:49], v[168:171], v[184:187], v[46:49]
	v_mfma_f32_16x16x32_bf16 v[42:45], v[176:179], v[184:187], v[42:45]
	v_mfma_f32_16x16x32_bf16 v[30:33], v[168:171], v[196:199], v[30:33]
	v_mfma_f32_16x16x32_bf16 v[26:29], v[176:179], v[196:199], v[26:29]
	v_mfma_f32_16x16x32_bf16 v[14:17], v[168:171], v[204:207], v[14:17]
	v_mfma_f32_16x16x32_bf16 v[10:13], v[176:179], v[204:207], v[10:13]
	v_mfma_f32_16x16x32_bf16 v[6:9], v[168:171], v[212:215], v[6:9]
	v_mfma_f32_16x16x32_bf16 v[2:5], v[176:179], v[212:215], v[2:5]
	s_setprio 0
	s_barrier
	s_add_i32 s58, s58, 2
	s_add_u32 s34, s34, 0x100
	s_addc_u32 s35, s35, 0
	s_add_u32 s56, s56, 0x100
	s_addc_u32 s57, s57, 0
	s_cmp_gt_u32 s58, 29
	s_cbranch_scc0 .LBB0_541

.Lpeel_10:
	ds_read_b128 v[150:153], v147
	ds_read_b128 v[154:157], v147 offset:1024
	s_add_u32 s28, s26, 0xfffe0080
	s_addc_u32 s29, s27, -1
	s_cmp_eq_u32 s50, 4
	s_cselect_b32 s31, s13, s29
	s_cselect_b32 s30, s46, s28
	s_cselect_b32 s29, s17, s49
	s_cselect_b32 s28, s47, s48
	s_add_i32 m0, s36, 0xc000
	global_load_lds_dwordx4 v138, s[26:27]
	s_add_i32 m0, s36, 0xe000
	s_nop 0
	global_load_lds_dwordx4 v140, s[26:27]
	s_waitcnt vmcnt(8)
	s_waitcnt lgkmcnt(0)
	s_barrier
	s_setprio 1
	s_waitcnt lgkmcnt(0)
	v_mfma_f32_16x16x32_bf16 v[126:129], v[150:153], v[182:185], 0
	v_mfma_f32_16x16x32_bf16 v[122:125], v[158:161], v[182:185], 0
	v_mfma_f32_16x16x32_bf16 v[118:121], v[150:153], v[190:193], 0
	v_mfma_f32_16x16x32_bf16 v[114:117], v[158:161], v[190:193], 0
	v_mfma_f32_16x16x32_bf16 v[102:105], v[150:153], v[210:213], 0
	v_mfma_f32_16x16x32_bf16 v[98:101], v[158:161], v[210:213], 0
	v_mfma_f32_16x16x32_bf16 v[86:89], v[150:153], v[218:221], 0
	v_mfma_f32_16x16x32_bf16 v[82:85], v[158:161], v[218:221], 0
	v_mfma_f32_16x16x32_bf16 v[126:129], v[154:157], v[186:189], v[126:129]
	v_mfma_f32_16x16x32_bf16 v[122:125], v[162:165], v[186:189], v[122:125]
	v_mfma_f32_16x16x32_bf16 v[118:121], v[154:157], v[198:201], v[118:121]
	v_mfma_f32_16x16x32_bf16 v[114:117], v[162:165], v[198:201], v[114:117]
	v_mfma_f32_16x16x32_bf16 v[102:105], v[154:157], v[214:217], v[102:105]
	v_mfma_f32_16x16x32_bf16 v[98:101], v[162:165], v[214:217], v[98:101]
	v_mfma_f32_16x16x32_bf16 v[86:89], v[154:157], v[222:225], v[86:89]
	v_mfma_f32_16x16x32_bf16 v[82:85], v[162:165], v[222:225], v[82:85]
	s_setprio 0
	s_setprio 1
	v_mfma_f32_16x16x32_bf16 v[110:113], v[166:169], v[182:185], 0
	v_mfma_f32_16x16x32_bf16 v[106:109], v[174:177], v[182:185], 0
	v_mfma_f32_16x16x32_bf16 v[94:97], v[166:169], v[190:193], 0
	v_mfma_f32_16x16x32_bf16 v[90:93], v[174:177], v[190:193], 0
	v_mfma_f32_16x16x32_bf16 v[78:81], v[166:169], v[210:213], 0
	v_mfma_f32_16x16x32_bf16 v[74:77], v[174:177], v[210:213], 0
	v_mfma_f32_16x16x32_bf16 v[70:73], v[166:169], v[218:221], 0
	v_mfma_f32_16x16x32_bf16 v[66:69], v[174:177], v[218:221], 0
	v_mfma_f32_16x16x32_bf16 v[110:113], v[170:173], v[186:189], v[110:113]
	v_mfma_f32_16x16x32_bf16 v[106:109], v[178:181], v[186:189], v[106:109]
	v_mfma_f32_16x16x32_bf16 v[94:97], v[170:173], v[198:201], v[94:97]
	v_mfma_f32_16x16x32_bf16 v[90:93], v[178:181], v[198:201], v[90:93]
	v_mfma_f32_16x16x32_bf16 v[78:81], v[170:173], v[214:217], v[78:81]
	v_mfma_f32_16x16x32_bf16 v[74:77], v[178:181], v[214:217], v[74:77]
	v_mfma_f32_16x16x32_bf16 v[70:73], v[170:173], v[222:225], v[70:73]
	v_mfma_f32_16x16x32_bf16 v[66:69], v[178:181], v[222:225], v[66:69]
	s_setprio 0
	s_barrier
	s_add_i32 s51, s43, s35
	v_lshl_add_u64 v[202:203], s[28:29], 0, v[132:133]
	s_mov_b32 m0, s51
	ds_read_b128 v[182:185], v149 offset:16384
	ds_read_b128 v[186:189], v149 offset:17408
	ds_read_b128 v[190:193], v149 offset:18432
	ds_read_b128 v[198:201], v149 offset:19456
	ds_read_b128 v[210:213], v149 offset:20480
	ds_read_b128 v[214:217], v149 offset:21504
	ds_read_b128 v[218:221], v149 offset:22528
	ds_read_b128 v[222:225], v149 offset:23552
	global_load_lds_dwordx4 v132, s[28:29]
	s_add_i32 m0, s51, 0x2000
	s_add_u32 s52, s28, 0x20000
	v_lshl_add_u64 v[206:207], s[28:29], 0, v[134:135]
	s_addc_u32 s53, s29, 0
	s_add_i32 s51, s44, s35
	global_load_lds_dwordx4 v134, s[28:29]
	s_mov_b32 m0, s51
	v_lshl_add_u64 v[228:229], s[30:31], 0, v[136:137]
	global_load_lds_dwordx4 v132, s[52:53]
	s_add_i32 m0, s51, 0x2000
	s_nop 0
	global_load_lds_dwordx4 v134, s[52:53]
	v_lshl_add_u64 v[226:227], s[30:31], 0, v[130:131]
	s_mov_b32 m0, s36
	s_nop 0
	global_load_lds_dwordx4 v130, s[30:31]
	s_mov_b32 m0, s37
	s_nop 0
	global_load_lds_dwordx4 v136, s[30:31]
	s_waitcnt vmcnt(8)
	s_waitcnt lgkmcnt(0)
	s_barrier
	s_setprio 1
	s_waitcnt lgkmcnt(0)
	v_mfma_f32_16x16x32_bf16 v[62:65], v[150:153], v[182:185], 0
	v_mfma_f32_16x16x32_bf16 v[58:61], v[158:161], v[182:185], 0
	v_mfma_f32_16x16x32_bf16 v[54:57], v[150:153], v[190:193], 0
	v_mfma_f32_16x16x32_bf16 v[50:53], v[158:161], v[190:193], 0
	v_mfma_f32_16x16x32_bf16 v[38:41], v[150:153], v[210:213], 0
	v_mfma_f32_16x16x32_bf16 v[34:37], v[158:161], v[210:213], 0
	v_mfma_f32_16x16x32_bf16 v[22:25], v[150:153], v[218:221], 0
	v_mfma_f32_16x16x32_bf16 v[18:21], v[158:161], v[218:221], 0
	v_mfma_f32_16x16x32_bf16 v[62:65], v[154:157], v[186:189], v[62:65]
	v_mfma_f32_16x16x32_bf16 v[58:61], v[162:165], v[186:189], v[58:61]
	v_mfma_f32_16x16x32_bf16 v[54:57], v[154:157], v[198:201], v[54:57]
	v_mfma_f32_16x16x32_bf16 v[50:53], v[162:165], v[198:201], v[50:53]
	v_mfma_f32_16x16x32_bf16 v[38:41], v[154:157], v[214:217], v[38:41]
	v_mfma_f32_16x16x32_bf16 v[34:37], v[162:165], v[214:217], v[34:37]
	v_mfma_f32_16x16x32_bf16 v[22:25], v[154:157], v[222:225], v[22:25]
	v_mfma_f32_16x16x32_bf16 v[18:21], v[162:165], v[222:225], v[18:21]
	s_setprio 0
	s_setprio 1
	v_mfma_f32_16x16x32_bf16 v[46:49], v[166:169], v[182:185], 0
	v_mfma_f32_16x16x32_bf16 v[42:45], v[174:177], v[182:185], 0
	v_mfma_f32_16x16x32_bf16 v[30:33], v[166:169], v[190:193], 0
	v_mfma_f32_16x16x32_bf16 v[26:29], v[174:177], v[190:193], 0
	v_mfma_f32_16x16x32_bf16 v[14:17], v[166:169], v[210:213], 0
	v_mfma_f32_16x16x32_bf16 v[10:13], v[174:177], v[210:213], 0
	v_mfma_f32_16x16x32_bf16 v[6:9], v[166:169], v[218:221], 0
	v_mfma_f32_16x16x32_bf16 v[2:5], v[174:177], v[218:221], 0
	v_mfma_f32_16x16x32_bf16 v[46:49], v[170:173], v[186:189], v[46:49]
	v_mfma_f32_16x16x32_bf16 v[42:45], v[178:181], v[186:189], v[42:45]
	v_mfma_f32_16x16x32_bf16 v[30:33], v[170:173], v[198:201], v[30:33]
	v_mfma_f32_16x16x32_bf16 v[26:29], v[178:181], v[198:201], v[26:29]
	v_mfma_f32_16x16x32_bf16 v[14:17], v[170:173], v[214:217], v[14:17]
	v_mfma_f32_16x16x32_bf16 v[10:13], v[178:181], v[214:217], v[10:13]
	v_mfma_f32_16x16x32_bf16 v[6:9], v[170:173], v[222:225], v[6:9]
	v_mfma_f32_16x16x32_bf16 v[2:5], v[178:181], v[222:225], v[2:5]
	s_setprio 0
	s_barrier
	s_add_i32 s51, 0, 0x18000
	s_add_i32 s52, 0, 0x1c000
	v_add_u32_e32 v162, s51, v145
	v_add_u32_e32 v178, s52, v145
	ds_read_b128 v[150:153], v162
	ds_read_b128 v[154:157], v162 offset:1024
	ds_read_b128 v[158:161], v162 offset:2048
	ds_read_b128 v[162:165], v162 offset:3072
	ds_read_b128 v[166:169], v178
	ds_read_b128 v[170:173], v178 offset:1024
	ds_read_b128 v[174:177], v178 offset:2048
	ds_read_b128 v[178:181], v178 offset:3072
	s_add_u32 s30, s30, 0x20000
	s_addc_u32 s31, s31, 0
	s_mov_b32 m0, s38
	ds_read_b128 v[182:185], v149 offset:32768
	ds_read_b128 v[186:189], v149 offset:33792
	ds_read_b128 v[190:193], v149 offset:34816
	ds_read_b128 v[198:201], v149 offset:35840
	ds_read_b128 v[210:213], v149 offset:36864
	ds_read_b128 v[214:217], v149 offset:37888
	ds_read_b128 v[218:221], v149 offset:38912
	ds_read_b128 v[222:225], v149 offset:39936
	global_load_lds_dwordx4 v130, s[30:31]
	v_lshl_add_u64 v[230:231], s[30:31], 0, v[136:137]
	s_mov_b32 m0, s39
	s_nop 0
	global_load_lds_dwordx4 v136, s[30:31]
	s_waitcnt vmcnt(8)
	s_waitcnt lgkmcnt(0)
	s_barrier
	s_setprio 1
	s_waitcnt lgkmcnt(0)
	v_mfma_f32_16x16x32_bf16 v[126:129], v[150:153], v[182:185], v[126:129]
	v_mfma_f32_16x16x32_bf16 v[122:125], v[158:161], v[182:185], v[122:125]
	v_mfma_f32_16x16x32_bf16 v[118:121], v[150:153], v[190:193], v[118:121]
	v_mfma_f32_16x16x32_bf16 v[114:117], v[158:161], v[190:193], v[114:117]
	v_mfma_f32_16x16x32_bf16 v[102:105], v[150:153], v[210:213], v[102:105]
	v_mfma_f32_16x16x32_bf16 v[98:101], v[158:161], v[210:213], v[98:101]
	v_mfma_f32_16x16x32_bf16 v[86:89], v[150:153], v[218:221], v[86:89]
	v_mfma_f32_16x16x32_bf16 v[82:85], v[158:161], v[218:221], v[82:85]
	v_mfma_f32_16x16x32_bf16 v[126:129], v[154:157], v[186:189], v[126:129]
	v_mfma_f32_16x16x32_bf16 v[122:125], v[162:165], v[186:189], v[122:125]
	v_mfma_f32_16x16x32_bf16 v[118:121], v[154:157], v[198:201], v[118:121]
	v_mfma_f32_16x16x32_bf16 v[114:117], v[162:165], v[198:201], v[114:117]
	v_mfma_f32_16x16x32_bf16 v[102:105], v[154:157], v[214:217], v[102:105]
	v_mfma_f32_16x16x32_bf16 v[98:101], v[162:165], v[214:217], v[98:101]
	v_mfma_f32_16x16x32_bf16 v[86:89], v[154:157], v[222:225], v[86:89]
	v_mfma_f32_16x16x32_bf16 v[82:85], v[162:165], v[222:225], v[82:85]
	s_setprio 0
	s_setprio 1
	v_mfma_f32_16x16x32_bf16 v[110:113], v[166:169], v[182:185], v[110:113]
	v_mfma_f32_16x16x32_bf16 v[106:109], v[174:177], v[182:185], v[106:109]
	v_mfma_f32_16x16x32_bf16 v[94:97], v[166:169], v[190:193], v[94:97]
	v_mfma_f32_16x16x32_bf16 v[90:93], v[174:177], v[190:193], v[90:93]
	v_mfma_f32_16x16x32_bf16 v[78:81], v[166:169], v[210:213], v[78:81]
	v_mfma_f32_16x16x32_bf16 v[74:77], v[174:177], v[210:213], v[74:77]
	v_mfma_f32_16x16x32_bf16 v[70:73], v[166:169], v[218:221], v[70:73]
	v_mfma_f32_16x16x32_bf16 v[66:69], v[174:177], v[218:221], v[66:69]
	v_mfma_f32_16x16x32_bf16 v[110:113], v[170:173], v[186:189], v[110:113]
	v_mfma_f32_16x16x32_bf16 v[106:109], v[178:181], v[186:189], v[106:109]
	v_mfma_f32_16x16x32_bf16 v[94:97], v[170:173], v[198:201], v[94:97]
	v_mfma_f32_16x16x32_bf16 v[90:93], v[178:181], v[198:201], v[90:93]
	v_mfma_f32_16x16x32_bf16 v[78:81], v[170:173], v[214:217], v[78:81]
	v_mfma_f32_16x16x32_bf16 v[74:77], v[178:181], v[214:217], v[74:77]
	v_mfma_f32_16x16x32_bf16 v[70:73], v[170:173], v[222:225], v[70:73]
	v_mfma_f32_16x16x32_bf16 v[66:69], v[178:181], v[222:225], v[66:69]
	s_setprio 0
	s_barrier
	s_add_i32 s30, s51, s35
	v_lshl_add_u64 v[202:203], v[202:203], 0, s[8:9]
	s_mov_b32 m0, s30
	ds_read_b128 v[182:185], v149 offset:49152
	ds_read_b128 v[186:189], v149 offset:50176
	ds_read_b128 v[190:193], v149 offset:51200
	ds_read_b128 v[198:201], v149 offset:52224
	ds_read_b128 v[210:213], v149 offset:53248
	ds_read_b128 v[214:217], v149 offset:54272
	ds_read_b128 v[218:221], v149 offset:55296
	ds_read_b128 v[222:225], v149 offset:56320
	global_load_lds_dwordx4 v[202:203], off
	s_add_i32 m0, s30, 0x2000
	s_add_u32 s28, s28, 0x20080
	v_lshl_add_u64 v[202:203], v[206:207], 0, s[8:9]
	s_addc_u32 s29, s29, 0
	s_add_i32 s30, s52, s35
	global_load_lds_dwordx4 v[202:203], off
	s_mov_b32 m0, s30
	s_nop 0
	global_load_lds_dwordx4 v132, s[28:29]
	s_add_i32 m0, s30, 0x2000
	s_nop 0
	global_load_lds_dwordx4 v134, s[28:29]
	v_lshl_add_u64 v[202:203], v[226:227], 0, s[8:9]
	s_mov_b32 m0, s41
	s_nop 0
	global_load_lds_dwordx4 v[202:203], off
	v_lshl_add_u64 v[202:203], v[228:229], 0, s[8:9]
	s_mov_b32 m0, s42
	s_nop 0
	global_load_lds_dwordx4 v[202:203], off
	s_waitcnt vmcnt(8)
	s_waitcnt lgkmcnt(0)
	s_barrier
	s_setprio 1
	s_waitcnt lgkmcnt(0)
	v_mfma_f32_16x16x32_bf16 v[62:65], v[150:153], v[182:185], v[62:65]
	v_mfma_f32_16x16x32_bf16 v[58:61], v[158:161], v[182:185], v[58:61]
	v_mfma_f32_16x16x32_bf16 v[54:57], v[150:153], v[190:193], v[54:57]
	v_mfma_f32_16x16x32_bf16 v[50:53], v[158:161], v[190:193], v[50:53]
	v_mfma_f32_16x16x32_bf16 v[38:41], v[150:153], v[210:213], v[38:41]
	v_mfma_f32_16x16x32_bf16 v[34:37], v[158:161], v[210:213], v[34:37]
	v_mfma_f32_16x16x32_bf16 v[22:25], v[150:153], v[218:221], v[22:25]
	v_mfma_f32_16x16x32_bf16 v[18:21], v[158:161], v[218:221], v[18:21]
	v_mfma_f32_16x16x32_bf16 v[62:65], v[154:157], v[186:189], v[62:65]
	v_mfma_f32_16x16x32_bf16 v[58:61], v[162:165], v[186:189], v[58:61]
	v_mfma_f32_16x16x32_bf16 v[54:57], v[154:157], v[198:201], v[54:57]
	v_mfma_f32_16x16x32_bf16 v[50:53], v[162:165], v[198:201], v[50:53]
	v_mfma_f32_16x16x32_bf16 v[38:41], v[154:157], v[214:217], v[38:41]
	v_mfma_f32_16x16x32_bf16 v[34:37], v[162:165], v[214:217], v[34:37]
	v_mfma_f32_16x16x32_bf16 v[22:25], v[154:157], v[222:225], v[22:25]
	v_mfma_f32_16x16x32_bf16 v[18:21], v[162:165], v[222:225], v[18:21]
	s_setprio 0
	s_setprio 1
	v_mfma_f32_16x16x32_bf16 v[46:49], v[166:169], v[182:185], v[46:49]
	v_mfma_f32_16x16x32_bf16 v[42:45], v[174:177], v[182:185], v[42:45]
	v_mfma_f32_16x16x32_bf16 v[30:33], v[166:169], v[190:193], v[30:33]
	v_mfma_f32_16x16x32_bf16 v[26:29], v[174:177], v[190:193], v[26:29]
	v_mfma_f32_16x16x32_bf16 v[14:17], v[166:169], v[210:213], v[14:17]
	v_mfma_f32_16x16x32_bf16 v[10:13], v[174:177], v[210:213], v[10:13]
	v_mfma_f32_16x16x32_bf16 v[6:9], v[166:169], v[218:221], v[6:9]
	v_mfma_f32_16x16x32_bf16 v[2:5], v[174:177], v[218:221], v[2:5]
	v_mfma_f32_16x16x32_bf16 v[46:49], v[170:173], v[186:189], v[46:49]
	v_mfma_f32_16x16x32_bf16 v[42:45], v[178:181], v[186:189], v[42:45]
	v_mfma_f32_16x16x32_bf16 v[30:33], v[170:173], v[198:201], v[30:33]
	v_mfma_f32_16x16x32_bf16 v[26:29], v[178:181], v[198:201], v[26:29]
	v_mfma_f32_16x16x32_bf16 v[14:17], v[170:173], v[214:217], v[14:17]
	v_mfma_f32_16x16x32_bf16 v[10:13], v[178:181], v[214:217], v[10:13]
	v_mfma_f32_16x16x32_bf16 v[6:9], v[170:173], v[222:225], v[6:9]
	v_mfma_f32_16x16x32_bf16 v[2:5], v[178:181], v[222:225], v[2:5]
	s_setprio 0
	s_barrier
	s_add_i32 s50, s50, 2
	s_add_u32 s26, s26, 0x100
	s_addc_u32 s27, s27, 0
	s_add_u32 s48, s48, 0x100
	s_addc_u32 s49, s49, 0
	s_cmp_gt_u32 s50, 5
	s_cbranch_scc0 .LBB0_690
	s_branch .Lpeeldone_10
.LBB0_690:
	ds_read_b128 v[150:153], v147
	ds_read_b128 v[154:157], v147 offset:1024
	ds_read_b128 v[158:161], v147 offset:2048
	ds_read_b128 v[162:165], v147 offset:3072
	ds_read_b128 v[166:169], v148
	ds_read_b128 v[170:173], v148 offset:1024
	ds_read_b128 v[174:177], v148 offset:2048
	ds_read_b128 v[178:181], v148 offset:3072
	s_add_u32 s28, s26, 0xfffe0080
	s_addc_u32 s29, s27, -1
	s_cmp_eq_u32 s50, 4
	s_cselect_b32 s31, s13, s29
	s_cselect_b32 s30, s46, s28
	s_cselect_b32 s29, s17, s49
	s_cselect_b32 s28, s47, s48
	s_add_i32 m0, s36, 0xc000
	ds_read_b128 v[182:185], v149
	ds_read_b128 v[186:189], v149 offset:1024
	ds_read_b128 v[190:193], v149 offset:2048
	ds_read_b128 v[198:201], v149 offset:3072
	ds_read_b128 v[210:213], v149 offset:4096
	ds_read_b128 v[214:217], v149 offset:5120
	ds_read_b128 v[218:221], v149 offset:6144
	ds_read_b128 v[222:225], v149 offset:7168
	global_load_lds_dwordx4 v138, s[26:27]
	s_add_i32 m0, s36, 0xe000
	s_nop 0
	global_load_lds_dwordx4 v140, s[26:27]
	s_waitcnt vmcnt(8)
	s_waitcnt lgkmcnt(0)
	s_barrier
	s_setprio 1
	s_waitcnt lgkmcnt(0)
	v_mfma_f32_16x16x32_bf16 v[126:129], v[150:153], v[182:185], v[126:129]
	v_mfma_f32_16x16x32_bf16 v[122:125], v[158:161], v[182:185], v[122:125]
	v_mfma_f32_16x16x32_bf16 v[118:121], v[150:153], v[190:193], v[118:121]
	v_mfma_f32_16x16x32_bf16 v[114:117], v[158:161], v[190:193], v[114:117]
	v_mfma_f32_16x16x32_bf16 v[102:105], v[150:153], v[210:213], v[102:105]
	v_mfma_f32_16x16x32_bf16 v[98:101], v[158:161], v[210:213], v[98:101]
	v_mfma_f32_16x16x32_bf16 v[86:89], v[150:153], v[218:221], v[86:89]
	v_mfma_f32_16x16x32_bf16 v[82:85], v[158:161], v[218:221], v[82:85]
	v_mfma_f32_16x16x32_bf16 v[126:129], v[154:157], v[186:189], v[126:129]
	v_mfma_f32_16x16x32_bf16 v[122:125], v[162:165], v[186:189], v[122:125]
	v_mfma_f32_16x16x32_bf16 v[118:121], v[154:157], v[198:201], v[118:121]
	v_mfma_f32_16x16x32_bf16 v[114:117], v[162:165], v[198:201], v[114:117]
	v_mfma_f32_16x16x32_bf16 v[102:105], v[154:157], v[214:217], v[102:105]
	v_mfma_f32_16x16x32_bf16 v[98:101], v[162:165], v[214:217], v[98:101]
	v_mfma_f32_16x16x32_bf16 v[86:89], v[154:157], v[222:225], v[86:89]
	v_mfma_f32_16x16x32_bf16 v[82:85], v[162:165], v[222:225], v[82:85]
	s_setprio 0
	s_setprio 1
	v_mfma_f32_16x16x32_bf16 v[110:113], v[166:169], v[182:185], v[110:113]
	v_mfma_f32_16x16x32_bf16 v[106:109], v[174:177], v[182:185], v[106:109]
	v_mfma_f32_16x16x32_bf16 v[94:97], v[166:169], v[190:193], v[94:97]
	v_mfma_f32_16x16x32_bf16 v[90:93], v[174:177], v[190:193], v[90:93]
	v_mfma_f32_16x16x32_bf16 v[78:81], v[166:169], v[210:213], v[78:81]
	v_mfma_f32_16x16x32_bf16 v[74:77], v[174:177], v[210:213], v[74:77]
	v_mfma_f32_16x16x32_bf16 v[70:73], v[166:169], v[218:221], v[70:73]
	v_mfma_f32_16x16x32_bf16 v[66:69], v[174:177], v[218:221], v[66:69]
	v_mfma_f32_16x16x32_bf16 v[110:113], v[170:173], v[186:189], v[110:113]
	v_mfma_f32_16x16x32_bf16 v[106:109], v[178:181], v[186:189], v[106:109]
	v_mfma_f32_16x16x32_bf16 v[94:97], v[170:173], v[198:201], v[94:97]
	v_mfma_f32_16x16x32_bf16 v[90:93], v[178:181], v[198:201], v[90:93]
	v_mfma_f32_16x16x32_bf16 v[78:81], v[170:173], v[214:217], v[78:81]
	v_mfma_f32_16x16x32_bf16 v[74:77], v[178:181], v[214:217], v[74:77]
	v_mfma_f32_16x16x32_bf16 v[70:73], v[170:173], v[222:225], v[70:73]
	v_mfma_f32_16x16x32_bf16 v[66:69], v[178:181], v[222:225], v[66:69]
	s_setprio 0
	s_barrier
	s_add_i32 s51, s43, s35
	v_lshl_add_u64 v[202:203], s[28:29], 0, v[132:133]
	s_mov_b32 m0, s51
	ds_read_b128 v[182:185], v149 offset:16384
	ds_read_b128 v[186:189], v149 offset:17408
	ds_read_b128 v[190:193], v149 offset:18432
	ds_read_b128 v[198:201], v149 offset:19456
	ds_read_b128 v[210:213], v149 offset:20480
	ds_read_b128 v[214:217], v149 offset:21504
	ds_read_b128 v[218:221], v149 offset:22528
	ds_read_b128 v[222:225], v149 offset:23552
	global_load_lds_dwordx4 v132, s[28:29]
	s_add_i32 m0, s51, 0x2000
	s_add_u32 s52, s28, 0x20000
	v_lshl_add_u64 v[206:207], s[28:29], 0, v[134:135]
	s_addc_u32 s53, s29, 0
	s_add_i32 s51, s44, s35
	global_load_lds_dwordx4 v134, s[28:29]
	s_mov_b32 m0, s51
	v_lshl_add_u64 v[228:229], s[30:31], 0, v[136:137]
	global_load_lds_dwordx4 v132, s[52:53]
	s_add_i32 m0, s51, 0x2000
	s_nop 0
	global_load_lds_dwordx4 v134, s[52:53]
	v_lshl_add_u64 v[226:227], s[30:31], 0, v[130:131]
	s_mov_b32 m0, s36
	s_nop 0
	global_load_lds_dwordx4 v130, s[30:31]
	s_mov_b32 m0, s37
	s_nop 0
	global_load_lds_dwordx4 v136, s[30:31]
	s_waitcnt vmcnt(8)
	s_waitcnt lgkmcnt(0)
	s_barrier
	s_setprio 1
	s_waitcnt lgkmcnt(0)
	v_mfma_f32_16x16x32_bf16 v[62:65], v[150:153], v[182:185], v[62:65]
	v_mfma_f32_16x16x32_bf16 v[58:61], v[158:161], v[182:185], v[58:61]
	v_mfma_f32_16x16x32_bf16 v[54:57], v[150:153], v[190:193], v[54:57]
	v_mfma_f32_16x16x32_bf16 v[50:53], v[158:161], v[190:193], v[50:53]
	v_mfma_f32_16x16x32_bf16 v[38:41], v[150:153], v[210:213], v[38:41]
	v_mfma_f32_16x16x32_bf16 v[34:37], v[158:161], v[210:213], v[34:37]
	v_mfma_f32_16x16x32_bf16 v[22:25], v[150:153], v[218:221], v[22:25]
	v_mfma_f32_16x16x32_bf16 v[18:21], v[158:161], v[218:221], v[18:21]
	v_mfma_f32_16x16x32_bf16 v[62:65], v[154:157], v[186:189], v[62:65]
	v_mfma_f32_16x16x32_bf16 v[58:61], v[162:165], v[186:189], v[58:61]
	v_mfma_f32_16x16x32_bf16 v[54:57], v[154:157], v[198:201], v[54:57]
	v_mfma_f32_16x16x32_bf16 v[50:53], v[162:165], v[198:201], v[50:53]
	v_mfma_f32_16x16x32_bf16 v[38:41], v[154:157], v[214:217], v[38:41]
	v_mfma_f32_16x16x32_bf16 v[34:37], v[162:165], v[214:217], v[34:37]
	v_mfma_f32_16x16x32_bf16 v[22:25], v[154:157], v[222:225], v[22:25]
	v_mfma_f32_16x16x32_bf16 v[18:21], v[162:165], v[222:225], v[18:21]
	s_setprio 0
	s_setprio 1
	v_mfma_f32_16x16x32_bf16 v[46:49], v[166:169], v[182:185], v[46:49]
	v_mfma_f32_16x16x32_bf16 v[42:45], v[174:177], v[182:185], v[42:45]
	v_mfma_f32_16x16x32_bf16 v[30:33], v[166:169], v[190:193], v[30:33]
	v_mfma_f32_16x16x32_bf16 v[26:29], v[174:177], v[190:193], v[26:29]
	v_mfma_f32_16x16x32_bf16 v[14:17], v[166:169], v[210:213], v[14:17]
	v_mfma_f32_16x16x32_bf16 v[10:13], v[174:177], v[210:213], v[10:13]
	v_mfma_f32_16x16x32_bf16 v[6:9], v[166:169], v[218:221], v[6:9]
	v_mfma_f32_16x16x32_bf16 v[2:5], v[174:177], v[218:221], v[2:5]
	v_mfma_f32_16x16x32_bf16 v[46:49], v[170:173], v[186:189], v[46:49]
	v_mfma_f32_16x16x32_bf16 v[42:45], v[178:181], v[186:189], v[42:45]
	v_mfma_f32_16x16x32_bf16 v[30:33], v[170:173], v[198:201], v[30:33]
	v_mfma_f32_16x16x32_bf16 v[26:29], v[178:181], v[198:201], v[26:29]
	v_mfma_f32_16x16x32_bf16 v[14:17], v[170:173], v[214:217], v[14:17]
	v_mfma_f32_16x16x32_bf16 v[10:13], v[178:181], v[214:217], v[10:13]
	v_mfma_f32_16x16x32_bf16 v[6:9], v[170:173], v[222:225], v[6:9]
	v_mfma_f32_16x16x32_bf16 v[2:5], v[178:181], v[222:225], v[2:5]
	s_setprio 0
	s_barrier
	s_add_i32 s51, 0, 0x18000
	s_add_i32 s52, 0, 0x1c000
	v_add_u32_e32 v162, s51, v145
	v_add_u32_e32 v178, s52, v145
	ds_read_b128 v[150:153], v162
	ds_read_b128 v[154:157], v162 offset:1024
	ds_read_b128 v[158:161], v162 offset:2048
	ds_read_b128 v[162:165], v162 offset:3072
	ds_read_b128 v[166:169], v178
	ds_read_b128 v[170:173], v178 offset:1024
	ds_read_b128 v[174:177], v178 offset:2048
	ds_read_b128 v[178:181], v178 offset:3072
	s_add_u32 s30, s30, 0x20000
	s_addc_u32 s31, s31, 0
	s_mov_b32 m0, s38
	ds_read_b128 v[182:185], v149 offset:32768
	ds_read_b128 v[186:189], v149 offset:33792
	ds_read_b128 v[190:193], v149 offset:34816
	ds_read_b128 v[198:201], v149 offset:35840
	ds_read_b128 v[210:213], v149 offset:36864
	ds_read_b128 v[214:217], v149 offset:37888
	ds_read_b128 v[218:221], v149 offset:38912
	ds_read_b128 v[222:225], v149 offset:39936
	global_load_lds_dwordx4 v130, s[30:31]
	v_lshl_add_u64 v[230:231], s[30:31], 0, v[136:137]
	s_mov_b32 m0, s39
	s_nop 0
	global_load_lds_dwordx4 v136, s[30:31]
	s_waitcnt vmcnt(8)
	s_waitcnt lgkmcnt(0)
	s_barrier
	s_setprio 1
	s_waitcnt lgkmcnt(0)
	v_mfma_f32_16x16x32_bf16 v[126:129], v[150:153], v[182:185], v[126:129]
	v_mfma_f32_16x16x32_bf16 v[122:125], v[158:161], v[182:185], v[122:125]
	v_mfma_f32_16x16x32_bf16 v[118:121], v[150:153], v[190:193], v[118:121]
	v_mfma_f32_16x16x32_bf16 v[114:117], v[158:161], v[190:193], v[114:117]
	v_mfma_f32_16x16x32_bf16 v[102:105], v[150:153], v[210:213], v[102:105]
	v_mfma_f32_16x16x32_bf16 v[98:101], v[158:161], v[210:213], v[98:101]
	v_mfma_f32_16x16x32_bf16 v[86:89], v[150:153], v[218:221], v[86:89]
	v_mfma_f32_16x16x32_bf16 v[82:85], v[158:161], v[218:221], v[82:85]
	v_mfma_f32_16x16x32_bf16 v[126:129], v[154:157], v[186:189], v[126:129]
	v_mfma_f32_16x16x32_bf16 v[122:125], v[162:165], v[186:189], v[122:125]
	v_mfma_f32_16x16x32_bf16 v[118:121], v[154:157], v[198:201], v[118:121]
	v_mfma_f32_16x16x32_bf16 v[114:117], v[162:165], v[198:201], v[114:117]
	v_mfma_f32_16x16x32_bf16 v[102:105], v[154:157], v[214:217], v[102:105]
	v_mfma_f32_16x16x32_bf16 v[98:101], v[162:165], v[214:217], v[98:101]
	v_mfma_f32_16x16x32_bf16 v[86:89], v[154:157], v[222:225], v[86:89]
	v_mfma_f32_16x16x32_bf16 v[82:85], v[162:165], v[222:225], v[82:85]
	s_setprio 0
	s_setprio 1
	v_mfma_f32_16x16x32_bf16 v[110:113], v[166:169], v[182:185], v[110:113]
	v_mfma_f32_16x16x32_bf16 v[106:109], v[174:177], v[182:185], v[106:109]
	v_mfma_f32_16x16x32_bf16 v[94:97], v[166:169], v[190:193], v[94:97]
	v_mfma_f32_16x16x32_bf16 v[90:93], v[174:177], v[190:193], v[90:93]
	v_mfma_f32_16x16x32_bf16 v[78:81], v[166:169], v[210:213], v[78:81]
	v_mfma_f32_16x16x32_bf16 v[74:77], v[174:177], v[210:213], v[74:77]
	v_mfma_f32_16x16x32_bf16 v[70:73], v[166:169], v[218:221], v[70:73]
	v_mfma_f32_16x16x32_bf16 v[66:69], v[174:177], v[218:221], v[66:69]
	v_mfma_f32_16x16x32_bf16 v[110:113], v[170:173], v[186:189], v[110:113]
	v_mfma_f32_16x16x32_bf16 v[106:109], v[178:181], v[186:189], v[106:109]
	v_mfma_f32_16x16x32_bf16 v[94:97], v[170:173], v[198:201], v[94:97]
	v_mfma_f32_16x16x32_bf16 v[90:93], v[178:181], v[198:201], v[90:93]
	v_mfma_f32_16x16x32_bf16 v[78:81], v[170:173], v[214:217], v[78:81]
	v_mfma_f32_16x16x32_bf16 v[74:77], v[178:181], v[214:217], v[74:77]
	v_mfma_f32_16x16x32_bf16 v[70:73], v[170:173], v[222:225], v[70:73]
	v_mfma_f32_16x16x32_bf16 v[66:69], v[178:181], v[222:225], v[66:69]
	s_setprio 0
	s_barrier
	s_add_i32 s30, s51, s35
	v_lshl_add_u64 v[202:203], v[202:203], 0, s[8:9]
	s_mov_b32 m0, s30
	ds_read_b128 v[182:185], v149 offset:49152
	ds_read_b128 v[186:189], v149 offset:50176
	ds_read_b128 v[190:193], v149 offset:51200
	ds_read_b128 v[198:201], v149 offset:52224
	ds_read_b128 v[210:213], v149 offset:53248
	ds_read_b128 v[214:217], v149 offset:54272
	ds_read_b128 v[218:221], v149 offset:55296
	ds_read_b128 v[222:225], v149 offset:56320
	global_load_lds_dwordx4 v[202:203], off
	s_add_i32 m0, s30, 0x2000
	s_add_u32 s28, s28, 0x20080
	v_lshl_add_u64 v[202:203], v[206:207], 0, s[8:9]
	s_addc_u32 s29, s29, 0
	s_add_i32 s30, s52, s35
	global_load_lds_dwordx4 v[202:203], off
	s_mov_b32 m0, s30
	s_nop 0
	global_load_lds_dwordx4 v132, s[28:29]
	s_add_i32 m0, s30, 0x2000
	s_nop 0
	global_load_lds_dwordx4 v134, s[28:29]
	v_lshl_add_u64 v[202:203], v[226:227], 0, s[8:9]
	s_mov_b32 m0, s41
	s_nop 0
	global_load_lds_dwordx4 v[202:203], off
	v_lshl_add_u64 v[202:203], v[228:229], 0, s[8:9]
	s_mov_b32 m0, s42
	s_nop 0
	global_load_lds_dwordx4 v[202:203], off
	s_waitcnt vmcnt(8)
	s_waitcnt lgkmcnt(0)
	s_barrier
	s_setprio 1
	s_waitcnt lgkmcnt(0)
	v_mfma_f32_16x16x32_bf16 v[62:65], v[150:153], v[182:185], v[62:65]
	v_mfma_f32_16x16x32_bf16 v[58:61], v[158:161], v[182:185], v[58:61]
	v_mfma_f32_16x16x32_bf16 v[54:57], v[150:153], v[190:193], v[54:57]
	v_mfma_f32_16x16x32_bf16 v[50:53], v[158:161], v[190:193], v[50:53]
	v_mfma_f32_16x16x32_bf16 v[38:41], v[150:153], v[210:213], v[38:41]
	v_mfma_f32_16x16x32_bf16 v[34:37], v[158:161], v[210:213], v[34:37]
	v_mfma_f32_16x16x32_bf16 v[22:25], v[150:153], v[218:221], v[22:25]
	v_mfma_f32_16x16x32_bf16 v[18:21], v[158:161], v[218:221], v[18:21]
	v_mfma_f32_16x16x32_bf16 v[62:65], v[154:157], v[186:189], v[62:65]
	v_mfma_f32_16x16x32_bf16 v[58:61], v[162:165], v[186:189], v[58:61]
	v_mfma_f32_16x16x32_bf16 v[54:57], v[154:157], v[198:201], v[54:57]
	v_mfma_f32_16x16x32_bf16 v[50:53], v[162:165], v[198:201], v[50:53]
	v_mfma_f32_16x16x32_bf16 v[38:41], v[154:157], v[214:217], v[38:41]
	v_mfma_f32_16x16x32_bf16 v[34:37], v[162:165], v[214:217], v[34:37]
	v_mfma_f32_16x16x32_bf16 v[22:25], v[154:157], v[222:225], v[22:25]
	v_mfma_f32_16x16x32_bf16 v[18:21], v[162:165], v[222:225], v[18:21]
	s_setprio 0
	s_setprio 1
	v_mfma_f32_16x16x32_bf16 v[46:49], v[166:169], v[182:185], v[46:49]
	v_mfma_f32_16x16x32_bf16 v[42:45], v[174:177], v[182:185], v[42:45]
	v_mfma_f32_16x16x32_bf16 v[30:33], v[166:169], v[190:193], v[30:33]
	v_mfma_f32_16x16x32_bf16 v[26:29], v[174:177], v[190:193], v[26:29]
	v_mfma_f32_16x16x32_bf16 v[14:17], v[166:169], v[210:213], v[14:17]
	v_mfma_f32_16x16x32_bf16 v[10:13], v[174:177], v[210:213], v[10:13]
	v_mfma_f32_16x16x32_bf16 v[6:9], v[166:169], v[218:221], v[6:9]
	v_mfma_f32_16x16x32_bf16 v[2:5], v[174:177], v[218:221], v[2:5]
	v_mfma_f32_16x16x32_bf16 v[46:49], v[170:173], v[186:189], v[46:49]
	v_mfma_f32_16x16x32_bf16 v[42:45], v[178:181], v[186:189], v[42:45]
	v_mfma_f32_16x16x32_bf16 v[30:33], v[170:173], v[198:201], v[30:33]
	v_mfma_f32_16x16x32_bf16 v[26:29], v[178:181], v[198:201], v[26:29]
	v_mfma_f32_16x16x32_bf16 v[14:17], v[170:173], v[214:217], v[14:17]
	v_mfma_f32_16x16x32_bf16 v[10:13], v[178:181], v[214:217], v[10:13]
	v_mfma_f32_16x16x32_bf16 v[6:9], v[170:173], v[222:225], v[6:9]
	v_mfma_f32_16x16x32_bf16 v[2:5], v[178:181], v[222:225], v[2:5]
	s_setprio 0
	s_barrier
	s_add_i32 s50, s50, 2
	s_add_u32 s26, s26, 0x100
	s_addc_u32 s27, s27, 0
	s_add_u32 s48, s48, 0x100
	s_addc_u32 s49, s49, 0
	s_cmp_gt_u32 s50, 5
	s_cbranch_scc0 .LBB0_690

.Lpeel_9:
	ds_read_b128 v[144:147], v140
	ds_read_b128 v[148:151], v140 offset:1024
	s_add_u32 s36, s34, 0xfffe0080
	s_addc_u32 s37, s35, -1
	s_cmp_eq_u32 s59, 4
	s_cselect_b32 s39, s21, s37
	s_cselect_b32 s38, s55, s36
	s_cselect_b32 s37, s25, s58
	s_cselect_b32 s36, s56, s57
	s_add_i32 m0, s27, 0xc000
	global_load_lds_dwordx4 v130, s[34:35]
	s_add_i32 m0, s27, 0xe000
	s_nop 0
	global_load_lds_dwordx4 v136, s[34:35]
	s_waitcnt vmcnt(8)
	s_waitcnt lgkmcnt(0)
	s_barrier
	s_setprio 1
	s_waitcnt lgkmcnt(0)
	v_mfma_f32_16x16x32_bf16 v[126:129], v[144:147], v[176:179], 0
	v_mfma_f32_16x16x32_bf16 v[122:125], v[152:155], v[176:179], 0
	v_mfma_f32_16x16x32_bf16 v[118:121], v[144:147], v[184:187], 0
	v_mfma_f32_16x16x32_bf16 v[114:117], v[152:155], v[184:187], 0
	v_mfma_f32_16x16x32_bf16 v[102:105], v[144:147], v[198:201], 0
	v_mfma_f32_16x16x32_bf16 v[98:101], v[152:155], v[198:201], 0
	v_mfma_f32_16x16x32_bf16 v[86:89], v[144:147], v[214:217], 0
	v_mfma_f32_16x16x32_bf16 v[82:85], v[152:155], v[214:217], 0
	v_mfma_f32_16x16x32_bf16 v[126:129], v[148:151], v[180:183], v[126:129]
	v_mfma_f32_16x16x32_bf16 v[122:125], v[156:159], v[180:183], v[122:125]
	v_mfma_f32_16x16x32_bf16 v[118:121], v[148:151], v[188:191], v[118:121]
	v_mfma_f32_16x16x32_bf16 v[114:117], v[156:159], v[188:191], v[114:117]
	v_mfma_f32_16x16x32_bf16 v[102:105], v[148:151], v[210:213], v[102:105]
	v_mfma_f32_16x16x32_bf16 v[98:101], v[156:159], v[210:213], v[98:101]
	v_mfma_f32_16x16x32_bf16 v[86:89], v[148:151], v[218:221], v[86:89]
	v_mfma_f32_16x16x32_bf16 v[82:85], v[156:159], v[218:221], v[82:85]
	s_setprio 0
	s_setprio 1
	v_mfma_f32_16x16x32_bf16 v[110:113], v[160:163], v[176:179], 0
	v_mfma_f32_16x16x32_bf16 v[106:109], v[168:171], v[176:179], 0
	v_mfma_f32_16x16x32_bf16 v[94:97], v[160:163], v[184:187], 0
	v_mfma_f32_16x16x32_bf16 v[90:93], v[168:171], v[184:187], 0
	v_mfma_f32_16x16x32_bf16 v[78:81], v[160:163], v[198:201], 0
	v_mfma_f32_16x16x32_bf16 v[74:77], v[168:171], v[198:201], 0
	v_mfma_f32_16x16x32_bf16 v[70:73], v[160:163], v[214:217], 0
	v_mfma_f32_16x16x32_bf16 v[66:69], v[168:171], v[214:217], 0
	v_mfma_f32_16x16x32_bf16 v[110:113], v[164:167], v[180:183], v[110:113]
	v_mfma_f32_16x16x32_bf16 v[106:109], v[172:175], v[180:183], v[106:109]
	v_mfma_f32_16x16x32_bf16 v[94:97], v[164:167], v[188:191], v[94:97]
	v_mfma_f32_16x16x32_bf16 v[90:93], v[172:175], v[188:191], v[90:93]
	v_mfma_f32_16x16x32_bf16 v[78:81], v[164:167], v[210:213], v[78:81]
	v_mfma_f32_16x16x32_bf16 v[74:77], v[172:175], v[210:213], v[74:77]
	v_mfma_f32_16x16x32_bf16 v[70:73], v[164:167], v[218:221], v[70:73]
	v_mfma_f32_16x16x32_bf16 v[66:69], v[172:175], v[218:221], v[66:69]
	s_setprio 0
	s_barrier
	s_add_i32 s60, s48, s41
	v_lshl_add_u64 v[192:193], s[36:37], 0, v[132:133]
	s_mov_b32 m0, s60
	ds_read_b128 v[176:179], v142 offset:16384
	ds_read_b128 v[180:183], v142 offset:17408
	ds_read_b128 v[184:187], v142 offset:18432
	ds_read_b128 v[188:191], v142 offset:19456
	ds_read_b128 v[198:201], v142 offset:20480
	ds_read_b128 v[210:213], v142 offset:21504
	ds_read_b128 v[214:217], v142 offset:22528
	ds_read_b128 v[218:221], v142 offset:23552
	global_load_lds_dwordx4 v132, s[36:37]
	s_add_i32 m0, s60, 0x2000
	s_add_u32 s60, s36, 0x20000
	v_lshl_add_u64 v[202:203], s[36:37], 0, v[134:135]
	s_addc_u32 s61, s37, 0
	s_add_i32 s62, s49, s41
	global_load_lds_dwordx4 v134, s[36:37]
	s_mov_b32 m0, s62
	v_lshl_add_u64 v[222:223], s[38:39], 0, v[136:137]
	global_load_lds_dwordx4 v132, s[60:61]
	s_add_i32 m0, s62, 0x2000
	s_nop 0
	global_load_lds_dwordx4 v134, s[60:61]
	v_lshl_add_u64 v[206:207], s[38:39], 0, v[130:131]
	s_mov_b32 m0, s27
	s_nop 0
	global_load_lds_dwordx4 v130, s[38:39]
	s_mov_b32 m0, s42
	s_nop 0
	global_load_lds_dwordx4 v136, s[38:39]
	s_waitcnt vmcnt(8)
	s_waitcnt lgkmcnt(0)
	s_barrier
	s_setprio 1
	s_waitcnt lgkmcnt(0)
	v_mfma_f32_16x16x32_bf16 v[62:65], v[144:147], v[176:179], 0
	v_mfma_f32_16x16x32_bf16 v[58:61], v[152:155], v[176:179], 0
	v_mfma_f32_16x16x32_bf16 v[54:57], v[144:147], v[184:187], 0
	v_mfma_f32_16x16x32_bf16 v[50:53], v[152:155], v[184:187], 0
	v_mfma_f32_16x16x32_bf16 v[38:41], v[144:147], v[198:201], 0
	v_mfma_f32_16x16x32_bf16 v[34:37], v[152:155], v[198:201], 0
	v_mfma_f32_16x16x32_bf16 v[22:25], v[144:147], v[214:217], 0
	v_mfma_f32_16x16x32_bf16 v[18:21], v[152:155], v[214:217], 0
	v_mfma_f32_16x16x32_bf16 v[62:65], v[148:151], v[180:183], v[62:65]
	v_mfma_f32_16x16x32_bf16 v[58:61], v[156:159], v[180:183], v[58:61]
	v_mfma_f32_16x16x32_bf16 v[54:57], v[148:151], v[188:191], v[54:57]
	v_mfma_f32_16x16x32_bf16 v[50:53], v[156:159], v[188:191], v[50:53]
	v_mfma_f32_16x16x32_bf16 v[38:41], v[148:151], v[210:213], v[38:41]
	v_mfma_f32_16x16x32_bf16 v[34:37], v[156:159], v[210:213], v[34:37]
	v_mfma_f32_16x16x32_bf16 v[22:25], v[148:151], v[218:221], v[22:25]
	v_mfma_f32_16x16x32_bf16 v[18:21], v[156:159], v[218:221], v[18:21]
	s_setprio 0
	s_setprio 1
	v_mfma_f32_16x16x32_bf16 v[46:49], v[160:163], v[176:179], 0
	v_mfma_f32_16x16x32_bf16 v[42:45], v[168:171], v[176:179], 0
	v_mfma_f32_16x16x32_bf16 v[30:33], v[160:163], v[184:187], 0
	v_mfma_f32_16x16x32_bf16 v[26:29], v[168:171], v[184:187], 0
	v_mfma_f32_16x16x32_bf16 v[14:17], v[160:163], v[198:201], 0
	v_mfma_f32_16x16x32_bf16 v[10:13], v[168:171], v[198:201], 0
	v_mfma_f32_16x16x32_bf16 v[6:9], v[160:163], v[214:217], 0
	v_mfma_f32_16x16x32_bf16 v[2:5], v[168:171], v[214:217], 0
	v_mfma_f32_16x16x32_bf16 v[46:49], v[164:167], v[180:183], v[46:49]
	v_mfma_f32_16x16x32_bf16 v[42:45], v[172:175], v[180:183], v[42:45]
	v_mfma_f32_16x16x32_bf16 v[30:33], v[164:167], v[188:191], v[30:33]
	v_mfma_f32_16x16x32_bf16 v[26:29], v[172:175], v[188:191], v[26:29]
	v_mfma_f32_16x16x32_bf16 v[14:17], v[164:167], v[210:213], v[14:17]
	v_mfma_f32_16x16x32_bf16 v[10:13], v[172:175], v[210:213], v[10:13]
	v_mfma_f32_16x16x32_bf16 v[6:9], v[164:167], v[218:221], v[6:9]
	v_mfma_f32_16x16x32_bf16 v[2:5], v[172:175], v[218:221], v[2:5]
	s_setprio 0
	s_barrier
	s_add_i32 s60, 0, 0x18000
	v_add_u32_e32 v143, s60, v139
	s_add_i32 s61, 0, 0x1c000
	ds_read_b128 v[144:147], v143
	ds_read_b128 v[148:151], v143 offset:1024
	ds_read_b128 v[152:155], v143 offset:2048
	ds_read_b128 v[156:159], v143 offset:3072
	v_add_u32_e32 v143, s61, v139
	ds_read_b128 v[160:163], v143
	ds_read_b128 v[164:167], v143 offset:1024
	ds_read_b128 v[168:171], v143 offset:2048
	ds_read_b128 v[172:175], v143 offset:3072
	s_add_u32 s38, s38, 0x20000
	s_addc_u32 s39, s39, 0
	s_mov_b32 m0, s43
	ds_read_b128 v[176:179], v142 offset:32768
	ds_read_b128 v[180:183], v142 offset:33792
	ds_read_b128 v[184:187], v142 offset:34816
	ds_read_b128 v[188:191], v142 offset:35840
	ds_read_b128 v[198:201], v142 offset:36864
	ds_read_b128 v[210:213], v142 offset:37888
	ds_read_b128 v[214:217], v142 offset:38912
	ds_read_b128 v[218:221], v142 offset:39936
	global_load_lds_dwordx4 v130, s[38:39]
	v_lshl_add_u64 v[224:225], s[38:39], 0, v[136:137]
	s_mov_b32 m0, s44
	s_nop 0
	global_load_lds_dwordx4 v136, s[38:39]
	s_waitcnt vmcnt(8)
	s_waitcnt lgkmcnt(0)
	s_barrier
	s_setprio 1
	s_waitcnt lgkmcnt(0)
	v_mfma_f32_16x16x32_bf16 v[126:129], v[144:147], v[176:179], v[126:129]
	v_mfma_f32_16x16x32_bf16 v[122:125], v[152:155], v[176:179], v[122:125]
	v_mfma_f32_16x16x32_bf16 v[118:121], v[144:147], v[184:187], v[118:121]
	v_mfma_f32_16x16x32_bf16 v[114:117], v[152:155], v[184:187], v[114:117]
	v_mfma_f32_16x16x32_bf16 v[102:105], v[144:147], v[198:201], v[102:105]
	v_mfma_f32_16x16x32_bf16 v[98:101], v[152:155], v[198:201], v[98:101]
	v_mfma_f32_16x16x32_bf16 v[86:89], v[144:147], v[214:217], v[86:89]
	v_mfma_f32_16x16x32_bf16 v[82:85], v[152:155], v[214:217], v[82:85]
	v_mfma_f32_16x16x32_bf16 v[126:129], v[148:151], v[180:183], v[126:129]
	v_mfma_f32_16x16x32_bf16 v[122:125], v[156:159], v[180:183], v[122:125]
	v_mfma_f32_16x16x32_bf16 v[118:121], v[148:151], v[188:191], v[118:121]
	v_mfma_f32_16x16x32_bf16 v[114:117], v[156:159], v[188:191], v[114:117]
	v_mfma_f32_16x16x32_bf16 v[102:105], v[148:151], v[210:213], v[102:105]
	v_mfma_f32_16x16x32_bf16 v[98:101], v[156:159], v[210:213], v[98:101]
	v_mfma_f32_16x16x32_bf16 v[86:89], v[148:151], v[218:221], v[86:89]
	v_mfma_f32_16x16x32_bf16 v[82:85], v[156:159], v[218:221], v[82:85]
	s_setprio 0
	s_setprio 1
	v_mfma_f32_16x16x32_bf16 v[110:113], v[160:163], v[176:179], v[110:113]
	v_mfma_f32_16x16x32_bf16 v[106:109], v[168:171], v[176:179], v[106:109]
	v_mfma_f32_16x16x32_bf16 v[94:97], v[160:163], v[184:187], v[94:97]
	v_mfma_f32_16x16x32_bf16 v[90:93], v[168:171], v[184:187], v[90:93]
	v_mfma_f32_16x16x32_bf16 v[78:81], v[160:163], v[198:201], v[78:81]
	v_mfma_f32_16x16x32_bf16 v[74:77], v[168:171], v[198:201], v[74:77]
	v_mfma_f32_16x16x32_bf16 v[70:73], v[160:163], v[214:217], v[70:73]
	v_mfma_f32_16x16x32_bf16 v[66:69], v[168:171], v[214:217], v[66:69]
	v_mfma_f32_16x16x32_bf16 v[110:113], v[164:167], v[180:183], v[110:113]
	v_mfma_f32_16x16x32_bf16 v[106:109], v[172:175], v[180:183], v[106:109]
	v_mfma_f32_16x16x32_bf16 v[94:97], v[164:167], v[188:191], v[94:97]
	v_mfma_f32_16x16x32_bf16 v[90:93], v[172:175], v[188:191], v[90:93]
	v_mfma_f32_16x16x32_bf16 v[78:81], v[164:167], v[210:213], v[78:81]
	v_mfma_f32_16x16x32_bf16 v[74:77], v[172:175], v[210:213], v[74:77]
	v_mfma_f32_16x16x32_bf16 v[70:73], v[164:167], v[218:221], v[70:73]
	v_mfma_f32_16x16x32_bf16 v[66:69], v[172:175], v[218:221], v[66:69]
	s_setprio 0
	s_barrier
	s_add_i32 s38, s60, s41
	v_lshl_add_u64 v[192:193], v[192:193], 0, s[6:7]
	s_mov_b32 m0, s38
	ds_read_b128 v[176:179], v142 offset:49152
	ds_read_b128 v[180:183], v142 offset:50176
	ds_read_b128 v[184:187], v142 offset:51200
	ds_read_b128 v[188:191], v142 offset:52224
	ds_read_b128 v[198:201], v142 offset:53248
	ds_read_b128 v[210:213], v142 offset:54272
	ds_read_b128 v[214:217], v142 offset:55296
	ds_read_b128 v[218:221], v142 offset:56320
	global_load_lds_dwordx4 v[192:193], off
	s_add_i32 m0, s38, 0x2000
	s_add_u32 s36, s36, 0x20080
	v_lshl_add_u64 v[192:193], v[202:203], 0, s[6:7]
	s_addc_u32 s37, s37, 0
	s_add_i32 s38, s61, s41
	global_load_lds_dwordx4 v[192:193], off
	s_mov_b32 m0, s38
	s_nop 0
	global_load_lds_dwordx4 v132, s[36:37]
	s_add_i32 m0, s38, 0x2000
	s_nop 0
	global_load_lds_dwordx4 v134, s[36:37]
	v_lshl_add_u64 v[192:193], v[206:207], 0, s[6:7]
	s_mov_b32 m0, s46
	s_nop 0
	global_load_lds_dwordx4 v[192:193], off
	v_lshl_add_u64 v[192:193], v[222:223], 0, s[6:7]
	s_mov_b32 m0, s47
	s_nop 0
	global_load_lds_dwordx4 v[192:193], off
	s_waitcnt vmcnt(8)
	s_waitcnt lgkmcnt(0)
	s_barrier
	s_setprio 1
	s_waitcnt lgkmcnt(0)
	v_mfma_f32_16x16x32_bf16 v[62:65], v[144:147], v[176:179], v[62:65]
	v_mfma_f32_16x16x32_bf16 v[58:61], v[152:155], v[176:179], v[58:61]
	v_mfma_f32_16x16x32_bf16 v[54:57], v[144:147], v[184:187], v[54:57]
	v_mfma_f32_16x16x32_bf16 v[50:53], v[152:155], v[184:187], v[50:53]
	v_mfma_f32_16x16x32_bf16 v[38:41], v[144:147], v[198:201], v[38:41]
	v_mfma_f32_16x16x32_bf16 v[34:37], v[152:155], v[198:201], v[34:37]
	v_mfma_f32_16x16x32_bf16 v[22:25], v[144:147], v[214:217], v[22:25]
	v_mfma_f32_16x16x32_bf16 v[18:21], v[152:155], v[214:217], v[18:21]
	v_mfma_f32_16x16x32_bf16 v[62:65], v[148:151], v[180:183], v[62:65]
	v_mfma_f32_16x16x32_bf16 v[58:61], v[156:159], v[180:183], v[58:61]
	v_mfma_f32_16x16x32_bf16 v[54:57], v[148:151], v[188:191], v[54:57]
	v_mfma_f32_16x16x32_bf16 v[50:53], v[156:159], v[188:191], v[50:53]
	v_mfma_f32_16x16x32_bf16 v[38:41], v[148:151], v[210:213], v[38:41]
	v_mfma_f32_16x16x32_bf16 v[34:37], v[156:159], v[210:213], v[34:37]
	v_mfma_f32_16x16x32_bf16 v[22:25], v[148:151], v[218:221], v[22:25]
	v_mfma_f32_16x16x32_bf16 v[18:21], v[156:159], v[218:221], v[18:21]
	s_setprio 0
	s_setprio 1
	v_mfma_f32_16x16x32_bf16 v[46:49], v[160:163], v[176:179], v[46:49]
	v_mfma_f32_16x16x32_bf16 v[42:45], v[168:171], v[176:179], v[42:45]
	v_mfma_f32_16x16x32_bf16 v[30:33], v[160:163], v[184:187], v[30:33]
	v_mfma_f32_16x16x32_bf16 v[26:29], v[168:171], v[184:187], v[26:29]
	v_mfma_f32_16x16x32_bf16 v[14:17], v[160:163], v[198:201], v[14:17]
	v_mfma_f32_16x16x32_bf16 v[10:13], v[168:171], v[198:201], v[10:13]
	v_mfma_f32_16x16x32_bf16 v[6:9], v[160:163], v[214:217], v[6:9]
	v_mfma_f32_16x16x32_bf16 v[2:5], v[168:171], v[214:217], v[2:5]
	v_mfma_f32_16x16x32_bf16 v[46:49], v[164:167], v[180:183], v[46:49]
	v_mfma_f32_16x16x32_bf16 v[42:45], v[172:175], v[180:183], v[42:45]
	v_mfma_f32_16x16x32_bf16 v[30:33], v[164:167], v[188:191], v[30:33]
	v_mfma_f32_16x16x32_bf16 v[26:29], v[172:175], v[188:191], v[26:29]
	v_mfma_f32_16x16x32_bf16 v[14:17], v[164:167], v[210:213], v[14:17]
	v_mfma_f32_16x16x32_bf16 v[10:13], v[172:175], v[210:213], v[10:13]
	v_mfma_f32_16x16x32_bf16 v[6:9], v[164:167], v[218:221], v[6:9]
	v_mfma_f32_16x16x32_bf16 v[2:5], v[172:175], v[218:221], v[2:5]
	s_setprio 0
	s_barrier
	s_add_i32 s59, s59, 2
	s_add_u32 s34, s34, 0x100
	s_addc_u32 s35, s35, 0
	s_add_u32 s57, s57, 0x100
	s_addc_u32 s58, s58, 0
	s_cmp_gt_u32 s59, 5
	s_cbranch_scc0 .LBB0_714
	s_branch .Lpeeldone_9
.LBB0_714:
	ds_read_b128 v[144:147], v140
	ds_read_b128 v[148:151], v140 offset:1024
	ds_read_b128 v[152:155], v140 offset:2048
	ds_read_b128 v[156:159], v140 offset:3072
	ds_read_b128 v[160:163], v141
	ds_read_b128 v[164:167], v141 offset:1024
	ds_read_b128 v[168:171], v141 offset:2048
	ds_read_b128 v[172:175], v141 offset:3072
	s_add_u32 s36, s34, 0xfffe0080
	s_addc_u32 s37, s35, -1
	s_cmp_eq_u32 s59, 4
	s_cselect_b32 s39, s21, s37
	s_cselect_b32 s38, s55, s36
	s_cselect_b32 s37, s25, s58
	s_cselect_b32 s36, s56, s57
	s_add_i32 m0, s27, 0xc000
	ds_read_b128 v[176:179], v142
	ds_read_b128 v[180:183], v142 offset:1024
	ds_read_b128 v[184:187], v142 offset:2048
	ds_read_b128 v[188:191], v142 offset:3072
	ds_read_b128 v[198:201], v142 offset:4096
	ds_read_b128 v[210:213], v142 offset:5120
	ds_read_b128 v[214:217], v142 offset:6144
	ds_read_b128 v[218:221], v142 offset:7168
	global_load_lds_dwordx4 v130, s[34:35]
	s_add_i32 m0, s27, 0xe000
	s_nop 0
	global_load_lds_dwordx4 v136, s[34:35]
	s_waitcnt vmcnt(8)
	s_waitcnt lgkmcnt(0)
	s_barrier
	s_setprio 1
	s_waitcnt lgkmcnt(0)
	v_mfma_f32_16x16x32_bf16 v[126:129], v[144:147], v[176:179], v[126:129]
	v_mfma_f32_16x16x32_bf16 v[122:125], v[152:155], v[176:179], v[122:125]
	v_mfma_f32_16x16x32_bf16 v[118:121], v[144:147], v[184:187], v[118:121]
	v_mfma_f32_16x16x32_bf16 v[114:117], v[152:155], v[184:187], v[114:117]
	v_mfma_f32_16x16x32_bf16 v[102:105], v[144:147], v[198:201], v[102:105]
	v_mfma_f32_16x16x32_bf16 v[98:101], v[152:155], v[198:201], v[98:101]
	v_mfma_f32_16x16x32_bf16 v[86:89], v[144:147], v[214:217], v[86:89]
	v_mfma_f32_16x16x32_bf16 v[82:85], v[152:155], v[214:217], v[82:85]
	v_mfma_f32_16x16x32_bf16 v[126:129], v[148:151], v[180:183], v[126:129]
	v_mfma_f32_16x16x32_bf16 v[122:125], v[156:159], v[180:183], v[122:125]
	v_mfma_f32_16x16x32_bf16 v[118:121], v[148:151], v[188:191], v[118:121]
	v_mfma_f32_16x16x32_bf16 v[114:117], v[156:159], v[188:191], v[114:117]
	v_mfma_f32_16x16x32_bf16 v[102:105], v[148:151], v[210:213], v[102:105]
	v_mfma_f32_16x16x32_bf16 v[98:101], v[156:159], v[210:213], v[98:101]
	v_mfma_f32_16x16x32_bf16 v[86:89], v[148:151], v[218:221], v[86:89]
	v_mfma_f32_16x16x32_bf16 v[82:85], v[156:159], v[218:221], v[82:85]
	s_setprio 0
	s_setprio 1
	v_mfma_f32_16x16x32_bf16 v[110:113], v[160:163], v[176:179], v[110:113]
	v_mfma_f32_16x16x32_bf16 v[106:109], v[168:171], v[176:179], v[106:109]
	v_mfma_f32_16x16x32_bf16 v[94:97], v[160:163], v[184:187], v[94:97]
	v_mfma_f32_16x16x32_bf16 v[90:93], v[168:171], v[184:187], v[90:93]
	v_mfma_f32_16x16x32_bf16 v[78:81], v[160:163], v[198:201], v[78:81]
	v_mfma_f32_16x16x32_bf16 v[74:77], v[168:171], v[198:201], v[74:77]
	v_mfma_f32_16x16x32_bf16 v[70:73], v[160:163], v[214:217], v[70:73]
	v_mfma_f32_16x16x32_bf16 v[66:69], v[168:171], v[214:217], v[66:69]
	v_mfma_f32_16x16x32_bf16 v[110:113], v[164:167], v[180:183], v[110:113]
	v_mfma_f32_16x16x32_bf16 v[106:109], v[172:175], v[180:183], v[106:109]
	v_mfma_f32_16x16x32_bf16 v[94:97], v[164:167], v[188:191], v[94:97]
	v_mfma_f32_16x16x32_bf16 v[90:93], v[172:175], v[188:191], v[90:93]
	v_mfma_f32_16x16x32_bf16 v[78:81], v[164:167], v[210:213], v[78:81]
	v_mfma_f32_16x16x32_bf16 v[74:77], v[172:175], v[210:213], v[74:77]
	v_mfma_f32_16x16x32_bf16 v[70:73], v[164:167], v[218:221], v[70:73]
	v_mfma_f32_16x16x32_bf16 v[66:69], v[172:175], v[218:221], v[66:69]
	s_setprio 0
	s_barrier
	s_add_i32 s60, s48, s41
	v_lshl_add_u64 v[192:193], s[36:37], 0, v[132:133]
	s_mov_b32 m0, s60
	ds_read_b128 v[176:179], v142 offset:16384
	ds_read_b128 v[180:183], v142 offset:17408
	ds_read_b128 v[184:187], v142 offset:18432
	ds_read_b128 v[188:191], v142 offset:19456
	ds_read_b128 v[198:201], v142 offset:20480
	ds_read_b128 v[210:213], v142 offset:21504
	ds_read_b128 v[214:217], v142 offset:22528
	ds_read_b128 v[218:221], v142 offset:23552
	global_load_lds_dwordx4 v132, s[36:37]
	s_add_i32 m0, s60, 0x2000
	s_add_u32 s60, s36, 0x20000
	v_lshl_add_u64 v[202:203], s[36:37], 0, v[134:135]
	s_addc_u32 s61, s37, 0
	s_add_i32 s62, s49, s41
	global_load_lds_dwordx4 v134, s[36:37]
	s_mov_b32 m0, s62
	v_lshl_add_u64 v[222:223], s[38:39], 0, v[136:137]
	global_load_lds_dwordx4 v132, s[60:61]
	s_add_i32 m0, s62, 0x2000
	s_nop 0
	global_load_lds_dwordx4 v134, s[60:61]
	v_lshl_add_u64 v[206:207], s[38:39], 0, v[130:131]
	s_mov_b32 m0, s27
	s_nop 0
	global_load_lds_dwordx4 v130, s[38:39]
	s_mov_b32 m0, s42
	s_nop 0
	global_load_lds_dwordx4 v136, s[38:39]
	s_waitcnt vmcnt(8)
	s_waitcnt lgkmcnt(0)
	s_barrier
	s_setprio 1
	s_waitcnt lgkmcnt(0)
	v_mfma_f32_16x16x32_bf16 v[62:65], v[144:147], v[176:179], v[62:65]
	v_mfma_f32_16x16x32_bf16 v[58:61], v[152:155], v[176:179], v[58:61]
	v_mfma_f32_16x16x32_bf16 v[54:57], v[144:147], v[184:187], v[54:57]
	v_mfma_f32_16x16x32_bf16 v[50:53], v[152:155], v[184:187], v[50:53]
	v_mfma_f32_16x16x32_bf16 v[38:41], v[144:147], v[198:201], v[38:41]
	v_mfma_f32_16x16x32_bf16 v[34:37], v[152:155], v[198:201], v[34:37]
	v_mfma_f32_16x16x32_bf16 v[22:25], v[144:147], v[214:217], v[22:25]
	v_mfma_f32_16x16x32_bf16 v[18:21], v[152:155], v[214:217], v[18:21]
	v_mfma_f32_16x16x32_bf16 v[62:65], v[148:151], v[180:183], v[62:65]
	v_mfma_f32_16x16x32_bf16 v[58:61], v[156:159], v[180:183], v[58:61]
	v_mfma_f32_16x16x32_bf16 v[54:57], v[148:151], v[188:191], v[54:57]
	v_mfma_f32_16x16x32_bf16 v[50:53], v[156:159], v[188:191], v[50:53]
	v_mfma_f32_16x16x32_bf16 v[38:41], v[148:151], v[210:213], v[38:41]
	v_mfma_f32_16x16x32_bf16 v[34:37], v[156:159], v[210:213], v[34:37]
	v_mfma_f32_16x16x32_bf16 v[22:25], v[148:151], v[218:221], v[22:25]
	v_mfma_f32_16x16x32_bf16 v[18:21], v[156:159], v[218:221], v[18:21]
	s_setprio 0
	s_setprio 1
	v_mfma_f32_16x16x32_bf16 v[46:49], v[160:163], v[176:179], v[46:49]
	v_mfma_f32_16x16x32_bf16 v[42:45], v[168:171], v[176:179], v[42:45]
	v_mfma_f32_16x16x32_bf16 v[30:33], v[160:163], v[184:187], v[30:33]
	v_mfma_f32_16x16x32_bf16 v[26:29], v[168:171], v[184:187], v[26:29]
	v_mfma_f32_16x16x32_bf16 v[14:17], v[160:163], v[198:201], v[14:17]
	v_mfma_f32_16x16x32_bf16 v[10:13], v[168:171], v[198:201], v[10:13]
	v_mfma_f32_16x16x32_bf16 v[6:9], v[160:163], v[214:217], v[6:9]
	v_mfma_f32_16x16x32_bf16 v[2:5], v[168:171], v[214:217], v[2:5]
	v_mfma_f32_16x16x32_bf16 v[46:49], v[164:167], v[180:183], v[46:49]
	v_mfma_f32_16x16x32_bf16 v[42:45], v[172:175], v[180:183], v[42:45]
	v_mfma_f32_16x16x32_bf16 v[30:33], v[164:167], v[188:191], v[30:33]
	v_mfma_f32_16x16x32_bf16 v[26:29], v[172:175], v[188:191], v[26:29]
	v_mfma_f32_16x16x32_bf16 v[14:17], v[164:167], v[210:213], v[14:17]
	v_mfma_f32_16x16x32_bf16 v[10:13], v[172:175], v[210:213], v[10:13]
	v_mfma_f32_16x16x32_bf16 v[6:9], v[164:167], v[218:221], v[6:9]
	v_mfma_f32_16x16x32_bf16 v[2:5], v[172:175], v[218:221], v[2:5]
	s_setprio 0
	s_barrier
	s_add_i32 s60, 0, 0x18000
	v_add_u32_e32 v143, s60, v139
	s_add_i32 s61, 0, 0x1c000
	ds_read_b128 v[144:147], v143
	ds_read_b128 v[148:151], v143 offset:1024
	ds_read_b128 v[152:155], v143 offset:2048
	ds_read_b128 v[156:159], v143 offset:3072
	v_add_u32_e32 v143, s61, v139
	ds_read_b128 v[160:163], v143
	ds_read_b128 v[164:167], v143 offset:1024
	ds_read_b128 v[168:171], v143 offset:2048
	ds_read_b128 v[172:175], v143 offset:3072
	s_add_u32 s38, s38, 0x20000
	s_addc_u32 s39, s39, 0
	s_mov_b32 m0, s43
	ds_read_b128 v[176:179], v142 offset:32768
	ds_read_b128 v[180:183], v142 offset:33792
	ds_read_b128 v[184:187], v142 offset:34816
	ds_read_b128 v[188:191], v142 offset:35840
	ds_read_b128 v[198:201], v142 offset:36864
	ds_read_b128 v[210:213], v142 offset:37888
	ds_read_b128 v[214:217], v142 offset:38912
	ds_read_b128 v[218:221], v142 offset:39936
	global_load_lds_dwordx4 v130, s[38:39]
	v_lshl_add_u64 v[224:225], s[38:39], 0, v[136:137]
	s_mov_b32 m0, s44
	s_nop 0
	global_load_lds_dwordx4 v136, s[38:39]
	s_waitcnt vmcnt(8)
	s_waitcnt lgkmcnt(0)
	s_barrier
	s_setprio 1
	s_waitcnt lgkmcnt(0)
	v_mfma_f32_16x16x32_bf16 v[126:129], v[144:147], v[176:179], v[126:129]
	v_mfma_f32_16x16x32_bf16 v[122:125], v[152:155], v[176:179], v[122:125]
	v_mfma_f32_16x16x32_bf16 v[118:121], v[144:147], v[184:187], v[118:121]
	v_mfma_f32_16x16x32_bf16 v[114:117], v[152:155], v[184:187], v[114:117]
	v_mfma_f32_16x16x32_bf16 v[102:105], v[144:147], v[198:201], v[102:105]
	v_mfma_f32_16x16x32_bf16 v[98:101], v[152:155], v[198:201], v[98:101]
	v_mfma_f32_16x16x32_bf16 v[86:89], v[144:147], v[214:217], v[86:89]
	v_mfma_f32_16x16x32_bf16 v[82:85], v[152:155], v[214:217], v[82:85]
	v_mfma_f32_16x16x32_bf16 v[126:129], v[148:151], v[180:183], v[126:129]
	v_mfma_f32_16x16x32_bf16 v[122:125], v[156:159], v[180:183], v[122:125]
	v_mfma_f32_16x16x32_bf16 v[118:121], v[148:151], v[188:191], v[118:121]
	v_mfma_f32_16x16x32_bf16 v[114:117], v[156:159], v[188:191], v[114:117]
	v_mfma_f32_16x16x32_bf16 v[102:105], v[148:151], v[210:213], v[102:105]
	v_mfma_f32_16x16x32_bf16 v[98:101], v[156:159], v[210:213], v[98:101]
	v_mfma_f32_16x16x32_bf16 v[86:89], v[148:151], v[218:221], v[86:89]
	v_mfma_f32_16x16x32_bf16 v[82:85], v[156:159], v[218:221], v[82:85]
	s_setprio 0
	s_setprio 1
	v_mfma_f32_16x16x32_bf16 v[110:113], v[160:163], v[176:179], v[110:113]
	v_mfma_f32_16x16x32_bf16 v[106:109], v[168:171], v[176:179], v[106:109]
	v_mfma_f32_16x16x32_bf16 v[94:97], v[160:163], v[184:187], v[94:97]
	v_mfma_f32_16x16x32_bf16 v[90:93], v[168:171], v[184:187], v[90:93]
	v_mfma_f32_16x16x32_bf16 v[78:81], v[160:163], v[198:201], v[78:81]
	v_mfma_f32_16x16x32_bf16 v[74:77], v[168:171], v[198:201], v[74:77]
	v_mfma_f32_16x16x32_bf16 v[70:73], v[160:163], v[214:217], v[70:73]
	v_mfma_f32_16x16x32_bf16 v[66:69], v[168:171], v[214:217], v[66:69]
	v_mfma_f32_16x16x32_bf16 v[110:113], v[164:167], v[180:183], v[110:113]
	v_mfma_f32_16x16x32_bf16 v[106:109], v[172:175], v[180:183], v[106:109]
	v_mfma_f32_16x16x32_bf16 v[94:97], v[164:167], v[188:191], v[94:97]
	v_mfma_f32_16x16x32_bf16 v[90:93], v[172:175], v[188:191], v[90:93]
	v_mfma_f32_16x16x32_bf16 v[78:81], v[164:167], v[210:213], v[78:81]
	v_mfma_f32_16x16x32_bf16 v[74:77], v[172:175], v[210:213], v[74:77]
	v_mfma_f32_16x16x32_bf16 v[70:73], v[164:167], v[218:221], v[70:73]
	v_mfma_f32_16x16x32_bf16 v[66:69], v[172:175], v[218:221], v[66:69]
	s_setprio 0
	s_barrier
	s_add_i32 s38, s60, s41
	v_lshl_add_u64 v[192:193], v[192:193], 0, s[6:7]
	s_mov_b32 m0, s38
	ds_read_b128 v[176:179], v142 offset:49152
	ds_read_b128 v[180:183], v142 offset:50176
	ds_read_b128 v[184:187], v142 offset:51200
	ds_read_b128 v[188:191], v142 offset:52224
	ds_read_b128 v[198:201], v142 offset:53248
	ds_read_b128 v[210:213], v142 offset:54272
	ds_read_b128 v[214:217], v142 offset:55296
	ds_read_b128 v[218:221], v142 offset:56320
	global_load_lds_dwordx4 v[192:193], off
	s_add_i32 m0, s38, 0x2000
	s_add_u32 s36, s36, 0x20080
	v_lshl_add_u64 v[192:193], v[202:203], 0, s[6:7]
	s_addc_u32 s37, s37, 0
	s_add_i32 s38, s61, s41
	global_load_lds_dwordx4 v[192:193], off
	s_mov_b32 m0, s38
	s_nop 0
	global_load_lds_dwordx4 v132, s[36:37]
	s_add_i32 m0, s38, 0x2000
	s_nop 0
	global_load_lds_dwordx4 v134, s[36:37]
	v_lshl_add_u64 v[192:193], v[206:207], 0, s[6:7]
	s_mov_b32 m0, s46
	s_nop 0
	global_load_lds_dwordx4 v[192:193], off
	v_lshl_add_u64 v[192:193], v[222:223], 0, s[6:7]
	s_mov_b32 m0, s47
	s_nop 0
	global_load_lds_dwordx4 v[192:193], off
	s_waitcnt vmcnt(8)
	s_waitcnt lgkmcnt(0)
	s_barrier
	s_setprio 1
	s_waitcnt lgkmcnt(0)
	v_mfma_f32_16x16x32_bf16 v[62:65], v[144:147], v[176:179], v[62:65]
	v_mfma_f32_16x16x32_bf16 v[58:61], v[152:155], v[176:179], v[58:61]
	v_mfma_f32_16x16x32_bf16 v[54:57], v[144:147], v[184:187], v[54:57]
	v_mfma_f32_16x16x32_bf16 v[50:53], v[152:155], v[184:187], v[50:53]
	v_mfma_f32_16x16x32_bf16 v[38:41], v[144:147], v[198:201], v[38:41]
	v_mfma_f32_16x16x32_bf16 v[34:37], v[152:155], v[198:201], v[34:37]
	v_mfma_f32_16x16x32_bf16 v[22:25], v[144:147], v[214:217], v[22:25]
	v_mfma_f32_16x16x32_bf16 v[18:21], v[152:155], v[214:217], v[18:21]
	v_mfma_f32_16x16x32_bf16 v[62:65], v[148:151], v[180:183], v[62:65]
	v_mfma_f32_16x16x32_bf16 v[58:61], v[156:159], v[180:183], v[58:61]
	v_mfma_f32_16x16x32_bf16 v[54:57], v[148:151], v[188:191], v[54:57]
	v_mfma_f32_16x16x32_bf16 v[50:53], v[156:159], v[188:191], v[50:53]
	v_mfma_f32_16x16x32_bf16 v[38:41], v[148:151], v[210:213], v[38:41]
	v_mfma_f32_16x16x32_bf16 v[34:37], v[156:159], v[210:213], v[34:37]
	v_mfma_f32_16x16x32_bf16 v[22:25], v[148:151], v[218:221], v[22:25]
	v_mfma_f32_16x16x32_bf16 v[18:21], v[156:159], v[218:221], v[18:21]
	s_setprio 0
	s_setprio 1
	v_mfma_f32_16x16x32_bf16 v[46:49], v[160:163], v[176:179], v[46:49]
	v_mfma_f32_16x16x32_bf16 v[42:45], v[168:171], v[176:179], v[42:45]
	v_mfma_f32_16x16x32_bf16 v[30:33], v[160:163], v[184:187], v[30:33]
	v_mfma_f32_16x16x32_bf16 v[26:29], v[168:171], v[184:187], v[26:29]
	v_mfma_f32_16x16x32_bf16 v[14:17], v[160:163], v[198:201], v[14:17]
	v_mfma_f32_16x16x32_bf16 v[10:13], v[168:171], v[198:201], v[10:13]
	v_mfma_f32_16x16x32_bf16 v[6:9], v[160:163], v[214:217], v[6:9]
	v_mfma_f32_16x16x32_bf16 v[2:5], v[168:171], v[214:217], v[2:5]
	v_mfma_f32_16x16x32_bf16 v[46:49], v[164:167], v[180:183], v[46:49]
	v_mfma_f32_16x16x32_bf16 v[42:45], v[172:175], v[180:183], v[42:45]
	v_mfma_f32_16x16x32_bf16 v[30:33], v[164:167], v[188:191], v[30:33]
	v_mfma_f32_16x16x32_bf16 v[26:29], v[172:175], v[188:191], v[26:29]
	v_mfma_f32_16x16x32_bf16 v[14:17], v[164:167], v[210:213], v[14:17]
	v_mfma_f32_16x16x32_bf16 v[10:13], v[172:175], v[210:213], v[10:13]
	v_mfma_f32_16x16x32_bf16 v[6:9], v[164:167], v[218:221], v[6:9]
	v_mfma_f32_16x16x32_bf16 v[2:5], v[172:175], v[218:221], v[2:5]
	s_setprio 0
	s_barrier
	s_add_i32 s59, s59, 2
	s_add_u32 s34, s34, 0x100
	s_addc_u32 s35, s35, 0
	s_add_u32 s57, s57, 0x100
	s_addc_u32 s58, s58, 0
	s_cmp_gt_u32 s59, 5
	s_cbranch_scc0 .LBB0_714

.Lpeel_8:
	ds_read_b128 v[130:133], v170
	ds_read_b128 v[134:137], v170 offset:1024
	ds_read_b128 v[138:141], v170 offset:2048
	ds_read_b128 v[142:145], v170 offset:3072
	ds_read_b128 v[160:163], v171
	ds_read_b128 v[164:167], v171 offset:1024
	ds_read_b128 v[174:177], v171 offset:2048
	ds_read_b128 v[178:181], v171 offset:3072
	s_add_i32 s31, s21, 2
	s_add_u32 s36, s34, 0xfff80080
	s_addc_u32 s37, s35, -1
	s_cmp_eq_u32 s30, s21
	s_cselect_b32 s39, s23, s37
	s_cselect_b32 s38, s22, s36
	s_cselect_b32 s37, s25, s19
	s_cselect_b32 s36, s24, s17
	s_add_i32 m0, s27, 0xc000
	ds_read_b128 v[182:185], v172
	ds_read_b128 v[186:189], v172 offset:1024
	ds_read_b128 v[190:193], v172 offset:2048
	ds_read_b128 v[198:201], v172 offset:3072
	ds_read_b128 v[210:213], v172 offset:4096
	ds_read_b128 v[214:217], v172 offset:5120
	global_load_lds_dwordx4 v156, s[34:35]
	s_add_i32 m0, s27, 0xe000
	s_nop 0
	global_load_lds_dwordx4 v158, s[34:35]
	s_waitcnt vmcnt(8)
	s_waitcnt lgkmcnt(0)
	s_barrier
	s_setprio 1
	s_waitcnt lgkmcnt(0)
	v_mfma_f32_16x16x32_bf16 v[126:129], v[130:133], v[182:185], 0
	v_mfma_f32_16x16x32_bf16 v[122:125], v[138:141], v[182:185], 0
	v_mfma_f32_16x16x32_bf16 v[118:121], v[130:133], v[190:193], 0
	v_mfma_f32_16x16x32_bf16 v[110:113], v[138:141], v[190:193], 0
	v_mfma_f32_16x16x32_bf16 v[94:97], v[130:133], v[210:213], 0
	v_mfma_f32_16x16x32_bf16 v[90:93], v[138:141], v[210:213], 0
	v_mfma_f32_16x16x32_bf16 v[78:81], v[130:133], v[218:221], 0
	v_mfma_f32_16x16x32_bf16 v[74:77], v[138:141], v[218:221], 0
	v_mfma_f32_16x16x32_bf16 v[126:129], v[134:137], v[186:189], v[126:129]
	v_mfma_f32_16x16x32_bf16 v[122:125], v[142:145], v[186:189], v[122:125]
	v_mfma_f32_16x16x32_bf16 v[118:121], v[134:137], v[198:201], v[118:121]
	v_mfma_f32_16x16x32_bf16 v[110:113], v[142:145], v[198:201], v[110:113]
	v_mfma_f32_16x16x32_bf16 v[94:97], v[134:137], v[214:217], v[94:97]
	v_mfma_f32_16x16x32_bf16 v[90:93], v[142:145], v[214:217], v[90:93]
	v_mfma_f32_16x16x32_bf16 v[78:81], v[134:137], v[222:225], v[78:81]
	v_mfma_f32_16x16x32_bf16 v[74:77], v[142:145], v[222:225], v[74:77]
	s_setprio 0
	s_setprio 1
	v_mfma_f32_16x16x32_bf16 v[114:117], v[160:163], v[182:185], 0
	v_mfma_f32_16x16x32_bf16 v[106:109], v[174:177], v[182:185], 0
	v_mfma_f32_16x16x32_bf16 v[102:105], v[160:163], v[190:193], 0
	v_mfma_f32_16x16x32_bf16 v[98:101], v[174:177], v[190:193], 0
	v_mfma_f32_16x16x32_bf16 v[86:89], v[160:163], v[210:213], 0
	v_mfma_f32_16x16x32_bf16 v[82:85], v[174:177], v[210:213], 0
	v_mfma_f32_16x16x32_bf16 v[70:73], v[160:163], v[218:221], 0
	v_mfma_f32_16x16x32_bf16 v[66:69], v[174:177], v[218:221], 0
	v_mfma_f32_16x16x32_bf16 v[114:117], v[164:167], v[186:189], v[114:117]
	v_mfma_f32_16x16x32_bf16 v[106:109], v[178:181], v[186:189], v[106:109]
	v_mfma_f32_16x16x32_bf16 v[102:105], v[164:167], v[198:201], v[102:105]
	v_mfma_f32_16x16x32_bf16 v[98:101], v[178:181], v[198:201], v[98:101]
	v_mfma_f32_16x16x32_bf16 v[86:89], v[164:167], v[214:217], v[86:89]
	v_mfma_f32_16x16x32_bf16 v[82:85], v[178:181], v[214:217], v[82:85]
	v_mfma_f32_16x16x32_bf16 v[70:73], v[164:167], v[222:225], v[70:73]
	v_mfma_f32_16x16x32_bf16 v[66:69], v[178:181], v[222:225], v[66:69]
	s_setprio 0
	s_barrier
	s_add_i32 s21, s63, s33
	v_lshl_add_u64 v[202:203], s[36:37], 0, v[148:149]
	s_mov_b32 m0, s21
	ds_read_b128 v[182:185], v172 offset:16384
	ds_read_b128 v[186:189], v172 offset:17408
	ds_read_b128 v[190:193], v172 offset:18432
	ds_read_b128 v[198:201], v172 offset:19456
	ds_read_b128 v[210:213], v172 offset:20480
	ds_read_b128 v[214:217], v172 offset:21504
	ds_read_b128 v[218:221], v172 offset:22528
	ds_read_b128 v[222:225], v172 offset:23552
	global_load_lds_dwordx4 v148, s[36:37]
	s_add_i32 m0, s21, 0x2000
	s_add_u32 s40, s36, 0x80000
	v_lshl_add_u64 v[206:207], s[36:37], 0, v[152:153]
	s_addc_u32 s41, s37, 0
	s_add_i32 s21, s64, s33
	global_load_lds_dwordx4 v152, s[36:37]
	s_mov_b32 m0, s21
	v_lshl_add_u64 v[228:229], s[38:39], 0, v[150:151]
	global_load_lds_dwordx4 v148, s[40:41]
	s_add_i32 m0, s21, 0x2000
	s_nop 0
	global_load_lds_dwordx4 v152, s[40:41]
	v_lshl_add_u64 v[226:227], s[38:39], 0, v[146:147]
	s_mov_b32 m0, s27
	s_nop 0
	global_load_lds_dwordx4 v146, s[38:39]
	s_mov_b32 m0, s29
	s_nop 0
	global_load_lds_dwordx4 v150, s[38:39]
	s_waitcnt vmcnt(8)
	s_waitcnt lgkmcnt(0)
	s_barrier
	s_setprio 1
	s_waitcnt lgkmcnt(0)
	v_mfma_f32_16x16x32_bf16 v[62:65], v[130:133], v[182:185], 0
	v_mfma_f32_16x16x32_bf16 v[58:61], v[138:141], v[182:185], 0
	v_mfma_f32_16x16x32_bf16 v[46:49], v[130:133], v[190:193], 0
	v_mfma_f32_16x16x32_bf16 v[42:45], v[138:141], v[190:193], 0
	v_mfma_f32_16x16x32_bf16 v[30:33], v[130:133], v[210:213], 0
	v_mfma_f32_16x16x32_bf16 v[26:29], v[138:141], v[210:213], 0
	v_mfma_f32_16x16x32_bf16 v[14:17], v[130:133], v[218:221], 0
	v_mfma_f32_16x16x32_bf16 v[10:13], v[138:141], v[218:221], 0
	v_mfma_f32_16x16x32_bf16 v[62:65], v[134:137], v[186:189], v[62:65]
	v_mfma_f32_16x16x32_bf16 v[58:61], v[142:145], v[186:189], v[58:61]
	v_mfma_f32_16x16x32_bf16 v[46:49], v[134:137], v[198:201], v[46:49]
	v_mfma_f32_16x16x32_bf16 v[42:45], v[142:145], v[198:201], v[42:45]
	v_mfma_f32_16x16x32_bf16 v[30:33], v[134:137], v[214:217], v[30:33]
	v_mfma_f32_16x16x32_bf16 v[26:29], v[142:145], v[214:217], v[26:29]
	v_mfma_f32_16x16x32_bf16 v[14:17], v[134:137], v[222:225], v[14:17]
	v_mfma_f32_16x16x32_bf16 v[10:13], v[142:145], v[222:225], v[10:13]
	s_setprio 0
	s_setprio 1
	v_mfma_f32_16x16x32_bf16 v[54:57], v[160:163], v[182:185], 0
	v_mfma_f32_16x16x32_bf16 v[50:53], v[174:177], v[182:185], 0
	v_mfma_f32_16x16x32_bf16 v[38:41], v[160:163], v[190:193], 0
	v_mfma_f32_16x16x32_bf16 v[34:37], v[174:177], v[190:193], 0
	v_mfma_f32_16x16x32_bf16 v[22:25], v[160:163], v[210:213], 0
	v_mfma_f32_16x16x32_bf16 v[18:21], v[174:177], v[210:213], 0
	v_mfma_f32_16x16x32_bf16 v[6:9], v[160:163], v[218:221], 0
	v_mfma_f32_16x16x32_bf16 v[2:5], v[174:177], v[218:221], 0
	v_mfma_f32_16x16x32_bf16 v[54:57], v[164:167], v[186:189], v[54:57]
	v_mfma_f32_16x16x32_bf16 v[50:53], v[178:181], v[186:189], v[50:53]
	v_mfma_f32_16x16x32_bf16 v[38:41], v[164:167], v[198:201], v[38:41]
	v_mfma_f32_16x16x32_bf16 v[34:37], v[178:181], v[198:201], v[34:37]
	v_mfma_f32_16x16x32_bf16 v[22:25], v[164:167], v[214:217], v[22:25]
	v_mfma_f32_16x16x32_bf16 v[18:21], v[178:181], v[214:217], v[18:21]
	v_mfma_f32_16x16x32_bf16 v[6:9], v[164:167], v[222:225], v[6:9]
	v_mfma_f32_16x16x32_bf16 v[2:5], v[178:181], v[222:225], v[2:5]
	s_setprio 0
	s_barrier
	s_add_i32 s21, 0, 0x18000
	s_add_i32 s40, 0, 0x1c000
	v_add_u32_e32 v142, s21, v168
	v_add_u32_e32 v173, s40, v168
	ds_read_b128 v[130:133], v142
	ds_read_b128 v[134:137], v142 offset:1024
	ds_read_b128 v[138:141], v142 offset:2048
	ds_read_b128 v[142:145], v142 offset:3072
	ds_read_b128 v[160:163], v173
	ds_read_b128 v[164:167], v173 offset:1024
	ds_read_b128 v[174:177], v173 offset:2048
	ds_read_b128 v[178:181], v173 offset:3072
	s_add_u32 s38, s38, 0x80000
	s_addc_u32 s39, s39, 0
	s_mov_b32 m0, s42
	ds_read_b128 v[182:185], v172 offset:32768
	ds_read_b128 v[186:189], v172 offset:33792
	ds_read_b128 v[190:193], v172 offset:34816
	ds_read_b128 v[198:201], v172 offset:35840
	ds_read_b128 v[210:213], v172 offset:36864
	ds_read_b128 v[214:217], v172 offset:37888
	ds_read_b128 v[218:221], v172 offset:38912
	ds_read_b128 v[222:225], v172 offset:39936
	global_load_lds_dwordx4 v146, s[38:39]
	v_lshl_add_u64 v[230:231], s[38:39], 0, v[150:151]
	s_mov_b32 m0, s43
	s_nop 0
	global_load_lds_dwordx4 v150, s[38:39]
	s_waitcnt vmcnt(8)
	s_waitcnt lgkmcnt(0)
	s_barrier
	s_setprio 1
	s_waitcnt lgkmcnt(0)
	v_mfma_f32_16x16x32_bf16 v[126:129], v[130:133], v[182:185], v[126:129]
	v_mfma_f32_16x16x32_bf16 v[122:125], v[138:141], v[182:185], v[122:125]
	v_mfma_f32_16x16x32_bf16 v[118:121], v[130:133], v[190:193], v[118:121]
	v_mfma_f32_16x16x32_bf16 v[110:113], v[138:141], v[190:193], v[110:113]
	v_mfma_f32_16x16x32_bf16 v[94:97], v[130:133], v[210:213], v[94:97]
	v_mfma_f32_16x16x32_bf16 v[90:93], v[138:141], v[210:213], v[90:93]
	v_mfma_f32_16x16x32_bf16 v[78:81], v[130:133], v[218:221], v[78:81]
	v_mfma_f32_16x16x32_bf16 v[74:77], v[138:141], v[218:221], v[74:77]
	v_mfma_f32_16x16x32_bf16 v[126:129], v[134:137], v[186:189], v[126:129]
	v_mfma_f32_16x16x32_bf16 v[122:125], v[142:145], v[186:189], v[122:125]
	v_mfma_f32_16x16x32_bf16 v[118:121], v[134:137], v[198:201], v[118:121]
	v_mfma_f32_16x16x32_bf16 v[110:113], v[142:145], v[198:201], v[110:113]
	v_mfma_f32_16x16x32_bf16 v[94:97], v[134:137], v[214:217], v[94:97]
	v_mfma_f32_16x16x32_bf16 v[90:93], v[142:145], v[214:217], v[90:93]
	v_mfma_f32_16x16x32_bf16 v[78:81], v[134:137], v[222:225], v[78:81]
	v_mfma_f32_16x16x32_bf16 v[74:77], v[142:145], v[222:225], v[74:77]
	s_setprio 0
	s_setprio 1
	v_mfma_f32_16x16x32_bf16 v[114:117], v[160:163], v[182:185], v[114:117]
	v_mfma_f32_16x16x32_bf16 v[106:109], v[174:177], v[182:185], v[106:109]
	v_mfma_f32_16x16x32_bf16 v[102:105], v[160:163], v[190:193], v[102:105]
	v_mfma_f32_16x16x32_bf16 v[98:101], v[174:177], v[190:193], v[98:101]
	v_mfma_f32_16x16x32_bf16 v[86:89], v[160:163], v[210:213], v[86:89]
	v_mfma_f32_16x16x32_bf16 v[82:85], v[174:177], v[210:213], v[82:85]
	v_mfma_f32_16x16x32_bf16 v[70:73], v[160:163], v[218:221], v[70:73]
	v_mfma_f32_16x16x32_bf16 v[66:69], v[174:177], v[218:221], v[66:69]
	v_mfma_f32_16x16x32_bf16 v[114:117], v[164:167], v[186:189], v[114:117]
	v_mfma_f32_16x16x32_bf16 v[106:109], v[178:181], v[186:189], v[106:109]
	v_mfma_f32_16x16x32_bf16 v[102:105], v[164:167], v[198:201], v[102:105]
	v_mfma_f32_16x16x32_bf16 v[98:101], v[178:181], v[198:201], v[98:101]
	v_mfma_f32_16x16x32_bf16 v[86:89], v[164:167], v[214:217], v[86:89]
	v_mfma_f32_16x16x32_bf16 v[82:85], v[178:181], v[214:217], v[82:85]
	v_mfma_f32_16x16x32_bf16 v[70:73], v[164:167], v[222:225], v[70:73]
	v_mfma_f32_16x16x32_bf16 v[66:69], v[178:181], v[222:225], v[66:69]
	s_setprio 0
	s_barrier
	s_add_i32 s21, s21, s33
	v_lshl_add_u64 v[202:203], v[202:203], 0, s[12:13]
	s_mov_b32 m0, s21
	ds_read_b128 v[182:185], v172 offset:49152
	ds_read_b128 v[186:189], v172 offset:50176
	ds_read_b128 v[190:193], v172 offset:51200
	ds_read_b128 v[198:201], v172 offset:52224
	ds_read_b128 v[210:213], v172 offset:53248
	ds_read_b128 v[214:217], v172 offset:54272
	ds_read_b128 v[218:221], v172 offset:55296
	ds_read_b128 v[222:225], v172 offset:56320
	global_load_lds_dwordx4 v[202:203], off
	s_add_i32 m0, s21, 0x2000
	s_add_u32 s36, s36, 0x80080
	v_lshl_add_u64 v[202:203], v[206:207], 0, s[12:13]
	s_addc_u32 s37, s37, 0
	s_add_i32 s21, s40, s33
	global_load_lds_dwordx4 v[202:203], off
	s_mov_b32 m0, s21
	s_nop 0
	global_load_lds_dwordx4 v148, s[36:37]
	s_add_i32 m0, s21, 0x2000
	s_nop 0
	global_load_lds_dwordx4 v152, s[36:37]
	v_lshl_add_u64 v[202:203], v[226:227], 0, s[12:13]
	s_mov_b32 m0, s53
	s_nop 0
	global_load_lds_dwordx4 v[202:203], off
	v_lshl_add_u64 v[202:203], v[228:229], 0, s[12:13]
	s_mov_b32 m0, s54
	s_nop 0
	global_load_lds_dwordx4 v[202:203], off
	s_waitcnt vmcnt(8)
	s_waitcnt lgkmcnt(0)
	s_barrier
	s_setprio 1
	s_waitcnt lgkmcnt(0)
	v_mfma_f32_16x16x32_bf16 v[62:65], v[130:133], v[182:185], v[62:65]
	v_mfma_f32_16x16x32_bf16 v[58:61], v[138:141], v[182:185], v[58:61]
	v_mfma_f32_16x16x32_bf16 v[46:49], v[130:133], v[190:193], v[46:49]
	v_mfma_f32_16x16x32_bf16 v[42:45], v[138:141], v[190:193], v[42:45]
	v_mfma_f32_16x16x32_bf16 v[30:33], v[130:133], v[210:213], v[30:33]
	v_mfma_f32_16x16x32_bf16 v[26:29], v[138:141], v[210:213], v[26:29]
	v_mfma_f32_16x16x32_bf16 v[14:17], v[130:133], v[218:221], v[14:17]
	v_mfma_f32_16x16x32_bf16 v[10:13], v[138:141], v[218:221], v[10:13]
	v_mfma_f32_16x16x32_bf16 v[62:65], v[134:137], v[186:189], v[62:65]
	v_mfma_f32_16x16x32_bf16 v[58:61], v[142:145], v[186:189], v[58:61]
	v_mfma_f32_16x16x32_bf16 v[46:49], v[134:137], v[198:201], v[46:49]
	v_mfma_f32_16x16x32_bf16 v[42:45], v[142:145], v[198:201], v[42:45]
	v_mfma_f32_16x16x32_bf16 v[30:33], v[134:137], v[214:217], v[30:33]
	v_mfma_f32_16x16x32_bf16 v[26:29], v[142:145], v[214:217], v[26:29]
	v_mfma_f32_16x16x32_bf16 v[14:17], v[134:137], v[222:225], v[14:17]
	v_mfma_f32_16x16x32_bf16 v[10:13], v[142:145], v[222:225], v[10:13]
	s_setprio 0
	s_setprio 1
	v_mfma_f32_16x16x32_bf16 v[54:57], v[160:163], v[182:185], v[54:57]
	v_mfma_f32_16x16x32_bf16 v[50:53], v[174:177], v[182:185], v[50:53]
	v_mfma_f32_16x16x32_bf16 v[38:41], v[160:163], v[190:193], v[38:41]
	v_mfma_f32_16x16x32_bf16 v[34:37], v[174:177], v[190:193], v[34:37]
	v_mfma_f32_16x16x32_bf16 v[22:25], v[160:163], v[210:213], v[22:25]
	v_mfma_f32_16x16x32_bf16 v[18:21], v[174:177], v[210:213], v[18:21]
	v_mfma_f32_16x16x32_bf16 v[6:9], v[160:163], v[218:221], v[6:9]
	v_mfma_f32_16x16x32_bf16 v[2:5], v[174:177], v[218:221], v[2:5]
	v_mfma_f32_16x16x32_bf16 v[54:57], v[164:167], v[186:189], v[54:57]
	v_mfma_f32_16x16x32_bf16 v[50:53], v[178:181], v[186:189], v[50:53]
	v_mfma_f32_16x16x32_bf16 v[38:41], v[164:167], v[198:201], v[38:41]
	v_mfma_f32_16x16x32_bf16 v[34:37], v[178:181], v[198:201], v[34:37]
	v_mfma_f32_16x16x32_bf16 v[22:25], v[164:167], v[214:217], v[22:25]
	v_mfma_f32_16x16x32_bf16 v[18:21], v[178:181], v[214:217], v[18:21]
	v_mfma_f32_16x16x32_bf16 v[6:9], v[164:167], v[222:225], v[6:9]
	v_mfma_f32_16x16x32_bf16 v[2:5], v[178:181], v[222:225], v[2:5]
	s_setprio 0
	s_barrier
	s_add_u32 s34, s34, 0x100
	s_addc_u32 s35, s35, 0
	s_add_u32 s17, s17, 0x100
	s_addc_u32 s19, s19, 0
	s_cmp_ge_i32 s31, s69
	s_mov_b32 s21, s31
	s_cbranch_scc0 .LBB0_1122
	s_branch .Lpeeldone_8
.LBB0_1122:
	ds_read_b128 v[130:133], v170
	ds_read_b128 v[134:137], v170 offset:1024
	ds_read_b128 v[138:141], v170 offset:2048
	ds_read_b128 v[142:145], v170 offset:3072
	ds_read_b128 v[160:163], v171
	ds_read_b128 v[164:167], v171 offset:1024
	ds_read_b128 v[174:177], v171 offset:2048
	ds_read_b128 v[178:181], v171 offset:3072
	s_add_i32 s31, s21, 2
	s_add_u32 s36, s34, 0xfff80080
	s_addc_u32 s37, s35, -1
	s_cmp_eq_u32 s30, s21
	s_cselect_b32 s39, s23, s37
	s_cselect_b32 s38, s22, s36
	s_cselect_b32 s37, s25, s19
	s_cselect_b32 s36, s24, s17
	s_add_i32 m0, s27, 0xc000
	ds_read_b128 v[182:185], v172
	ds_read_b128 v[186:189], v172 offset:1024
	ds_read_b128 v[190:193], v172 offset:2048
	ds_read_b128 v[198:201], v172 offset:3072
	ds_read_b128 v[210:213], v172 offset:4096
	ds_read_b128 v[214:217], v172 offset:5120
	ds_read_b128 v[218:221], v172 offset:6144
	ds_read_b128 v[222:225], v172 offset:7168
	global_load_lds_dwordx4 v156, s[34:35]
	s_add_i32 m0, s27, 0xe000
	s_nop 0
	global_load_lds_dwordx4 v158, s[34:35]
	s_waitcnt vmcnt(8)
	s_waitcnt lgkmcnt(0)
	s_barrier
	s_setprio 1
	s_waitcnt lgkmcnt(0)
	v_mfma_f32_16x16x32_bf16 v[126:129], v[130:133], v[182:185], v[126:129]
	v_mfma_f32_16x16x32_bf16 v[122:125], v[138:141], v[182:185], v[122:125]
	v_mfma_f32_16x16x32_bf16 v[118:121], v[130:133], v[190:193], v[118:121]
	v_mfma_f32_16x16x32_bf16 v[110:113], v[138:141], v[190:193], v[110:113]
	v_mfma_f32_16x16x32_bf16 v[94:97], v[130:133], v[210:213], v[94:97]
	v_mfma_f32_16x16x32_bf16 v[90:93], v[138:141], v[210:213], v[90:93]
	v_mfma_f32_16x16x32_bf16 v[78:81], v[130:133], v[218:221], v[78:81]
	v_mfma_f32_16x16x32_bf16 v[74:77], v[138:141], v[218:221], v[74:77]
	v_mfma_f32_16x16x32_bf16 v[126:129], v[134:137], v[186:189], v[126:129]
	v_mfma_f32_16x16x32_bf16 v[122:125], v[142:145], v[186:189], v[122:125]
	v_mfma_f32_16x16x32_bf16 v[118:121], v[134:137], v[198:201], v[118:121]
	v_mfma_f32_16x16x32_bf16 v[110:113], v[142:145], v[198:201], v[110:113]
	v_mfma_f32_16x16x32_bf16 v[94:97], v[134:137], v[214:217], v[94:97]
	v_mfma_f32_16x16x32_bf16 v[90:93], v[142:145], v[214:217], v[90:93]
	v_mfma_f32_16x16x32_bf16 v[78:81], v[134:137], v[222:225], v[78:81]
	v_mfma_f32_16x16x32_bf16 v[74:77], v[142:145], v[222:225], v[74:77]
	s_setprio 0
	s_setprio 1
	v_mfma_f32_16x16x32_bf16 v[114:117], v[160:163], v[182:185], v[114:117]
	v_mfma_f32_16x16x32_bf16 v[106:109], v[174:177], v[182:185], v[106:109]
	v_mfma_f32_16x16x32_bf16 v[102:105], v[160:163], v[190:193], v[102:105]
	v_mfma_f32_16x16x32_bf16 v[98:101], v[174:177], v[190:193], v[98:101]
	v_mfma_f32_16x16x32_bf16 v[86:89], v[160:163], v[210:213], v[86:89]
	v_mfma_f32_16x16x32_bf16 v[82:85], v[174:177], v[210:213], v[82:85]
	v_mfma_f32_16x16x32_bf16 v[70:73], v[160:163], v[218:221], v[70:73]
	v_mfma_f32_16x16x32_bf16 v[66:69], v[174:177], v[218:221], v[66:69]
	v_mfma_f32_16x16x32_bf16 v[114:117], v[164:167], v[186:189], v[114:117]
	v_mfma_f32_16x16x32_bf16 v[106:109], v[178:181], v[186:189], v[106:109]
	v_mfma_f32_16x16x32_bf16 v[102:105], v[164:167], v[198:201], v[102:105]
	v_mfma_f32_16x16x32_bf16 v[98:101], v[178:181], v[198:201], v[98:101]
	v_mfma_f32_16x16x32_bf16 v[86:89], v[164:167], v[214:217], v[86:89]
	v_mfma_f32_16x16x32_bf16 v[82:85], v[178:181], v[214:217], v[82:85]
	v_mfma_f32_16x16x32_bf16 v[70:73], v[164:167], v[222:225], v[70:73]
	v_mfma_f32_16x16x32_bf16 v[66:69], v[178:181], v[222:225], v[66:69]
	s_setprio 0
	s_barrier
	s_add_i32 s21, s63, s33
	v_lshl_add_u64 v[202:203], s[36:37], 0, v[148:149]
	s_mov_b32 m0, s21
	ds_read_b128 v[182:185], v172 offset:16384
	ds_read_b128 v[186:189], v172 offset:17408
	ds_read_b128 v[190:193], v172 offset:18432
	ds_read_b128 v[198:201], v172 offset:19456
	ds_read_b128 v[210:213], v172 offset:20480
	ds_read_b128 v[214:217], v172 offset:21504
	ds_read_b128 v[218:221], v172 offset:22528
	ds_read_b128 v[222:225], v172 offset:23552
	global_load_lds_dwordx4 v148, s[36:37]
	s_add_i32 m0, s21, 0x2000
	s_add_u32 s40, s36, 0x80000
	v_lshl_add_u64 v[206:207], s[36:37], 0, v[152:153]
	s_addc_u32 s41, s37, 0
	s_add_i32 s21, s64, s33
	global_load_lds_dwordx4 v152, s[36:37]
	s_mov_b32 m0, s21
	v_lshl_add_u64 v[228:229], s[38:39], 0, v[150:151]
	global_load_lds_dwordx4 v148, s[40:41]
	s_add_i32 m0, s21, 0x2000
	s_nop 0
	global_load_lds_dwordx4 v152, s[40:41]
	v_lshl_add_u64 v[226:227], s[38:39], 0, v[146:147]
	s_mov_b32 m0, s27
	s_nop 0
	global_load_lds_dwordx4 v146, s[38:39]
	s_mov_b32 m0, s29
	s_nop 0
	global_load_lds_dwordx4 v150, s[38:39]
	s_waitcnt vmcnt(8)
	s_waitcnt lgkmcnt(0)
	s_barrier
	s_setprio 1
	s_waitcnt lgkmcnt(0)
	v_mfma_f32_16x16x32_bf16 v[62:65], v[130:133], v[182:185], v[62:65]
	v_mfma_f32_16x16x32_bf16 v[58:61], v[138:141], v[182:185], v[58:61]
	v_mfma_f32_16x16x32_bf16 v[46:49], v[130:133], v[190:193], v[46:49]
	v_mfma_f32_16x16x32_bf16 v[42:45], v[138:141], v[190:193], v[42:45]
	v_mfma_f32_16x16x32_bf16 v[30:33], v[130:133], v[210:213], v[30:33]
	v_mfma_f32_16x16x32_bf16 v[26:29], v[138:141], v[210:213], v[26:29]
	v_mfma_f32_16x16x32_bf16 v[14:17], v[130:133], v[218:221], v[14:17]
	v_mfma_f32_16x16x32_bf16 v[10:13], v[138:141], v[218:221], v[10:13]
	v_mfma_f32_16x16x32_bf16 v[62:65], v[134:137], v[186:189], v[62:65]
	v_mfma_f32_16x16x32_bf16 v[58:61], v[142:145], v[186:189], v[58:61]
	v_mfma_f32_16x16x32_bf16 v[46:49], v[134:137], v[198:201], v[46:49]
	v_mfma_f32_16x16x32_bf16 v[42:45], v[142:145], v[198:201], v[42:45]
	v_mfma_f32_16x16x32_bf16 v[30:33], v[134:137], v[214:217], v[30:33]
	v_mfma_f32_16x16x32_bf16 v[26:29], v[142:145], v[214:217], v[26:29]
	v_mfma_f32_16x16x32_bf16 v[14:17], v[134:137], v[222:225], v[14:17]
	v_mfma_f32_16x16x32_bf16 v[10:13], v[142:145], v[222:225], v[10:13]
	s_setprio 0
	s_setprio 1
	v_mfma_f32_16x16x32_bf16 v[54:57], v[160:163], v[182:185], v[54:57]
	v_mfma_f32_16x16x32_bf16 v[50:53], v[174:177], v[182:185], v[50:53]
	v_mfma_f32_16x16x32_bf16 v[38:41], v[160:163], v[190:193], v[38:41]
	v_mfma_f32_16x16x32_bf16 v[34:37], v[174:177], v[190:193], v[34:37]
	v_mfma_f32_16x16x32_bf16 v[22:25], v[160:163], v[210:213], v[22:25]
	v_mfma_f32_16x16x32_bf16 v[18:21], v[174:177], v[210:213], v[18:21]
	v_mfma_f32_16x16x32_bf16 v[6:9], v[160:163], v[218:221], v[6:9]
	v_mfma_f32_16x16x32_bf16 v[2:5], v[174:177], v[218:221], v[2:5]
	v_mfma_f32_16x16x32_bf16 v[54:57], v[164:167], v[186:189], v[54:57]
	v_mfma_f32_16x16x32_bf16 v[50:53], v[178:181], v[186:189], v[50:53]
	v_mfma_f32_16x16x32_bf16 v[38:41], v[164:167], v[198:201], v[38:41]
	v_mfma_f32_16x16x32_bf16 v[34:37], v[178:181], v[198:201], v[34:37]
	v_mfma_f32_16x16x32_bf16 v[22:25], v[164:167], v[214:217], v[22:25]
	v_mfma_f32_16x16x32_bf16 v[18:21], v[178:181], v[214:217], v[18:21]
	v_mfma_f32_16x16x32_bf16 v[6:9], v[164:167], v[222:225], v[6:9]
	v_mfma_f32_16x16x32_bf16 v[2:5], v[178:181], v[222:225], v[2:5]
	s_setprio 0
	s_barrier
	s_add_i32 s21, 0, 0x18000
	s_add_i32 s40, 0, 0x1c000
	v_add_u32_e32 v142, s21, v168
	v_add_u32_e32 v173, s40, v168
	ds_read_b128 v[130:133], v142
	ds_read_b128 v[134:137], v142 offset:1024
	ds_read_b128 v[138:141], v142 offset:2048
	ds_read_b128 v[142:145], v142 offset:3072
	ds_read_b128 v[160:163], v173
	ds_read_b128 v[164:167], v173 offset:1024
	ds_read_b128 v[174:177], v173 offset:2048
	ds_read_b128 v[178:181], v173 offset:3072
	s_add_u32 s38, s38, 0x80000
	s_addc_u32 s39, s39, 0
	s_mov_b32 m0, s42
	ds_read_b128 v[182:185], v172 offset:32768
	ds_read_b128 v[186:189], v172 offset:33792
	ds_read_b128 v[190:193], v172 offset:34816
	ds_read_b128 v[198:201], v172 offset:35840
	ds_read_b128 v[210:213], v172 offset:36864
	ds_read_b128 v[214:217], v172 offset:37888
	ds_read_b128 v[218:221], v172 offset:38912
	ds_read_b128 v[222:225], v172 offset:39936
	global_load_lds_dwordx4 v146, s[38:39]
	v_lshl_add_u64 v[230:231], s[38:39], 0, v[150:151]
	s_mov_b32 m0, s43
	s_nop 0
	global_load_lds_dwordx4 v150, s[38:39]
	s_waitcnt vmcnt(8)
	s_waitcnt lgkmcnt(0)
	s_barrier
	s_setprio 1
	s_waitcnt lgkmcnt(0)
	v_mfma_f32_16x16x32_bf16 v[126:129], v[130:133], v[182:185], v[126:129]
	v_mfma_f32_16x16x32_bf16 v[122:125], v[138:141], v[182:185], v[122:125]
	v_mfma_f32_16x16x32_bf16 v[118:121], v[130:133], v[190:193], v[118:121]
	v_mfma_f32_16x16x32_bf16 v[110:113], v[138:141], v[190:193], v[110:113]
	v_mfma_f32_16x16x32_bf16 v[94:97], v[130:133], v[210:213], v[94:97]
	v_mfma_f32_16x16x32_bf16 v[90:93], v[138:141], v[210:213], v[90:93]
	v_mfma_f32_16x16x32_bf16 v[78:81], v[130:133], v[218:221], v[78:81]
	v_mfma_f32_16x16x32_bf16 v[74:77], v[138:141], v[218:221], v[74:77]
	v_mfma_f32_16x16x32_bf16 v[126:129], v[134:137], v[186:189], v[126:129]
	v_mfma_f32_16x16x32_bf16 v[122:125], v[142:145], v[186:189], v[122:125]
	v_mfma_f32_16x16x32_bf16 v[118:121], v[134:137], v[198:201], v[118:121]
	v_mfma_f32_16x16x32_bf16 v[110:113], v[142:145], v[198:201], v[110:113]
	v_mfma_f32_16x16x32_bf16 v[94:97], v[134:137], v[214:217], v[94:97]
	v_mfma_f32_16x16x32_bf16 v[90:93], v[142:145], v[214:217], v[90:93]
	v_mfma_f32_16x16x32_bf16 v[78:81], v[134:137], v[222:225], v[78:81]
	v_mfma_f32_16x16x32_bf16 v[74:77], v[142:145], v[222:225], v[74:77]
	s_setprio 0
	s_setprio 1
	v_mfma_f32_16x16x32_bf16 v[114:117], v[160:163], v[182:185], v[114:117]
	v_mfma_f32_16x16x32_bf16 v[106:109], v[174:177], v[182:185], v[106:109]
	v_mfma_f32_16x16x32_bf16 v[102:105], v[160:163], v[190:193], v[102:105]
	v_mfma_f32_16x16x32_bf16 v[98:101], v[174:177], v[190:193], v[98:101]
	v_mfma_f32_16x16x32_bf16 v[86:89], v[160:163], v[210:213], v[86:89]
	v_mfma_f32_16x16x32_bf16 v[82:85], v[174:177], v[210:213], v[82:85]
	v_mfma_f32_16x16x32_bf16 v[70:73], v[160:163], v[218:221], v[70:73]
	v_mfma_f32_16x16x32_bf16 v[66:69], v[174:177], v[218:221], v[66:69]
	v_mfma_f32_16x16x32_bf16 v[114:117], v[164:167], v[186:189], v[114:117]
	v_mfma_f32_16x16x32_bf16 v[106:109], v[178:181], v[186:189], v[106:109]
	v_mfma_f32_16x16x32_bf16 v[102:105], v[164:167], v[198:201], v[102:105]
	v_mfma_f32_16x16x32_bf16 v[98:101], v[178:181], v[198:201], v[98:101]
	v_mfma_f32_16x16x32_bf16 v[86:89], v[164:167], v[214:217], v[86:89]
	v_mfma_f32_16x16x32_bf16 v[82:85], v[178:181], v[214:217], v[82:85]
	v_mfma_f32_16x16x32_bf16 v[70:73], v[164:167], v[222:225], v[70:73]
	v_mfma_f32_16x16x32_bf16 v[66:69], v[178:181], v[222:225], v[66:69]
	s_setprio 0
	s_barrier
	s_add_i32 s21, s21, s33
	v_lshl_add_u64 v[202:203], v[202:203], 0, s[12:13]
	s_mov_b32 m0, s21
	ds_read_b128 v[182:185], v172 offset:49152
	ds_read_b128 v[186:189], v172 offset:50176
	ds_read_b128 v[190:193], v172 offset:51200
	ds_read_b128 v[198:201], v172 offset:52224
	ds_read_b128 v[210:213], v172 offset:53248
	ds_read_b128 v[214:217], v172 offset:54272
	ds_read_b128 v[218:221], v172 offset:55296
	ds_read_b128 v[222:225], v172 offset:56320
	global_load_lds_dwordx4 v[202:203], off
	s_add_i32 m0, s21, 0x2000
	s_add_u32 s36, s36, 0x80080
	v_lshl_add_u64 v[202:203], v[206:207], 0, s[12:13]
	s_addc_u32 s37, s37, 0
	s_add_i32 s21, s40, s33
	global_load_lds_dwordx4 v[202:203], off
	s_mov_b32 m0, s21
	s_nop 0
	global_load_lds_dwordx4 v148, s[36:37]
	s_add_i32 m0, s21, 0x2000
	s_nop 0
	global_load_lds_dwordx4 v152, s[36:37]
	v_lshl_add_u64 v[202:203], v[226:227], 0, s[12:13]
	s_mov_b32 m0, s53
	s_nop 0
	global_load_lds_dwordx4 v[202:203], off
	v_lshl_add_u64 v[202:203], v[228:229], 0, s[12:13]
	s_mov_b32 m0, s54
	s_nop 0
	global_load_lds_dwordx4 v[202:203], off
	s_waitcnt vmcnt(8)
	s_waitcnt lgkmcnt(0)
	s_barrier
	s_setprio 1
	s_waitcnt lgkmcnt(0)
	v_mfma_f32_16x16x32_bf16 v[62:65], v[130:133], v[182:185], v[62:65]
	v_mfma_f32_16x16x32_bf16 v[58:61], v[138:141], v[182:185], v[58:61]
	v_mfma_f32_16x16x32_bf16 v[46:49], v[130:133], v[190:193], v[46:49]
	v_mfma_f32_16x16x32_bf16 v[42:45], v[138:141], v[190:193], v[42:45]
	v_mfma_f32_16x16x32_bf16 v[30:33], v[130:133], v[210:213], v[30:33]
	v_mfma_f32_16x16x32_bf16 v[26:29], v[138:141], v[210:213], v[26:29]
	v_mfma_f32_16x16x32_bf16 v[14:17], v[130:133], v[218:221], v[14:17]
	v_mfma_f32_16x16x32_bf16 v[10:13], v[138:141], v[218:221], v[10:13]
	v_mfma_f32_16x16x32_bf16 v[62:65], v[134:137], v[186:189], v[62:65]
	v_mfma_f32_16x16x32_bf16 v[58:61], v[142:145], v[186:189], v[58:61]
	v_mfma_f32_16x16x32_bf16 v[46:49], v[134:137], v[198:201], v[46:49]
	v_mfma_f32_16x16x32_bf16 v[42:45], v[142:145], v[198:201], v[42:45]
	v_mfma_f32_16x16x32_bf16 v[30:33], v[134:137], v[214:217], v[30:33]
	v_mfma_f32_16x16x32_bf16 v[26:29], v[142:145], v[214:217], v[26:29]
	v_mfma_f32_16x16x32_bf16 v[14:17], v[134:137], v[222:225], v[14:17]
	v_mfma_f32_16x16x32_bf16 v[10:13], v[142:145], v[222:225], v[10:13]
	s_setprio 0
	s_setprio 1
	v_mfma_f32_16x16x32_bf16 v[54:57], v[160:163], v[182:185], v[54:57]
	v_mfma_f32_16x16x32_bf16 v[50:53], v[174:177], v[182:185], v[50:53]
	v_mfma_f32_16x16x32_bf16 v[38:41], v[160:163], v[190:193], v[38:41]
	v_mfma_f32_16x16x32_bf16 v[34:37], v[174:177], v[190:193], v[34:37]
	v_mfma_f32_16x16x32_bf16 v[22:25], v[160:163], v[210:213], v[22:25]
	v_mfma_f32_16x16x32_bf16 v[18:21], v[174:177], v[210:213], v[18:21]
	v_mfma_f32_16x16x32_bf16 v[6:9], v[160:163], v[218:221], v[6:9]
	v_mfma_f32_16x16x32_bf16 v[2:5], v[174:177], v[218:221], v[2:5]
	v_mfma_f32_16x16x32_bf16 v[54:57], v[164:167], v[186:189], v[54:57]
	v_mfma_f32_16x16x32_bf16 v[50:53], v[178:181], v[186:189], v[50:53]
	v_mfma_f32_16x16x32_bf16 v[38:41], v[164:167], v[198:201], v[38:41]
	v_mfma_f32_16x16x32_bf16 v[34:37], v[178:181], v[198:201], v[34:37]
	v_mfma_f32_16x16x32_bf16 v[22:25], v[164:167], v[214:217], v[22:25]
	v_mfma_f32_16x16x32_bf16 v[18:21], v[178:181], v[214:217], v[18:21]
	v_mfma_f32_16x16x32_bf16 v[6:9], v[164:167], v[222:225], v[6:9]
	v_mfma_f32_16x16x32_bf16 v[2:5], v[178:181], v[222:225], v[2:5]
	s_setprio 0
	s_barrier
	s_add_u32 s34, s34, 0x100
	s_addc_u32 s35, s35, 0
	s_add_u32 s17, s17, 0x100
	s_addc_u32 s19, s19, 0
	s_cmp_ge_i32 s31, s69
	s_mov_b32 s21, s31
	s_cbranch_scc0 .LBB0_1122

.Lpeel_7:
	ds_read_b128 v[152:155], v148
	ds_read_b128 v[156:159], v148 offset:1024
	s_add_i32 s29, s19, 2
	s_add_u32 s34, s30, 0xfff80080
	s_addc_u32 s35, s31, -1
	s_cmp_eq_u32 s28, s19
	s_cselect_b32 s37, s21, s35
	s_cselect_b32 s36, s20, s34
	s_cselect_b32 s35, s23, s17
	s_cselect_b32 s34, s22, s15
	s_add_i32 m0, s27, 0xc000
	global_load_lds_dwordx4 v140, s[30:31]
	s_add_i32 m0, s27, 0xe000
	s_nop 0
	global_load_lds_dwordx4 v142, s[30:31]
	s_waitcnt vmcnt(8)
	s_waitcnt lgkmcnt(0)
	s_barrier
	s_setprio 1
	s_waitcnt lgkmcnt(0)
	v_mfma_f32_16x16x32_bf16 v[126:129], v[152:155], v[184:187], 0
	v_mfma_f32_16x16x32_bf16 v[122:125], v[160:163], v[184:187], 0
	v_mfma_f32_16x16x32_bf16 v[110:113], v[152:155], v[198:201], 0
	v_mfma_f32_16x16x32_bf16 v[106:109], v[160:163], v[198:201], 0
	v_mfma_f32_16x16x32_bf16 v[94:97], v[152:155], v[214:217], 0
	v_mfma_f32_16x16x32_bf16 v[90:93], v[160:163], v[214:217], 0
	v_mfma_f32_16x16x32_bf16 v[78:81], v[152:155], v[222:225], 0
	v_mfma_f32_16x16x32_bf16 v[74:77], v[160:163], v[222:225], 0
	v_mfma_f32_16x16x32_bf16 v[126:129], v[156:159], v[188:191], v[126:129]
	v_mfma_f32_16x16x32_bf16 v[122:125], v[164:167], v[188:191], v[122:125]
	v_mfma_f32_16x16x32_bf16 v[110:113], v[156:159], v[210:213], v[110:113]
	v_mfma_f32_16x16x32_bf16 v[106:109], v[164:167], v[210:213], v[106:109]
	v_mfma_f32_16x16x32_bf16 v[94:97], v[156:159], v[218:221], v[94:97]
	v_mfma_f32_16x16x32_bf16 v[90:93], v[164:167], v[218:221], v[90:93]
	v_mfma_f32_16x16x32_bf16 v[78:81], v[156:159], v[226:229], v[78:81]
	v_mfma_f32_16x16x32_bf16 v[74:77], v[164:167], v[226:229], v[74:77]
	s_setprio 0
	s_setprio 1
	v_mfma_f32_16x16x32_bf16 v[118:121], v[168:171], v[184:187], 0
	v_mfma_f32_16x16x32_bf16 v[114:117], v[176:179], v[184:187], 0
	v_mfma_f32_16x16x32_bf16 v[102:105], v[168:171], v[198:201], 0
	v_mfma_f32_16x16x32_bf16 v[98:101], v[176:179], v[198:201], 0
	v_mfma_f32_16x16x32_bf16 v[86:89], v[168:171], v[214:217], 0
	v_mfma_f32_16x16x32_bf16 v[82:85], v[176:179], v[214:217], 0
	v_mfma_f32_16x16x32_bf16 v[70:73], v[168:171], v[222:225], 0
	v_mfma_f32_16x16x32_bf16 v[66:69], v[176:179], v[222:225], 0
	v_mfma_f32_16x16x32_bf16 v[118:121], v[172:175], v[188:191], v[118:121]
	v_mfma_f32_16x16x32_bf16 v[114:117], v[180:183], v[188:191], v[114:117]
	v_mfma_f32_16x16x32_bf16 v[102:105], v[172:175], v[210:213], v[102:105]
	v_mfma_f32_16x16x32_bf16 v[98:101], v[180:183], v[210:213], v[98:101]
	v_mfma_f32_16x16x32_bf16 v[86:89], v[172:175], v[218:221], v[86:89]
	v_mfma_f32_16x16x32_bf16 v[82:85], v[180:183], v[218:221], v[82:85]
	v_mfma_f32_16x16x32_bf16 v[70:73], v[172:175], v[226:229], v[70:73]
	v_mfma_f32_16x16x32_bf16 v[66:69], v[180:183], v[226:229], v[66:69]
	s_setprio 0
	s_barrier
	s_add_i32 s19, s60, s33
	v_lshl_add_u64 v[144:145], s[34:35], 0, v[132:133]
	s_mov_b32 m0, s19
	ds_read_b128 v[184:187], v150 offset:16384
	ds_read_b128 v[188:191], v150 offset:17408
	ds_read_b128 v[198:201], v150 offset:18432
	ds_read_b128 v[210:213], v150 offset:19456
	ds_read_b128 v[214:217], v150 offset:20480
	ds_read_b128 v[218:221], v150 offset:21504
	ds_read_b128 v[222:225], v150 offset:22528
	ds_read_b128 v[226:229], v150 offset:23552
	global_load_lds_dwordx4 v132, s[34:35]
	s_add_i32 m0, s19, 0x2000
	s_add_u32 s38, s34, 0x80000
	v_lshl_add_u64 v[192:193], s[34:35], 0, v[136:137]
	s_addc_u32 s39, s35, 0
	s_add_i32 s19, s61, s33
	global_load_lds_dwordx4 v136, s[34:35]
	s_mov_b32 m0, s19
	v_lshl_add_u64 v[206:207], s[36:37], 0, v[134:135]
	global_load_lds_dwordx4 v132, s[38:39]
	s_add_i32 m0, s19, 0x2000
	s_nop 0
	global_load_lds_dwordx4 v136, s[38:39]
	v_lshl_add_u64 v[202:203], s[36:37], 0, v[130:131]
	s_mov_b32 m0, s27
	s_nop 0
	global_load_lds_dwordx4 v130, s[36:37]
	s_mov_b32 m0, s41
	s_nop 0
	global_load_lds_dwordx4 v134, s[36:37]
	s_waitcnt vmcnt(8)
	s_waitcnt lgkmcnt(0)
	s_barrier
	s_setprio 1
	s_waitcnt lgkmcnt(0)
	v_mfma_f32_16x16x32_bf16 v[62:65], v[152:155], v[184:187], 0
	v_mfma_f32_16x16x32_bf16 v[58:61], v[160:163], v[184:187], 0
	v_mfma_f32_16x16x32_bf16 v[46:49], v[152:155], v[198:201], 0
	v_mfma_f32_16x16x32_bf16 v[42:45], v[160:163], v[198:201], 0
	v_mfma_f32_16x16x32_bf16 v[30:33], v[152:155], v[214:217], 0
	v_mfma_f32_16x16x32_bf16 v[26:29], v[160:163], v[214:217], 0
	v_mfma_f32_16x16x32_bf16 v[14:17], v[152:155], v[222:225], 0
	v_mfma_f32_16x16x32_bf16 v[10:13], v[160:163], v[222:225], 0
	v_mfma_f32_16x16x32_bf16 v[62:65], v[156:159], v[188:191], v[62:65]
	v_mfma_f32_16x16x32_bf16 v[58:61], v[164:167], v[188:191], v[58:61]
	v_mfma_f32_16x16x32_bf16 v[46:49], v[156:159], v[210:213], v[46:49]
	v_mfma_f32_16x16x32_bf16 v[42:45], v[164:167], v[210:213], v[42:45]
	v_mfma_f32_16x16x32_bf16 v[30:33], v[156:159], v[218:221], v[30:33]
	v_mfma_f32_16x16x32_bf16 v[26:29], v[164:167], v[218:221], v[26:29]
	v_mfma_f32_16x16x32_bf16 v[14:17], v[156:159], v[226:229], v[14:17]
	v_mfma_f32_16x16x32_bf16 v[10:13], v[164:167], v[226:229], v[10:13]
	s_setprio 0
	s_setprio 1
	v_mfma_f32_16x16x32_bf16 v[54:57], v[168:171], v[184:187], 0
	v_mfma_f32_16x16x32_bf16 v[50:53], v[176:179], v[184:187], 0
	v_mfma_f32_16x16x32_bf16 v[38:41], v[168:171], v[198:201], 0
	v_mfma_f32_16x16x32_bf16 v[34:37], v[176:179], v[198:201], 0
	v_mfma_f32_16x16x32_bf16 v[22:25], v[168:171], v[214:217], 0
	v_mfma_f32_16x16x32_bf16 v[18:21], v[176:179], v[214:217], 0
	v_mfma_f32_16x16x32_bf16 v[6:9], v[168:171], v[222:225], 0
	v_mfma_f32_16x16x32_bf16 v[2:5], v[176:179], v[222:225], 0
	v_mfma_f32_16x16x32_bf16 v[54:57], v[172:175], v[188:191], v[54:57]
	v_mfma_f32_16x16x32_bf16 v[50:53], v[180:183], v[188:191], v[50:53]
	v_mfma_f32_16x16x32_bf16 v[38:41], v[172:175], v[210:213], v[38:41]
	v_mfma_f32_16x16x32_bf16 v[34:37], v[180:183], v[210:213], v[34:37]
	v_mfma_f32_16x16x32_bf16 v[22:25], v[172:175], v[218:221], v[22:25]
	v_mfma_f32_16x16x32_bf16 v[18:21], v[180:183], v[218:221], v[18:21]
	v_mfma_f32_16x16x32_bf16 v[6:9], v[172:175], v[226:229], v[6:9]
	v_mfma_f32_16x16x32_bf16 v[2:5], v[180:183], v[226:229], v[2:5]
	s_setprio 0
	s_barrier
	s_add_i32 s19, 0, 0x18000
	v_add_u32_e32 v151, s19, v146
	s_add_i32 s38, 0, 0x1c000
	ds_read_b128 v[152:155], v151
	ds_read_b128 v[156:159], v151 offset:1024
	ds_read_b128 v[160:163], v151 offset:2048
	ds_read_b128 v[164:167], v151 offset:3072
	v_add_u32_e32 v151, s38, v146
	ds_read_b128 v[168:171], v151
	ds_read_b128 v[172:175], v151 offset:1024
	ds_read_b128 v[176:179], v151 offset:2048
	ds_read_b128 v[180:183], v151 offset:3072
	s_add_u32 s36, s36, 0x80000
	s_addc_u32 s37, s37, 0
	s_mov_b32 m0, s42
	ds_read_b128 v[184:187], v150 offset:32768
	ds_read_b128 v[188:191], v150 offset:33792
	ds_read_b128 v[198:201], v150 offset:34816
	ds_read_b128 v[210:213], v150 offset:35840
	ds_read_b128 v[214:217], v150 offset:36864
	ds_read_b128 v[218:221], v150 offset:37888
	ds_read_b128 v[222:225], v150 offset:38912
	ds_read_b128 v[226:229], v150 offset:39936
	global_load_lds_dwordx4 v130, s[36:37]
	v_lshl_add_u64 v[230:231], s[36:37], 0, v[134:135]
	s_mov_b32 m0, s43
	s_nop 0
	global_load_lds_dwordx4 v134, s[36:37]
	s_waitcnt vmcnt(8)
	s_waitcnt lgkmcnt(0)
	s_barrier
	s_setprio 1
	s_waitcnt lgkmcnt(0)
	v_mfma_f32_16x16x32_bf16 v[126:129], v[152:155], v[184:187], v[126:129]
	v_mfma_f32_16x16x32_bf16 v[122:125], v[160:163], v[184:187], v[122:125]
	v_mfma_f32_16x16x32_bf16 v[110:113], v[152:155], v[198:201], v[110:113]
	v_mfma_f32_16x16x32_bf16 v[106:109], v[160:163], v[198:201], v[106:109]
	v_mfma_f32_16x16x32_bf16 v[94:97], v[152:155], v[214:217], v[94:97]
	v_mfma_f32_16x16x32_bf16 v[90:93], v[160:163], v[214:217], v[90:93]
	v_mfma_f32_16x16x32_bf16 v[78:81], v[152:155], v[222:225], v[78:81]
	v_mfma_f32_16x16x32_bf16 v[74:77], v[160:163], v[222:225], v[74:77]
	v_mfma_f32_16x16x32_bf16 v[126:129], v[156:159], v[188:191], v[126:129]
	v_mfma_f32_16x16x32_bf16 v[122:125], v[164:167], v[188:191], v[122:125]
	v_mfma_f32_16x16x32_bf16 v[110:113], v[156:159], v[210:213], v[110:113]
	v_mfma_f32_16x16x32_bf16 v[106:109], v[164:167], v[210:213], v[106:109]
	v_mfma_f32_16x16x32_bf16 v[94:97], v[156:159], v[218:221], v[94:97]
	v_mfma_f32_16x16x32_bf16 v[90:93], v[164:167], v[218:221], v[90:93]
	v_mfma_f32_16x16x32_bf16 v[78:81], v[156:159], v[226:229], v[78:81]
	v_mfma_f32_16x16x32_bf16 v[74:77], v[164:167], v[226:229], v[74:77]
	s_setprio 0
	s_setprio 1
	v_mfma_f32_16x16x32_bf16 v[118:121], v[168:171], v[184:187], v[118:121]
	v_mfma_f32_16x16x32_bf16 v[114:117], v[176:179], v[184:187], v[114:117]
	v_mfma_f32_16x16x32_bf16 v[102:105], v[168:171], v[198:201], v[102:105]
	v_mfma_f32_16x16x32_bf16 v[98:101], v[176:179], v[198:201], v[98:101]
	v_mfma_f32_16x16x32_bf16 v[86:89], v[168:171], v[214:217], v[86:89]
	v_mfma_f32_16x16x32_bf16 v[82:85], v[176:179], v[214:217], v[82:85]
	v_mfma_f32_16x16x32_bf16 v[70:73], v[168:171], v[222:225], v[70:73]
	v_mfma_f32_16x16x32_bf16 v[66:69], v[176:179], v[222:225], v[66:69]
	v_mfma_f32_16x16x32_bf16 v[118:121], v[172:175], v[188:191], v[118:121]
	v_mfma_f32_16x16x32_bf16 v[114:117], v[180:183], v[188:191], v[114:117]
	v_mfma_f32_16x16x32_bf16 v[102:105], v[172:175], v[210:213], v[102:105]
	v_mfma_f32_16x16x32_bf16 v[98:101], v[180:183], v[210:213], v[98:101]
	v_mfma_f32_16x16x32_bf16 v[86:89], v[172:175], v[218:221], v[86:89]
	v_mfma_f32_16x16x32_bf16 v[82:85], v[180:183], v[218:221], v[82:85]
	v_mfma_f32_16x16x32_bf16 v[70:73], v[172:175], v[226:229], v[70:73]
	v_mfma_f32_16x16x32_bf16 v[66:69], v[180:183], v[226:229], v[66:69]
	s_setprio 0
	s_barrier
	s_add_i32 s19, s19, s33
	v_lshl_add_u64 v[144:145], v[144:145], 0, s[10:11]
	s_mov_b32 m0, s19
	ds_read_b128 v[184:187], v150 offset:49152
	ds_read_b128 v[188:191], v150 offset:50176
	ds_read_b128 v[198:201], v150 offset:51200
	ds_read_b128 v[210:213], v150 offset:52224
	ds_read_b128 v[214:217], v150 offset:53248
	ds_read_b128 v[218:221], v150 offset:54272
	ds_read_b128 v[222:225], v150 offset:55296
	ds_read_b128 v[226:229], v150 offset:56320
	global_load_lds_dwordx4 v[144:145], off
	s_add_i32 m0, s19, 0x2000
	s_add_u32 s34, s34, 0x80080
	v_lshl_add_u64 v[144:145], v[192:193], 0, s[10:11]
	s_addc_u32 s35, s35, 0
	s_add_i32 s19, s38, s33
	global_load_lds_dwordx4 v[144:145], off
	s_mov_b32 m0, s19
	s_nop 0
	global_load_lds_dwordx4 v132, s[34:35]
	s_add_i32 m0, s19, 0x2000
	s_nop 0
	global_load_lds_dwordx4 v136, s[34:35]
	v_lshl_add_u64 v[144:145], v[202:203], 0, s[10:11]
	s_mov_b32 m0, s51
	s_nop 0
	global_load_lds_dwordx4 v[144:145], off
	v_lshl_add_u64 v[144:145], v[206:207], 0, s[10:11]
	s_mov_b32 m0, s52
	s_nop 0
	global_load_lds_dwordx4 v[144:145], off
	s_waitcnt vmcnt(8)
	s_waitcnt lgkmcnt(0)
	s_barrier
	s_setprio 1
	s_waitcnt lgkmcnt(0)
	v_mfma_f32_16x16x32_bf16 v[62:65], v[152:155], v[184:187], v[62:65]
	v_mfma_f32_16x16x32_bf16 v[58:61], v[160:163], v[184:187], v[58:61]
	v_mfma_f32_16x16x32_bf16 v[46:49], v[152:155], v[198:201], v[46:49]
	v_mfma_f32_16x16x32_bf16 v[42:45], v[160:163], v[198:201], v[42:45]
	v_mfma_f32_16x16x32_bf16 v[30:33], v[152:155], v[214:217], v[30:33]
	v_mfma_f32_16x16x32_bf16 v[26:29], v[160:163], v[214:217], v[26:29]
	v_mfma_f32_16x16x32_bf16 v[14:17], v[152:155], v[222:225], v[14:17]
	v_mfma_f32_16x16x32_bf16 v[10:13], v[160:163], v[222:225], v[10:13]
	v_mfma_f32_16x16x32_bf16 v[62:65], v[156:159], v[188:191], v[62:65]
	v_mfma_f32_16x16x32_bf16 v[58:61], v[164:167], v[188:191], v[58:61]
	v_mfma_f32_16x16x32_bf16 v[46:49], v[156:159], v[210:213], v[46:49]
	v_mfma_f32_16x16x32_bf16 v[42:45], v[164:167], v[210:213], v[42:45]
	v_mfma_f32_16x16x32_bf16 v[30:33], v[156:159], v[218:221], v[30:33]
	v_mfma_f32_16x16x32_bf16 v[26:29], v[164:167], v[218:221], v[26:29]
	v_mfma_f32_16x16x32_bf16 v[14:17], v[156:159], v[226:229], v[14:17]
	v_mfma_f32_16x16x32_bf16 v[10:13], v[164:167], v[226:229], v[10:13]
	s_setprio 0
	s_setprio 1
	v_mfma_f32_16x16x32_bf16 v[54:57], v[168:171], v[184:187], v[54:57]
	v_mfma_f32_16x16x32_bf16 v[50:53], v[176:179], v[184:187], v[50:53]
	v_mfma_f32_16x16x32_bf16 v[38:41], v[168:171], v[198:201], v[38:41]
	v_mfma_f32_16x16x32_bf16 v[34:37], v[176:179], v[198:201], v[34:37]
	v_mfma_f32_16x16x32_bf16 v[22:25], v[168:171], v[214:217], v[22:25]
	v_mfma_f32_16x16x32_bf16 v[18:21], v[176:179], v[214:217], v[18:21]
	v_mfma_f32_16x16x32_bf16 v[6:9], v[168:171], v[222:225], v[6:9]
	v_mfma_f32_16x16x32_bf16 v[2:5], v[176:179], v[222:225], v[2:5]
	v_mfma_f32_16x16x32_bf16 v[54:57], v[172:175], v[188:191], v[54:57]
	v_mfma_f32_16x16x32_bf16 v[50:53], v[180:183], v[188:191], v[50:53]
	v_mfma_f32_16x16x32_bf16 v[38:41], v[172:175], v[210:213], v[38:41]
	v_mfma_f32_16x16x32_bf16 v[34:37], v[180:183], v[210:213], v[34:37]
	v_mfma_f32_16x16x32_bf16 v[22:25], v[172:175], v[218:221], v[22:25]
	v_mfma_f32_16x16x32_bf16 v[18:21], v[180:183], v[218:221], v[18:21]
	v_mfma_f32_16x16x32_bf16 v[6:9], v[172:175], v[226:229], v[6:9]
	v_mfma_f32_16x16x32_bf16 v[2:5], v[180:183], v[226:229], v[2:5]
	s_setprio 0
	s_barrier
	s_add_u32 s30, s30, 0x100
	s_addc_u32 s31, s31, 0
	s_add_u32 s15, s15, 0x100
	s_addc_u32 s17, s17, 0
	s_cmp_ge_i32 s29, s68
	s_mov_b32 s19, s29
	s_cbranch_scc0 .LBB0_1315
	s_branch .Lpeeldone_7
.LBB0_1315:
	ds_read_b128 v[152:155], v148
	ds_read_b128 v[156:159], v148 offset:1024
	ds_read_b128 v[160:163], v148 offset:2048
	ds_read_b128 v[164:167], v148 offset:3072
	ds_read_b128 v[168:171], v149
	ds_read_b128 v[172:175], v149 offset:1024
	ds_read_b128 v[176:179], v149 offset:2048
	ds_read_b128 v[180:183], v149 offset:3072
	s_add_i32 s29, s19, 2
	s_add_u32 s34, s30, 0xfff80080
	s_addc_u32 s35, s31, -1
	s_cmp_eq_u32 s28, s19
	s_cselect_b32 s37, s21, s35
	s_cselect_b32 s36, s20, s34
	s_cselect_b32 s35, s23, s17
	s_cselect_b32 s34, s22, s15
	s_add_i32 m0, s27, 0xc000
	ds_read_b128 v[184:187], v150
	ds_read_b128 v[188:191], v150 offset:1024
	ds_read_b128 v[198:201], v150 offset:2048
	ds_read_b128 v[210:213], v150 offset:3072
	ds_read_b128 v[214:217], v150 offset:4096
	ds_read_b128 v[218:221], v150 offset:5120
	ds_read_b128 v[222:225], v150 offset:6144
	ds_read_b128 v[226:229], v150 offset:7168
	global_load_lds_dwordx4 v140, s[30:31]
	s_add_i32 m0, s27, 0xe000
	s_nop 0
	global_load_lds_dwordx4 v142, s[30:31]
	s_waitcnt vmcnt(8)
	s_waitcnt lgkmcnt(0)
	s_barrier
	s_setprio 1
	s_waitcnt lgkmcnt(0)
	v_mfma_f32_16x16x32_bf16 v[126:129], v[152:155], v[184:187], v[126:129]
	v_mfma_f32_16x16x32_bf16 v[122:125], v[160:163], v[184:187], v[122:125]
	v_mfma_f32_16x16x32_bf16 v[110:113], v[152:155], v[198:201], v[110:113]
	v_mfma_f32_16x16x32_bf16 v[106:109], v[160:163], v[198:201], v[106:109]
	v_mfma_f32_16x16x32_bf16 v[94:97], v[152:155], v[214:217], v[94:97]
	v_mfma_f32_16x16x32_bf16 v[90:93], v[160:163], v[214:217], v[90:93]
	v_mfma_f32_16x16x32_bf16 v[78:81], v[152:155], v[222:225], v[78:81]
	v_mfma_f32_16x16x32_bf16 v[74:77], v[160:163], v[222:225], v[74:77]
	v_mfma_f32_16x16x32_bf16 v[126:129], v[156:159], v[188:191], v[126:129]
	v_mfma_f32_16x16x32_bf16 v[122:125], v[164:167], v[188:191], v[122:125]
	v_mfma_f32_16x16x32_bf16 v[110:113], v[156:159], v[210:213], v[110:113]
	v_mfma_f32_16x16x32_bf16 v[106:109], v[164:167], v[210:213], v[106:109]
	v_mfma_f32_16x16x32_bf16 v[94:97], v[156:159], v[218:221], v[94:97]
	v_mfma_f32_16x16x32_bf16 v[90:93], v[164:167], v[218:221], v[90:93]
	v_mfma_f32_16x16x32_bf16 v[78:81], v[156:159], v[226:229], v[78:81]
	v_mfma_f32_16x16x32_bf16 v[74:77], v[164:167], v[226:229], v[74:77]
	s_setprio 0
	s_setprio 1
	v_mfma_f32_16x16x32_bf16 v[118:121], v[168:171], v[184:187], v[118:121]
	v_mfma_f32_16x16x32_bf16 v[114:117], v[176:179], v[184:187], v[114:117]
	v_mfma_f32_16x16x32_bf16 v[102:105], v[168:171], v[198:201], v[102:105]
	v_mfma_f32_16x16x32_bf16 v[98:101], v[176:179], v[198:201], v[98:101]
	v_mfma_f32_16x16x32_bf16 v[86:89], v[168:171], v[214:217], v[86:89]
	v_mfma_f32_16x16x32_bf16 v[82:85], v[176:179], v[214:217], v[82:85]
	v_mfma_f32_16x16x32_bf16 v[70:73], v[168:171], v[222:225], v[70:73]
	v_mfma_f32_16x16x32_bf16 v[66:69], v[176:179], v[222:225], v[66:69]
	v_mfma_f32_16x16x32_bf16 v[118:121], v[172:175], v[188:191], v[118:121]
	v_mfma_f32_16x16x32_bf16 v[114:117], v[180:183], v[188:191], v[114:117]
	v_mfma_f32_16x16x32_bf16 v[102:105], v[172:175], v[210:213], v[102:105]
	v_mfma_f32_16x16x32_bf16 v[98:101], v[180:183], v[210:213], v[98:101]
	v_mfma_f32_16x16x32_bf16 v[86:89], v[172:175], v[218:221], v[86:89]
	v_mfma_f32_16x16x32_bf16 v[82:85], v[180:183], v[218:221], v[82:85]
	v_mfma_f32_16x16x32_bf16 v[70:73], v[172:175], v[226:229], v[70:73]
	v_mfma_f32_16x16x32_bf16 v[66:69], v[180:183], v[226:229], v[66:69]
	s_setprio 0
	s_barrier
	s_add_i32 s19, s60, s33
	v_lshl_add_u64 v[144:145], s[34:35], 0, v[132:133]
	s_mov_b32 m0, s19
	ds_read_b128 v[184:187], v150 offset:16384
	ds_read_b128 v[188:191], v150 offset:17408
	ds_read_b128 v[198:201], v150 offset:18432
	ds_read_b128 v[210:213], v150 offset:19456
	ds_read_b128 v[214:217], v150 offset:20480
	ds_read_b128 v[218:221], v150 offset:21504
	ds_read_b128 v[222:225], v150 offset:22528
	ds_read_b128 v[226:229], v150 offset:23552
	global_load_lds_dwordx4 v132, s[34:35]
	s_add_i32 m0, s19, 0x2000
	s_add_u32 s38, s34, 0x80000
	v_lshl_add_u64 v[192:193], s[34:35], 0, v[136:137]
	s_addc_u32 s39, s35, 0
	s_add_i32 s19, s61, s33
	global_load_lds_dwordx4 v136, s[34:35]
	s_mov_b32 m0, s19
	v_lshl_add_u64 v[206:207], s[36:37], 0, v[134:135]
	global_load_lds_dwordx4 v132, s[38:39]
	s_add_i32 m0, s19, 0x2000
	s_nop 0
	global_load_lds_dwordx4 v136, s[38:39]
	v_lshl_add_u64 v[202:203], s[36:37], 0, v[130:131]
	s_mov_b32 m0, s27
	s_nop 0
	global_load_lds_dwordx4 v130, s[36:37]
	s_mov_b32 m0, s41
	s_nop 0
	global_load_lds_dwordx4 v134, s[36:37]
	s_waitcnt vmcnt(8)
	s_waitcnt lgkmcnt(0)
	s_barrier
	s_setprio 1
	s_waitcnt lgkmcnt(0)
	v_mfma_f32_16x16x32_bf16 v[62:65], v[152:155], v[184:187], v[62:65]
	v_mfma_f32_16x16x32_bf16 v[58:61], v[160:163], v[184:187], v[58:61]
	v_mfma_f32_16x16x32_bf16 v[46:49], v[152:155], v[198:201], v[46:49]
	v_mfma_f32_16x16x32_bf16 v[42:45], v[160:163], v[198:201], v[42:45]
	v_mfma_f32_16x16x32_bf16 v[30:33], v[152:155], v[214:217], v[30:33]
	v_mfma_f32_16x16x32_bf16 v[26:29], v[160:163], v[214:217], v[26:29]
	v_mfma_f32_16x16x32_bf16 v[14:17], v[152:155], v[222:225], v[14:17]
	v_mfma_f32_16x16x32_bf16 v[10:13], v[160:163], v[222:225], v[10:13]
	v_mfma_f32_16x16x32_bf16 v[62:65], v[156:159], v[188:191], v[62:65]
	v_mfma_f32_16x16x32_bf16 v[58:61], v[164:167], v[188:191], v[58:61]
	v_mfma_f32_16x16x32_bf16 v[46:49], v[156:159], v[210:213], v[46:49]
	v_mfma_f32_16x16x32_bf16 v[42:45], v[164:167], v[210:213], v[42:45]
	v_mfma_f32_16x16x32_bf16 v[30:33], v[156:159], v[218:221], v[30:33]
	v_mfma_f32_16x16x32_bf16 v[26:29], v[164:167], v[218:221], v[26:29]
	v_mfma_f32_16x16x32_bf16 v[14:17], v[156:159], v[226:229], v[14:17]
	v_mfma_f32_16x16x32_bf16 v[10:13], v[164:167], v[226:229], v[10:13]
	s_setprio 0
	s_setprio 1
	v_mfma_f32_16x16x32_bf16 v[54:57], v[168:171], v[184:187], v[54:57]
	v_mfma_f32_16x16x32_bf16 v[50:53], v[176:179], v[184:187], v[50:53]
	v_mfma_f32_16x16x32_bf16 v[38:41], v[168:171], v[198:201], v[38:41]
	v_mfma_f32_16x16x32_bf16 v[34:37], v[176:179], v[198:201], v[34:37]
	v_mfma_f32_16x16x32_bf16 v[22:25], v[168:171], v[214:217], v[22:25]
	v_mfma_f32_16x16x32_bf16 v[18:21], v[176:179], v[214:217], v[18:21]
	v_mfma_f32_16x16x32_bf16 v[6:9], v[168:171], v[222:225], v[6:9]
	v_mfma_f32_16x16x32_bf16 v[2:5], v[176:179], v[222:225], v[2:5]
	v_mfma_f32_16x16x32_bf16 v[54:57], v[172:175], v[188:191], v[54:57]
	v_mfma_f32_16x16x32_bf16 v[50:53], v[180:183], v[188:191], v[50:53]
	v_mfma_f32_16x16x32_bf16 v[38:41], v[172:175], v[210:213], v[38:41]
	v_mfma_f32_16x16x32_bf16 v[34:37], v[180:183], v[210:213], v[34:37]
	v_mfma_f32_16x16x32_bf16 v[22:25], v[172:175], v[218:221], v[22:25]
	v_mfma_f32_16x16x32_bf16 v[18:21], v[180:183], v[218:221], v[18:21]
	v_mfma_f32_16x16x32_bf16 v[6:9], v[172:175], v[226:229], v[6:9]
	v_mfma_f32_16x16x32_bf16 v[2:5], v[180:183], v[226:229], v[2:5]
	s_setprio 0
	s_barrier
	s_add_i32 s19, 0, 0x18000
	v_add_u32_e32 v151, s19, v146
	s_add_i32 s38, 0, 0x1c000
	ds_read_b128 v[152:155], v151
	ds_read_b128 v[156:159], v151 offset:1024
	ds_read_b128 v[160:163], v151 offset:2048
	ds_read_b128 v[164:167], v151 offset:3072
	v_add_u32_e32 v151, s38, v146
	ds_read_b128 v[168:171], v151
	ds_read_b128 v[172:175], v151 offset:1024
	ds_read_b128 v[176:179], v151 offset:2048
	ds_read_b128 v[180:183], v151 offset:3072
	s_add_u32 s36, s36, 0x80000
	s_addc_u32 s37, s37, 0
	s_mov_b32 m0, s42
	ds_read_b128 v[184:187], v150 offset:32768
	ds_read_b128 v[188:191], v150 offset:33792
	ds_read_b128 v[198:201], v150 offset:34816
	ds_read_b128 v[210:213], v150 offset:35840
	ds_read_b128 v[214:217], v150 offset:36864
	ds_read_b128 v[218:221], v150 offset:37888
	ds_read_b128 v[222:225], v150 offset:38912
	ds_read_b128 v[226:229], v150 offset:39936
	global_load_lds_dwordx4 v130, s[36:37]
	v_lshl_add_u64 v[230:231], s[36:37], 0, v[134:135]
	s_mov_b32 m0, s43
	s_nop 0
	global_load_lds_dwordx4 v134, s[36:37]
	s_waitcnt vmcnt(8)
	s_waitcnt lgkmcnt(0)
	s_barrier
	s_setprio 1
	s_waitcnt lgkmcnt(0)
	v_mfma_f32_16x16x32_bf16 v[126:129], v[152:155], v[184:187], v[126:129]
	v_mfma_f32_16x16x32_bf16 v[122:125], v[160:163], v[184:187], v[122:125]
	v_mfma_f32_16x16x32_bf16 v[110:113], v[152:155], v[198:201], v[110:113]
	v_mfma_f32_16x16x32_bf16 v[106:109], v[160:163], v[198:201], v[106:109]
	v_mfma_f32_16x16x32_bf16 v[94:97], v[152:155], v[214:217], v[94:97]
	v_mfma_f32_16x16x32_bf16 v[90:93], v[160:163], v[214:217], v[90:93]
	v_mfma_f32_16x16x32_bf16 v[78:81], v[152:155], v[222:225], v[78:81]
	v_mfma_f32_16x16x32_bf16 v[74:77], v[160:163], v[222:225], v[74:77]
	v_mfma_f32_16x16x32_bf16 v[126:129], v[156:159], v[188:191], v[126:129]
	v_mfma_f32_16x16x32_bf16 v[122:125], v[164:167], v[188:191], v[122:125]
	v_mfma_f32_16x16x32_bf16 v[110:113], v[156:159], v[210:213], v[110:113]
	v_mfma_f32_16x16x32_bf16 v[106:109], v[164:167], v[210:213], v[106:109]
	v_mfma_f32_16x16x32_bf16 v[94:97], v[156:159], v[218:221], v[94:97]
	v_mfma_f32_16x16x32_bf16 v[90:93], v[164:167], v[218:221], v[90:93]
	v_mfma_f32_16x16x32_bf16 v[78:81], v[156:159], v[226:229], v[78:81]
	v_mfma_f32_16x16x32_bf16 v[74:77], v[164:167], v[226:229], v[74:77]
	s_setprio 0
	s_setprio 1
	v_mfma_f32_16x16x32_bf16 v[118:121], v[168:171], v[184:187], v[118:121]
	v_mfma_f32_16x16x32_bf16 v[114:117], v[176:179], v[184:187], v[114:117]
	v_mfma_f32_16x16x32_bf16 v[102:105], v[168:171], v[198:201], v[102:105]
	v_mfma_f32_16x16x32_bf16 v[98:101], v[176:179], v[198:201], v[98:101]
	v_mfma_f32_16x16x32_bf16 v[86:89], v[168:171], v[214:217], v[86:89]
	v_mfma_f32_16x16x32_bf16 v[82:85], v[176:179], v[214:217], v[82:85]
	v_mfma_f32_16x16x32_bf16 v[70:73], v[168:171], v[222:225], v[70:73]
	v_mfma_f32_16x16x32_bf16 v[66:69], v[176:179], v[222:225], v[66:69]
	v_mfma_f32_16x16x32_bf16 v[118:121], v[172:175], v[188:191], v[118:121]
	v_mfma_f32_16x16x32_bf16 v[114:117], v[180:183], v[188:191], v[114:117]
	v_mfma_f32_16x16x32_bf16 v[102:105], v[172:175], v[210:213], v[102:105]
	v_mfma_f32_16x16x32_bf16 v[98:101], v[180:183], v[210:213], v[98:101]
	v_mfma_f32_16x16x32_bf16 v[86:89], v[172:175], v[218:221], v[86:89]
	v_mfma_f32_16x16x32_bf16 v[82:85], v[180:183], v[218:221], v[82:85]
	v_mfma_f32_16x16x32_bf16 v[70:73], v[172:175], v[226:229], v[70:73]
	v_mfma_f32_16x16x32_bf16 v[66:69], v[180:183], v[226:229], v[66:69]
	s_setprio 0
	s_barrier
	s_add_i32 s19, s19, s33
	v_lshl_add_u64 v[144:145], v[144:145], 0, s[10:11]
	s_mov_b32 m0, s19
	ds_read_b128 v[184:187], v150 offset:49152
	ds_read_b128 v[188:191], v150 offset:50176
	ds_read_b128 v[198:201], v150 offset:51200
	ds_read_b128 v[210:213], v150 offset:52224
	ds_read_b128 v[214:217], v150 offset:53248
	ds_read_b128 v[218:221], v150 offset:54272
	ds_read_b128 v[222:225], v150 offset:55296
	ds_read_b128 v[226:229], v150 offset:56320
	global_load_lds_dwordx4 v[144:145], off
	s_add_i32 m0, s19, 0x2000
	s_add_u32 s34, s34, 0x80080
	v_lshl_add_u64 v[144:145], v[192:193], 0, s[10:11]
	s_addc_u32 s35, s35, 0
	s_add_i32 s19, s38, s33
	global_load_lds_dwordx4 v[144:145], off
	s_mov_b32 m0, s19
	s_nop 0
	global_load_lds_dwordx4 v132, s[34:35]
	s_add_i32 m0, s19, 0x2000
	s_nop 0
	global_load_lds_dwordx4 v136, s[34:35]
	v_lshl_add_u64 v[144:145], v[202:203], 0, s[10:11]
	s_mov_b32 m0, s51
	s_nop 0
	global_load_lds_dwordx4 v[144:145], off
	v_lshl_add_u64 v[144:145], v[206:207], 0, s[10:11]
	s_mov_b32 m0, s52
	s_nop 0
	global_load_lds_dwordx4 v[144:145], off
	s_waitcnt vmcnt(8)
	s_waitcnt lgkmcnt(0)
	s_barrier
	s_setprio 1
	s_waitcnt lgkmcnt(0)
	v_mfma_f32_16x16x32_bf16 v[62:65], v[152:155], v[184:187], v[62:65]
	v_mfma_f32_16x16x32_bf16 v[58:61], v[160:163], v[184:187], v[58:61]
	v_mfma_f32_16x16x32_bf16 v[46:49], v[152:155], v[198:201], v[46:49]
	v_mfma_f32_16x16x32_bf16 v[42:45], v[160:163], v[198:201], v[42:45]
	v_mfma_f32_16x16x32_bf16 v[30:33], v[152:155], v[214:217], v[30:33]
	v_mfma_f32_16x16x32_bf16 v[26:29], v[160:163], v[214:217], v[26:29]
	v_mfma_f32_16x16x32_bf16 v[14:17], v[152:155], v[222:225], v[14:17]
	v_mfma_f32_16x16x32_bf16 v[10:13], v[160:163], v[222:225], v[10:13]
	v_mfma_f32_16x16x32_bf16 v[62:65], v[156:159], v[188:191], v[62:65]
	v_mfma_f32_16x16x32_bf16 v[58:61], v[164:167], v[188:191], v[58:61]
	v_mfma_f32_16x16x32_bf16 v[46:49], v[156:159], v[210:213], v[46:49]
	v_mfma_f32_16x16x32_bf16 v[42:45], v[164:167], v[210:213], v[42:45]
	v_mfma_f32_16x16x32_bf16 v[30:33], v[156:159], v[218:221], v[30:33]
	v_mfma_f32_16x16x32_bf16 v[26:29], v[164:167], v[218:221], v[26:29]
	v_mfma_f32_16x16x32_bf16 v[14:17], v[156:159], v[226:229], v[14:17]
	v_mfma_f32_16x16x32_bf16 v[10:13], v[164:167], v[226:229], v[10:13]
	s_setprio 0
	s_setprio 1
	v_mfma_f32_16x16x32_bf16 v[54:57], v[168:171], v[184:187], v[54:57]
	v_mfma_f32_16x16x32_bf16 v[50:53], v[176:179], v[184:187], v[50:53]
	v_mfma_f32_16x16x32_bf16 v[38:41], v[168:171], v[198:201], v[38:41]
	v_mfma_f32_16x16x32_bf16 v[34:37], v[176:179], v[198:201], v[34:37]
	v_mfma_f32_16x16x32_bf16 v[22:25], v[168:171], v[214:217], v[22:25]
	v_mfma_f32_16x16x32_bf16 v[18:21], v[176:179], v[214:217], v[18:21]
	v_mfma_f32_16x16x32_bf16 v[6:9], v[168:171], v[222:225], v[6:9]
	v_mfma_f32_16x16x32_bf16 v[2:5], v[176:179], v[222:225], v[2:5]
	v_mfma_f32_16x16x32_bf16 v[54:57], v[172:175], v[188:191], v[54:57]
	v_mfma_f32_16x16x32_bf16 v[50:53], v[180:183], v[188:191], v[50:53]
	v_mfma_f32_16x16x32_bf16 v[38:41], v[172:175], v[210:213], v[38:41]
	v_mfma_f32_16x16x32_bf16 v[34:37], v[180:183], v[210:213], v[34:37]
	v_mfma_f32_16x16x32_bf16 v[22:25], v[172:175], v[218:221], v[22:25]
	v_mfma_f32_16x16x32_bf16 v[18:21], v[180:183], v[218:221], v[18:21]
	v_mfma_f32_16x16x32_bf16 v[6:9], v[172:175], v[226:229], v[6:9]
	v_mfma_f32_16x16x32_bf16 v[2:5], v[180:183], v[226:229], v[2:5]
	s_setprio 0
	s_barrier
	s_add_u32 s30, s30, 0x100
	s_addc_u32 s31, s31, 0
	s_add_u32 s15, s15, 0x100
	s_addc_u32 s17, s17, 0
	s_cmp_ge_i32 s29, s68
	s_mov_b32 s19, s29
	s_cbranch_scc0 .LBB0_1315

.Lpeel_6:
	ds_read_b128 v[144:147], v166
	ds_read_b128 v[148:151], v166 offset:1024
	ds_read_b128 v[152:155], v166 offset:2048
	ds_read_b128 v[156:159], v166 offset:3072
	ds_read_b128 v[160:163], v167
	ds_read_b128 v[170:173], v167 offset:1024
	ds_read_b128 v[174:177], v167 offset:2048
	ds_read_b128 v[178:181], v167 offset:3072
	s_add_i32 s30, s26, 2
	s_add_u32 s27, s24, 0xffea0080
	s_addc_u32 s28, s25, -1
	s_cmp_eq_u32 s22, s26
	s_cselect_b32 s26, s20, s17
	s_cselect_b32 s29, s19, s28
	s_cselect_b32 s28, s18, s27
	s_cselect_b32 s27, s21, s23
	s_add_i32 m0, s34, 0xc000
	ds_read_b128 v[182:185], v168
	ds_read_b128 v[186:189], v168 offset:1024
	ds_read_b128 v[190:193], v168 offset:2048
	ds_read_b128 v[198:201], v168 offset:3072
	ds_read_b128 v[210:213], v168 offset:4096
	ds_read_b128 v[214:217], v168 offset:5120
	ds_read_b128 v[218:221], v168 offset:6144
	ds_read_b128 v[222:225], v168 offset:7168
	global_load_lds_dwordx4 v140, s[24:25]
	s_add_i32 m0, s34, 0xe000
	s_nop 0
	global_load_lds_dwordx4 v142, s[24:25]
	s_waitcnt vmcnt(8)
	s_waitcnt lgkmcnt(0)
	s_barrier
	s_setprio 1
	s_waitcnt lgkmcnt(0)
	v_mfma_f32_16x16x32_bf16 v[126:129], v[144:147], v[182:185], 0
	v_mfma_f32_16x16x32_bf16 v[122:125], v[152:155], v[182:185], 0
	v_mfma_f32_16x16x32_bf16 v[114:117], v[144:147], v[190:193], 0
	v_mfma_f32_16x16x32_bf16 v[106:109], v[152:155], v[190:193], 0
	v_mfma_f32_16x16x32_bf16 v[94:97], v[144:147], v[210:213], 0
	v_mfma_f32_16x16x32_bf16 v[90:93], v[152:155], v[210:213], 0
	v_mfma_f32_16x16x32_bf16 v[78:81], v[144:147], v[218:221], 0
	v_mfma_f32_16x16x32_bf16 v[74:77], v[152:155], v[218:221], 0
	v_mfma_f32_16x16x32_bf16 v[126:129], v[148:151], v[186:189], v[126:129]
	v_mfma_f32_16x16x32_bf16 v[122:125], v[156:159], v[186:189], v[122:125]
	v_mfma_f32_16x16x32_bf16 v[114:117], v[148:151], v[198:201], v[114:117]
	v_mfma_f32_16x16x32_bf16 v[106:109], v[156:159], v[198:201], v[106:109]
	v_mfma_f32_16x16x32_bf16 v[94:97], v[148:151], v[214:217], v[94:97]
	v_mfma_f32_16x16x32_bf16 v[90:93], v[156:159], v[214:217], v[90:93]
	v_mfma_f32_16x16x32_bf16 v[78:81], v[148:151], v[222:225], v[78:81]
	v_mfma_f32_16x16x32_bf16 v[74:77], v[156:159], v[222:225], v[74:77]
	s_setprio 0
	s_setprio 1
	v_mfma_f32_16x16x32_bf16 v[118:121], v[160:163], v[182:185], 0
	v_mfma_f32_16x16x32_bf16 v[110:113], v[174:177], v[182:185], 0
	v_mfma_f32_16x16x32_bf16 v[102:105], v[160:163], v[190:193], 0
	v_mfma_f32_16x16x32_bf16 v[98:101], v[174:177], v[190:193], 0
	v_mfma_f32_16x16x32_bf16 v[86:89], v[160:163], v[210:213], 0
	v_mfma_f32_16x16x32_bf16 v[82:85], v[174:177], v[210:213], 0
	v_mfma_f32_16x16x32_bf16 v[70:73], v[160:163], v[218:221], 0
	v_mfma_f32_16x16x32_bf16 v[66:69], v[174:177], v[218:221], 0
	v_mfma_f32_16x16x32_bf16 v[118:121], v[170:173], v[186:189], v[118:121]
	v_mfma_f32_16x16x32_bf16 v[110:113], v[178:181], v[186:189], v[110:113]
	v_mfma_f32_16x16x32_bf16 v[102:105], v[170:173], v[198:201], v[102:105]
	v_mfma_f32_16x16x32_bf16 v[98:101], v[178:181], v[198:201], v[98:101]
	v_mfma_f32_16x16x32_bf16 v[86:89], v[170:173], v[214:217], v[86:89]
	v_mfma_f32_16x16x32_bf16 v[82:85], v[178:181], v[214:217], v[82:85]
	v_mfma_f32_16x16x32_bf16 v[70:73], v[170:173], v[222:225], v[70:73]
	v_mfma_f32_16x16x32_bf16 v[66:69], v[178:181], v[222:225], v[66:69]
	s_setprio 0
	s_barrier
	s_add_i32 s31, s57, s33
	v_lshl_add_u64 v[202:203], s[26:27], 0, v[132:133]
	s_mov_b32 m0, s31
	ds_read_b128 v[182:185], v168 offset:16384
	ds_read_b128 v[186:189], v168 offset:17408
	ds_read_b128 v[190:193], v168 offset:18432
	ds_read_b128 v[198:201], v168 offset:19456
	ds_read_b128 v[210:213], v168 offset:20480
	ds_read_b128 v[214:217], v168 offset:21504
	ds_read_b128 v[218:221], v168 offset:22528
	ds_read_b128 v[222:225], v168 offset:23552
	global_load_lds_dwordx4 v132, s[26:27]
	s_add_i32 m0, s31, 0x2000
	s_add_u32 s68, s26, 0x160000
	v_lshl_add_u64 v[206:207], s[26:27], 0, v[136:137]
	s_addc_u32 s69, s27, 0
	s_add_i32 s31, s58, s33
	global_load_lds_dwordx4 v136, s[26:27]
	s_mov_b32 m0, s31
	v_lshl_add_u64 v[228:229], s[28:29], 0, v[134:135]
	global_load_lds_dwordx4 v132, s[68:69]
	s_add_i32 m0, s31, 0x2000
	s_nop 0
	global_load_lds_dwordx4 v136, s[68:69]
	v_lshl_add_u64 v[226:227], s[28:29], 0, v[130:131]
	s_mov_b32 m0, s34
	s_nop 0
	global_load_lds_dwordx4 v130, s[28:29]
	s_mov_b32 m0, s35
	s_nop 0
	global_load_lds_dwordx4 v134, s[28:29]
	s_waitcnt vmcnt(8)
	s_waitcnt lgkmcnt(0)
	s_barrier
	s_setprio 1
	s_waitcnt lgkmcnt(0)
	v_mfma_f32_16x16x32_bf16 v[62:65], v[144:147], v[182:185], 0
	v_mfma_f32_16x16x32_bf16 v[58:61], v[152:155], v[182:185], 0
	v_mfma_f32_16x16x32_bf16 v[46:49], v[144:147], v[190:193], 0
	v_mfma_f32_16x16x32_bf16 v[42:45], v[152:155], v[190:193], 0
	v_mfma_f32_16x16x32_bf16 v[30:33], v[144:147], v[210:213], 0
	v_mfma_f32_16x16x32_bf16 v[26:29], v[152:155], v[210:213], 0
	v_mfma_f32_16x16x32_bf16 v[14:17], v[144:147], v[218:221], 0
	v_mfma_f32_16x16x32_bf16 v[10:13], v[152:155], v[218:221], 0
	v_mfma_f32_16x16x32_bf16 v[62:65], v[148:151], v[186:189], v[62:65]
	v_mfma_f32_16x16x32_bf16 v[58:61], v[156:159], v[186:189], v[58:61]
	v_mfma_f32_16x16x32_bf16 v[46:49], v[148:151], v[198:201], v[46:49]
	v_mfma_f32_16x16x32_bf16 v[42:45], v[156:159], v[198:201], v[42:45]
	v_mfma_f32_16x16x32_bf16 v[30:33], v[148:151], v[214:217], v[30:33]
	v_mfma_f32_16x16x32_bf16 v[26:29], v[156:159], v[214:217], v[26:29]
	v_mfma_f32_16x16x32_bf16 v[14:17], v[148:151], v[222:225], v[14:17]
	v_mfma_f32_16x16x32_bf16 v[10:13], v[156:159], v[222:225], v[10:13]
	s_setprio 0
	s_setprio 1
	v_mfma_f32_16x16x32_bf16 v[54:57], v[160:163], v[182:185], 0
	v_mfma_f32_16x16x32_bf16 v[50:53], v[174:177], v[182:185], 0
	v_mfma_f32_16x16x32_bf16 v[38:41], v[160:163], v[190:193], 0
	v_mfma_f32_16x16x32_bf16 v[34:37], v[174:177], v[190:193], 0
	v_mfma_f32_16x16x32_bf16 v[22:25], v[160:163], v[210:213], 0
	v_mfma_f32_16x16x32_bf16 v[18:21], v[174:177], v[210:213], 0
	v_mfma_f32_16x16x32_bf16 v[6:9], v[160:163], v[218:221], 0
	v_mfma_f32_16x16x32_bf16 v[2:5], v[174:177], v[218:221], 0
	v_mfma_f32_16x16x32_bf16 v[54:57], v[170:173], v[186:189], v[54:57]
	v_mfma_f32_16x16x32_bf16 v[50:53], v[178:181], v[186:189], v[50:53]
	v_mfma_f32_16x16x32_bf16 v[38:41], v[170:173], v[198:201], v[38:41]
	v_mfma_f32_16x16x32_bf16 v[34:37], v[178:181], v[198:201], v[34:37]
	v_mfma_f32_16x16x32_bf16 v[22:25], v[170:173], v[214:217], v[22:25]
	v_mfma_f32_16x16x32_bf16 v[18:21], v[178:181], v[214:217], v[18:21]
	v_mfma_f32_16x16x32_bf16 v[6:9], v[170:173], v[222:225], v[6:9]
	v_mfma_f32_16x16x32_bf16 v[2:5], v[178:181], v[222:225], v[2:5]
	s_setprio 0
	s_barrier
	s_add_i32 s31, 0, 0x18000
	s_add_i32 s68, 0, 0x1c000
	v_add_u32_e32 v156, s31, v164
	v_add_u32_e32 v169, s68, v164
	ds_read_b128 v[144:147], v156
	ds_read_b128 v[148:151], v156 offset:1024
	ds_read_b128 v[152:155], v156 offset:2048
	ds_read_b128 v[156:159], v156 offset:3072
	ds_read_b128 v[160:163], v169
	ds_read_b128 v[170:173], v169 offset:1024
	ds_read_b128 v[174:177], v169 offset:2048
	ds_read_b128 v[178:181], v169 offset:3072
	s_add_u32 s28, s28, 0x160000
	s_addc_u32 s29, s29, 0
	s_mov_b32 m0, s36
	ds_read_b128 v[182:185], v168 offset:32768
	ds_read_b128 v[186:189], v168 offset:33792
	ds_read_b128 v[190:193], v168 offset:34816
	ds_read_b128 v[198:201], v168 offset:35840
	ds_read_b128 v[210:213], v168 offset:36864
	ds_read_b128 v[214:217], v168 offset:37888
	ds_read_b128 v[218:221], v168 offset:38912
	ds_read_b128 v[222:225], v168 offset:39936
	global_load_lds_dwordx4 v130, s[28:29]
	v_lshl_add_u64 v[230:231], s[28:29], 0, v[134:135]
	s_mov_b32 m0, s37
	s_nop 0
	global_load_lds_dwordx4 v134, s[28:29]
	s_waitcnt vmcnt(8)
	s_waitcnt lgkmcnt(0)
	s_barrier
	s_setprio 1
	s_waitcnt lgkmcnt(0)
	v_mfma_f32_16x16x32_bf16 v[126:129], v[144:147], v[182:185], v[126:129]
	v_mfma_f32_16x16x32_bf16 v[122:125], v[152:155], v[182:185], v[122:125]
	v_mfma_f32_16x16x32_bf16 v[114:117], v[144:147], v[190:193], v[114:117]
	v_mfma_f32_16x16x32_bf16 v[106:109], v[152:155], v[190:193], v[106:109]
	v_mfma_f32_16x16x32_bf16 v[94:97], v[144:147], v[210:213], v[94:97]
	v_mfma_f32_16x16x32_bf16 v[90:93], v[152:155], v[210:213], v[90:93]
	v_mfma_f32_16x16x32_bf16 v[78:81], v[144:147], v[218:221], v[78:81]
	v_mfma_f32_16x16x32_bf16 v[74:77], v[152:155], v[218:221], v[74:77]
	v_mfma_f32_16x16x32_bf16 v[126:129], v[148:151], v[186:189], v[126:129]
	v_mfma_f32_16x16x32_bf16 v[122:125], v[156:159], v[186:189], v[122:125]
	v_mfma_f32_16x16x32_bf16 v[114:117], v[148:151], v[198:201], v[114:117]
	v_mfma_f32_16x16x32_bf16 v[106:109], v[156:159], v[198:201], v[106:109]
	v_mfma_f32_16x16x32_bf16 v[94:97], v[148:151], v[214:217], v[94:97]
	v_mfma_f32_16x16x32_bf16 v[90:93], v[156:159], v[214:217], v[90:93]
	v_mfma_f32_16x16x32_bf16 v[78:81], v[148:151], v[222:225], v[78:81]
	v_mfma_f32_16x16x32_bf16 v[74:77], v[156:159], v[222:225], v[74:77]
	s_setprio 0
	s_setprio 1
	v_mfma_f32_16x16x32_bf16 v[118:121], v[160:163], v[182:185], v[118:121]
	v_mfma_f32_16x16x32_bf16 v[110:113], v[174:177], v[182:185], v[110:113]
	v_mfma_f32_16x16x32_bf16 v[102:105], v[160:163], v[190:193], v[102:105]
	v_mfma_f32_16x16x32_bf16 v[98:101], v[174:177], v[190:193], v[98:101]
	v_mfma_f32_16x16x32_bf16 v[86:89], v[160:163], v[210:213], v[86:89]
	v_mfma_f32_16x16x32_bf16 v[82:85], v[174:177], v[210:213], v[82:85]
	v_mfma_f32_16x16x32_bf16 v[70:73], v[160:163], v[218:221], v[70:73]
	v_mfma_f32_16x16x32_bf16 v[66:69], v[174:177], v[218:221], v[66:69]
	v_mfma_f32_16x16x32_bf16 v[118:121], v[170:173], v[186:189], v[118:121]
	v_mfma_f32_16x16x32_bf16 v[110:113], v[178:181], v[186:189], v[110:113]
	v_mfma_f32_16x16x32_bf16 v[102:105], v[170:173], v[198:201], v[102:105]
	v_mfma_f32_16x16x32_bf16 v[98:101], v[178:181], v[198:201], v[98:101]
	v_mfma_f32_16x16x32_bf16 v[86:89], v[170:173], v[214:217], v[86:89]
	v_mfma_f32_16x16x32_bf16 v[82:85], v[178:181], v[214:217], v[82:85]
	v_mfma_f32_16x16x32_bf16 v[70:73], v[170:173], v[222:225], v[70:73]
	v_mfma_f32_16x16x32_bf16 v[66:69], v[178:181], v[222:225], v[66:69]
	s_setprio 0
	s_barrier
	s_add_i32 s28, s31, s33
	v_lshl_add_u64 v[202:203], v[202:203], 0, s[12:13]
	s_mov_b32 m0, s28
	ds_read_b128 v[182:185], v168 offset:49152
	ds_read_b128 v[186:189], v168 offset:50176
	ds_read_b128 v[190:193], v168 offset:51200
	ds_read_b128 v[198:201], v168 offset:52224
	ds_read_b128 v[210:213], v168 offset:53248
	ds_read_b128 v[214:217], v168 offset:54272
	ds_read_b128 v[218:221], v168 offset:55296
	ds_read_b128 v[222:225], v168 offset:56320
	global_load_lds_dwordx4 v[202:203], off
	s_add_i32 m0, s28, 0x2000
	s_add_u32 s26, s26, 0x160080
	v_lshl_add_u64 v[202:203], v[206:207], 0, s[12:13]
	s_addc_u32 s27, s27, 0
	s_add_i32 s28, s68, s33
	global_load_lds_dwordx4 v[202:203], off
	s_mov_b32 m0, s28
	s_nop 0
	global_load_lds_dwordx4 v132, s[26:27]
	s_add_i32 m0, s28, 0x2000
	s_nop 0
	global_load_lds_dwordx4 v136, s[26:27]
	v_lshl_add_u64 v[202:203], v[226:227], 0, s[12:13]
	s_mov_b32 m0, s47
	s_nop 0
	global_load_lds_dwordx4 v[202:203], off
	v_lshl_add_u64 v[202:203], v[228:229], 0, s[12:13]
	s_mov_b32 m0, s48
	s_nop 0
	global_load_lds_dwordx4 v[202:203], off
	s_waitcnt vmcnt(8)
	s_waitcnt lgkmcnt(0)
	s_barrier
	s_setprio 1
	s_waitcnt lgkmcnt(0)
	v_mfma_f32_16x16x32_bf16 v[62:65], v[144:147], v[182:185], v[62:65]
	v_mfma_f32_16x16x32_bf16 v[58:61], v[152:155], v[182:185], v[58:61]
	v_mfma_f32_16x16x32_bf16 v[46:49], v[144:147], v[190:193], v[46:49]
	v_mfma_f32_16x16x32_bf16 v[42:45], v[152:155], v[190:193], v[42:45]
	v_mfma_f32_16x16x32_bf16 v[30:33], v[144:147], v[210:213], v[30:33]
	v_mfma_f32_16x16x32_bf16 v[26:29], v[152:155], v[210:213], v[26:29]
	v_mfma_f32_16x16x32_bf16 v[14:17], v[144:147], v[218:221], v[14:17]
	v_mfma_f32_16x16x32_bf16 v[10:13], v[152:155], v[218:221], v[10:13]
	v_mfma_f32_16x16x32_bf16 v[62:65], v[148:151], v[186:189], v[62:65]
	v_mfma_f32_16x16x32_bf16 v[58:61], v[156:159], v[186:189], v[58:61]
	v_mfma_f32_16x16x32_bf16 v[46:49], v[148:151], v[198:201], v[46:49]
	v_mfma_f32_16x16x32_bf16 v[42:45], v[156:159], v[198:201], v[42:45]
	v_mfma_f32_16x16x32_bf16 v[30:33], v[148:151], v[214:217], v[30:33]
	v_mfma_f32_16x16x32_bf16 v[26:29], v[156:159], v[214:217], v[26:29]
	v_mfma_f32_16x16x32_bf16 v[14:17], v[148:151], v[222:225], v[14:17]
	v_mfma_f32_16x16x32_bf16 v[10:13], v[156:159], v[222:225], v[10:13]
	s_setprio 0
	s_setprio 1
	v_mfma_f32_16x16x32_bf16 v[54:57], v[160:163], v[182:185], v[54:57]
	v_mfma_f32_16x16x32_bf16 v[50:53], v[174:177], v[182:185], v[50:53]
	v_mfma_f32_16x16x32_bf16 v[38:41], v[160:163], v[190:193], v[38:41]
	v_mfma_f32_16x16x32_bf16 v[34:37], v[174:177], v[190:193], v[34:37]
	v_mfma_f32_16x16x32_bf16 v[22:25], v[160:163], v[210:213], v[22:25]
	v_mfma_f32_16x16x32_bf16 v[18:21], v[174:177], v[210:213], v[18:21]
	v_mfma_f32_16x16x32_bf16 v[6:9], v[160:163], v[218:221], v[6:9]
	v_mfma_f32_16x16x32_bf16 v[2:5], v[174:177], v[218:221], v[2:5]
	v_mfma_f32_16x16x32_bf16 v[54:57], v[170:173], v[186:189], v[54:57]
	v_mfma_f32_16x16x32_bf16 v[50:53], v[178:181], v[186:189], v[50:53]
	v_mfma_f32_16x16x32_bf16 v[38:41], v[170:173], v[198:201], v[38:41]
	v_mfma_f32_16x16x32_bf16 v[34:37], v[178:181], v[198:201], v[34:37]
	v_mfma_f32_16x16x32_bf16 v[22:25], v[170:173], v[214:217], v[22:25]
	v_mfma_f32_16x16x32_bf16 v[18:21], v[178:181], v[214:217], v[18:21]
	v_mfma_f32_16x16x32_bf16 v[6:9], v[170:173], v[222:225], v[6:9]
	v_mfma_f32_16x16x32_bf16 v[2:5], v[178:181], v[222:225], v[2:5]
	s_setprio 0
	s_barrier
	s_add_u32 s24, s24, 0x100
	s_addc_u32 s25, s25, 0
	s_add_u32 s17, s17, 0x100
	s_addc_u32 s23, s23, 0
	s_cmp_ge_i32 s30, s67
	s_mov_b32 s26, s30
	s_cbranch_scc0 .LBB0_1451
	s_branch .Lpeeldone_6
.LBB0_1451:
	ds_read_b128 v[144:147], v166
	ds_read_b128 v[148:151], v166 offset:1024
	ds_read_b128 v[152:155], v166 offset:2048
	ds_read_b128 v[156:159], v166 offset:3072
	ds_read_b128 v[160:163], v167
	ds_read_b128 v[170:173], v167 offset:1024
	ds_read_b128 v[174:177], v167 offset:2048
	ds_read_b128 v[178:181], v167 offset:3072
	s_add_i32 s30, s26, 2
	s_add_u32 s27, s24, 0xffea0080
	s_addc_u32 s28, s25, -1
	s_cmp_eq_u32 s22, s26
	s_cselect_b32 s26, s20, s17
	s_cselect_b32 s29, s19, s28
	s_cselect_b32 s28, s18, s27
	s_cselect_b32 s27, s21, s23
	s_add_i32 m0, s34, 0xc000
	ds_read_b128 v[182:185], v168
	ds_read_b128 v[186:189], v168 offset:1024
	ds_read_b128 v[190:193], v168 offset:2048
	ds_read_b128 v[198:201], v168 offset:3072
	ds_read_b128 v[210:213], v168 offset:4096
	ds_read_b128 v[214:217], v168 offset:5120
	ds_read_b128 v[218:221], v168 offset:6144
	ds_read_b128 v[222:225], v168 offset:7168
	global_load_lds_dwordx4 v140, s[24:25]
	s_add_i32 m0, s34, 0xe000
	s_nop 0
	global_load_lds_dwordx4 v142, s[24:25]
	s_waitcnt vmcnt(8)
	s_waitcnt lgkmcnt(0)
	s_barrier
	s_setprio 1
	s_waitcnt lgkmcnt(0)
	v_mfma_f32_16x16x32_bf16 v[126:129], v[144:147], v[182:185], v[126:129]
	v_mfma_f32_16x16x32_bf16 v[122:125], v[152:155], v[182:185], v[122:125]
	v_mfma_f32_16x16x32_bf16 v[114:117], v[144:147], v[190:193], v[114:117]
	v_mfma_f32_16x16x32_bf16 v[106:109], v[152:155], v[190:193], v[106:109]
	v_mfma_f32_16x16x32_bf16 v[94:97], v[144:147], v[210:213], v[94:97]
	v_mfma_f32_16x16x32_bf16 v[90:93], v[152:155], v[210:213], v[90:93]
	v_mfma_f32_16x16x32_bf16 v[78:81], v[144:147], v[218:221], v[78:81]
	v_mfma_f32_16x16x32_bf16 v[74:77], v[152:155], v[218:221], v[74:77]
	v_mfma_f32_16x16x32_bf16 v[126:129], v[148:151], v[186:189], v[126:129]
	v_mfma_f32_16x16x32_bf16 v[122:125], v[156:159], v[186:189], v[122:125]
	v_mfma_f32_16x16x32_bf16 v[114:117], v[148:151], v[198:201], v[114:117]
	v_mfma_f32_16x16x32_bf16 v[106:109], v[156:159], v[198:201], v[106:109]
	v_mfma_f32_16x16x32_bf16 v[94:97], v[148:151], v[214:217], v[94:97]
	v_mfma_f32_16x16x32_bf16 v[90:93], v[156:159], v[214:217], v[90:93]
	v_mfma_f32_16x16x32_bf16 v[78:81], v[148:151], v[222:225], v[78:81]
	v_mfma_f32_16x16x32_bf16 v[74:77], v[156:159], v[222:225], v[74:77]
	s_setprio 0
	s_setprio 1
	v_mfma_f32_16x16x32_bf16 v[118:121], v[160:163], v[182:185], v[118:121]
	v_mfma_f32_16x16x32_bf16 v[110:113], v[174:177], v[182:185], v[110:113]
	v_mfma_f32_16x16x32_bf16 v[102:105], v[160:163], v[190:193], v[102:105]
	v_mfma_f32_16x16x32_bf16 v[98:101], v[174:177], v[190:193], v[98:101]
	v_mfma_f32_16x16x32_bf16 v[86:89], v[160:163], v[210:213], v[86:89]
	v_mfma_f32_16x16x32_bf16 v[82:85], v[174:177], v[210:213], v[82:85]
	v_mfma_f32_16x16x32_bf16 v[70:73], v[160:163], v[218:221], v[70:73]
	v_mfma_f32_16x16x32_bf16 v[66:69], v[174:177], v[218:221], v[66:69]
	v_mfma_f32_16x16x32_bf16 v[118:121], v[170:173], v[186:189], v[118:121]
	v_mfma_f32_16x16x32_bf16 v[110:113], v[178:181], v[186:189], v[110:113]
	v_mfma_f32_16x16x32_bf16 v[102:105], v[170:173], v[198:201], v[102:105]
	v_mfma_f32_16x16x32_bf16 v[98:101], v[178:181], v[198:201], v[98:101]
	v_mfma_f32_16x16x32_bf16 v[86:89], v[170:173], v[214:217], v[86:89]
	v_mfma_f32_16x16x32_bf16 v[82:85], v[178:181], v[214:217], v[82:85]
	v_mfma_f32_16x16x32_bf16 v[70:73], v[170:173], v[222:225], v[70:73]
	v_mfma_f32_16x16x32_bf16 v[66:69], v[178:181], v[222:225], v[66:69]
	s_setprio 0
	s_barrier
	s_add_i32 s31, s57, s33
	v_lshl_add_u64 v[202:203], s[26:27], 0, v[132:133]
	s_mov_b32 m0, s31
	ds_read_b128 v[182:185], v168 offset:16384
	ds_read_b128 v[186:189], v168 offset:17408
	ds_read_b128 v[190:193], v168 offset:18432
	ds_read_b128 v[198:201], v168 offset:19456
	ds_read_b128 v[210:213], v168 offset:20480
	ds_read_b128 v[214:217], v168 offset:21504
	ds_read_b128 v[218:221], v168 offset:22528
	ds_read_b128 v[222:225], v168 offset:23552
	global_load_lds_dwordx4 v132, s[26:27]
	s_add_i32 m0, s31, 0x2000
	s_add_u32 s68, s26, 0x160000
	v_lshl_add_u64 v[206:207], s[26:27], 0, v[136:137]
	s_addc_u32 s69, s27, 0
	s_add_i32 s31, s58, s33
	global_load_lds_dwordx4 v136, s[26:27]
	s_mov_b32 m0, s31
	v_lshl_add_u64 v[228:229], s[28:29], 0, v[134:135]
	global_load_lds_dwordx4 v132, s[68:69]
	s_add_i32 m0, s31, 0x2000
	s_nop 0
	global_load_lds_dwordx4 v136, s[68:69]
	v_lshl_add_u64 v[226:227], s[28:29], 0, v[130:131]
	s_mov_b32 m0, s34
	s_nop 0
	global_load_lds_dwordx4 v130, s[28:29]
	s_mov_b32 m0, s35
	s_nop 0
	global_load_lds_dwordx4 v134, s[28:29]
	s_waitcnt vmcnt(8)
	s_waitcnt lgkmcnt(0)
	s_barrier
	s_setprio 1
	s_waitcnt lgkmcnt(0)
	v_mfma_f32_16x16x32_bf16 v[62:65], v[144:147], v[182:185], v[62:65]
	v_mfma_f32_16x16x32_bf16 v[58:61], v[152:155], v[182:185], v[58:61]
	v_mfma_f32_16x16x32_bf16 v[46:49], v[144:147], v[190:193], v[46:49]
	v_mfma_f32_16x16x32_bf16 v[42:45], v[152:155], v[190:193], v[42:45]
	v_mfma_f32_16x16x32_bf16 v[30:33], v[144:147], v[210:213], v[30:33]
	v_mfma_f32_16x16x32_bf16 v[26:29], v[152:155], v[210:213], v[26:29]
	v_mfma_f32_16x16x32_bf16 v[14:17], v[144:147], v[218:221], v[14:17]
	v_mfma_f32_16x16x32_bf16 v[10:13], v[152:155], v[218:221], v[10:13]
	v_mfma_f32_16x16x32_bf16 v[62:65], v[148:151], v[186:189], v[62:65]
	v_mfma_f32_16x16x32_bf16 v[58:61], v[156:159], v[186:189], v[58:61]
	v_mfma_f32_16x16x32_bf16 v[46:49], v[148:151], v[198:201], v[46:49]
	v_mfma_f32_16x16x32_bf16 v[42:45], v[156:159], v[198:201], v[42:45]
	v_mfma_f32_16x16x32_bf16 v[30:33], v[148:151], v[214:217], v[30:33]
	v_mfma_f32_16x16x32_bf16 v[26:29], v[156:159], v[214:217], v[26:29]
	v_mfma_f32_16x16x32_bf16 v[14:17], v[148:151], v[222:225], v[14:17]
	v_mfma_f32_16x16x32_bf16 v[10:13], v[156:159], v[222:225], v[10:13]
	s_setprio 0
	s_setprio 1
	v_mfma_f32_16x16x32_bf16 v[54:57], v[160:163], v[182:185], v[54:57]
	v_mfma_f32_16x16x32_bf16 v[50:53], v[174:177], v[182:185], v[50:53]
	v_mfma_f32_16x16x32_bf16 v[38:41], v[160:163], v[190:193], v[38:41]
	v_mfma_f32_16x16x32_bf16 v[34:37], v[174:177], v[190:193], v[34:37]
	v_mfma_f32_16x16x32_bf16 v[22:25], v[160:163], v[210:213], v[22:25]
	v_mfma_f32_16x16x32_bf16 v[18:21], v[174:177], v[210:213], v[18:21]
	v_mfma_f32_16x16x32_bf16 v[6:9], v[160:163], v[218:221], v[6:9]
	v_mfma_f32_16x16x32_bf16 v[2:5], v[174:177], v[218:221], v[2:5]
	v_mfma_f32_16x16x32_bf16 v[54:57], v[170:173], v[186:189], v[54:57]
	v_mfma_f32_16x16x32_bf16 v[50:53], v[178:181], v[186:189], v[50:53]
	v_mfma_f32_16x16x32_bf16 v[38:41], v[170:173], v[198:201], v[38:41]
	v_mfma_f32_16x16x32_bf16 v[34:37], v[178:181], v[198:201], v[34:37]
	v_mfma_f32_16x16x32_bf16 v[22:25], v[170:173], v[214:217], v[22:25]
	v_mfma_f32_16x16x32_bf16 v[18:21], v[178:181], v[214:217], v[18:21]
	v_mfma_f32_16x16x32_bf16 v[6:9], v[170:173], v[222:225], v[6:9]
	v_mfma_f32_16x16x32_bf16 v[2:5], v[178:181], v[222:225], v[2:5]
	s_setprio 0
	s_barrier
	s_add_i32 s31, 0, 0x18000
	s_add_i32 s68, 0, 0x1c000
	v_add_u32_e32 v156, s31, v164
	v_add_u32_e32 v169, s68, v164
	ds_read_b128 v[144:147], v156
	ds_read_b128 v[148:151], v156 offset:1024
	ds_read_b128 v[152:155], v156 offset:2048
	ds_read_b128 v[156:159], v156 offset:3072
	ds_read_b128 v[160:163], v169
	ds_read_b128 v[170:173], v169 offset:1024
	ds_read_b128 v[174:177], v169 offset:2048
	ds_read_b128 v[178:181], v169 offset:3072
	s_add_u32 s28, s28, 0x160000
	s_addc_u32 s29, s29, 0
	s_mov_b32 m0, s36
	ds_read_b128 v[182:185], v168 offset:32768
	ds_read_b128 v[186:189], v168 offset:33792
	ds_read_b128 v[190:193], v168 offset:34816
	ds_read_b128 v[198:201], v168 offset:35840
	ds_read_b128 v[210:213], v168 offset:36864
	ds_read_b128 v[214:217], v168 offset:37888
	ds_read_b128 v[218:221], v168 offset:38912
	ds_read_b128 v[222:225], v168 offset:39936
	global_load_lds_dwordx4 v130, s[28:29]
	v_lshl_add_u64 v[230:231], s[28:29], 0, v[134:135]
	s_mov_b32 m0, s37
	s_nop 0
	global_load_lds_dwordx4 v134, s[28:29]
	s_waitcnt vmcnt(8)
	s_waitcnt lgkmcnt(0)
	s_barrier
	s_setprio 1
	s_waitcnt lgkmcnt(0)
	v_mfma_f32_16x16x32_bf16 v[126:129], v[144:147], v[182:185], v[126:129]
	v_mfma_f32_16x16x32_bf16 v[122:125], v[152:155], v[182:185], v[122:125]
	v_mfma_f32_16x16x32_bf16 v[114:117], v[144:147], v[190:193], v[114:117]
	v_mfma_f32_16x16x32_bf16 v[106:109], v[152:155], v[190:193], v[106:109]
	v_mfma_f32_16x16x32_bf16 v[94:97], v[144:147], v[210:213], v[94:97]
	v_mfma_f32_16x16x32_bf16 v[90:93], v[152:155], v[210:213], v[90:93]
	v_mfma_f32_16x16x32_bf16 v[78:81], v[144:147], v[218:221], v[78:81]
	v_mfma_f32_16x16x32_bf16 v[74:77], v[152:155], v[218:221], v[74:77]
	v_mfma_f32_16x16x32_bf16 v[126:129], v[148:151], v[186:189], v[126:129]
	v_mfma_f32_16x16x32_bf16 v[122:125], v[156:159], v[186:189], v[122:125]
	v_mfma_f32_16x16x32_bf16 v[114:117], v[148:151], v[198:201], v[114:117]
	v_mfma_f32_16x16x32_bf16 v[106:109], v[156:159], v[198:201], v[106:109]
	v_mfma_f32_16x16x32_bf16 v[94:97], v[148:151], v[214:217], v[94:97]
	v_mfma_f32_16x16x32_bf16 v[90:93], v[156:159], v[214:217], v[90:93]
	v_mfma_f32_16x16x32_bf16 v[78:81], v[148:151], v[222:225], v[78:81]
	v_mfma_f32_16x16x32_bf16 v[74:77], v[156:159], v[222:225], v[74:77]
	s_setprio 0
	s_setprio 1
	v_mfma_f32_16x16x32_bf16 v[118:121], v[160:163], v[182:185], v[118:121]
	v_mfma_f32_16x16x32_bf16 v[110:113], v[174:177], v[182:185], v[110:113]
	v_mfma_f32_16x16x32_bf16 v[102:105], v[160:163], v[190:193], v[102:105]
	v_mfma_f32_16x16x32_bf16 v[98:101], v[174:177], v[190:193], v[98:101]
	v_mfma_f32_16x16x32_bf16 v[86:89], v[160:163], v[210:213], v[86:89]
	v_mfma_f32_16x16x32_bf16 v[82:85], v[174:177], v[210:213], v[82:85]
	v_mfma_f32_16x16x32_bf16 v[70:73], v[160:163], v[218:221], v[70:73]
	v_mfma_f32_16x16x32_bf16 v[66:69], v[174:177], v[218:221], v[66:69]
	v_mfma_f32_16x16x32_bf16 v[118:121], v[170:173], v[186:189], v[118:121]
	v_mfma_f32_16x16x32_bf16 v[110:113], v[178:181], v[186:189], v[110:113]
	v_mfma_f32_16x16x32_bf16 v[102:105], v[170:173], v[198:201], v[102:105]
	v_mfma_f32_16x16x32_bf16 v[98:101], v[178:181], v[198:201], v[98:101]
	v_mfma_f32_16x16x32_bf16 v[86:89], v[170:173], v[214:217], v[86:89]
	v_mfma_f32_16x16x32_bf16 v[82:85], v[178:181], v[214:217], v[82:85]
	v_mfma_f32_16x16x32_bf16 v[70:73], v[170:173], v[222:225], v[70:73]
	v_mfma_f32_16x16x32_bf16 v[66:69], v[178:181], v[222:225], v[66:69]
	s_setprio 0
	s_barrier
	s_add_i32 s28, s31, s33
	v_lshl_add_u64 v[202:203], v[202:203], 0, s[12:13]
	s_mov_b32 m0, s28
	ds_read_b128 v[182:185], v168 offset:49152
	ds_read_b128 v[186:189], v168 offset:50176
	ds_read_b128 v[190:193], v168 offset:51200
	ds_read_b128 v[198:201], v168 offset:52224
	ds_read_b128 v[210:213], v168 offset:53248
	ds_read_b128 v[214:217], v168 offset:54272
	ds_read_b128 v[218:221], v168 offset:55296
	ds_read_b128 v[222:225], v168 offset:56320
	global_load_lds_dwordx4 v[202:203], off
	s_add_i32 m0, s28, 0x2000
	s_add_u32 s26, s26, 0x160080
	v_lshl_add_u64 v[202:203], v[206:207], 0, s[12:13]
	s_addc_u32 s27, s27, 0
	s_add_i32 s28, s68, s33
	global_load_lds_dwordx4 v[202:203], off
	s_mov_b32 m0, s28
	s_nop 0
	global_load_lds_dwordx4 v132, s[26:27]
	s_add_i32 m0, s28, 0x2000
	s_nop 0
	global_load_lds_dwordx4 v136, s[26:27]
	v_lshl_add_u64 v[202:203], v[226:227], 0, s[12:13]
	s_mov_b32 m0, s47
	s_nop 0
	global_load_lds_dwordx4 v[202:203], off
	v_lshl_add_u64 v[202:203], v[228:229], 0, s[12:13]
	s_mov_b32 m0, s48
	s_nop 0
	global_load_lds_dwordx4 v[202:203], off
	s_waitcnt vmcnt(8)
	s_waitcnt lgkmcnt(0)
	s_barrier
	s_setprio 1
	s_waitcnt lgkmcnt(0)
	v_mfma_f32_16x16x32_bf16 v[62:65], v[144:147], v[182:185], v[62:65]
	v_mfma_f32_16x16x32_bf16 v[58:61], v[152:155], v[182:185], v[58:61]
	v_mfma_f32_16x16x32_bf16 v[46:49], v[144:147], v[190:193], v[46:49]
	v_mfma_f32_16x16x32_bf16 v[42:45], v[152:155], v[190:193], v[42:45]
	v_mfma_f32_16x16x32_bf16 v[30:33], v[144:147], v[210:213], v[30:33]
	v_mfma_f32_16x16x32_bf16 v[26:29], v[152:155], v[210:213], v[26:29]
	v_mfma_f32_16x16x32_bf16 v[14:17], v[144:147], v[218:221], v[14:17]
	v_mfma_f32_16x16x32_bf16 v[10:13], v[152:155], v[218:221], v[10:13]
	v_mfma_f32_16x16x32_bf16 v[62:65], v[148:151], v[186:189], v[62:65]
	v_mfma_f32_16x16x32_bf16 v[58:61], v[156:159], v[186:189], v[58:61]
	v_mfma_f32_16x16x32_bf16 v[46:49], v[148:151], v[198:201], v[46:49]
	v_mfma_f32_16x16x32_bf16 v[42:45], v[156:159], v[198:201], v[42:45]
	v_mfma_f32_16x16x32_bf16 v[30:33], v[148:151], v[214:217], v[30:33]
	v_mfma_f32_16x16x32_bf16 v[26:29], v[156:159], v[214:217], v[26:29]
	v_mfma_f32_16x16x32_bf16 v[14:17], v[148:151], v[222:225], v[14:17]
	v_mfma_f32_16x16x32_bf16 v[10:13], v[156:159], v[222:225], v[10:13]
	s_setprio 0
	s_setprio 1
	v_mfma_f32_16x16x32_bf16 v[54:57], v[160:163], v[182:185], v[54:57]
	v_mfma_f32_16x16x32_bf16 v[50:53], v[174:177], v[182:185], v[50:53]
	v_mfma_f32_16x16x32_bf16 v[38:41], v[160:163], v[190:193], v[38:41]
	v_mfma_f32_16x16x32_bf16 v[34:37], v[174:177], v[190:193], v[34:37]
	v_mfma_f32_16x16x32_bf16 v[22:25], v[160:163], v[210:213], v[22:25]
	v_mfma_f32_16x16x32_bf16 v[18:21], v[174:177], v[210:213], v[18:21]
	v_mfma_f32_16x16x32_bf16 v[6:9], v[160:163], v[218:221], v[6:9]
	v_mfma_f32_16x16x32_bf16 v[2:5], v[174:177], v[218:221], v[2:5]
	v_mfma_f32_16x16x32_bf16 v[54:57], v[170:173], v[186:189], v[54:57]
	v_mfma_f32_16x16x32_bf16 v[50:53], v[178:181], v[186:189], v[50:53]
	v_mfma_f32_16x16x32_bf16 v[38:41], v[170:173], v[198:201], v[38:41]
	v_mfma_f32_16x16x32_bf16 v[34:37], v[178:181], v[198:201], v[34:37]
	v_mfma_f32_16x16x32_bf16 v[22:25], v[170:173], v[214:217], v[22:25]
	v_mfma_f32_16x16x32_bf16 v[18:21], v[178:181], v[214:217], v[18:21]
	v_mfma_f32_16x16x32_bf16 v[6:9], v[170:173], v[222:225], v[6:9]
	v_mfma_f32_16x16x32_bf16 v[2:5], v[178:181], v[222:225], v[2:5]
	s_setprio 0
	s_barrier
	s_add_u32 s24, s24, 0x100
	s_addc_u32 s25, s25, 0
	s_add_u32 s17, s17, 0x100
	s_addc_u32 s23, s23, 0
	s_cmp_ge_i32 s30, s67
	s_mov_b32 s26, s30
	s_cbranch_scc0 .LBB0_1451

.Lpeel_3:
	s_add_i32 s29, s23, 2
	s_add_u32 s34, s30, 0xfff80080
	s_addc_u32 s35, s31, -1
	s_cmp_eq_u32 s28, s23
	s_cselect_b32 s37, s25, s35
	s_cselect_b32 s36, s24, s34
	s_cselect_b32 s35, s27, s21
	s_cselect_b32 s34, s26, s19
	s_add_i32 m0, s15, 0xc000
	global_load_lds_dwordx4 v140, s[30:31]
	s_add_i32 m0, s15, 0xe000
	s_nop 0
	global_load_lds_dwordx4 v142, s[30:31]
	s_waitcnt vmcnt(8)
	s_waitcnt lgkmcnt(0)
	s_barrier
	s_setprio 1
	s_waitcnt lgkmcnt(0)
	v_mfma_f32_16x16x32_bf16 v[126:129], v[150:153], v[182:185], 0
	v_mfma_f32_16x16x32_bf16 v[122:125], v[158:161], v[182:185], 0
	v_mfma_f32_16x16x32_bf16 v[118:121], v[150:153], v[190:193], 0
	v_mfma_f32_16x16x32_bf16 v[114:117], v[158:161], v[190:193], 0
	v_mfma_f32_16x16x32_bf16 v[110:113], v[150:153], v[210:213], 0
	v_mfma_f32_16x16x32_bf16 v[106:109], v[158:161], v[210:213], 0
	v_mfma_f32_16x16x32_bf16 v[102:105], v[150:153], v[218:221], 0
	v_mfma_f32_16x16x32_bf16 v[98:101], v[158:161], v[218:221], 0
	v_mfma_f32_16x16x32_bf16 v[126:129], v[154:157], v[186:189], v[126:129]
	v_mfma_f32_16x16x32_bf16 v[122:125], v[162:165], v[186:189], v[122:125]
	v_mfma_f32_16x16x32_bf16 v[118:121], v[154:157], v[198:201], v[118:121]
	v_mfma_f32_16x16x32_bf16 v[114:117], v[162:165], v[198:201], v[114:117]
	v_mfma_f32_16x16x32_bf16 v[110:113], v[154:157], v[214:217], v[110:113]
	v_mfma_f32_16x16x32_bf16 v[106:109], v[162:165], v[214:217], v[106:109]
	v_mfma_f32_16x16x32_bf16 v[102:105], v[154:157], v[222:225], v[102:105]
	v_mfma_f32_16x16x32_bf16 v[98:101], v[162:165], v[222:225], v[98:101]
	s_setprio 0
	s_setprio 1
	v_mfma_f32_16x16x32_bf16 v[94:97], v[166:169], v[182:185], 0
	v_mfma_f32_16x16x32_bf16 v[90:93], v[174:177], v[182:185], 0
	v_mfma_f32_16x16x32_bf16 v[86:89], v[166:169], v[190:193], 0
	v_mfma_f32_16x16x32_bf16 v[82:85], v[174:177], v[190:193], 0
	v_mfma_f32_16x16x32_bf16 v[78:81], v[166:169], v[210:213], 0
	v_mfma_f32_16x16x32_bf16 v[74:77], v[174:177], v[210:213], 0
	v_mfma_f32_16x16x32_bf16 v[70:73], v[166:169], v[218:221], 0
	v_mfma_f32_16x16x32_bf16 v[66:69], v[174:177], v[218:221], 0
	v_mfma_f32_16x16x32_bf16 v[94:97], v[170:173], v[186:189], v[94:97]
	v_mfma_f32_16x16x32_bf16 v[90:93], v[178:181], v[186:189], v[90:93]
	v_mfma_f32_16x16x32_bf16 v[86:89], v[170:173], v[198:201], v[86:89]
	v_mfma_f32_16x16x32_bf16 v[82:85], v[178:181], v[198:201], v[82:85]
	v_mfma_f32_16x16x32_bf16 v[78:81], v[170:173], v[214:217], v[78:81]
	v_mfma_f32_16x16x32_bf16 v[74:77], v[178:181], v[214:217], v[74:77]
	v_mfma_f32_16x16x32_bf16 v[70:73], v[170:173], v[222:225], v[70:73]
	v_mfma_f32_16x16x32_bf16 v[66:69], v[178:181], v[222:225], v[66:69]
	s_setprio 0
	s_barrier
	s_add_i32 s23, s60, s33
	v_lshl_add_u64 v[202:203], s[34:35], 0, v[132:133]
	s_mov_b32 m0, s23
	ds_read_b128 v[182:185], v148 offset:16384
	ds_read_b128 v[186:189], v148 offset:17408
	ds_read_b128 v[190:193], v148 offset:18432
	ds_read_b128 v[198:201], v148 offset:19456
	ds_read_b128 v[210:213], v148 offset:20480
	ds_read_b128 v[214:217], v148 offset:21504
	ds_read_b128 v[218:221], v148 offset:22528
	ds_read_b128 v[222:225], v148 offset:23552
	global_load_lds_dwordx4 v132, s[34:35]
	s_add_i32 m0, s23, 0x2000
	s_add_u32 s38, s34, 0x80000
	v_lshl_add_u64 v[206:207], s[34:35], 0, v[136:137]
	s_addc_u32 s39, s35, 0
	s_add_i32 s23, s61, s33
	global_load_lds_dwordx4 v136, s[34:35]
	s_mov_b32 m0, s23
	v_lshl_add_u64 v[228:229], s[36:37], 0, v[134:135]
	global_load_lds_dwordx4 v132, s[38:39]
	s_add_i32 m0, s23, 0x2000
	s_nop 0
	global_load_lds_dwordx4 v136, s[38:39]
	v_lshl_add_u64 v[226:227], s[36:37], 0, v[130:131]
	s_mov_b32 m0, s15
	s_nop 0
	global_load_lds_dwordx4 v130, s[36:37]
	s_mov_b32 m0, s41
	s_nop 0
	global_load_lds_dwordx4 v134, s[36:37]
	s_waitcnt vmcnt(8)
	s_waitcnt lgkmcnt(0)
	s_barrier
	s_setprio 1
	s_waitcnt lgkmcnt(0)
	v_mfma_f32_16x16x32_bf16 v[62:65], v[150:153], v[182:185], 0
	v_mfma_f32_16x16x32_bf16 v[58:61], v[158:161], v[182:185], 0
	v_mfma_f32_16x16x32_bf16 v[54:57], v[150:153], v[190:193], 0
	v_mfma_f32_16x16x32_bf16 v[50:53], v[158:161], v[190:193], 0
	v_mfma_f32_16x16x32_bf16 v[46:49], v[150:153], v[210:213], 0
	v_mfma_f32_16x16x32_bf16 v[42:45], v[158:161], v[210:213], 0
	v_mfma_f32_16x16x32_bf16 v[38:41], v[150:153], v[218:221], 0
	v_mfma_f32_16x16x32_bf16 v[34:37], v[158:161], v[218:221], 0
	v_mfma_f32_16x16x32_bf16 v[62:65], v[154:157], v[186:189], v[62:65]
	v_mfma_f32_16x16x32_bf16 v[58:61], v[162:165], v[186:189], v[58:61]
	v_mfma_f32_16x16x32_bf16 v[54:57], v[154:157], v[198:201], v[54:57]
	v_mfma_f32_16x16x32_bf16 v[50:53], v[162:165], v[198:201], v[50:53]
	v_mfma_f32_16x16x32_bf16 v[46:49], v[154:157], v[214:217], v[46:49]
	v_mfma_f32_16x16x32_bf16 v[42:45], v[162:165], v[214:217], v[42:45]
	v_mfma_f32_16x16x32_bf16 v[38:41], v[154:157], v[222:225], v[38:41]
	v_mfma_f32_16x16x32_bf16 v[34:37], v[162:165], v[222:225], v[34:37]
	s_setprio 0
	s_setprio 1
	v_mfma_f32_16x16x32_bf16 v[30:33], v[166:169], v[182:185], 0
	v_mfma_f32_16x16x32_bf16 v[26:29], v[174:177], v[182:185], 0
	v_mfma_f32_16x16x32_bf16 v[22:25], v[166:169], v[190:193], 0
	v_mfma_f32_16x16x32_bf16 v[18:21], v[174:177], v[190:193], 0
	v_mfma_f32_16x16x32_bf16 v[14:17], v[166:169], v[210:213], 0
	v_mfma_f32_16x16x32_bf16 v[10:13], v[174:177], v[210:213], 0
	v_mfma_f32_16x16x32_bf16 v[6:9], v[166:169], v[218:221], 0
	v_mfma_f32_16x16x32_bf16 v[2:5], v[174:177], v[218:221], 0
	v_mfma_f32_16x16x32_bf16 v[30:33], v[170:173], v[186:189], v[30:33]
	v_mfma_f32_16x16x32_bf16 v[26:29], v[178:181], v[186:189], v[26:29]
	v_mfma_f32_16x16x32_bf16 v[22:25], v[170:173], v[198:201], v[22:25]
	v_mfma_f32_16x16x32_bf16 v[18:21], v[178:181], v[198:201], v[18:21]
	v_mfma_f32_16x16x32_bf16 v[14:17], v[170:173], v[214:217], v[14:17]
	v_mfma_f32_16x16x32_bf16 v[10:13], v[178:181], v[214:217], v[10:13]
	v_mfma_f32_16x16x32_bf16 v[6:9], v[170:173], v[222:225], v[6:9]
	v_mfma_f32_16x16x32_bf16 v[2:5], v[178:181], v[222:225], v[2:5]
	s_setprio 0
	s_barrier
	s_add_i32 s23, 0, 0x18000
	v_add_u32_e32 v149, s23, v144
	s_add_i32 s38, 0, 0x1c000
	ds_read_b128 v[150:153], v149
	ds_read_b128 v[154:157], v149 offset:1024
	ds_read_b128 v[158:161], v149 offset:2048
	ds_read_b128 v[162:165], v149 offset:3072
	v_add_u32_e32 v149, s38, v144
	ds_read_b128 v[166:169], v149
	ds_read_b128 v[170:173], v149 offset:1024
	ds_read_b128 v[174:177], v149 offset:2048
	ds_read_b128 v[178:181], v149 offset:3072
	s_add_u32 s36, s36, 0x80000
	s_addc_u32 s37, s37, 0
	s_mov_b32 m0, s42
	ds_read_b128 v[182:185], v148 offset:32768
	ds_read_b128 v[186:189], v148 offset:33792
	ds_read_b128 v[190:193], v148 offset:34816
	ds_read_b128 v[198:201], v148 offset:35840
	ds_read_b128 v[210:213], v148 offset:36864
	ds_read_b128 v[214:217], v148 offset:37888
	ds_read_b128 v[218:221], v148 offset:38912
	ds_read_b128 v[222:225], v148 offset:39936
	global_load_lds_dwordx4 v130, s[36:37]
	v_lshl_add_u64 v[230:231], s[36:37], 0, v[134:135]
	s_mov_b32 m0, s43
	s_nop 0
	global_load_lds_dwordx4 v134, s[36:37]
	s_waitcnt vmcnt(8)
	s_waitcnt lgkmcnt(0)
	s_barrier
	s_setprio 1
	s_waitcnt lgkmcnt(0)
	v_mfma_f32_16x16x32_bf16 v[126:129], v[150:153], v[182:185], v[126:129]
	v_mfma_f32_16x16x32_bf16 v[122:125], v[158:161], v[182:185], v[122:125]
	v_mfma_f32_16x16x32_bf16 v[118:121], v[150:153], v[190:193], v[118:121]
	v_mfma_f32_16x16x32_bf16 v[114:117], v[158:161], v[190:193], v[114:117]
	v_mfma_f32_16x16x32_bf16 v[110:113], v[150:153], v[210:213], v[110:113]
	v_mfma_f32_16x16x32_bf16 v[106:109], v[158:161], v[210:213], v[106:109]
	v_mfma_f32_16x16x32_bf16 v[102:105], v[150:153], v[218:221], v[102:105]
	v_mfma_f32_16x16x32_bf16 v[98:101], v[158:161], v[218:221], v[98:101]
	v_mfma_f32_16x16x32_bf16 v[126:129], v[154:157], v[186:189], v[126:129]
	v_mfma_f32_16x16x32_bf16 v[122:125], v[162:165], v[186:189], v[122:125]
	v_mfma_f32_16x16x32_bf16 v[118:121], v[154:157], v[198:201], v[118:121]
	v_mfma_f32_16x16x32_bf16 v[114:117], v[162:165], v[198:201], v[114:117]
	v_mfma_f32_16x16x32_bf16 v[110:113], v[154:157], v[214:217], v[110:113]
	v_mfma_f32_16x16x32_bf16 v[106:109], v[162:165], v[214:217], v[106:109]
	v_mfma_f32_16x16x32_bf16 v[102:105], v[154:157], v[222:225], v[102:105]
	v_mfma_f32_16x16x32_bf16 v[98:101], v[162:165], v[222:225], v[98:101]
	s_setprio 0
	s_setprio 1
	v_mfma_f32_16x16x32_bf16 v[94:97], v[166:169], v[182:185], v[94:97]
	v_mfma_f32_16x16x32_bf16 v[90:93], v[174:177], v[182:185], v[90:93]
	v_mfma_f32_16x16x32_bf16 v[86:89], v[166:169], v[190:193], v[86:89]
	v_mfma_f32_16x16x32_bf16 v[82:85], v[174:177], v[190:193], v[82:85]
	v_mfma_f32_16x16x32_bf16 v[78:81], v[166:169], v[210:213], v[78:81]
	v_mfma_f32_16x16x32_bf16 v[74:77], v[174:177], v[210:213], v[74:77]
	v_mfma_f32_16x16x32_bf16 v[70:73], v[166:169], v[218:221], v[70:73]
	v_mfma_f32_16x16x32_bf16 v[66:69], v[174:177], v[218:221], v[66:69]
	v_mfma_f32_16x16x32_bf16 v[94:97], v[170:173], v[186:189], v[94:97]
	v_mfma_f32_16x16x32_bf16 v[90:93], v[178:181], v[186:189], v[90:93]
	v_mfma_f32_16x16x32_bf16 v[86:89], v[170:173], v[198:201], v[86:89]
	v_mfma_f32_16x16x32_bf16 v[82:85], v[178:181], v[198:201], v[82:85]
	v_mfma_f32_16x16x32_bf16 v[78:81], v[170:173], v[214:217], v[78:81]
	v_mfma_f32_16x16x32_bf16 v[74:77], v[178:181], v[214:217], v[74:77]
	v_mfma_f32_16x16x32_bf16 v[70:73], v[170:173], v[222:225], v[70:73]
	v_mfma_f32_16x16x32_bf16 v[66:69], v[178:181], v[222:225], v[66:69]
	s_setprio 0
	s_barrier
	s_add_i32 s23, s23, s33
	v_lshl_add_u64 v[202:203], v[202:203], 0, s[10:11]
	s_mov_b32 m0, s23
	ds_read_b128 v[182:185], v148 offset:49152
	ds_read_b128 v[186:189], v148 offset:50176
	ds_read_b128 v[190:193], v148 offset:51200
	ds_read_b128 v[198:201], v148 offset:52224
	ds_read_b128 v[210:213], v148 offset:53248
	ds_read_b128 v[214:217], v148 offset:54272
	ds_read_b128 v[218:221], v148 offset:55296
	ds_read_b128 v[222:225], v148 offset:56320
	global_load_lds_dwordx4 v[202:203], off
	s_add_i32 m0, s23, 0x2000
	s_add_u32 s34, s34, 0x80080
	v_lshl_add_u64 v[202:203], v[206:207], 0, s[10:11]
	s_addc_u32 s35, s35, 0
	s_add_i32 s23, s38, s33
	global_load_lds_dwordx4 v[202:203], off
	s_mov_b32 m0, s23
	s_nop 0
	global_load_lds_dwordx4 v132, s[34:35]
	s_add_i32 m0, s23, 0x2000
	s_nop 0
	global_load_lds_dwordx4 v136, s[34:35]
	v_lshl_add_u64 v[202:203], v[226:227], 0, s[10:11]
	s_mov_b32 m0, s51
	s_nop 0
	global_load_lds_dwordx4 v[202:203], off
	v_lshl_add_u64 v[202:203], v[228:229], 0, s[10:11]
	s_mov_b32 m0, s52
	s_nop 0
	global_load_lds_dwordx4 v[202:203], off
	s_waitcnt vmcnt(8)
	s_waitcnt lgkmcnt(0)
	s_barrier
	s_setprio 1
	s_waitcnt lgkmcnt(0)
	v_mfma_f32_16x16x32_bf16 v[62:65], v[150:153], v[182:185], v[62:65]
	v_mfma_f32_16x16x32_bf16 v[58:61], v[158:161], v[182:185], v[58:61]
	v_mfma_f32_16x16x32_bf16 v[54:57], v[150:153], v[190:193], v[54:57]
	v_mfma_f32_16x16x32_bf16 v[50:53], v[158:161], v[190:193], v[50:53]
	v_mfma_f32_16x16x32_bf16 v[46:49], v[150:153], v[210:213], v[46:49]
	v_mfma_f32_16x16x32_bf16 v[42:45], v[158:161], v[210:213], v[42:45]
	v_mfma_f32_16x16x32_bf16 v[38:41], v[150:153], v[218:221], v[38:41]
	v_mfma_f32_16x16x32_bf16 v[34:37], v[158:161], v[218:221], v[34:37]
	v_mfma_f32_16x16x32_bf16 v[62:65], v[154:157], v[186:189], v[62:65]
	v_mfma_f32_16x16x32_bf16 v[58:61], v[162:165], v[186:189], v[58:61]
	v_mfma_f32_16x16x32_bf16 v[54:57], v[154:157], v[198:201], v[54:57]
	v_mfma_f32_16x16x32_bf16 v[50:53], v[162:165], v[198:201], v[50:53]
	v_mfma_f32_16x16x32_bf16 v[46:49], v[154:157], v[214:217], v[46:49]
	v_mfma_f32_16x16x32_bf16 v[42:45], v[162:165], v[214:217], v[42:45]
	v_mfma_f32_16x16x32_bf16 v[38:41], v[154:157], v[222:225], v[38:41]
	v_mfma_f32_16x16x32_bf16 v[34:37], v[162:165], v[222:225], v[34:37]
	s_setprio 0
	s_setprio 1
	v_mfma_f32_16x16x32_bf16 v[30:33], v[166:169], v[182:185], v[30:33]
	v_mfma_f32_16x16x32_bf16 v[26:29], v[174:177], v[182:185], v[26:29]
	v_mfma_f32_16x16x32_bf16 v[22:25], v[166:169], v[190:193], v[22:25]
	v_mfma_f32_16x16x32_bf16 v[18:21], v[174:177], v[190:193], v[18:21]
	v_mfma_f32_16x16x32_bf16 v[14:17], v[166:169], v[210:213], v[14:17]
	v_mfma_f32_16x16x32_bf16 v[10:13], v[174:177], v[210:213], v[10:13]
	v_mfma_f32_16x16x32_bf16 v[6:9], v[166:169], v[218:221], v[6:9]
	v_mfma_f32_16x16x32_bf16 v[2:5], v[174:177], v[218:221], v[2:5]
	v_mfma_f32_16x16x32_bf16 v[30:33], v[170:173], v[186:189], v[30:33]
	v_mfma_f32_16x16x32_bf16 v[26:29], v[178:181], v[186:189], v[26:29]
	v_mfma_f32_16x16x32_bf16 v[22:25], v[170:173], v[198:201], v[22:25]
	v_mfma_f32_16x16x32_bf16 v[18:21], v[178:181], v[198:201], v[18:21]
	v_mfma_f32_16x16x32_bf16 v[14:17], v[170:173], v[214:217], v[14:17]
	v_mfma_f32_16x16x32_bf16 v[10:13], v[178:181], v[214:217], v[10:13]
	v_mfma_f32_16x16x32_bf16 v[6:9], v[170:173], v[222:225], v[6:9]
	v_mfma_f32_16x16x32_bf16 v[2:5], v[178:181], v[222:225], v[2:5]
	s_setprio 0
	s_barrier
	s_add_u32 s30, s30, 0x100
	s_addc_u32 s31, s31, 0
	s_add_u32 s19, s19, 0x100
	s_addc_u32 s21, s21, 0
	s_cmp_ge_i32 s29, s68
	s_mov_b32 s23, s29
	s_cbranch_scc0 .LBB0_1973
	s_branch .Lpeeldone_3
.LBB0_1973:
	ds_read_b128 v[150:153], v146
	ds_read_b128 v[154:157], v146 offset:1024
	ds_read_b128 v[158:161], v146 offset:2048
	ds_read_b128 v[162:165], v146 offset:3072
	ds_read_b128 v[166:169], v147
	ds_read_b128 v[170:173], v147 offset:1024
	ds_read_b128 v[174:177], v147 offset:2048
	ds_read_b128 v[178:181], v147 offset:3072
	s_add_i32 s29, s23, 2
	s_add_u32 s34, s30, 0xfff80080
	s_addc_u32 s35, s31, -1
	s_cmp_eq_u32 s28, s23
	s_cselect_b32 s37, s25, s35
	s_cselect_b32 s36, s24, s34
	s_cselect_b32 s35, s27, s21
	s_cselect_b32 s34, s26, s19
	s_add_i32 m0, s15, 0xc000
	ds_read_b128 v[182:185], v148
	ds_read_b128 v[186:189], v148 offset:1024
	ds_read_b128 v[190:193], v148 offset:2048
	ds_read_b128 v[198:201], v148 offset:3072
	ds_read_b128 v[210:213], v148 offset:4096
	ds_read_b128 v[214:217], v148 offset:5120
	ds_read_b128 v[218:221], v148 offset:6144
	ds_read_b128 v[222:225], v148 offset:7168
	global_load_lds_dwordx4 v140, s[30:31]
	s_add_i32 m0, s15, 0xe000
	s_nop 0
	global_load_lds_dwordx4 v142, s[30:31]
	s_waitcnt vmcnt(8)
	s_waitcnt lgkmcnt(0)
	s_barrier
	s_setprio 1
	s_waitcnt lgkmcnt(0)
	v_mfma_f32_16x16x32_bf16 v[126:129], v[150:153], v[182:185], v[126:129]
	v_mfma_f32_16x16x32_bf16 v[122:125], v[158:161], v[182:185], v[122:125]
	v_mfma_f32_16x16x32_bf16 v[118:121], v[150:153], v[190:193], v[118:121]
	v_mfma_f32_16x16x32_bf16 v[114:117], v[158:161], v[190:193], v[114:117]
	v_mfma_f32_16x16x32_bf16 v[110:113], v[150:153], v[210:213], v[110:113]
	v_mfma_f32_16x16x32_bf16 v[106:109], v[158:161], v[210:213], v[106:109]
	v_mfma_f32_16x16x32_bf16 v[102:105], v[150:153], v[218:221], v[102:105]
	v_mfma_f32_16x16x32_bf16 v[98:101], v[158:161], v[218:221], v[98:101]
	v_mfma_f32_16x16x32_bf16 v[126:129], v[154:157], v[186:189], v[126:129]
	v_mfma_f32_16x16x32_bf16 v[122:125], v[162:165], v[186:189], v[122:125]
	v_mfma_f32_16x16x32_bf16 v[118:121], v[154:157], v[198:201], v[118:121]
	v_mfma_f32_16x16x32_bf16 v[114:117], v[162:165], v[198:201], v[114:117]
	v_mfma_f32_16x16x32_bf16 v[110:113], v[154:157], v[214:217], v[110:113]
	v_mfma_f32_16x16x32_bf16 v[106:109], v[162:165], v[214:217], v[106:109]
	v_mfma_f32_16x16x32_bf16 v[102:105], v[154:157], v[222:225], v[102:105]
	v_mfma_f32_16x16x32_bf16 v[98:101], v[162:165], v[222:225], v[98:101]
	s_setprio 0
	s_setprio 1
	v_mfma_f32_16x16x32_bf16 v[94:97], v[166:169], v[182:185], v[94:97]
	v_mfma_f32_16x16x32_bf16 v[90:93], v[174:177], v[182:185], v[90:93]
	v_mfma_f32_16x16x32_bf16 v[86:89], v[166:169], v[190:193], v[86:89]
	v_mfma_f32_16x16x32_bf16 v[82:85], v[174:177], v[190:193], v[82:85]
	v_mfma_f32_16x16x32_bf16 v[78:81], v[166:169], v[210:213], v[78:81]
	v_mfma_f32_16x16x32_bf16 v[74:77], v[174:177], v[210:213], v[74:77]
	v_mfma_f32_16x16x32_bf16 v[70:73], v[166:169], v[218:221], v[70:73]
	v_mfma_f32_16x16x32_bf16 v[66:69], v[174:177], v[218:221], v[66:69]
	v_mfma_f32_16x16x32_bf16 v[94:97], v[170:173], v[186:189], v[94:97]
	v_mfma_f32_16x16x32_bf16 v[90:93], v[178:181], v[186:189], v[90:93]
	v_mfma_f32_16x16x32_bf16 v[86:89], v[170:173], v[198:201], v[86:89]
	v_mfma_f32_16x16x32_bf16 v[82:85], v[178:181], v[198:201], v[82:85]
	v_mfma_f32_16x16x32_bf16 v[78:81], v[170:173], v[214:217], v[78:81]
	v_mfma_f32_16x16x32_bf16 v[74:77], v[178:181], v[214:217], v[74:77]
	v_mfma_f32_16x16x32_bf16 v[70:73], v[170:173], v[222:225], v[70:73]
	v_mfma_f32_16x16x32_bf16 v[66:69], v[178:181], v[222:225], v[66:69]
	s_setprio 0
	s_barrier
	s_add_i32 s23, s60, s33
	v_lshl_add_u64 v[202:203], s[34:35], 0, v[132:133]
	s_mov_b32 m0, s23
	ds_read_b128 v[182:185], v148 offset:16384
	ds_read_b128 v[186:189], v148 offset:17408
	ds_read_b128 v[190:193], v148 offset:18432
	ds_read_b128 v[198:201], v148 offset:19456
	ds_read_b128 v[210:213], v148 offset:20480
	ds_read_b128 v[214:217], v148 offset:21504
	ds_read_b128 v[218:221], v148 offset:22528
	ds_read_b128 v[222:225], v148 offset:23552
	global_load_lds_dwordx4 v132, s[34:35]
	s_add_i32 m0, s23, 0x2000
	s_add_u32 s38, s34, 0x80000
	v_lshl_add_u64 v[206:207], s[34:35], 0, v[136:137]
	s_addc_u32 s39, s35, 0
	s_add_i32 s23, s61, s33
	global_load_lds_dwordx4 v136, s[34:35]
	s_mov_b32 m0, s23
	v_lshl_add_u64 v[228:229], s[36:37], 0, v[134:135]
	global_load_lds_dwordx4 v132, s[38:39]
	s_add_i32 m0, s23, 0x2000
	s_nop 0
	global_load_lds_dwordx4 v136, s[38:39]
	v_lshl_add_u64 v[226:227], s[36:37], 0, v[130:131]
	s_mov_b32 m0, s15
	s_nop 0
	global_load_lds_dwordx4 v130, s[36:37]
	s_mov_b32 m0, s41
	s_nop 0
	global_load_lds_dwordx4 v134, s[36:37]
	s_waitcnt vmcnt(8)
	s_waitcnt lgkmcnt(0)
	s_barrier
	s_setprio 1
	s_waitcnt lgkmcnt(0)
	v_mfma_f32_16x16x32_bf16 v[62:65], v[150:153], v[182:185], v[62:65]
	v_mfma_f32_16x16x32_bf16 v[58:61], v[158:161], v[182:185], v[58:61]
	v_mfma_f32_16x16x32_bf16 v[54:57], v[150:153], v[190:193], v[54:57]
	v_mfma_f32_16x16x32_bf16 v[50:53], v[158:161], v[190:193], v[50:53]
	v_mfma_f32_16x16x32_bf16 v[46:49], v[150:153], v[210:213], v[46:49]
	v_mfma_f32_16x16x32_bf16 v[42:45], v[158:161], v[210:213], v[42:45]
	v_mfma_f32_16x16x32_bf16 v[38:41], v[150:153], v[218:221], v[38:41]
	v_mfma_f32_16x16x32_bf16 v[34:37], v[158:161], v[218:221], v[34:37]
	v_mfma_f32_16x16x32_bf16 v[62:65], v[154:157], v[186:189], v[62:65]
	v_mfma_f32_16x16x32_bf16 v[58:61], v[162:165], v[186:189], v[58:61]
	v_mfma_f32_16x16x32_bf16 v[54:57], v[154:157], v[198:201], v[54:57]
	v_mfma_f32_16x16x32_bf16 v[50:53], v[162:165], v[198:201], v[50:53]
	v_mfma_f32_16x16x32_bf16 v[46:49], v[154:157], v[214:217], v[46:49]
	v_mfma_f32_16x16x32_bf16 v[42:45], v[162:165], v[214:217], v[42:45]
	v_mfma_f32_16x16x32_bf16 v[38:41], v[154:157], v[222:225], v[38:41]
	v_mfma_f32_16x16x32_bf16 v[34:37], v[162:165], v[222:225], v[34:37]
	s_setprio 0
	s_setprio 1
	v_mfma_f32_16x16x32_bf16 v[30:33], v[166:169], v[182:185], v[30:33]
	v_mfma_f32_16x16x32_bf16 v[26:29], v[174:177], v[182:185], v[26:29]
	v_mfma_f32_16x16x32_bf16 v[22:25], v[166:169], v[190:193], v[22:25]
	v_mfma_f32_16x16x32_bf16 v[18:21], v[174:177], v[190:193], v[18:21]
	v_mfma_f32_16x16x32_bf16 v[14:17], v[166:169], v[210:213], v[14:17]
	v_mfma_f32_16x16x32_bf16 v[10:13], v[174:177], v[210:213], v[10:13]
	v_mfma_f32_16x16x32_bf16 v[6:9], v[166:169], v[218:221], v[6:9]
	v_mfma_f32_16x16x32_bf16 v[2:5], v[174:177], v[218:221], v[2:5]
	v_mfma_f32_16x16x32_bf16 v[30:33], v[170:173], v[186:189], v[30:33]
	v_mfma_f32_16x16x32_bf16 v[26:29], v[178:181], v[186:189], v[26:29]
	v_mfma_f32_16x16x32_bf16 v[22:25], v[170:173], v[198:201], v[22:25]
	v_mfma_f32_16x16x32_bf16 v[18:21], v[178:181], v[198:201], v[18:21]
	v_mfma_f32_16x16x32_bf16 v[14:17], v[170:173], v[214:217], v[14:17]
	v_mfma_f32_16x16x32_bf16 v[10:13], v[178:181], v[214:217], v[10:13]
	v_mfma_f32_16x16x32_bf16 v[6:9], v[170:173], v[222:225], v[6:9]
	v_mfma_f32_16x16x32_bf16 v[2:5], v[178:181], v[222:225], v[2:5]
	s_setprio 0
	s_barrier
	s_add_i32 s23, 0, 0x18000
	v_add_u32_e32 v149, s23, v144
	s_add_i32 s38, 0, 0x1c000
	ds_read_b128 v[150:153], v149
	ds_read_b128 v[154:157], v149 offset:1024
	ds_read_b128 v[158:161], v149 offset:2048
	ds_read_b128 v[162:165], v149 offset:3072
	v_add_u32_e32 v149, s38, v144
	ds_read_b128 v[166:169], v149
	ds_read_b128 v[170:173], v149 offset:1024
	ds_read_b128 v[174:177], v149 offset:2048
	ds_read_b128 v[178:181], v149 offset:3072
	s_add_u32 s36, s36, 0x80000
	s_addc_u32 s37, s37, 0
	s_mov_b32 m0, s42
	ds_read_b128 v[182:185], v148 offset:32768
	ds_read_b128 v[186:189], v148 offset:33792
	ds_read_b128 v[190:193], v148 offset:34816
	ds_read_b128 v[198:201], v148 offset:35840
	ds_read_b128 v[210:213], v148 offset:36864
	ds_read_b128 v[214:217], v148 offset:37888
	ds_read_b128 v[218:221], v148 offset:38912
	ds_read_b128 v[222:225], v148 offset:39936
	global_load_lds_dwordx4 v130, s[36:37]
	v_lshl_add_u64 v[230:231], s[36:37], 0, v[134:135]
	s_mov_b32 m0, s43
	s_nop 0
	global_load_lds_dwordx4 v134, s[36:37]
	s_waitcnt vmcnt(8)
	s_waitcnt lgkmcnt(0)
	s_barrier
	s_setprio 1
	s_waitcnt lgkmcnt(0)
	v_mfma_f32_16x16x32_bf16 v[126:129], v[150:153], v[182:185], v[126:129]
	v_mfma_f32_16x16x32_bf16 v[122:125], v[158:161], v[182:185], v[122:125]
	v_mfma_f32_16x16x32_bf16 v[118:121], v[150:153], v[190:193], v[118:121]
	v_mfma_f32_16x16x32_bf16 v[114:117], v[158:161], v[190:193], v[114:117]
	v_mfma_f32_16x16x32_bf16 v[110:113], v[150:153], v[210:213], v[110:113]
	v_mfma_f32_16x16x32_bf16 v[106:109], v[158:161], v[210:213], v[106:109]
	v_mfma_f32_16x16x32_bf16 v[102:105], v[150:153], v[218:221], v[102:105]
	v_mfma_f32_16x16x32_bf16 v[98:101], v[158:161], v[218:221], v[98:101]
	v_mfma_f32_16x16x32_bf16 v[126:129], v[154:157], v[186:189], v[126:129]
	v_mfma_f32_16x16x32_bf16 v[122:125], v[162:165], v[186:189], v[122:125]
	v_mfma_f32_16x16x32_bf16 v[118:121], v[154:157], v[198:201], v[118:121]
	v_mfma_f32_16x16x32_bf16 v[114:117], v[162:165], v[198:201], v[114:117]
	v_mfma_f32_16x16x32_bf16 v[110:113], v[154:157], v[214:217], v[110:113]
	v_mfma_f32_16x16x32_bf16 v[106:109], v[162:165], v[214:217], v[106:109]
	v_mfma_f32_16x16x32_bf16 v[102:105], v[154:157], v[222:225], v[102:105]
	v_mfma_f32_16x16x32_bf16 v[98:101], v[162:165], v[222:225], v[98:101]
	s_setprio 0
	s_setprio 1
	v_mfma_f32_16x16x32_bf16 v[94:97], v[166:169], v[182:185], v[94:97]
	v_mfma_f32_16x16x32_bf16 v[90:93], v[174:177], v[182:185], v[90:93]
	v_mfma_f32_16x16x32_bf16 v[86:89], v[166:169], v[190:193], v[86:89]
	v_mfma_f32_16x16x32_bf16 v[82:85], v[174:177], v[190:193], v[82:85]
	v_mfma_f32_16x16x32_bf16 v[78:81], v[166:169], v[210:213], v[78:81]
	v_mfma_f32_16x16x32_bf16 v[74:77], v[174:177], v[210:213], v[74:77]
	v_mfma_f32_16x16x32_bf16 v[70:73], v[166:169], v[218:221], v[70:73]
	v_mfma_f32_16x16x32_bf16 v[66:69], v[174:177], v[218:221], v[66:69]
	v_mfma_f32_16x16x32_bf16 v[94:97], v[170:173], v[186:189], v[94:97]
	v_mfma_f32_16x16x32_bf16 v[90:93], v[178:181], v[186:189], v[90:93]
	v_mfma_f32_16x16x32_bf16 v[86:89], v[170:173], v[198:201], v[86:89]
	v_mfma_f32_16x16x32_bf16 v[82:85], v[178:181], v[198:201], v[82:85]
	v_mfma_f32_16x16x32_bf16 v[78:81], v[170:173], v[214:217], v[78:81]
	v_mfma_f32_16x16x32_bf16 v[74:77], v[178:181], v[214:217], v[74:77]
	v_mfma_f32_16x16x32_bf16 v[70:73], v[170:173], v[222:225], v[70:73]
	v_mfma_f32_16x16x32_bf16 v[66:69], v[178:181], v[222:225], v[66:69]
	s_setprio 0
	s_barrier
	s_add_i32 s23, s23, s33
	v_lshl_add_u64 v[202:203], v[202:203], 0, s[10:11]
	s_mov_b32 m0, s23
	ds_read_b128 v[182:185], v148 offset:49152
	ds_read_b128 v[186:189], v148 offset:50176
	ds_read_b128 v[190:193], v148 offset:51200
	ds_read_b128 v[198:201], v148 offset:52224
	ds_read_b128 v[210:213], v148 offset:53248
	ds_read_b128 v[214:217], v148 offset:54272
	ds_read_b128 v[218:221], v148 offset:55296
	ds_read_b128 v[222:225], v148 offset:56320
	global_load_lds_dwordx4 v[202:203], off
	s_add_i32 m0, s23, 0x2000
	s_add_u32 s34, s34, 0x80080
	v_lshl_add_u64 v[202:203], v[206:207], 0, s[10:11]
	s_addc_u32 s35, s35, 0
	s_add_i32 s23, s38, s33
	global_load_lds_dwordx4 v[202:203], off
	s_mov_b32 m0, s23
	s_nop 0
	global_load_lds_dwordx4 v132, s[34:35]
	s_add_i32 m0, s23, 0x2000
	s_nop 0
	global_load_lds_dwordx4 v136, s[34:35]
	v_lshl_add_u64 v[202:203], v[226:227], 0, s[10:11]
	s_mov_b32 m0, s51
	s_nop 0
	global_load_lds_dwordx4 v[202:203], off
	v_lshl_add_u64 v[202:203], v[228:229], 0, s[10:11]
	s_mov_b32 m0, s52
	s_nop 0
	global_load_lds_dwordx4 v[202:203], off
	s_waitcnt vmcnt(8)
	s_waitcnt lgkmcnt(0)
	s_barrier
	s_setprio 1
	s_waitcnt lgkmcnt(0)
	v_mfma_f32_16x16x32_bf16 v[62:65], v[150:153], v[182:185], v[62:65]
	v_mfma_f32_16x16x32_bf16 v[58:61], v[158:161], v[182:185], v[58:61]
	v_mfma_f32_16x16x32_bf16 v[54:57], v[150:153], v[190:193], v[54:57]
	v_mfma_f32_16x16x32_bf16 v[50:53], v[158:161], v[190:193], v[50:53]
	v_mfma_f32_16x16x32_bf16 v[46:49], v[150:153], v[210:213], v[46:49]
	v_mfma_f32_16x16x32_bf16 v[42:45], v[158:161], v[210:213], v[42:45]
	v_mfma_f32_16x16x32_bf16 v[38:41], v[150:153], v[218:221], v[38:41]
	v_mfma_f32_16x16x32_bf16 v[34:37], v[158:161], v[218:221], v[34:37]
	v_mfma_f32_16x16x32_bf16 v[62:65], v[154:157], v[186:189], v[62:65]
	v_mfma_f32_16x16x32_bf16 v[58:61], v[162:165], v[186:189], v[58:61]
	v_mfma_f32_16x16x32_bf16 v[54:57], v[154:157], v[198:201], v[54:57]
	v_mfma_f32_16x16x32_bf16 v[50:53], v[162:165], v[198:201], v[50:53]
	v_mfma_f32_16x16x32_bf16 v[46:49], v[154:157], v[214:217], v[46:49]
	v_mfma_f32_16x16x32_bf16 v[42:45], v[162:165], v[214:217], v[42:45]
	v_mfma_f32_16x16x32_bf16 v[38:41], v[154:157], v[222:225], v[38:41]
	v_mfma_f32_16x16x32_bf16 v[34:37], v[162:165], v[222:225], v[34:37]
	s_setprio 0
	s_setprio 1
	v_mfma_f32_16x16x32_bf16 v[30:33], v[166:169], v[182:185], v[30:33]
	v_mfma_f32_16x16x32_bf16 v[26:29], v[174:177], v[182:185], v[26:29]
	v_mfma_f32_16x16x32_bf16 v[22:25], v[166:169], v[190:193], v[22:25]
	v_mfma_f32_16x16x32_bf16 v[18:21], v[174:177], v[190:193], v[18:21]
	v_mfma_f32_16x16x32_bf16 v[14:17], v[166:169], v[210:213], v[14:17]
	v_mfma_f32_16x16x32_bf16 v[10:13], v[174:177], v[210:213], v[10:13]
	v_mfma_f32_16x16x32_bf16 v[6:9], v[166:169], v[218:221], v[6:9]
	v_mfma_f32_16x16x32_bf16 v[2:5], v[174:177], v[218:221], v[2:5]
	v_mfma_f32_16x16x32_bf16 v[30:33], v[170:173], v[186:189], v[30:33]
	v_mfma_f32_16x16x32_bf16 v[26:29], v[178:181], v[186:189], v[26:29]
	v_mfma_f32_16x16x32_bf16 v[22:25], v[170:173], v[198:201], v[22:25]
	v_mfma_f32_16x16x32_bf16 v[18:21], v[178:181], v[198:201], v[18:21]
	v_mfma_f32_16x16x32_bf16 v[14:17], v[170:173], v[214:217], v[14:17]
	v_mfma_f32_16x16x32_bf16 v[10:13], v[178:181], v[214:217], v[10:13]
	v_mfma_f32_16x16x32_bf16 v[6:9], v[170:173], v[222:225], v[6:9]
	v_mfma_f32_16x16x32_bf16 v[2:5], v[178:181], v[222:225], v[2:5]
	s_setprio 0
	s_barrier
	s_add_u32 s30, s30, 0x100
	s_addc_u32 s31, s31, 0
	s_add_u32 s19, s19, 0x100
	s_addc_u32 s21, s21, 0
	s_cmp_ge_i32 s29, s68
	s_mov_b32 s23, s29
	s_cbranch_scc0 .LBB0_1973

.Lpeel_1:
	ds_read_b128 v[152:155], v148
	ds_read_b128 v[156:159], v148 offset:1024
	s_add_i32 s29, s19, 2
	s_add_u32 s34, s30, 0xfff80080
	s_addc_u32 s35, s31, -1
	s_cmp_eq_u32 s28, s19
	s_cselect_b32 s37, s21, s35
	s_cselect_b32 s36, s20, s34
	s_cselect_b32 s35, s23, s17
	s_cselect_b32 s34, s22, s15
	s_add_i32 m0, s27, 0xc000
	global_load_lds_dwordx4 v140, s[30:31]
	s_add_i32 m0, s27, 0xe000
	s_nop 0
	global_load_lds_dwordx4 v142, s[30:31]
	s_waitcnt vmcnt(8)
	s_waitcnt lgkmcnt(0)
	s_barrier
	s_setprio 1
	s_waitcnt lgkmcnt(0)
	v_mfma_f32_16x16x32_bf16 v[126:129], v[152:155], v[184:187], 0
	v_mfma_f32_16x16x32_bf16 v[122:125], v[160:163], v[184:187], 0
	v_mfma_f32_16x16x32_bf16 v[110:113], v[152:155], v[192:195], 0
	v_mfma_f32_16x16x32_bf16 v[106:109], v[160:163], v[192:195], 0
	v_mfma_f32_16x16x32_bf16 v[94:97], v[152:155], v[210:213], 0
	v_mfma_f32_16x16x32_bf16 v[90:93], v[160:163], v[210:213], 0
	v_mfma_f32_16x16x32_bf16 v[78:81], v[152:155], v[218:221], 0
	v_mfma_f32_16x16x32_bf16 v[74:77], v[160:163], v[218:221], 0
	v_mfma_f32_16x16x32_bf16 v[126:129], v[156:159], v[188:191], v[126:129]
	v_mfma_f32_16x16x32_bf16 v[122:125], v[164:167], v[188:191], v[122:125]
	v_mfma_f32_16x16x32_bf16 v[110:113], v[156:159], v[198:201], v[110:113]
	v_mfma_f32_16x16x32_bf16 v[106:109], v[164:167], v[198:201], v[106:109]
	v_mfma_f32_16x16x32_bf16 v[94:97], v[156:159], v[214:217], v[94:97]
	v_mfma_f32_16x16x32_bf16 v[90:93], v[164:167], v[214:217], v[90:93]
	v_mfma_f32_16x16x32_bf16 v[78:81], v[156:159], v[222:225], v[78:81]
	v_mfma_f32_16x16x32_bf16 v[74:77], v[164:167], v[222:225], v[74:77]
	s_setprio 0
	s_setprio 1
	v_mfma_f32_16x16x32_bf16 v[118:121], v[168:171], v[184:187], 0
	v_mfma_f32_16x16x32_bf16 v[114:117], v[176:179], v[184:187], 0
	v_mfma_f32_16x16x32_bf16 v[102:105], v[168:171], v[192:195], 0
	v_mfma_f32_16x16x32_bf16 v[98:101], v[176:179], v[192:195], 0
	v_mfma_f32_16x16x32_bf16 v[86:89], v[168:171], v[210:213], 0
	v_mfma_f32_16x16x32_bf16 v[82:85], v[176:179], v[210:213], 0
	v_mfma_f32_16x16x32_bf16 v[70:73], v[168:171], v[218:221], 0
	v_mfma_f32_16x16x32_bf16 v[66:69], v[176:179], v[218:221], 0
	v_mfma_f32_16x16x32_bf16 v[118:121], v[172:175], v[188:191], v[118:121]
	v_mfma_f32_16x16x32_bf16 v[114:117], v[180:183], v[188:191], v[114:117]
	v_mfma_f32_16x16x32_bf16 v[102:105], v[172:175], v[198:201], v[102:105]
	v_mfma_f32_16x16x32_bf16 v[98:101], v[180:183], v[198:201], v[98:101]
	v_mfma_f32_16x16x32_bf16 v[86:89], v[172:175], v[214:217], v[86:89]
	v_mfma_f32_16x16x32_bf16 v[82:85], v[180:183], v[214:217], v[82:85]
	v_mfma_f32_16x16x32_bf16 v[70:73], v[172:175], v[222:225], v[70:73]
	v_mfma_f32_16x16x32_bf16 v[66:69], v[180:183], v[222:225], v[66:69]
	s_setprio 0
	s_barrier
	s_add_i32 s19, s60, s33
	v_lshl_add_u64 v[144:145], s[34:35], 0, v[132:133]
	s_mov_b32 m0, s19
	ds_read_b128 v[184:187], v150 offset:16384
	ds_read_b128 v[188:191], v150 offset:17408
	ds_read_b128 v[192:195], v150 offset:18432
	ds_read_b128 v[198:201], v150 offset:19456
	ds_read_b128 v[210:213], v150 offset:20480
	ds_read_b128 v[214:217], v150 offset:21504
	ds_read_b128 v[218:221], v150 offset:22528
	ds_read_b128 v[222:225], v150 offset:23552
	global_load_lds_dwordx4 v132, s[34:35]
	s_add_i32 m0, s19, 0x2000
	s_add_u32 s38, s34, 0x80000
	v_lshl_add_u64 v[202:203], s[34:35], 0, v[136:137]
	s_addc_u32 s39, s35, 0
	s_add_i32 s19, s61, s33
	global_load_lds_dwordx4 v136, s[34:35]
	s_mov_b32 m0, s19
	v_lshl_add_u64 v[226:227], s[36:37], 0, v[134:135]
	global_load_lds_dwordx4 v132, s[38:39]
	s_add_i32 m0, s19, 0x2000
	s_nop 0
	global_load_lds_dwordx4 v136, s[38:39]
	v_lshl_add_u64 v[206:207], s[36:37], 0, v[130:131]
	s_mov_b32 m0, s27
	s_nop 0
	global_load_lds_dwordx4 v130, s[36:37]
	s_mov_b32 m0, s41
	s_nop 0
	global_load_lds_dwordx4 v134, s[36:37]
	s_waitcnt vmcnt(8)
	s_waitcnt lgkmcnt(0)
	s_barrier
	s_setprio 1
	s_waitcnt lgkmcnt(0)
	v_mfma_f32_16x16x32_bf16 v[62:65], v[152:155], v[184:187], 0
	v_mfma_f32_16x16x32_bf16 v[58:61], v[160:163], v[184:187], 0
	v_mfma_f32_16x16x32_bf16 v[46:49], v[152:155], v[192:195], 0
	v_mfma_f32_16x16x32_bf16 v[42:45], v[160:163], v[192:195], 0
	v_mfma_f32_16x16x32_bf16 v[30:33], v[152:155], v[210:213], 0
	v_mfma_f32_16x16x32_bf16 v[26:29], v[160:163], v[210:213], 0
	v_mfma_f32_16x16x32_bf16 v[14:17], v[152:155], v[218:221], 0
	v_mfma_f32_16x16x32_bf16 v[10:13], v[160:163], v[218:221], 0
	v_mfma_f32_16x16x32_bf16 v[62:65], v[156:159], v[188:191], v[62:65]
	v_mfma_f32_16x16x32_bf16 v[58:61], v[164:167], v[188:191], v[58:61]
	v_mfma_f32_16x16x32_bf16 v[46:49], v[156:159], v[198:201], v[46:49]
	v_mfma_f32_16x16x32_bf16 v[42:45], v[164:167], v[198:201], v[42:45]
	v_mfma_f32_16x16x32_bf16 v[30:33], v[156:159], v[214:217], v[30:33]
	v_mfma_f32_16x16x32_bf16 v[26:29], v[164:167], v[214:217], v[26:29]
	v_mfma_f32_16x16x32_bf16 v[14:17], v[156:159], v[222:225], v[14:17]
	v_mfma_f32_16x16x32_bf16 v[10:13], v[164:167], v[222:225], v[10:13]
	s_setprio 0
	s_setprio 1
	v_mfma_f32_16x16x32_bf16 v[54:57], v[168:171], v[184:187], 0
	v_mfma_f32_16x16x32_bf16 v[50:53], v[176:179], v[184:187], 0
	v_mfma_f32_16x16x32_bf16 v[38:41], v[168:171], v[192:195], 0
	v_mfma_f32_16x16x32_bf16 v[34:37], v[176:179], v[192:195], 0
	v_mfma_f32_16x16x32_bf16 v[22:25], v[168:171], v[210:213], 0
	v_mfma_f32_16x16x32_bf16 v[18:21], v[176:179], v[210:213], 0
	v_mfma_f32_16x16x32_bf16 v[6:9], v[168:171], v[218:221], 0
	v_mfma_f32_16x16x32_bf16 v[2:5], v[176:179], v[218:221], 0
	v_mfma_f32_16x16x32_bf16 v[54:57], v[172:175], v[188:191], v[54:57]
	v_mfma_f32_16x16x32_bf16 v[50:53], v[180:183], v[188:191], v[50:53]
	v_mfma_f32_16x16x32_bf16 v[38:41], v[172:175], v[198:201], v[38:41]
	v_mfma_f32_16x16x32_bf16 v[34:37], v[180:183], v[198:201], v[34:37]
	v_mfma_f32_16x16x32_bf16 v[22:25], v[172:175], v[214:217], v[22:25]
	v_mfma_f32_16x16x32_bf16 v[18:21], v[180:183], v[214:217], v[18:21]
	v_mfma_f32_16x16x32_bf16 v[6:9], v[172:175], v[222:225], v[6:9]
	v_mfma_f32_16x16x32_bf16 v[2:5], v[180:183], v[222:225], v[2:5]
	s_setprio 0
	s_barrier
	s_add_i32 s19, 0, 0x18000
	v_add_u32_e32 v151, s19, v146
	s_add_i32 s38, 0, 0x1c000
	ds_read_b128 v[152:155], v151
	ds_read_b128 v[156:159], v151 offset:1024
	ds_read_b128 v[160:163], v151 offset:2048
	ds_read_b128 v[164:167], v151 offset:3072
	v_add_u32_e32 v151, s38, v146
	ds_read_b128 v[168:171], v151
	ds_read_b128 v[172:175], v151 offset:1024
	ds_read_b128 v[176:179], v151 offset:2048
	ds_read_b128 v[180:183], v151 offset:3072
	s_add_u32 s36, s36, 0x80000
	s_addc_u32 s37, s37, 0
	s_mov_b32 m0, s42
	ds_read_b128 v[184:187], v150 offset:32768
	ds_read_b128 v[188:191], v150 offset:33792
	ds_read_b128 v[192:195], v150 offset:34816
	ds_read_b128 v[198:201], v150 offset:35840
	ds_read_b128 v[210:213], v150 offset:36864
	ds_read_b128 v[214:217], v150 offset:37888
	ds_read_b128 v[218:221], v150 offset:38912
	ds_read_b128 v[222:225], v150 offset:39936
	global_load_lds_dwordx4 v130, s[36:37]
	v_lshl_add_u64 v[228:229], s[36:37], 0, v[134:135]
	s_mov_b32 m0, s43
	s_nop 0
	global_load_lds_dwordx4 v134, s[36:37]
	s_waitcnt vmcnt(8)
	s_waitcnt lgkmcnt(0)
	s_barrier
	s_setprio 1
	s_waitcnt lgkmcnt(0)
	v_mfma_f32_16x16x32_bf16 v[126:129], v[152:155], v[184:187], v[126:129]
	v_mfma_f32_16x16x32_bf16 v[122:125], v[160:163], v[184:187], v[122:125]
	v_mfma_f32_16x16x32_bf16 v[110:113], v[152:155], v[192:195], v[110:113]
	v_mfma_f32_16x16x32_bf16 v[106:109], v[160:163], v[192:195], v[106:109]
	v_mfma_f32_16x16x32_bf16 v[94:97], v[152:155], v[210:213], v[94:97]
	v_mfma_f32_16x16x32_bf16 v[90:93], v[160:163], v[210:213], v[90:93]
	v_mfma_f32_16x16x32_bf16 v[78:81], v[152:155], v[218:221], v[78:81]
	v_mfma_f32_16x16x32_bf16 v[74:77], v[160:163], v[218:221], v[74:77]
	v_mfma_f32_16x16x32_bf16 v[126:129], v[156:159], v[188:191], v[126:129]
	v_mfma_f32_16x16x32_bf16 v[122:125], v[164:167], v[188:191], v[122:125]
	v_mfma_f32_16x16x32_bf16 v[110:113], v[156:159], v[198:201], v[110:113]
	v_mfma_f32_16x16x32_bf16 v[106:109], v[164:167], v[198:201], v[106:109]
	v_mfma_f32_16x16x32_bf16 v[94:97], v[156:159], v[214:217], v[94:97]
	v_mfma_f32_16x16x32_bf16 v[90:93], v[164:167], v[214:217], v[90:93]
	v_mfma_f32_16x16x32_bf16 v[78:81], v[156:159], v[222:225], v[78:81]
	v_mfma_f32_16x16x32_bf16 v[74:77], v[164:167], v[222:225], v[74:77]
	s_setprio 0
	s_setprio 1
	v_mfma_f32_16x16x32_bf16 v[118:121], v[168:171], v[184:187], v[118:121]
	v_mfma_f32_16x16x32_bf16 v[114:117], v[176:179], v[184:187], v[114:117]
	v_mfma_f32_16x16x32_bf16 v[102:105], v[168:171], v[192:195], v[102:105]
	v_mfma_f32_16x16x32_bf16 v[98:101], v[176:179], v[192:195], v[98:101]
	v_mfma_f32_16x16x32_bf16 v[86:89], v[168:171], v[210:213], v[86:89]
	v_mfma_f32_16x16x32_bf16 v[82:85], v[176:179], v[210:213], v[82:85]
	v_mfma_f32_16x16x32_bf16 v[70:73], v[168:171], v[218:221], v[70:73]
	v_mfma_f32_16x16x32_bf16 v[66:69], v[176:179], v[218:221], v[66:69]
	v_mfma_f32_16x16x32_bf16 v[118:121], v[172:175], v[188:191], v[118:121]
	v_mfma_f32_16x16x32_bf16 v[114:117], v[180:183], v[188:191], v[114:117]
	v_mfma_f32_16x16x32_bf16 v[102:105], v[172:175], v[198:201], v[102:105]
	v_mfma_f32_16x16x32_bf16 v[98:101], v[180:183], v[198:201], v[98:101]
	v_mfma_f32_16x16x32_bf16 v[86:89], v[172:175], v[214:217], v[86:89]
	v_mfma_f32_16x16x32_bf16 v[82:85], v[180:183], v[214:217], v[82:85]
	v_mfma_f32_16x16x32_bf16 v[70:73], v[172:175], v[222:225], v[70:73]
	v_mfma_f32_16x16x32_bf16 v[66:69], v[180:183], v[222:225], v[66:69]
	s_setprio 0
	s_barrier
	s_add_i32 s19, s19, s33
	v_lshl_add_u64 v[144:145], v[144:145], 0, s[10:11]
	s_mov_b32 m0, s19
	ds_read_b128 v[184:187], v150 offset:49152
	ds_read_b128 v[188:191], v150 offset:50176
	ds_read_b128 v[192:195], v150 offset:51200
	ds_read_b128 v[198:201], v150 offset:52224
	ds_read_b128 v[210:213], v150 offset:53248
	ds_read_b128 v[214:217], v150 offset:54272
	ds_read_b128 v[218:221], v150 offset:55296
	ds_read_b128 v[222:225], v150 offset:56320
	global_load_lds_dwordx4 v[144:145], off
	s_add_i32 m0, s19, 0x2000
	s_add_u32 s34, s34, 0x80080
	v_lshl_add_u64 v[144:145], v[202:203], 0, s[10:11]
	s_addc_u32 s35, s35, 0
	s_add_i32 s19, s38, s33
	global_load_lds_dwordx4 v[144:145], off
	s_mov_b32 m0, s19
	s_nop 0
	global_load_lds_dwordx4 v132, s[34:35]
	s_add_i32 m0, s19, 0x2000
	s_nop 0
	global_load_lds_dwordx4 v136, s[34:35]
	v_lshl_add_u64 v[144:145], v[206:207], 0, s[10:11]
	s_mov_b32 m0, s51
	s_nop 0
	global_load_lds_dwordx4 v[144:145], off
	v_lshl_add_u64 v[144:145], v[226:227], 0, s[10:11]
	s_mov_b32 m0, s52
	s_nop 0
	global_load_lds_dwordx4 v[144:145], off
	s_waitcnt vmcnt(8)
	s_waitcnt lgkmcnt(0)
	s_barrier
	s_setprio 1
	s_waitcnt lgkmcnt(0)
	v_mfma_f32_16x16x32_bf16 v[62:65], v[152:155], v[184:187], v[62:65]
	v_mfma_f32_16x16x32_bf16 v[58:61], v[160:163], v[184:187], v[58:61]
	v_mfma_f32_16x16x32_bf16 v[46:49], v[152:155], v[192:195], v[46:49]
	v_mfma_f32_16x16x32_bf16 v[42:45], v[160:163], v[192:195], v[42:45]
	v_mfma_f32_16x16x32_bf16 v[30:33], v[152:155], v[210:213], v[30:33]
	v_mfma_f32_16x16x32_bf16 v[26:29], v[160:163], v[210:213], v[26:29]
	v_mfma_f32_16x16x32_bf16 v[14:17], v[152:155], v[218:221], v[14:17]
	v_mfma_f32_16x16x32_bf16 v[10:13], v[160:163], v[218:221], v[10:13]
	v_mfma_f32_16x16x32_bf16 v[62:65], v[156:159], v[188:191], v[62:65]
	v_mfma_f32_16x16x32_bf16 v[58:61], v[164:167], v[188:191], v[58:61]
	v_mfma_f32_16x16x32_bf16 v[46:49], v[156:159], v[198:201], v[46:49]
	v_mfma_f32_16x16x32_bf16 v[42:45], v[164:167], v[198:201], v[42:45]
	v_mfma_f32_16x16x32_bf16 v[30:33], v[156:159], v[214:217], v[30:33]
	v_mfma_f32_16x16x32_bf16 v[26:29], v[164:167], v[214:217], v[26:29]
	v_mfma_f32_16x16x32_bf16 v[14:17], v[156:159], v[222:225], v[14:17]
	v_mfma_f32_16x16x32_bf16 v[10:13], v[164:167], v[222:225], v[10:13]
	s_setprio 0
	s_setprio 1
	v_mfma_f32_16x16x32_bf16 v[54:57], v[168:171], v[184:187], v[54:57]
	v_mfma_f32_16x16x32_bf16 v[50:53], v[176:179], v[184:187], v[50:53]
	v_mfma_f32_16x16x32_bf16 v[38:41], v[168:171], v[192:195], v[38:41]
	v_mfma_f32_16x16x32_bf16 v[34:37], v[176:179], v[192:195], v[34:37]
	v_mfma_f32_16x16x32_bf16 v[22:25], v[168:171], v[210:213], v[22:25]
	v_mfma_f32_16x16x32_bf16 v[18:21], v[176:179], v[210:213], v[18:21]
	v_mfma_f32_16x16x32_bf16 v[6:9], v[168:171], v[218:221], v[6:9]
	v_mfma_f32_16x16x32_bf16 v[2:5], v[176:179], v[218:221], v[2:5]
	v_mfma_f32_16x16x32_bf16 v[54:57], v[172:175], v[188:191], v[54:57]
	v_mfma_f32_16x16x32_bf16 v[50:53], v[180:183], v[188:191], v[50:53]
	v_mfma_f32_16x16x32_bf16 v[38:41], v[172:175], v[198:201], v[38:41]
	v_mfma_f32_16x16x32_bf16 v[34:37], v[180:183], v[198:201], v[34:37]
	v_mfma_f32_16x16x32_bf16 v[22:25], v[172:175], v[214:217], v[22:25]
	v_mfma_f32_16x16x32_bf16 v[18:21], v[180:183], v[214:217], v[18:21]
	v_mfma_f32_16x16x32_bf16 v[6:9], v[172:175], v[222:225], v[6:9]
	v_mfma_f32_16x16x32_bf16 v[2:5], v[180:183], v[222:225], v[2:5]
	s_setprio 0
	s_barrier
	s_add_u32 s30, s30, 0x100
	s_addc_u32 s31, s31, 0
	s_add_u32 s15, s15, 0x100
	s_addc_u32 s17, s17, 0
	s_cmp_ge_i32 s29, s68
	s_mov_b32 s19, s29
	s_cbranch_scc0 .LBB0_2547
	s_branch .Lpeeldone_1
.LBB0_2547:
	ds_read_b128 v[152:155], v148
	ds_read_b128 v[156:159], v148 offset:1024
	ds_read_b128 v[160:163], v148 offset:2048
	ds_read_b128 v[164:167], v148 offset:3072
	ds_read_b128 v[168:171], v149
	ds_read_b128 v[172:175], v149 offset:1024
	ds_read_b128 v[176:179], v149 offset:2048
	ds_read_b128 v[180:183], v149 offset:3072
	s_add_i32 s29, s19, 2
	s_add_u32 s34, s30, 0xfff80080
	s_addc_u32 s35, s31, -1
	s_cmp_eq_u32 s28, s19
	s_cselect_b32 s37, s21, s35
	s_cselect_b32 s36, s20, s34
	s_cselect_b32 s35, s23, s17
	s_cselect_b32 s34, s22, s15
	s_add_i32 m0, s27, 0xc000
	ds_read_b128 v[184:187], v150
	ds_read_b128 v[188:191], v150 offset:1024
	ds_read_b128 v[192:195], v150 offset:2048
	ds_read_b128 v[198:201], v150 offset:3072
	ds_read_b128 v[210:213], v150 offset:4096
	ds_read_b128 v[214:217], v150 offset:5120
	ds_read_b128 v[218:221], v150 offset:6144
	ds_read_b128 v[222:225], v150 offset:7168
	global_load_lds_dwordx4 v140, s[30:31]
	s_add_i32 m0, s27, 0xe000
	s_nop 0
	global_load_lds_dwordx4 v142, s[30:31]
	s_waitcnt vmcnt(8)
	s_waitcnt lgkmcnt(0)
	s_barrier
	s_setprio 1
	s_waitcnt lgkmcnt(0)
	v_mfma_f32_16x16x32_bf16 v[126:129], v[152:155], v[184:187], v[126:129]
	v_mfma_f32_16x16x32_bf16 v[122:125], v[160:163], v[184:187], v[122:125]
	v_mfma_f32_16x16x32_bf16 v[110:113], v[152:155], v[192:195], v[110:113]
	v_mfma_f32_16x16x32_bf16 v[106:109], v[160:163], v[192:195], v[106:109]
	v_mfma_f32_16x16x32_bf16 v[94:97], v[152:155], v[210:213], v[94:97]
	v_mfma_f32_16x16x32_bf16 v[90:93], v[160:163], v[210:213], v[90:93]
	v_mfma_f32_16x16x32_bf16 v[78:81], v[152:155], v[218:221], v[78:81]
	v_mfma_f32_16x16x32_bf16 v[74:77], v[160:163], v[218:221], v[74:77]
	v_mfma_f32_16x16x32_bf16 v[126:129], v[156:159], v[188:191], v[126:129]
	v_mfma_f32_16x16x32_bf16 v[122:125], v[164:167], v[188:191], v[122:125]
	v_mfma_f32_16x16x32_bf16 v[110:113], v[156:159], v[198:201], v[110:113]
	v_mfma_f32_16x16x32_bf16 v[106:109], v[164:167], v[198:201], v[106:109]
	v_mfma_f32_16x16x32_bf16 v[94:97], v[156:159], v[214:217], v[94:97]
	v_mfma_f32_16x16x32_bf16 v[90:93], v[164:167], v[214:217], v[90:93]
	v_mfma_f32_16x16x32_bf16 v[78:81], v[156:159], v[222:225], v[78:81]
	v_mfma_f32_16x16x32_bf16 v[74:77], v[164:167], v[222:225], v[74:77]
	s_setprio 0
	s_setprio 1
	v_mfma_f32_16x16x32_bf16 v[118:121], v[168:171], v[184:187], v[118:121]
	v_mfma_f32_16x16x32_bf16 v[114:117], v[176:179], v[184:187], v[114:117]
	v_mfma_f32_16x16x32_bf16 v[102:105], v[168:171], v[192:195], v[102:105]
	v_mfma_f32_16x16x32_bf16 v[98:101], v[176:179], v[192:195], v[98:101]
	v_mfma_f32_16x16x32_bf16 v[86:89], v[168:171], v[210:213], v[86:89]
	v_mfma_f32_16x16x32_bf16 v[82:85], v[176:179], v[210:213], v[82:85]
	v_mfma_f32_16x16x32_bf16 v[70:73], v[168:171], v[218:221], v[70:73]
	v_mfma_f32_16x16x32_bf16 v[66:69], v[176:179], v[218:221], v[66:69]
	v_mfma_f32_16x16x32_bf16 v[118:121], v[172:175], v[188:191], v[118:121]
	v_mfma_f32_16x16x32_bf16 v[114:117], v[180:183], v[188:191], v[114:117]
	v_mfma_f32_16x16x32_bf16 v[102:105], v[172:175], v[198:201], v[102:105]
	v_mfma_f32_16x16x32_bf16 v[98:101], v[180:183], v[198:201], v[98:101]
	v_mfma_f32_16x16x32_bf16 v[86:89], v[172:175], v[214:217], v[86:89]
	v_mfma_f32_16x16x32_bf16 v[82:85], v[180:183], v[214:217], v[82:85]
	v_mfma_f32_16x16x32_bf16 v[70:73], v[172:175], v[222:225], v[70:73]
	v_mfma_f32_16x16x32_bf16 v[66:69], v[180:183], v[222:225], v[66:69]
	s_setprio 0
	s_barrier
	s_add_i32 s19, s60, s33
	v_lshl_add_u64 v[144:145], s[34:35], 0, v[132:133]
	s_mov_b32 m0, s19
	ds_read_b128 v[184:187], v150 offset:16384
	ds_read_b128 v[188:191], v150 offset:17408
	ds_read_b128 v[192:195], v150 offset:18432
	ds_read_b128 v[198:201], v150 offset:19456
	ds_read_b128 v[210:213], v150 offset:20480
	ds_read_b128 v[214:217], v150 offset:21504
	ds_read_b128 v[218:221], v150 offset:22528
	ds_read_b128 v[222:225], v150 offset:23552
	global_load_lds_dwordx4 v132, s[34:35]
	s_add_i32 m0, s19, 0x2000
	s_add_u32 s38, s34, 0x80000
	v_lshl_add_u64 v[202:203], s[34:35], 0, v[136:137]
	s_addc_u32 s39, s35, 0
	s_add_i32 s19, s61, s33
	global_load_lds_dwordx4 v136, s[34:35]
	s_mov_b32 m0, s19
	v_lshl_add_u64 v[226:227], s[36:37], 0, v[134:135]
	global_load_lds_dwordx4 v132, s[38:39]
	s_add_i32 m0, s19, 0x2000
	s_nop 0
	global_load_lds_dwordx4 v136, s[38:39]
	v_lshl_add_u64 v[206:207], s[36:37], 0, v[130:131]
	s_mov_b32 m0, s27
	s_nop 0
	global_load_lds_dwordx4 v130, s[36:37]
	s_mov_b32 m0, s41
	s_nop 0
	global_load_lds_dwordx4 v134, s[36:37]
	s_waitcnt vmcnt(8)
	s_waitcnt lgkmcnt(0)
	s_barrier
	s_setprio 1
	s_waitcnt lgkmcnt(0)
	v_mfma_f32_16x16x32_bf16 v[62:65], v[152:155], v[184:187], v[62:65]
	v_mfma_f32_16x16x32_bf16 v[58:61], v[160:163], v[184:187], v[58:61]
	v_mfma_f32_16x16x32_bf16 v[46:49], v[152:155], v[192:195], v[46:49]
	v_mfma_f32_16x16x32_bf16 v[42:45], v[160:163], v[192:195], v[42:45]
	v_mfma_f32_16x16x32_bf16 v[30:33], v[152:155], v[210:213], v[30:33]
	v_mfma_f32_16x16x32_bf16 v[26:29], v[160:163], v[210:213], v[26:29]
	v_mfma_f32_16x16x32_bf16 v[14:17], v[152:155], v[218:221], v[14:17]
	v_mfma_f32_16x16x32_bf16 v[10:13], v[160:163], v[218:221], v[10:13]
	v_mfma_f32_16x16x32_bf16 v[62:65], v[156:159], v[188:191], v[62:65]
	v_mfma_f32_16x16x32_bf16 v[58:61], v[164:167], v[188:191], v[58:61]
	v_mfma_f32_16x16x32_bf16 v[46:49], v[156:159], v[198:201], v[46:49]
	v_mfma_f32_16x16x32_bf16 v[42:45], v[164:167], v[198:201], v[42:45]
	v_mfma_f32_16x16x32_bf16 v[30:33], v[156:159], v[214:217], v[30:33]
	v_mfma_f32_16x16x32_bf16 v[26:29], v[164:167], v[214:217], v[26:29]
	v_mfma_f32_16x16x32_bf16 v[14:17], v[156:159], v[222:225], v[14:17]
	v_mfma_f32_16x16x32_bf16 v[10:13], v[164:167], v[222:225], v[10:13]
	s_setprio 0
	s_setprio 1
	v_mfma_f32_16x16x32_bf16 v[54:57], v[168:171], v[184:187], v[54:57]
	v_mfma_f32_16x16x32_bf16 v[50:53], v[176:179], v[184:187], v[50:53]
	v_mfma_f32_16x16x32_bf16 v[38:41], v[168:171], v[192:195], v[38:41]
	v_mfma_f32_16x16x32_bf16 v[34:37], v[176:179], v[192:195], v[34:37]
	v_mfma_f32_16x16x32_bf16 v[22:25], v[168:171], v[210:213], v[22:25]
	v_mfma_f32_16x16x32_bf16 v[18:21], v[176:179], v[210:213], v[18:21]
	v_mfma_f32_16x16x32_bf16 v[6:9], v[168:171], v[218:221], v[6:9]
	v_mfma_f32_16x16x32_bf16 v[2:5], v[176:179], v[218:221], v[2:5]
	v_mfma_f32_16x16x32_bf16 v[54:57], v[172:175], v[188:191], v[54:57]
	v_mfma_f32_16x16x32_bf16 v[50:53], v[180:183], v[188:191], v[50:53]
	v_mfma_f32_16x16x32_bf16 v[38:41], v[172:175], v[198:201], v[38:41]
	v_mfma_f32_16x16x32_bf16 v[34:37], v[180:183], v[198:201], v[34:37]
	v_mfma_f32_16x16x32_bf16 v[22:25], v[172:175], v[214:217], v[22:25]
	v_mfma_f32_16x16x32_bf16 v[18:21], v[180:183], v[214:217], v[18:21]
	v_mfma_f32_16x16x32_bf16 v[6:9], v[172:175], v[222:225], v[6:9]
	v_mfma_f32_16x16x32_bf16 v[2:5], v[180:183], v[222:225], v[2:5]
	s_setprio 0
	s_barrier
	s_add_i32 s19, 0, 0x18000
	v_add_u32_e32 v151, s19, v146
	s_add_i32 s38, 0, 0x1c000
	ds_read_b128 v[152:155], v151
	ds_read_b128 v[156:159], v151 offset:1024
	ds_read_b128 v[160:163], v151 offset:2048
	ds_read_b128 v[164:167], v151 offset:3072
	v_add_u32_e32 v151, s38, v146
	ds_read_b128 v[168:171], v151
	ds_read_b128 v[172:175], v151 offset:1024
	ds_read_b128 v[176:179], v151 offset:2048
	ds_read_b128 v[180:183], v151 offset:3072
	s_add_u32 s36, s36, 0x80000
	s_addc_u32 s37, s37, 0
	s_mov_b32 m0, s42
	ds_read_b128 v[184:187], v150 offset:32768
	ds_read_b128 v[188:191], v150 offset:33792
	ds_read_b128 v[192:195], v150 offset:34816
	ds_read_b128 v[198:201], v150 offset:35840
	ds_read_b128 v[210:213], v150 offset:36864
	ds_read_b128 v[214:217], v150 offset:37888
	ds_read_b128 v[218:221], v150 offset:38912
	ds_read_b128 v[222:225], v150 offset:39936
	global_load_lds_dwordx4 v130, s[36:37]
	v_lshl_add_u64 v[228:229], s[36:37], 0, v[134:135]
	s_mov_b32 m0, s43
	s_nop 0
	global_load_lds_dwordx4 v134, s[36:37]
	s_waitcnt vmcnt(8)
	s_waitcnt lgkmcnt(0)
	s_barrier
	s_setprio 1
	s_waitcnt lgkmcnt(0)
	v_mfma_f32_16x16x32_bf16 v[126:129], v[152:155], v[184:187], v[126:129]
	v_mfma_f32_16x16x32_bf16 v[122:125], v[160:163], v[184:187], v[122:125]
	v_mfma_f32_16x16x32_bf16 v[110:113], v[152:155], v[192:195], v[110:113]
	v_mfma_f32_16x16x32_bf16 v[106:109], v[160:163], v[192:195], v[106:109]
	v_mfma_f32_16x16x32_bf16 v[94:97], v[152:155], v[210:213], v[94:97]
	v_mfma_f32_16x16x32_bf16 v[90:93], v[160:163], v[210:213], v[90:93]
	v_mfma_f32_16x16x32_bf16 v[78:81], v[152:155], v[218:221], v[78:81]
	v_mfma_f32_16x16x32_bf16 v[74:77], v[160:163], v[218:221], v[74:77]
	v_mfma_f32_16x16x32_bf16 v[126:129], v[156:159], v[188:191], v[126:129]
	v_mfma_f32_16x16x32_bf16 v[122:125], v[164:167], v[188:191], v[122:125]
	v_mfma_f32_16x16x32_bf16 v[110:113], v[156:159], v[198:201], v[110:113]
	v_mfma_f32_16x16x32_bf16 v[106:109], v[164:167], v[198:201], v[106:109]
	v_mfma_f32_16x16x32_bf16 v[94:97], v[156:159], v[214:217], v[94:97]
	v_mfma_f32_16x16x32_bf16 v[90:93], v[164:167], v[214:217], v[90:93]
	v_mfma_f32_16x16x32_bf16 v[78:81], v[156:159], v[222:225], v[78:81]
	v_mfma_f32_16x16x32_bf16 v[74:77], v[164:167], v[222:225], v[74:77]
	s_setprio 0
	s_setprio 1
	v_mfma_f32_16x16x32_bf16 v[118:121], v[168:171], v[184:187], v[118:121]
	v_mfma_f32_16x16x32_bf16 v[114:117], v[176:179], v[184:187], v[114:117]
	v_mfma_f32_16x16x32_bf16 v[102:105], v[168:171], v[192:195], v[102:105]
	v_mfma_f32_16x16x32_bf16 v[98:101], v[176:179], v[192:195], v[98:101]
	v_mfma_f32_16x16x32_bf16 v[86:89], v[168:171], v[210:213], v[86:89]
	v_mfma_f32_16x16x32_bf16 v[82:85], v[176:179], v[210:213], v[82:85]
	v_mfma_f32_16x16x32_bf16 v[70:73], v[168:171], v[218:221], v[70:73]
	v_mfma_f32_16x16x32_bf16 v[66:69], v[176:179], v[218:221], v[66:69]
	v_mfma_f32_16x16x32_bf16 v[118:121], v[172:175], v[188:191], v[118:121]
	v_mfma_f32_16x16x32_bf16 v[114:117], v[180:183], v[188:191], v[114:117]
	v_mfma_f32_16x16x32_bf16 v[102:105], v[172:175], v[198:201], v[102:105]
	v_mfma_f32_16x16x32_bf16 v[98:101], v[180:183], v[198:201], v[98:101]
	v_mfma_f32_16x16x32_bf16 v[86:89], v[172:175], v[214:217], v[86:89]
	v_mfma_f32_16x16x32_bf16 v[82:85], v[180:183], v[214:217], v[82:85]
	v_mfma_f32_16x16x32_bf16 v[70:73], v[172:175], v[222:225], v[70:73]
	v_mfma_f32_16x16x32_bf16 v[66:69], v[180:183], v[222:225], v[66:69]
	s_setprio 0
	s_barrier
	s_add_i32 s19, s19, s33
	v_lshl_add_u64 v[144:145], v[144:145], 0, s[10:11]
	s_mov_b32 m0, s19
	ds_read_b128 v[184:187], v150 offset:49152
	ds_read_b128 v[188:191], v150 offset:50176
	ds_read_b128 v[192:195], v150 offset:51200
	ds_read_b128 v[198:201], v150 offset:52224
	ds_read_b128 v[210:213], v150 offset:53248
	ds_read_b128 v[214:217], v150 offset:54272
	ds_read_b128 v[218:221], v150 offset:55296
	ds_read_b128 v[222:225], v150 offset:56320
	global_load_lds_dwordx4 v[144:145], off
	s_add_i32 m0, s19, 0x2000
	s_add_u32 s34, s34, 0x80080
	v_lshl_add_u64 v[144:145], v[202:203], 0, s[10:11]
	s_addc_u32 s35, s35, 0
	s_add_i32 s19, s38, s33
	global_load_lds_dwordx4 v[144:145], off
	s_mov_b32 m0, s19
	s_nop 0
	global_load_lds_dwordx4 v132, s[34:35]
	s_add_i32 m0, s19, 0x2000
	s_nop 0
	global_load_lds_dwordx4 v136, s[34:35]
	v_lshl_add_u64 v[144:145], v[206:207], 0, s[10:11]
	s_mov_b32 m0, s51
	s_nop 0
	global_load_lds_dwordx4 v[144:145], off
	v_lshl_add_u64 v[144:145], v[226:227], 0, s[10:11]
	s_mov_b32 m0, s52
	s_nop 0
	global_load_lds_dwordx4 v[144:145], off
	s_waitcnt vmcnt(8)
	s_waitcnt lgkmcnt(0)
	s_barrier
	s_setprio 1
	s_waitcnt lgkmcnt(0)
	v_mfma_f32_16x16x32_bf16 v[62:65], v[152:155], v[184:187], v[62:65]
	v_mfma_f32_16x16x32_bf16 v[58:61], v[160:163], v[184:187], v[58:61]
	v_mfma_f32_16x16x32_bf16 v[46:49], v[152:155], v[192:195], v[46:49]
	v_mfma_f32_16x16x32_bf16 v[42:45], v[160:163], v[192:195], v[42:45]
	v_mfma_f32_16x16x32_bf16 v[30:33], v[152:155], v[210:213], v[30:33]
	v_mfma_f32_16x16x32_bf16 v[26:29], v[160:163], v[210:213], v[26:29]
	v_mfma_f32_16x16x32_bf16 v[14:17], v[152:155], v[218:221], v[14:17]
	v_mfma_f32_16x16x32_bf16 v[10:13], v[160:163], v[218:221], v[10:13]
	v_mfma_f32_16x16x32_bf16 v[62:65], v[156:159], v[188:191], v[62:65]
	v_mfma_f32_16x16x32_bf16 v[58:61], v[164:167], v[188:191], v[58:61]
	v_mfma_f32_16x16x32_bf16 v[46:49], v[156:159], v[198:201], v[46:49]
	v_mfma_f32_16x16x32_bf16 v[42:45], v[164:167], v[198:201], v[42:45]
	v_mfma_f32_16x16x32_bf16 v[30:33], v[156:159], v[214:217], v[30:33]
	v_mfma_f32_16x16x32_bf16 v[26:29], v[164:167], v[214:217], v[26:29]
	v_mfma_f32_16x16x32_bf16 v[14:17], v[156:159], v[222:225], v[14:17]
	v_mfma_f32_16x16x32_bf16 v[10:13], v[164:167], v[222:225], v[10:13]
	s_setprio 0
	s_setprio 1
	v_mfma_f32_16x16x32_bf16 v[54:57], v[168:171], v[184:187], v[54:57]
	v_mfma_f32_16x16x32_bf16 v[50:53], v[176:179], v[184:187], v[50:53]
	v_mfma_f32_16x16x32_bf16 v[38:41], v[168:171], v[192:195], v[38:41]
	v_mfma_f32_16x16x32_bf16 v[34:37], v[176:179], v[192:195], v[34:37]
	v_mfma_f32_16x16x32_bf16 v[22:25], v[168:171], v[210:213], v[22:25]
	v_mfma_f32_16x16x32_bf16 v[18:21], v[176:179], v[210:213], v[18:21]
	v_mfma_f32_16x16x32_bf16 v[6:9], v[168:171], v[218:221], v[6:9]
	v_mfma_f32_16x16x32_bf16 v[2:5], v[176:179], v[218:221], v[2:5]
	v_mfma_f32_16x16x32_bf16 v[54:57], v[172:175], v[188:191], v[54:57]
	v_mfma_f32_16x16x32_bf16 v[50:53], v[180:183], v[188:191], v[50:53]
	v_mfma_f32_16x16x32_bf16 v[38:41], v[172:175], v[198:201], v[38:41]
	v_mfma_f32_16x16x32_bf16 v[34:37], v[180:183], v[198:201], v[34:37]
	v_mfma_f32_16x16x32_bf16 v[22:25], v[172:175], v[214:217], v[22:25]
	v_mfma_f32_16x16x32_bf16 v[18:21], v[180:183], v[214:217], v[18:21]
	v_mfma_f32_16x16x32_bf16 v[6:9], v[172:175], v[222:225], v[6:9]
	v_mfma_f32_16x16x32_bf16 v[2:5], v[180:183], v[222:225], v[2:5]
	s_setprio 0
	s_barrier
	s_add_u32 s30, s30, 0x100
	s_addc_u32 s31, s31, 0
	s_add_u32 s15, s15, 0x100
	s_addc_u32 s17, s17, 0
	s_cmp_ge_i32 s29, s68
	s_mov_b32 s19, s29
	s_cbranch_scc0 .LBB0_2547

.Lpeel_0:
	ds_read_b128 v[144:147], v170
	ds_read_b128 v[148:151], v170 offset:1024
	ds_read_b128 v[152:155], v170 offset:2048
	ds_read_b128 v[156:159], v170 offset:3072
	ds_read_b128 v[160:163], v171
	ds_read_b128 v[164:167], v171 offset:1024
	ds_read_b128 v[174:177], v171 offset:2048
	ds_read_b128 v[178:181], v171 offset:3072
	s_add_i32 s30, s26, 2
	s_add_u32 s27, s24, 0xffea0080
	s_addc_u32 s28, s25, -1
	s_cmp_eq_u32 s22, s26
	s_cselect_b32 s26, s20, s17
	s_cselect_b32 s29, s19, s28
	s_cselect_b32 s28, s18, s27
	s_cselect_b32 s27, s21, s23
	s_add_i32 m0, s34, 0xc000
	ds_read_b128 v[182:185], v172
	ds_read_b128 v[186:189], v172 offset:1024
	ds_read_b128 v[190:193], v172 offset:2048
	ds_read_b128 v[194:197], v172 offset:3072
	ds_read_b128 v[198:201], v172 offset:4096
	ds_read_b128 v[202:205], v172 offset:5120
	ds_read_b128 v[206:209], v172 offset:6144
	ds_read_b128 v[210:213], v172 offset:7168
	global_load_lds_dwordx4 v140, s[24:25]
	s_add_i32 m0, s34, 0xe000
	s_nop 0
	global_load_lds_dwordx4 v142, s[24:25]
	s_waitcnt vmcnt(8)
	s_waitcnt lgkmcnt(0)
	s_barrier
	s_setprio 1
	s_waitcnt lgkmcnt(0)
	v_mfma_f32_16x16x32_bf16 v[126:129], v[144:147], v[182:185], 0
	v_mfma_f32_16x16x32_bf16 v[122:125], v[152:155], v[182:185], 0
	v_mfma_f32_16x16x32_bf16 v[118:121], v[144:147], v[190:193], 0
	v_mfma_f32_16x16x32_bf16 v[110:113], v[152:155], v[190:193], 0
	v_mfma_f32_16x16x32_bf16 v[94:97], v[144:147], v[198:201], 0
	v_mfma_f32_16x16x32_bf16 v[90:93], v[152:155], v[198:201], 0
	v_mfma_f32_16x16x32_bf16 v[82:85], v[144:147], v[206:209], 0
	v_mfma_f32_16x16x32_bf16 v[74:77], v[152:155], v[206:209], 0
	v_mfma_f32_16x16x32_bf16 v[126:129], v[148:151], v[186:189], v[126:129]
	v_mfma_f32_16x16x32_bf16 v[122:125], v[156:159], v[186:189], v[122:125]
	v_mfma_f32_16x16x32_bf16 v[118:121], v[148:151], v[194:197], v[118:121]
	v_mfma_f32_16x16x32_bf16 v[110:113], v[156:159], v[194:197], v[110:113]
	v_mfma_f32_16x16x32_bf16 v[94:97], v[148:151], v[202:205], v[94:97]
	v_mfma_f32_16x16x32_bf16 v[90:93], v[156:159], v[202:205], v[90:93]
	v_mfma_f32_16x16x32_bf16 v[82:85], v[148:151], v[210:213], v[82:85]
	v_mfma_f32_16x16x32_bf16 v[74:77], v[156:159], v[210:213], v[74:77]
	s_setprio 0
	s_setprio 1
	v_mfma_f32_16x16x32_bf16 v[114:117], v[160:163], v[182:185], 0
	v_mfma_f32_16x16x32_bf16 v[106:109], v[174:177], v[182:185], 0
	v_mfma_f32_16x16x32_bf16 v[102:105], v[160:163], v[190:193], 0
	v_mfma_f32_16x16x32_bf16 v[98:101], v[174:177], v[190:193], 0
	v_mfma_f32_16x16x32_bf16 v[86:89], v[160:163], v[198:201], 0
	v_mfma_f32_16x16x32_bf16 v[78:81], v[174:177], v[198:201], 0
	v_mfma_f32_16x16x32_bf16 v[70:73], v[160:163], v[206:209], 0
	v_mfma_f32_16x16x32_bf16 v[66:69], v[174:177], v[206:209], 0
	v_mfma_f32_16x16x32_bf16 v[114:117], v[164:167], v[186:189], v[114:117]
	v_mfma_f32_16x16x32_bf16 v[106:109], v[178:181], v[186:189], v[106:109]
	v_mfma_f32_16x16x32_bf16 v[102:105], v[164:167], v[194:197], v[102:105]
	v_mfma_f32_16x16x32_bf16 v[98:101], v[178:181], v[194:197], v[98:101]
	v_mfma_f32_16x16x32_bf16 v[86:89], v[164:167], v[202:205], v[86:89]
	v_mfma_f32_16x16x32_bf16 v[78:81], v[178:181], v[202:205], v[78:81]
	v_mfma_f32_16x16x32_bf16 v[70:73], v[164:167], v[210:213], v[70:73]
	v_mfma_f32_16x16x32_bf16 v[66:69], v[178:181], v[210:213], v[66:69]
	s_setprio 0
	s_barrier
	s_add_i32 s31, s57, s33
	v_lshl_add_u64 v[214:215], s[26:27], 0, v[132:133]
	s_mov_b32 m0, s31
	ds_read_b128 v[182:185], v172 offset:16384
	ds_read_b128 v[186:189], v172 offset:17408
	ds_read_b128 v[190:193], v172 offset:18432
	ds_read_b128 v[194:197], v172 offset:19456
	ds_read_b128 v[198:201], v172 offset:20480
	ds_read_b128 v[202:205], v172 offset:21504
	ds_read_b128 v[206:209], v172 offset:22528
	ds_read_b128 v[210:213], v172 offset:23552
	global_load_lds_dwordx4 v132, s[26:27]
	s_add_i32 m0, s31, 0x2000
	s_add_u32 s68, s26, 0x160000
	v_lshl_add_u64 v[216:217], s[26:27], 0, v[136:137]
	s_addc_u32 s69, s27, 0
	s_add_i32 s31, s58, s33
	global_load_lds_dwordx4 v136, s[26:27]
	s_mov_b32 m0, s31
	v_lshl_add_u64 v[220:221], s[28:29], 0, v[134:135]
	global_load_lds_dwordx4 v132, s[68:69]
	s_add_i32 m0, s31, 0x2000
	s_nop 0
	global_load_lds_dwordx4 v136, s[68:69]
	v_lshl_add_u64 v[218:219], s[28:29], 0, v[130:131]
	s_mov_b32 m0, s34
	s_nop 0
	global_load_lds_dwordx4 v130, s[28:29]
	s_mov_b32 m0, s35
	s_nop 0
	global_load_lds_dwordx4 v134, s[28:29]
	s_waitcnt vmcnt(8)
	s_waitcnt lgkmcnt(0)
	s_barrier
	s_setprio 1
	s_waitcnt lgkmcnt(0)
	v_mfma_f32_16x16x32_bf16 v[62:65], v[144:147], v[182:185], 0
	v_mfma_f32_16x16x32_bf16 v[58:61], v[152:155], v[182:185], 0
	v_mfma_f32_16x16x32_bf16 v[50:53], v[144:147], v[190:193], 0
	v_mfma_f32_16x16x32_bf16 v[42:45], v[152:155], v[190:193], 0
	v_mfma_f32_16x16x32_bf16 v[30:33], v[144:147], v[198:201], 0
	v_mfma_f32_16x16x32_bf16 v[26:29], v[152:155], v[198:201], 0
	v_mfma_f32_16x16x32_bf16 v[18:21], v[144:147], v[206:209], 0
	v_mfma_f32_16x16x32_bf16 v[10:13], v[152:155], v[206:209], 0
	v_mfma_f32_16x16x32_bf16 v[62:65], v[148:151], v[186:189], v[62:65]
	v_mfma_f32_16x16x32_bf16 v[58:61], v[156:159], v[186:189], v[58:61]
	v_mfma_f32_16x16x32_bf16 v[50:53], v[148:151], v[194:197], v[50:53]
	v_mfma_f32_16x16x32_bf16 v[42:45], v[156:159], v[194:197], v[42:45]
	v_mfma_f32_16x16x32_bf16 v[30:33], v[148:151], v[202:205], v[30:33]
	v_mfma_f32_16x16x32_bf16 v[26:29], v[156:159], v[202:205], v[26:29]
	v_mfma_f32_16x16x32_bf16 v[18:21], v[148:151], v[210:213], v[18:21]
	v_mfma_f32_16x16x32_bf16 v[10:13], v[156:159], v[210:213], v[10:13]
	s_setprio 0
	s_setprio 1
	v_mfma_f32_16x16x32_bf16 v[54:57], v[160:163], v[182:185], 0
	v_mfma_f32_16x16x32_bf16 v[46:49], v[174:177], v[182:185], 0
	v_mfma_f32_16x16x32_bf16 v[38:41], v[160:163], v[190:193], 0
	v_mfma_f32_16x16x32_bf16 v[34:37], v[174:177], v[190:193], 0
	v_mfma_f32_16x16x32_bf16 v[22:25], v[160:163], v[198:201], 0
	v_mfma_f32_16x16x32_bf16 v[14:17], v[174:177], v[198:201], 0
	v_mfma_f32_16x16x32_bf16 v[6:9], v[160:163], v[206:209], 0
	v_mfma_f32_16x16x32_bf16 v[2:5], v[174:177], v[206:209], 0
	v_mfma_f32_16x16x32_bf16 v[54:57], v[164:167], v[186:189], v[54:57]
	v_mfma_f32_16x16x32_bf16 v[46:49], v[178:181], v[186:189], v[46:49]
	v_mfma_f32_16x16x32_bf16 v[38:41], v[164:167], v[194:197], v[38:41]
	v_mfma_f32_16x16x32_bf16 v[34:37], v[178:181], v[194:197], v[34:37]
	v_mfma_f32_16x16x32_bf16 v[22:25], v[164:167], v[202:205], v[22:25]
	v_mfma_f32_16x16x32_bf16 v[14:17], v[178:181], v[202:205], v[14:17]
	v_mfma_f32_16x16x32_bf16 v[6:9], v[164:167], v[210:213], v[6:9]
	v_mfma_f32_16x16x32_bf16 v[2:5], v[178:181], v[210:213], v[2:5]
	s_setprio 0
	s_barrier
	s_add_i32 s31, 0, 0x18000
	s_add_i32 s68, 0, 0x1c000
	v_add_u32_e32 v156, s31, v168
	v_add_u32_e32 v173, s68, v168
	ds_read_b128 v[144:147], v156
	ds_read_b128 v[148:151], v156 offset:1024
	ds_read_b128 v[152:155], v156 offset:2048
	ds_read_b128 v[156:159], v156 offset:3072
	ds_read_b128 v[160:163], v173
	ds_read_b128 v[164:167], v173 offset:1024
	ds_read_b128 v[174:177], v173 offset:2048
	ds_read_b128 v[178:181], v173 offset:3072
	s_add_u32 s28, s28, 0x160000
	s_addc_u32 s29, s29, 0
	s_mov_b32 m0, s36
	ds_read_b128 v[182:185], v172 offset:32768
	ds_read_b128 v[186:189], v172 offset:33792
	ds_read_b128 v[190:193], v172 offset:34816
	ds_read_b128 v[194:197], v172 offset:35840
	ds_read_b128 v[198:201], v172 offset:36864
	ds_read_b128 v[202:205], v172 offset:37888
	ds_read_b128 v[206:209], v172 offset:38912
	ds_read_b128 v[210:213], v172 offset:39936
	global_load_lds_dwordx4 v130, s[28:29]
	v_lshl_add_u64 v[222:223], s[28:29], 0, v[134:135]
	s_mov_b32 m0, s37
	s_nop 0
	global_load_lds_dwordx4 v134, s[28:29]
	s_waitcnt vmcnt(8)
	s_waitcnt lgkmcnt(0)
	s_barrier
	s_setprio 1
	s_waitcnt lgkmcnt(0)
	v_mfma_f32_16x16x32_bf16 v[126:129], v[144:147], v[182:185], v[126:129]
	v_mfma_f32_16x16x32_bf16 v[122:125], v[152:155], v[182:185], v[122:125]
	v_mfma_f32_16x16x32_bf16 v[118:121], v[144:147], v[190:193], v[118:121]
	v_mfma_f32_16x16x32_bf16 v[110:113], v[152:155], v[190:193], v[110:113]
	v_mfma_f32_16x16x32_bf16 v[94:97], v[144:147], v[198:201], v[94:97]
	v_mfma_f32_16x16x32_bf16 v[90:93], v[152:155], v[198:201], v[90:93]
	v_mfma_f32_16x16x32_bf16 v[82:85], v[144:147], v[206:209], v[82:85]
	v_mfma_f32_16x16x32_bf16 v[74:77], v[152:155], v[206:209], v[74:77]
	v_mfma_f32_16x16x32_bf16 v[126:129], v[148:151], v[186:189], v[126:129]
	v_mfma_f32_16x16x32_bf16 v[122:125], v[156:159], v[186:189], v[122:125]
	v_mfma_f32_16x16x32_bf16 v[118:121], v[148:151], v[194:197], v[118:121]
	v_mfma_f32_16x16x32_bf16 v[110:113], v[156:159], v[194:197], v[110:113]
	v_mfma_f32_16x16x32_bf16 v[94:97], v[148:151], v[202:205], v[94:97]
	v_mfma_f32_16x16x32_bf16 v[90:93], v[156:159], v[202:205], v[90:93]
	v_mfma_f32_16x16x32_bf16 v[82:85], v[148:151], v[210:213], v[82:85]
	v_mfma_f32_16x16x32_bf16 v[74:77], v[156:159], v[210:213], v[74:77]
	s_setprio 0
	s_setprio 1
	v_mfma_f32_16x16x32_bf16 v[114:117], v[160:163], v[182:185], v[114:117]
	v_mfma_f32_16x16x32_bf16 v[106:109], v[174:177], v[182:185], v[106:109]
	v_mfma_f32_16x16x32_bf16 v[102:105], v[160:163], v[190:193], v[102:105]
	v_mfma_f32_16x16x32_bf16 v[98:101], v[174:177], v[190:193], v[98:101]
	v_mfma_f32_16x16x32_bf16 v[86:89], v[160:163], v[198:201], v[86:89]
	v_mfma_f32_16x16x32_bf16 v[78:81], v[174:177], v[198:201], v[78:81]
	v_mfma_f32_16x16x32_bf16 v[70:73], v[160:163], v[206:209], v[70:73]
	v_mfma_f32_16x16x32_bf16 v[66:69], v[174:177], v[206:209], v[66:69]
	v_mfma_f32_16x16x32_bf16 v[114:117], v[164:167], v[186:189], v[114:117]
	v_mfma_f32_16x16x32_bf16 v[106:109], v[178:181], v[186:189], v[106:109]
	v_mfma_f32_16x16x32_bf16 v[102:105], v[164:167], v[194:197], v[102:105]
	v_mfma_f32_16x16x32_bf16 v[98:101], v[178:181], v[194:197], v[98:101]
	v_mfma_f32_16x16x32_bf16 v[86:89], v[164:167], v[202:205], v[86:89]
	v_mfma_f32_16x16x32_bf16 v[78:81], v[178:181], v[202:205], v[78:81]
	v_mfma_f32_16x16x32_bf16 v[70:73], v[164:167], v[210:213], v[70:73]
	v_mfma_f32_16x16x32_bf16 v[66:69], v[178:181], v[210:213], v[66:69]
	s_setprio 0
	s_barrier
	s_add_i32 s28, s31, s33
	v_lshl_add_u64 v[214:215], v[214:215], 0, s[12:13]
	s_mov_b32 m0, s28
	ds_read_b128 v[182:185], v172 offset:49152
	ds_read_b128 v[186:189], v172 offset:50176
	ds_read_b128 v[190:193], v172 offset:51200
	ds_read_b128 v[194:197], v172 offset:52224
	ds_read_b128 v[198:201], v172 offset:53248
	ds_read_b128 v[202:205], v172 offset:54272
	ds_read_b128 v[206:209], v172 offset:55296
	ds_read_b128 v[210:213], v172 offset:56320
	global_load_lds_dwordx4 v[214:215], off
	s_add_i32 m0, s28, 0x2000
	s_add_u32 s26, s26, 0x160080
	v_lshl_add_u64 v[214:215], v[216:217], 0, s[12:13]
	s_addc_u32 s27, s27, 0
	s_add_i32 s28, s68, s33
	global_load_lds_dwordx4 v[214:215], off
	s_mov_b32 m0, s28
	s_nop 0
	global_load_lds_dwordx4 v132, s[26:27]
	s_add_i32 m0, s28, 0x2000
	s_nop 0
	global_load_lds_dwordx4 v136, s[26:27]
	v_lshl_add_u64 v[214:215], v[218:219], 0, s[12:13]
	s_mov_b32 m0, s47
	s_nop 0
	global_load_lds_dwordx4 v[214:215], off
	v_lshl_add_u64 v[214:215], v[220:221], 0, s[12:13]
	s_mov_b32 m0, s48
	s_nop 0
	global_load_lds_dwordx4 v[214:215], off
	s_waitcnt vmcnt(8)
	s_waitcnt lgkmcnt(0)
	s_barrier
	s_setprio 1
	s_waitcnt lgkmcnt(0)
	v_mfma_f32_16x16x32_bf16 v[62:65], v[144:147], v[182:185], v[62:65]
	v_mfma_f32_16x16x32_bf16 v[58:61], v[152:155], v[182:185], v[58:61]
	v_mfma_f32_16x16x32_bf16 v[50:53], v[144:147], v[190:193], v[50:53]
	v_mfma_f32_16x16x32_bf16 v[42:45], v[152:155], v[190:193], v[42:45]
	v_mfma_f32_16x16x32_bf16 v[30:33], v[144:147], v[198:201], v[30:33]
	v_mfma_f32_16x16x32_bf16 v[26:29], v[152:155], v[198:201], v[26:29]
	v_mfma_f32_16x16x32_bf16 v[18:21], v[144:147], v[206:209], v[18:21]
	v_mfma_f32_16x16x32_bf16 v[10:13], v[152:155], v[206:209], v[10:13]
	v_mfma_f32_16x16x32_bf16 v[62:65], v[148:151], v[186:189], v[62:65]
	v_mfma_f32_16x16x32_bf16 v[58:61], v[156:159], v[186:189], v[58:61]
	v_mfma_f32_16x16x32_bf16 v[50:53], v[148:151], v[194:197], v[50:53]
	v_mfma_f32_16x16x32_bf16 v[42:45], v[156:159], v[194:197], v[42:45]
	v_mfma_f32_16x16x32_bf16 v[30:33], v[148:151], v[202:205], v[30:33]
	v_mfma_f32_16x16x32_bf16 v[26:29], v[156:159], v[202:205], v[26:29]
	v_mfma_f32_16x16x32_bf16 v[18:21], v[148:151], v[210:213], v[18:21]
	v_mfma_f32_16x16x32_bf16 v[10:13], v[156:159], v[210:213], v[10:13]
	s_setprio 0
	s_setprio 1
	v_mfma_f32_16x16x32_bf16 v[54:57], v[160:163], v[182:185], v[54:57]
	v_mfma_f32_16x16x32_bf16 v[46:49], v[174:177], v[182:185], v[46:49]
	v_mfma_f32_16x16x32_bf16 v[38:41], v[160:163], v[190:193], v[38:41]
	v_mfma_f32_16x16x32_bf16 v[34:37], v[174:177], v[190:193], v[34:37]
	v_mfma_f32_16x16x32_bf16 v[22:25], v[160:163], v[198:201], v[22:25]
	v_mfma_f32_16x16x32_bf16 v[14:17], v[174:177], v[198:201], v[14:17]
	v_mfma_f32_16x16x32_bf16 v[6:9], v[160:163], v[206:209], v[6:9]
	v_mfma_f32_16x16x32_bf16 v[2:5], v[174:177], v[206:209], v[2:5]
	v_mfma_f32_16x16x32_bf16 v[54:57], v[164:167], v[186:189], v[54:57]
	v_mfma_f32_16x16x32_bf16 v[46:49], v[178:181], v[186:189], v[46:49]
	v_mfma_f32_16x16x32_bf16 v[38:41], v[164:167], v[194:197], v[38:41]
	v_mfma_f32_16x16x32_bf16 v[34:37], v[178:181], v[194:197], v[34:37]
	v_mfma_f32_16x16x32_bf16 v[22:25], v[164:167], v[202:205], v[22:25]
	v_mfma_f32_16x16x32_bf16 v[14:17], v[178:181], v[202:205], v[14:17]
	v_mfma_f32_16x16x32_bf16 v[6:9], v[164:167], v[210:213], v[6:9]
	v_mfma_f32_16x16x32_bf16 v[2:5], v[178:181], v[210:213], v[2:5]
	s_setprio 0
	s_barrier
	s_add_u32 s24, s24, 0x100
	s_addc_u32 s25, s25, 0
	s_add_u32 s17, s17, 0x100
	s_addc_u32 s23, s23, 0
	s_cmp_ge_i32 s30, s67
	s_mov_b32 s26, s30
	s_cbranch_scc0 .LBB0_2683
	s_branch .Lpeeldone_0
.LBB0_2683:
	ds_read_b128 v[144:147], v170
	ds_read_b128 v[148:151], v170 offset:1024
	ds_read_b128 v[152:155], v170 offset:2048
	ds_read_b128 v[156:159], v170 offset:3072
	ds_read_b128 v[160:163], v171
	ds_read_b128 v[164:167], v171 offset:1024
	ds_read_b128 v[174:177], v171 offset:2048
	ds_read_b128 v[178:181], v171 offset:3072
	s_add_i32 s30, s26, 2
	s_add_u32 s27, s24, 0xffea0080
	s_addc_u32 s28, s25, -1
	s_cmp_eq_u32 s22, s26
	s_cselect_b32 s26, s20, s17
	s_cselect_b32 s29, s19, s28
	s_cselect_b32 s28, s18, s27
	s_cselect_b32 s27, s21, s23
	s_add_i32 m0, s34, 0xc000
	ds_read_b128 v[182:185], v172
	ds_read_b128 v[186:189], v172 offset:1024
	ds_read_b128 v[190:193], v172 offset:2048
	ds_read_b128 v[194:197], v172 offset:3072
	ds_read_b128 v[198:201], v172 offset:4096
	ds_read_b128 v[202:205], v172 offset:5120
	ds_read_b128 v[206:209], v172 offset:6144
	ds_read_b128 v[210:213], v172 offset:7168
	global_load_lds_dwordx4 v140, s[24:25]
	s_add_i32 m0, s34, 0xe000
	s_nop 0
	global_load_lds_dwordx4 v142, s[24:25]
	s_waitcnt vmcnt(8)
	s_waitcnt lgkmcnt(0)
	s_barrier
	s_setprio 1
	s_waitcnt lgkmcnt(0)
	v_mfma_f32_16x16x32_bf16 v[126:129], v[144:147], v[182:185], v[126:129]
	v_mfma_f32_16x16x32_bf16 v[122:125], v[152:155], v[182:185], v[122:125]
	v_mfma_f32_16x16x32_bf16 v[118:121], v[144:147], v[190:193], v[118:121]
	v_mfma_f32_16x16x32_bf16 v[110:113], v[152:155], v[190:193], v[110:113]
	v_mfma_f32_16x16x32_bf16 v[94:97], v[144:147], v[198:201], v[94:97]
	v_mfma_f32_16x16x32_bf16 v[90:93], v[152:155], v[198:201], v[90:93]
	v_mfma_f32_16x16x32_bf16 v[82:85], v[144:147], v[206:209], v[82:85]
	v_mfma_f32_16x16x32_bf16 v[74:77], v[152:155], v[206:209], v[74:77]
	v_mfma_f32_16x16x32_bf16 v[126:129], v[148:151], v[186:189], v[126:129]
	v_mfma_f32_16x16x32_bf16 v[122:125], v[156:159], v[186:189], v[122:125]
	v_mfma_f32_16x16x32_bf16 v[118:121], v[148:151], v[194:197], v[118:121]
	v_mfma_f32_16x16x32_bf16 v[110:113], v[156:159], v[194:197], v[110:113]
	v_mfma_f32_16x16x32_bf16 v[94:97], v[148:151], v[202:205], v[94:97]
	v_mfma_f32_16x16x32_bf16 v[90:93], v[156:159], v[202:205], v[90:93]
	v_mfma_f32_16x16x32_bf16 v[82:85], v[148:151], v[210:213], v[82:85]
	v_mfma_f32_16x16x32_bf16 v[74:77], v[156:159], v[210:213], v[74:77]
	s_setprio 0
	s_setprio 1
	v_mfma_f32_16x16x32_bf16 v[114:117], v[160:163], v[182:185], v[114:117]
	v_mfma_f32_16x16x32_bf16 v[106:109], v[174:177], v[182:185], v[106:109]
	v_mfma_f32_16x16x32_bf16 v[102:105], v[160:163], v[190:193], v[102:105]
	v_mfma_f32_16x16x32_bf16 v[98:101], v[174:177], v[190:193], v[98:101]
	v_mfma_f32_16x16x32_bf16 v[86:89], v[160:163], v[198:201], v[86:89]
	v_mfma_f32_16x16x32_bf16 v[78:81], v[174:177], v[198:201], v[78:81]
	v_mfma_f32_16x16x32_bf16 v[70:73], v[160:163], v[206:209], v[70:73]
	v_mfma_f32_16x16x32_bf16 v[66:69], v[174:177], v[206:209], v[66:69]
	v_mfma_f32_16x16x32_bf16 v[114:117], v[164:167], v[186:189], v[114:117]
	v_mfma_f32_16x16x32_bf16 v[106:109], v[178:181], v[186:189], v[106:109]
	v_mfma_f32_16x16x32_bf16 v[102:105], v[164:167], v[194:197], v[102:105]
	v_mfma_f32_16x16x32_bf16 v[98:101], v[178:181], v[194:197], v[98:101]
	v_mfma_f32_16x16x32_bf16 v[86:89], v[164:167], v[202:205], v[86:89]
	v_mfma_f32_16x16x32_bf16 v[78:81], v[178:181], v[202:205], v[78:81]
	v_mfma_f32_16x16x32_bf16 v[70:73], v[164:167], v[210:213], v[70:73]
	v_mfma_f32_16x16x32_bf16 v[66:69], v[178:181], v[210:213], v[66:69]
	s_setprio 0
	s_barrier
	s_add_i32 s31, s57, s33
	v_lshl_add_u64 v[214:215], s[26:27], 0, v[132:133]
	s_mov_b32 m0, s31
	ds_read_b128 v[182:185], v172 offset:16384
	ds_read_b128 v[186:189], v172 offset:17408
	ds_read_b128 v[190:193], v172 offset:18432
	ds_read_b128 v[194:197], v172 offset:19456
	ds_read_b128 v[198:201], v172 offset:20480
	ds_read_b128 v[202:205], v172 offset:21504
	ds_read_b128 v[206:209], v172 offset:22528
	ds_read_b128 v[210:213], v172 offset:23552
	global_load_lds_dwordx4 v132, s[26:27]
	s_add_i32 m0, s31, 0x2000
	s_add_u32 s68, s26, 0x160000
	v_lshl_add_u64 v[216:217], s[26:27], 0, v[136:137]
	s_addc_u32 s69, s27, 0
	s_add_i32 s31, s58, s33
	global_load_lds_dwordx4 v136, s[26:27]
	s_mov_b32 m0, s31
	v_lshl_add_u64 v[220:221], s[28:29], 0, v[134:135]
	global_load_lds_dwordx4 v132, s[68:69]
	s_add_i32 m0, s31, 0x2000
	s_nop 0
	global_load_lds_dwordx4 v136, s[68:69]
	v_lshl_add_u64 v[218:219], s[28:29], 0, v[130:131]
	s_mov_b32 m0, s34
	s_nop 0
	global_load_lds_dwordx4 v130, s[28:29]
	s_mov_b32 m0, s35
	s_nop 0
	global_load_lds_dwordx4 v134, s[28:29]
	s_waitcnt vmcnt(8)
	s_waitcnt lgkmcnt(0)
	s_barrier
	s_setprio 1
	s_waitcnt lgkmcnt(0)
	v_mfma_f32_16x16x32_bf16 v[62:65], v[144:147], v[182:185], v[62:65]
	v_mfma_f32_16x16x32_bf16 v[58:61], v[152:155], v[182:185], v[58:61]
	v_mfma_f32_16x16x32_bf16 v[50:53], v[144:147], v[190:193], v[50:53]
	v_mfma_f32_16x16x32_bf16 v[42:45], v[152:155], v[190:193], v[42:45]
	v_mfma_f32_16x16x32_bf16 v[30:33], v[144:147], v[198:201], v[30:33]
	v_mfma_f32_16x16x32_bf16 v[26:29], v[152:155], v[198:201], v[26:29]
	v_mfma_f32_16x16x32_bf16 v[18:21], v[144:147], v[206:209], v[18:21]
	v_mfma_f32_16x16x32_bf16 v[10:13], v[152:155], v[206:209], v[10:13]
	v_mfma_f32_16x16x32_bf16 v[62:65], v[148:151], v[186:189], v[62:65]
	v_mfma_f32_16x16x32_bf16 v[58:61], v[156:159], v[186:189], v[58:61]
	v_mfma_f32_16x16x32_bf16 v[50:53], v[148:151], v[194:197], v[50:53]
	v_mfma_f32_16x16x32_bf16 v[42:45], v[156:159], v[194:197], v[42:45]
	v_mfma_f32_16x16x32_bf16 v[30:33], v[148:151], v[202:205], v[30:33]
	v_mfma_f32_16x16x32_bf16 v[26:29], v[156:159], v[202:205], v[26:29]
	v_mfma_f32_16x16x32_bf16 v[18:21], v[148:151], v[210:213], v[18:21]
	v_mfma_f32_16x16x32_bf16 v[10:13], v[156:159], v[210:213], v[10:13]
	s_setprio 0
	s_setprio 1
	v_mfma_f32_16x16x32_bf16 v[54:57], v[160:163], v[182:185], v[54:57]
	v_mfma_f32_16x16x32_bf16 v[46:49], v[174:177], v[182:185], v[46:49]
	v_mfma_f32_16x16x32_bf16 v[38:41], v[160:163], v[190:193], v[38:41]
	v_mfma_f32_16x16x32_bf16 v[34:37], v[174:177], v[190:193], v[34:37]
	v_mfma_f32_16x16x32_bf16 v[22:25], v[160:163], v[198:201], v[22:25]
	v_mfma_f32_16x16x32_bf16 v[14:17], v[174:177], v[198:201], v[14:17]
	v_mfma_f32_16x16x32_bf16 v[6:9], v[160:163], v[206:209], v[6:9]
	v_mfma_f32_16x16x32_bf16 v[2:5], v[174:177], v[206:209], v[2:5]
	v_mfma_f32_16x16x32_bf16 v[54:57], v[164:167], v[186:189], v[54:57]
	v_mfma_f32_16x16x32_bf16 v[46:49], v[178:181], v[186:189], v[46:49]
	v_mfma_f32_16x16x32_bf16 v[38:41], v[164:167], v[194:197], v[38:41]
	v_mfma_f32_16x16x32_bf16 v[34:37], v[178:181], v[194:197], v[34:37]
	v_mfma_f32_16x16x32_bf16 v[22:25], v[164:167], v[202:205], v[22:25]
	v_mfma_f32_16x16x32_bf16 v[14:17], v[178:181], v[202:205], v[14:17]
	v_mfma_f32_16x16x32_bf16 v[6:9], v[164:167], v[210:213], v[6:9]
	v_mfma_f32_16x16x32_bf16 v[2:5], v[178:181], v[210:213], v[2:5]
	s_setprio 0
	s_barrier
	s_add_i32 s31, 0, 0x18000
	s_add_i32 s68, 0, 0x1c000
	v_add_u32_e32 v156, s31, v168
	v_add_u32_e32 v173, s68, v168
	ds_read_b128 v[144:147], v156
	ds_read_b128 v[148:151], v156 offset:1024
	ds_read_b128 v[152:155], v156 offset:2048
	ds_read_b128 v[156:159], v156 offset:3072
	ds_read_b128 v[160:163], v173
	ds_read_b128 v[164:167], v173 offset:1024
	ds_read_b128 v[174:177], v173 offset:2048
	ds_read_b128 v[178:181], v173 offset:3072
	s_add_u32 s28, s28, 0x160000
	s_addc_u32 s29, s29, 0
	s_mov_b32 m0, s36
	ds_read_b128 v[182:185], v172 offset:32768
	ds_read_b128 v[186:189], v172 offset:33792
	ds_read_b128 v[190:193], v172 offset:34816
	ds_read_b128 v[194:197], v172 offset:35840
	ds_read_b128 v[198:201], v172 offset:36864
	ds_read_b128 v[202:205], v172 offset:37888
	ds_read_b128 v[206:209], v172 offset:38912
	ds_read_b128 v[210:213], v172 offset:39936
	global_load_lds_dwordx4 v130, s[28:29]
	v_lshl_add_u64 v[222:223], s[28:29], 0, v[134:135]
	s_mov_b32 m0, s37
	s_nop 0
	global_load_lds_dwordx4 v134, s[28:29]
	s_waitcnt vmcnt(8)
	s_waitcnt lgkmcnt(0)
	s_barrier
	s_setprio 1
	s_waitcnt lgkmcnt(0)
	v_mfma_f32_16x16x32_bf16 v[126:129], v[144:147], v[182:185], v[126:129]
	v_mfma_f32_16x16x32_bf16 v[122:125], v[152:155], v[182:185], v[122:125]
	v_mfma_f32_16x16x32_bf16 v[118:121], v[144:147], v[190:193], v[118:121]
	v_mfma_f32_16x16x32_bf16 v[110:113], v[152:155], v[190:193], v[110:113]
	v_mfma_f32_16x16x32_bf16 v[94:97], v[144:147], v[198:201], v[94:97]
	v_mfma_f32_16x16x32_bf16 v[90:93], v[152:155], v[198:201], v[90:93]
	v_mfma_f32_16x16x32_bf16 v[82:85], v[144:147], v[206:209], v[82:85]
	v_mfma_f32_16x16x32_bf16 v[74:77], v[152:155], v[206:209], v[74:77]
	v_mfma_f32_16x16x32_bf16 v[126:129], v[148:151], v[186:189], v[126:129]
	v_mfma_f32_16x16x32_bf16 v[122:125], v[156:159], v[186:189], v[122:125]
	v_mfma_f32_16x16x32_bf16 v[118:121], v[148:151], v[194:197], v[118:121]
	v_mfma_f32_16x16x32_bf16 v[110:113], v[156:159], v[194:197], v[110:113]
	v_mfma_f32_16x16x32_bf16 v[94:97], v[148:151], v[202:205], v[94:97]
	v_mfma_f32_16x16x32_bf16 v[90:93], v[156:159], v[202:205], v[90:93]
	v_mfma_f32_16x16x32_bf16 v[82:85], v[148:151], v[210:213], v[82:85]
	v_mfma_f32_16x16x32_bf16 v[74:77], v[156:159], v[210:213], v[74:77]
	s_setprio 0
	s_setprio 1
	v_mfma_f32_16x16x32_bf16 v[114:117], v[160:163], v[182:185], v[114:117]
	v_mfma_f32_16x16x32_bf16 v[106:109], v[174:177], v[182:185], v[106:109]
	v_mfma_f32_16x16x32_bf16 v[102:105], v[160:163], v[190:193], v[102:105]
	v_mfma_f32_16x16x32_bf16 v[98:101], v[174:177], v[190:193], v[98:101]
	v_mfma_f32_16x16x32_bf16 v[86:89], v[160:163], v[198:201], v[86:89]
	v_mfma_f32_16x16x32_bf16 v[78:81], v[174:177], v[198:201], v[78:81]
	v_mfma_f32_16x16x32_bf16 v[70:73], v[160:163], v[206:209], v[70:73]
	v_mfma_f32_16x16x32_bf16 v[66:69], v[174:177], v[206:209], v[66:69]
	v_mfma_f32_16x16x32_bf16 v[114:117], v[164:167], v[186:189], v[114:117]
	v_mfma_f32_16x16x32_bf16 v[106:109], v[178:181], v[186:189], v[106:109]
	v_mfma_f32_16x16x32_bf16 v[102:105], v[164:167], v[194:197], v[102:105]
	v_mfma_f32_16x16x32_bf16 v[98:101], v[178:181], v[194:197], v[98:101]
	v_mfma_f32_16x16x32_bf16 v[86:89], v[164:167], v[202:205], v[86:89]
	v_mfma_f32_16x16x32_bf16 v[78:81], v[178:181], v[202:205], v[78:81]
	v_mfma_f32_16x16x32_bf16 v[70:73], v[164:167], v[210:213], v[70:73]
	v_mfma_f32_16x16x32_bf16 v[66:69], v[178:181], v[210:213], v[66:69]
	s_setprio 0
	s_barrier
	s_add_i32 s28, s31, s33
	v_lshl_add_u64 v[214:215], v[214:215], 0, s[12:13]
	s_mov_b32 m0, s28
	ds_read_b128 v[182:185], v172 offset:49152
	ds_read_b128 v[186:189], v172 offset:50176
	ds_read_b128 v[190:193], v172 offset:51200
	ds_read_b128 v[194:197], v172 offset:52224
	ds_read_b128 v[198:201], v172 offset:53248
	ds_read_b128 v[202:205], v172 offset:54272
	ds_read_b128 v[206:209], v172 offset:55296
	ds_read_b128 v[210:213], v172 offset:56320
	global_load_lds_dwordx4 v[214:215], off
	s_add_i32 m0, s28, 0x2000
	s_add_u32 s26, s26, 0x160080
	v_lshl_add_u64 v[214:215], v[216:217], 0, s[12:13]
	s_addc_u32 s27, s27, 0
	s_add_i32 s28, s68, s33
	global_load_lds_dwordx4 v[214:215], off
	s_mov_b32 m0, s28
	s_nop 0
	global_load_lds_dwordx4 v132, s[26:27]
	s_add_i32 m0, s28, 0x2000
	s_nop 0
	global_load_lds_dwordx4 v136, s[26:27]
	v_lshl_add_u64 v[214:215], v[218:219], 0, s[12:13]
	s_mov_b32 m0, s47
	s_nop 0
	global_load_lds_dwordx4 v[214:215], off
	v_lshl_add_u64 v[214:215], v[220:221], 0, s[12:13]
	s_mov_b32 m0, s48
	s_nop 0
	global_load_lds_dwordx4 v[214:215], off
	s_waitcnt vmcnt(8)
	s_waitcnt lgkmcnt(0)
	s_barrier
	s_setprio 1
	s_waitcnt lgkmcnt(0)
	v_mfma_f32_16x16x32_bf16 v[62:65], v[144:147], v[182:185], v[62:65]
	v_mfma_f32_16x16x32_bf16 v[58:61], v[152:155], v[182:185], v[58:61]
	v_mfma_f32_16x16x32_bf16 v[50:53], v[144:147], v[190:193], v[50:53]
	v_mfma_f32_16x16x32_bf16 v[42:45], v[152:155], v[190:193], v[42:45]
	v_mfma_f32_16x16x32_bf16 v[30:33], v[144:147], v[198:201], v[30:33]
	v_mfma_f32_16x16x32_bf16 v[26:29], v[152:155], v[198:201], v[26:29]
	v_mfma_f32_16x16x32_bf16 v[18:21], v[144:147], v[206:209], v[18:21]
	v_mfma_f32_16x16x32_bf16 v[10:13], v[152:155], v[206:209], v[10:13]
	v_mfma_f32_16x16x32_bf16 v[62:65], v[148:151], v[186:189], v[62:65]
	v_mfma_f32_16x16x32_bf16 v[58:61], v[156:159], v[186:189], v[58:61]
	v_mfma_f32_16x16x32_bf16 v[50:53], v[148:151], v[194:197], v[50:53]
	v_mfma_f32_16x16x32_bf16 v[42:45], v[156:159], v[194:197], v[42:45]
	v_mfma_f32_16x16x32_bf16 v[30:33], v[148:151], v[202:205], v[30:33]
	v_mfma_f32_16x16x32_bf16 v[26:29], v[156:159], v[202:205], v[26:29]
	v_mfma_f32_16x16x32_bf16 v[18:21], v[148:151], v[210:213], v[18:21]
	v_mfma_f32_16x16x32_bf16 v[10:13], v[156:159], v[210:213], v[10:13]
	s_setprio 0
	s_setprio 1
	v_mfma_f32_16x16x32_bf16 v[54:57], v[160:163], v[182:185], v[54:57]
	v_mfma_f32_16x16x32_bf16 v[46:49], v[174:177], v[182:185], v[46:49]
	v_mfma_f32_16x16x32_bf16 v[38:41], v[160:163], v[190:193], v[38:41]
	v_mfma_f32_16x16x32_bf16 v[34:37], v[174:177], v[190:193], v[34:37]
	v_mfma_f32_16x16x32_bf16 v[22:25], v[160:163], v[198:201], v[22:25]
	v_mfma_f32_16x16x32_bf16 v[14:17], v[174:177], v[198:201], v[14:17]
	v_mfma_f32_16x16x32_bf16 v[6:9], v[160:163], v[206:209], v[6:9]
	v_mfma_f32_16x16x32_bf16 v[2:5], v[174:177], v[206:209], v[2:5]
	v_mfma_f32_16x16x32_bf16 v[54:57], v[164:167], v[186:189], v[54:57]
	v_mfma_f32_16x16x32_bf16 v[46:49], v[178:181], v[186:189], v[46:49]
	v_mfma_f32_16x16x32_bf16 v[38:41], v[164:167], v[194:197], v[38:41]
	v_mfma_f32_16x16x32_bf16 v[34:37], v[178:181], v[194:197], v[34:37]
	v_mfma_f32_16x16x32_bf16 v[22:25], v[164:167], v[202:205], v[22:25]
	v_mfma_f32_16x16x32_bf16 v[14:17], v[178:181], v[202:205], v[14:17]
	v_mfma_f32_16x16x32_bf16 v[6:9], v[164:167], v[210:213], v[6:9]
	v_mfma_f32_16x16x32_bf16 v[2:5], v[178:181], v[210:213], v[2:5]
	s_setprio 0
	s_barrier
	s_add_u32 s24, s24, 0x100
	s_addc_u32 s25, s25, 0
	s_add_u32 s17, s17, 0x100
	s_addc_u32 s23, s23, 0
	s_cmp_ge_i32 s30, s67
	s_mov_b32 s26, s30
	s_cbranch_scc0 .LBB0_2683
